# MFMA walk with the B-side fragment held for 8 consecutive MFMAs (n outer, m snake inner), accumulator pairs adjacent
# baseline (speedup 1.0000x reference)
; #define PG8_STAGE(bufoff, gbase, voff) do { _Pragma("unroll") for (int _i = 0; _i < 2; ++_i) \
;         __builtin_amdgcn_global_load_lds((const unsigned*)((const char*)(gbase) + (voff)[_i]), (PG8_LAS unsigned*)(lds + (bufoff) + ldsw + _i * 8192), 16, 0, 0); } while (0)
; #define PG8_LDA(dst, b, h) do { _Pragma("unroll") for (int m = 0; m < 4; ++m) _Pragma("unroll") for (int k = 0; k < 2; ++k) dst[m][k] = *(const PG8_LAS bf16x8*)(lds + PG8_SA(b, h) + aoff + m * 2048 + k * 1024); } while (0)
; #define PG8_LDB(dst, b, h) do { _Pragma("unroll") for (int n = 0; n < 2; ++n) _Pragma("unroll") for (int k = 0; k < 2; ++k) dst[n][k] = *(const PG8_LAS bf16x8*)(lds + PG8_SB(b, h) + boff + n * 2048 + k * 1024); } while (0)
; #define PG8_MMA(ai, bj, At, Bt) do { __builtin_amdgcn_s_setprio(1); _Pragma("unroll") for (int m = 0; m < 4; ++m) _Pragma("unroll") for (int n = 0; n < 2; ++n) _Pragma("unroll") for (int k = 0; k < 2; ++k) \
;         acc[ai][bj][m][n] = __builtin_amdgcn_mfma_f32_16x16x32_bf16(Bt[n][k], At[m][k], acc[ai][bj][m][n], 0, 0, 0); __builtin_amdgcn_s_setprio(0); } while (0)
; #define PG8_WAIT_V(n) asm volatile("s_waitcnt vmcnt(" #n ")" ::: "memory")
; #define PG8_WAIT_L(n) asm volatile("s_waitcnt lgkmcnt(" #n ")" ::: "memory")
; #define PG8_BAR __builtin_amdgcn_s_barrier()
; #define PG8_SCHED __builtin_amdgcn_sched_barrier(0)
; template <class Epi, class Sched, bool ALIGN_EPI = false, bool SP2 = false>
; __device__ __forceinline__ void gemm_phase(PG8_LAS unsigned char* lds, const Gemm g, const Sched& S, const Epi& E) {
;     ...
;             PG8_LDB(B0, 0, 0); PG8_LDB(B1, 0, 1); PG8_SCHED; PG8_LDA(At, 0, 0); PG8_STAGE(PG8_SA(1, 1), a1 + hstep, voffA);
;             PG8_WAIT_V(8); PG8_WAIT_L(0); PG8_BAR; PG8_MMA(0, 0, At, B0); PG8_MMA(0, 1, At, B1); PG8_BAR; PG8_SCHED;
;             PG8_LDA(At, 0, 1); PG8_STAGE(PG8_SB(0, 0), b2, voffB); PG8_STAGE(PG8_SB(0, 1), b2 + hstep, voffB); PG8_STAGE(PG8_SA(0, 0), a2, voffA);
;             PG8_WAIT_V(8); PG8_WAIT_L(0); PG8_BAR; PG8_MMA(1, 0, At, B0); PG8_MMA(1, 1, At, B1); PG8_BAR; PG8_SCHED;
.LBB0_110:
	ds_read_b128 v[136:139], v161
	ds_read_b128 v[140:143], v161 offset:1024
	ds_read_b128 v[176:179], v161 offset:2048
	ds_read_b128 v[180:183], v161 offset:3072
	ds_read_b128 v[184:187], v162
	ds_read_b128 v[202:205], v162 offset:1024
	ds_read_b128 v[206:209], v162 offset:2048
	ds_read_b128 v[210:213], v162 offset:3072
	s_add_u32 s28, s52, 0xfff80080
	s_addc_u32 s29, s53, -1
	s_cmp_eq_u32 s74, 28
	s_cselect_b32 s49, s25, s29
	s_cselect_b32 s48, s34, s28
	s_cselect_b32 s29, s23, s73
	s_cselect_b32 s28, s35, s72
	v_lshl_add_u64 v[246:247], s[52:53], 0, v[128:129]
	s_add_i32 m0, s9, 0xc000
	ds_read_b128 v[214:217], v163
	ds_read_b128 v[218:221], v163 offset:1024
	ds_read_b128 v[222:225], v163 offset:2048
	ds_read_b128 v[226:229], v163 offset:3072
	ds_read_b128 v[230:233], v163 offset:4096
	ds_read_b128 v[234:237], v163 offset:5120
	ds_read_b128 v[238:241], v163 offset:6144
	ds_read_b128 v[242:245], v163 offset:7168
	global_load_lds_dwordx4 v[246:247], off
	v_lshl_add_u64 v[246:247], s[52:53], 0, v[130:131]
	s_add_i32 m0, s9, 0xe000
	s_nop 0
	global_load_lds_dwordx4 v[246:247], off
	s_waitcnt vmcnt(8)
	s_waitcnt lgkmcnt(0)
	s_barrier
	s_setprio 1
	s_waitcnt lgkmcnt(0)
	v_mfma_f32_16x16x32_bf16 v[124:127], v[136:139], v[214:217], v[124:127]
	v_mfma_f32_16x16x32_bf16 v[124:127], v[140:143], v[218:221], v[124:127]
	v_mfma_f32_16x16x32_bf16 v[108:111], v[140:143], v[226:229], v[108:111]
	v_mfma_f32_16x16x32_bf16 v[108:111], v[136:139], v[222:225], v[108:111]
	v_mfma_f32_16x16x32_bf16 v[96:99], v[136:139], v[230:233], v[96:99]
	v_mfma_f32_16x16x32_bf16 v[96:99], v[140:143], v[234:237], v[96:99]
	v_mfma_f32_16x16x32_bf16 v[80:83], v[140:143], v[242:245], v[80:83]
	v_mfma_f32_16x16x32_bf16 v[80:83], v[136:139], v[238:241], v[80:83]
	v_mfma_f32_16x16x32_bf16 v[72:75], v[176:179], v[238:241], v[72:75]
	v_mfma_f32_16x16x32_bf16 v[72:75], v[180:183], v[242:245], v[72:75]
	v_mfma_f32_16x16x32_bf16 v[88:91], v[180:183], v[234:237], v[88:91]
	v_mfma_f32_16x16x32_bf16 v[88:91], v[176:179], v[230:233], v[88:91]
	v_mfma_f32_16x16x32_bf16 v[104:107], v[176:179], v[222:225], v[104:107]
	v_mfma_f32_16x16x32_bf16 v[104:107], v[180:183], v[226:229], v[104:107]
	v_mfma_f32_16x16x32_bf16 v[120:123], v[180:183], v[218:221], v[120:123]
	v_mfma_f32_16x16x32_bf16 v[120:123], v[176:179], v[214:217], v[120:123]
	s_setprio 0
	s_setprio 1
	v_mfma_f32_16x16x32_bf16 v[116:119], v[184:187], v[214:217], v[116:119]
	v_mfma_f32_16x16x32_bf16 v[116:119], v[202:205], v[218:221], v[116:119]
	v_mfma_f32_16x16x32_bf16 v[100:103], v[202:205], v[226:229], v[100:103]
	v_mfma_f32_16x16x32_bf16 v[100:103], v[184:187], v[222:225], v[100:103]
	v_mfma_f32_16x16x32_bf16 v[84:87], v[184:187], v[230:233], v[84:87]
	v_mfma_f32_16x16x32_bf16 v[84:87], v[202:205], v[234:237], v[84:87]
	v_mfma_f32_16x16x32_bf16 v[68:71], v[202:205], v[242:245], v[68:71]
	v_mfma_f32_16x16x32_bf16 v[68:71], v[184:187], v[238:241], v[68:71]
	v_mfma_f32_16x16x32_bf16 v[64:67], v[206:209], v[238:241], v[64:67]
	v_mfma_f32_16x16x32_bf16 v[64:67], v[210:213], v[242:245], v[64:67]
	v_mfma_f32_16x16x32_bf16 v[76:79], v[210:213], v[234:237], v[76:79]
	v_mfma_f32_16x16x32_bf16 v[76:79], v[206:209], v[230:233], v[76:79]
	v_mfma_f32_16x16x32_bf16 v[92:95], v[206:209], v[222:225], v[92:95]
	v_mfma_f32_16x16x32_bf16 v[92:95], v[210:213], v[226:229], v[92:95]
	s_setprio 2
	s_barrier
	v_mfma_f32_16x16x32_bf16 v[112:115], v[210:213], v[218:221], v[112:115]
	v_mfma_f32_16x16x32_bf16 v[112:115], v[206:209], v[214:217], v[112:115]
	s_setprio 0
	s_add_i32 s75, s63, s45
	v_lshl_add_u64 v[246:247], s[28:29], 0, v[166:167]
	s_mov_b32 m0, s75
	ds_read_b128 v[214:217], v163 offset:16384
	ds_read_b128 v[218:221], v163 offset:17408
	ds_read_b128 v[222:225], v163 offset:18432
	ds_read_b128 v[226:229], v163 offset:19456
	ds_read_b128 v[230:233], v163 offset:20480
	ds_read_b128 v[234:237], v163 offset:21504
	ds_read_b128 v[238:241], v163 offset:22528
	ds_read_b128 v[242:245], v163 offset:23552
	global_load_lds_dwordx4 v[246:247], off
	s_add_i32 m0, s75, 0x2000
	s_add_u32 s76, s28, 0x80000
	v_lshl_add_u64 v[248:249], s[28:29], 0, v[170:171]
	s_addc_u32 s77, s29, 0
	s_add_i32 s75, s64, s45
	global_load_lds_dwordx4 v[248:249], off
	v_lshl_add_u64 v[250:251], s[76:77], 0, v[166:167]
	s_mov_b32 m0, s75
	v_lshl_add_u64 v[252:253], s[48:49], 0, v[168:169]
	global_load_lds_dwordx4 v[250:251], off
	v_lshl_add_u64 v[250:251], s[76:77], 0, v[170:171]
	s_add_i32 m0, s75, 0x2000
	s_nop 0
	global_load_lds_dwordx4 v[250:251], off
	v_lshl_add_u64 v[250:251], s[48:49], 0, v[164:165]
	s_mov_b32 m0, s9
	s_nop 0
	global_load_lds_dwordx4 v[250:251], off
	s_mov_b32 m0, s57
	s_nop 0
	global_load_lds_dwordx4 v[252:253], off
	s_waitcnt vmcnt(8)
	s_waitcnt lgkmcnt(0)
	s_barrier
; #define PG8_STAGE(bufoff, gbase, voff) do { _Pragma("unroll") for (int _i = 0; _i < 2; ++_i) \
;         __builtin_amdgcn_global_load_lds((const unsigned*)((const char*)(gbase) + (voff)[_i]), (PG8_LAS unsigned*)(lds + (bufoff) + ldsw + _i * 8192), 16, 0, 0); } while (0)
; #define PG8_LDA(dst, b, h) do { _Pragma("unroll") for (int m = 0; m < 4; ++m) _Pragma("unroll") for (int k = 0; k < 2; ++k) dst[m][k] = *(const PG8_LAS bf16x8*)(lds + PG8_SA(b, h) + aoff + m * 2048 + k * 1024); } while (0)
; #define PG8_LDB(dst, b, h) do { _Pragma("unroll") for (int n = 0; n < 2; ++n) _Pragma("unroll") for (int k = 0; k < 2; ++k) dst[n][k] = *(const PG8_LAS bf16x8*)(lds + PG8_SB(b, h) + boff + n * 2048 + k * 1024); } while (0)
; #define PG8_MMA(ai, bj, At, Bt) do { __builtin_amdgcn_s_setprio(1); _Pragma("unroll") for (int m = 0; m < 4; ++m) _Pragma("unroll") for (int n = 0; n < 2; ++n) _Pragma("unroll") for (int k = 0; k < 2; ++k) \
;         acc[ai][bj][m][n] = __builtin_amdgcn_mfma_f32_16x16x32_bf16(Bt[n][k], At[m][k], acc[ai][bj][m][n], 0, 0, 0); __builtin_amdgcn_s_setprio(0); } while (0)
; #define PG8_WAIT_V(n) asm volatile("s_waitcnt vmcnt(" #n ")" ::: "memory")
; #define PG8_WAIT_L(n) asm volatile("s_waitcnt lgkmcnt(" #n ")" ::: "memory")
; #define PG8_BAR __builtin_amdgcn_s_barrier()
; #define PG8_SCHED __builtin_amdgcn_sched_barrier(0)
; template <class Epi, class Sched, bool ALIGN_EPI = false, bool SP2 = false>
; __device__ __forceinline__ void gemm_phase(PG8_LAS unsigned char* lds, const Gemm g, const Sched& S, const Epi& E) {
;     ...
;             PG8_WAIT_V(8); PG8_WAIT_L(0); PG8_BAR; PG8_MMA(1, 0, At, B0); PG8_MMA(1, 1, At, B1); PG8_BAR; PG8_SCHED;
;             PG8_LDB(B0, 1, 0); PG8_LDB(B1, 1, 1); PG8_SCHED; PG8_LDA(At, 1, 0); PG8_STAGE(PG8_SA(0, 1), a2 + hstep, voffA);
;             PG8_WAIT_V(8); PG8_WAIT_L(0); PG8_BAR; PG8_MMA(0, 0, At, B0); PG8_MMA(0, 1, At, B1); PG8_BAR; PG8_SCHED;
	s_setprio 1
	s_waitcnt lgkmcnt(0)
	v_mfma_f32_16x16x32_bf16 v[60:63], v[136:139], v[214:217], v[60:63]
	v_mfma_f32_16x16x32_bf16 v[60:63], v[140:143], v[218:221], v[60:63]
	v_mfma_f32_16x16x32_bf16 v[48:51], v[140:143], v[226:229], v[48:51]
	v_mfma_f32_16x16x32_bf16 v[48:51], v[136:139], v[222:225], v[48:51]
	v_mfma_f32_16x16x32_bf16 v[32:35], v[136:139], v[230:233], v[32:35]
	v_mfma_f32_16x16x32_bf16 v[32:35], v[140:143], v[234:237], v[32:35]
	v_mfma_f32_16x16x32_bf16 v[12:15], v[140:143], v[242:245], v[12:15]
	v_mfma_f32_16x16x32_bf16 v[12:15], v[136:139], v[238:241], v[12:15]
	v_mfma_f32_16x16x32_bf16 v[8:11], v[176:179], v[238:241], v[8:11]
	v_mfma_f32_16x16x32_bf16 v[8:11], v[180:183], v[242:245], v[8:11]
	v_mfma_f32_16x16x32_bf16 v[24:27], v[180:183], v[234:237], v[24:27]
	v_mfma_f32_16x16x32_bf16 v[24:27], v[176:179], v[230:233], v[24:27]
	v_mfma_f32_16x16x32_bf16 v[40:43], v[176:179], v[222:225], v[40:43]
	v_mfma_f32_16x16x32_bf16 v[40:43], v[180:183], v[226:229], v[40:43]
	v_mfma_f32_16x16x32_bf16 v[56:59], v[180:183], v[218:221], v[56:59]
	v_mfma_f32_16x16x32_bf16 v[56:59], v[176:179], v[214:217], v[56:59]
	s_setprio 0
	s_setprio 1
	v_mfma_f32_16x16x32_bf16 v[52:55], v[184:187], v[214:217], v[52:55]
	v_mfma_f32_16x16x32_bf16 v[52:55], v[202:205], v[218:221], v[52:55]
	v_mfma_f32_16x16x32_bf16 v[36:39], v[202:205], v[226:229], v[36:39]
	v_mfma_f32_16x16x32_bf16 v[36:39], v[184:187], v[222:225], v[36:39]
	v_mfma_f32_16x16x32_bf16 v[20:23], v[184:187], v[230:233], v[20:23]
	v_mfma_f32_16x16x32_bf16 v[20:23], v[202:205], v[234:237], v[20:23]
	v_mfma_f32_16x16x32_bf16 v[4:7], v[202:205], v[242:245], v[4:7]
	v_mfma_f32_16x16x32_bf16 v[4:7], v[184:187], v[238:241], v[4:7]
	v_mfma_f32_16x16x32_bf16 v[0:3], v[206:209], v[238:241], v[0:3]
	v_mfma_f32_16x16x32_bf16 v[0:3], v[210:213], v[242:245], v[0:3]
	v_mfma_f32_16x16x32_bf16 v[16:19], v[210:213], v[234:237], v[16:19]
	v_mfma_f32_16x16x32_bf16 v[16:19], v[206:209], v[230:233], v[16:19]
	v_mfma_f32_16x16x32_bf16 v[28:31], v[206:209], v[222:225], v[28:31]
	v_mfma_f32_16x16x32_bf16 v[28:31], v[210:213], v[226:229], v[28:31]
	s_setprio 2
	s_barrier
	v_mfma_f32_16x16x32_bf16 v[44:47], v[210:213], v[218:221], v[44:47]
	v_mfma_f32_16x16x32_bf16 v[44:47], v[206:209], v[214:217], v[44:47]
	s_setprio 0
	s_add_i32 s75, 0, 0x18000
	v_add_u32_e32 v144, s75, v151
	s_add_i32 s76, 0, 0x1c000
	ds_read_b128 v[136:139], v144
	ds_read_b128 v[140:143], v144 offset:1024
	ds_read_b128 v[176:179], v144 offset:2048
	ds_read_b128 v[180:183], v144 offset:3072
	v_add_u32_e32 v144, s76, v151
	ds_read_b128 v[184:187], v144
	ds_read_b128 v[202:205], v144 offset:1024
	ds_read_b128 v[206:209], v144 offset:2048
	ds_read_b128 v[210:213], v144 offset:3072
	s_add_u32 s48, s48, 0x80000
	s_addc_u32 s49, s49, 0
	s_mov_b32 m0, s58
	v_lshl_add_u64 v[200:201], s[48:49], 0, v[164:165]
	ds_read_b128 v[214:217], v163 offset:32768
	ds_read_b128 v[218:221], v163 offset:33792
	ds_read_b128 v[222:225], v163 offset:34816
	ds_read_b128 v[226:229], v163 offset:35840
	ds_read_b128 v[230:233], v163 offset:36864
	ds_read_b128 v[234:237], v163 offset:37888
	ds_read_b128 v[238:241], v163 offset:38912
	ds_read_b128 v[242:245], v163 offset:39936
	global_load_lds_dwordx4 v[200:201], off
	v_lshl_add_u64 v[200:201], s[48:49], 0, v[168:169]
	s_mov_b32 m0, s59
	s_nop 0
	global_load_lds_dwordx4 v[200:201], off
	s_waitcnt vmcnt(8)
	s_waitcnt lgkmcnt(0)
	s_barrier
	s_setprio 1
	s_waitcnt lgkmcnt(0)
	v_mfma_f32_16x16x32_bf16 v[124:127], v[136:139], v[214:217], v[124:127]
	v_mfma_f32_16x16x32_bf16 v[124:127], v[140:143], v[218:221], v[124:127]
	v_mfma_f32_16x16x32_bf16 v[108:111], v[140:143], v[226:229], v[108:111]
	v_mfma_f32_16x16x32_bf16 v[108:111], v[136:139], v[222:225], v[108:111]
	v_mfma_f32_16x16x32_bf16 v[96:99], v[136:139], v[230:233], v[96:99]
	v_mfma_f32_16x16x32_bf16 v[96:99], v[140:143], v[234:237], v[96:99]
	v_mfma_f32_16x16x32_bf16 v[80:83], v[140:143], v[242:245], v[80:83]
	v_mfma_f32_16x16x32_bf16 v[80:83], v[136:139], v[238:241], v[80:83]
	v_mfma_f32_16x16x32_bf16 v[72:75], v[176:179], v[238:241], v[72:75]
	v_mfma_f32_16x16x32_bf16 v[72:75], v[180:183], v[242:245], v[72:75]
	v_mfma_f32_16x16x32_bf16 v[88:91], v[180:183], v[234:237], v[88:91]
	v_mfma_f32_16x16x32_bf16 v[88:91], v[176:179], v[230:233], v[88:91]
	v_mfma_f32_16x16x32_bf16 v[104:107], v[176:179], v[222:225], v[104:107]
	v_mfma_f32_16x16x32_bf16 v[104:107], v[180:183], v[226:229], v[104:107]
	v_mfma_f32_16x16x32_bf16 v[120:123], v[180:183], v[218:221], v[120:123]
	v_mfma_f32_16x16x32_bf16 v[120:123], v[176:179], v[214:217], v[120:123]
	s_setprio 0
	s_setprio 1
	v_mfma_f32_16x16x32_bf16 v[116:119], v[184:187], v[214:217], v[116:119]
	v_mfma_f32_16x16x32_bf16 v[116:119], v[202:205], v[218:221], v[116:119]
	v_mfma_f32_16x16x32_bf16 v[100:103], v[202:205], v[226:229], v[100:103]
	v_mfma_f32_16x16x32_bf16 v[100:103], v[184:187], v[222:225], v[100:103]
	v_mfma_f32_16x16x32_bf16 v[84:87], v[184:187], v[230:233], v[84:87]
	v_mfma_f32_16x16x32_bf16 v[84:87], v[202:205], v[234:237], v[84:87]
	v_mfma_f32_16x16x32_bf16 v[68:71], v[202:205], v[242:245], v[68:71]
	v_mfma_f32_16x16x32_bf16 v[68:71], v[184:187], v[238:241], v[68:71]
	v_mfma_f32_16x16x32_bf16 v[64:67], v[206:209], v[238:241], v[64:67]
	v_mfma_f32_16x16x32_bf16 v[64:67], v[210:213], v[242:245], v[64:67]
	v_mfma_f32_16x16x32_bf16 v[76:79], v[210:213], v[234:237], v[76:79]
	v_mfma_f32_16x16x32_bf16 v[76:79], v[206:209], v[230:233], v[76:79]
	v_mfma_f32_16x16x32_bf16 v[92:95], v[206:209], v[222:225], v[92:95]
	v_mfma_f32_16x16x32_bf16 v[92:95], v[210:213], v[226:229], v[92:95]
	s_setprio 2
	s_barrier
; #define PG8_STAGE(bufoff, gbase, voff) do { _Pragma("unroll") for (int _i = 0; _i < 2; ++_i) \
;         __builtin_amdgcn_global_load_lds((const unsigned*)((const char*)(gbase) + (voff)[_i]), (PG8_LAS unsigned*)(lds + (bufoff) + ldsw + _i * 8192), 16, 0, 0); } while (0)
; #define PG8_LDA(dst, b, h) do { _Pragma("unroll") for (int m = 0; m < 4; ++m) _Pragma("unroll") for (int k = 0; k < 2; ++k) dst[m][k] = *(const PG8_LAS bf16x8*)(lds + PG8_SA(b, h) + aoff + m * 2048 + k * 1024); } while (0)
; #define PG8_MMA(ai, bj, At, Bt) do { __builtin_amdgcn_s_setprio(1); _Pragma("unroll") for (int m = 0; m < 4; ++m) _Pragma("unroll") for (int n = 0; n < 2; ++n) _Pragma("unroll") for (int k = 0; k < 2; ++k) \
;         acc[ai][bj][m][n] = __builtin_amdgcn_mfma_f32_16x16x32_bf16(Bt[n][k], At[m][k], acc[ai][bj][m][n], 0, 0, 0); __builtin_amdgcn_s_setprio(0); } while (0)
; #define PG8_WAIT_V(n) asm volatile("s_waitcnt vmcnt(" #n ")" ::: "memory")
; #define PG8_WAIT_L(n) asm volatile("s_waitcnt lgkmcnt(" #n ")" ::: "memory")
; #define PG8_BAR __builtin_amdgcn_s_barrier()
; #define PG8_SCHED __builtin_amdgcn_sched_barrier(0)
; template <class Epi, class Sched, bool ALIGN_EPI = false, bool SP2 = false>
; __device__ __forceinline__ void gemm_phase(PG8_LAS unsigned char* lds, const Gemm g, const Sched& S, const Epi& E) {
;     ...
;         for (int t = 0; t < nt; t += 2) {
;     ...
;             PG8_WAIT_V(8); PG8_WAIT_L(0); PG8_BAR; PG8_MMA(0, 0, At, B0); PG8_MMA(0, 1, At, B1); PG8_BAR; PG8_SCHED;
;             PG8_LDA(At, 1, 1); PG8_STAGE(PG8_SB(1, 0), b3, voffB); PG8_STAGE(PG8_SB(1, 1), b3 + hstep, voffB); PG8_STAGE(PG8_SA(1, 0), a3, voffA);
;             PG8_WAIT_V(8); PG8_WAIT_L(0); PG8_BAR; PG8_MMA(1, 0, At, B0); PG8_MMA(1, 1, At, B1); PG8_BAR; PG8_SCHED;
	v_mfma_f32_16x16x32_bf16 v[112:115], v[210:213], v[218:221], v[112:115]
	v_mfma_f32_16x16x32_bf16 v[112:115], v[206:209], v[214:217], v[112:115]
	s_setprio 0
	s_add_i32 s48, s75, s45
	v_lshl_add_u64 v[200:201], v[246:247], 0, s[18:19]
	s_mov_b32 m0, s48
	ds_read_b128 v[214:217], v163 offset:49152
	ds_read_b128 v[218:221], v163 offset:50176
	ds_read_b128 v[222:225], v163 offset:51200
	ds_read_b128 v[226:229], v163 offset:52224
	ds_read_b128 v[230:233], v163 offset:53248
	ds_read_b128 v[234:237], v163 offset:54272
	ds_read_b128 v[238:241], v163 offset:55296
	ds_read_b128 v[242:245], v163 offset:56320
	global_load_lds_dwordx4 v[200:201], off
	s_add_i32 m0, s48, 0x2000
	s_add_u32 s28, s28, 0x80080
	v_lshl_add_u64 v[200:201], v[248:249], 0, s[18:19]
	s_addc_u32 s29, s29, 0
	s_add_i32 s48, s76, s45
	global_load_lds_dwordx4 v[200:201], off
	v_lshl_add_u64 v[200:201], s[28:29], 0, v[166:167]
	s_mov_b32 m0, s48
	s_nop 0
	global_load_lds_dwordx4 v[200:201], off
	v_lshl_add_u64 v[200:201], s[28:29], 0, v[170:171]
	s_add_i32 m0, s48, 0x2000
	s_nop 0
	global_load_lds_dwordx4 v[200:201], off
	v_lshl_add_u64 v[200:201], v[250:251], 0, s[18:19]
	s_mov_b32 m0, s61
	s_nop 0
	global_load_lds_dwordx4 v[200:201], off
	v_lshl_add_u64 v[200:201], v[252:253], 0, s[18:19]
	s_mov_b32 m0, s62
	s_nop 0
	global_load_lds_dwordx4 v[200:201], off
	s_waitcnt vmcnt(8)
	s_waitcnt lgkmcnt(0)
	s_barrier
	s_setprio 1
	s_waitcnt lgkmcnt(0)
	v_mfma_f32_16x16x32_bf16 v[60:63], v[136:139], v[214:217], v[60:63]
	v_mfma_f32_16x16x32_bf16 v[60:63], v[140:143], v[218:221], v[60:63]
	v_mfma_f32_16x16x32_bf16 v[48:51], v[140:143], v[226:229], v[48:51]
	v_mfma_f32_16x16x32_bf16 v[48:51], v[136:139], v[222:225], v[48:51]
	v_mfma_f32_16x16x32_bf16 v[32:35], v[136:139], v[230:233], v[32:35]
	v_mfma_f32_16x16x32_bf16 v[32:35], v[140:143], v[234:237], v[32:35]
	v_mfma_f32_16x16x32_bf16 v[12:15], v[140:143], v[242:245], v[12:15]
	v_mfma_f32_16x16x32_bf16 v[12:15], v[136:139], v[238:241], v[12:15]
	v_mfma_f32_16x16x32_bf16 v[8:11], v[176:179], v[238:241], v[8:11]
	v_mfma_f32_16x16x32_bf16 v[8:11], v[180:183], v[242:245], v[8:11]
	v_mfma_f32_16x16x32_bf16 v[24:27], v[180:183], v[234:237], v[24:27]
	v_mfma_f32_16x16x32_bf16 v[24:27], v[176:179], v[230:233], v[24:27]
	v_mfma_f32_16x16x32_bf16 v[40:43], v[176:179], v[222:225], v[40:43]
	v_mfma_f32_16x16x32_bf16 v[40:43], v[180:183], v[226:229], v[40:43]
	v_mfma_f32_16x16x32_bf16 v[56:59], v[180:183], v[218:221], v[56:59]
	v_mfma_f32_16x16x32_bf16 v[56:59], v[176:179], v[214:217], v[56:59]
	s_setprio 0
	s_setprio 1
	v_mfma_f32_16x16x32_bf16 v[52:55], v[184:187], v[214:217], v[52:55]
	v_mfma_f32_16x16x32_bf16 v[52:55], v[202:205], v[218:221], v[52:55]
	v_mfma_f32_16x16x32_bf16 v[36:39], v[202:205], v[226:229], v[36:39]
	v_mfma_f32_16x16x32_bf16 v[36:39], v[184:187], v[222:225], v[36:39]
	v_mfma_f32_16x16x32_bf16 v[20:23], v[184:187], v[230:233], v[20:23]
	v_mfma_f32_16x16x32_bf16 v[20:23], v[202:205], v[234:237], v[20:23]
	v_mfma_f32_16x16x32_bf16 v[4:7], v[202:205], v[242:245], v[4:7]
	v_mfma_f32_16x16x32_bf16 v[4:7], v[184:187], v[238:241], v[4:7]
	v_mfma_f32_16x16x32_bf16 v[0:3], v[206:209], v[238:241], v[0:3]
	v_mfma_f32_16x16x32_bf16 v[0:3], v[210:213], v[242:245], v[0:3]
	v_mfma_f32_16x16x32_bf16 v[16:19], v[210:213], v[234:237], v[16:19]
	v_mfma_f32_16x16x32_bf16 v[16:19], v[206:209], v[230:233], v[16:19]
	v_mfma_f32_16x16x32_bf16 v[28:31], v[206:209], v[222:225], v[28:31]
	v_mfma_f32_16x16x32_bf16 v[28:31], v[210:213], v[226:229], v[28:31]
	s_setprio 2
	s_barrier
	v_mfma_f32_16x16x32_bf16 v[44:47], v[210:213], v[218:221], v[44:47]
	v_mfma_f32_16x16x32_bf16 v[44:47], v[206:209], v[214:217], v[44:47]
	s_setprio 0
	s_add_i32 s74, s74, 2
	s_add_u32 s52, s52, 0x100
	s_addc_u32 s53, s53, 0
	s_add_u32 s72, s72, 0x100
	s_addc_u32 s73, s73, 0
	s_cmp_gt_u32 s74, 29
	s_cbranch_scc0 .LBB0_110
	s_and_b64 vcc, exec, s[20:21]
	s_cbranch_vccz .LBB0_113
	s_barrier

; #define PG8_STAGE(bufoff, gbase, voff) do { _Pragma("unroll") for (int _i = 0; _i < 2; ++_i) \
;         __builtin_amdgcn_global_load_lds((const unsigned*)((const char*)(gbase) + (voff)[_i]), (PG8_LAS unsigned*)(lds + (bufoff) + ldsw + _i * 8192), 16, 0, 0); } while (0)
; #define PG8_LDA(dst, b, h) do { _Pragma("unroll") for (int m = 0; m < 4; ++m) _Pragma("unroll") for (int k = 0; k < 2; ++k) dst[m][k] = *(const PG8_LAS bf16x8*)(lds + PG8_SA(b, h) + aoff + m * 2048 + k * 1024); } while (0)
; #define PG8_LDB(dst, b, h) do { _Pragma("unroll") for (int n = 0; n < 2; ++n) _Pragma("unroll") for (int k = 0; k < 2; ++k) dst[n][k] = *(const PG8_LAS bf16x8*)(lds + PG8_SB(b, h) + boff + n * 2048 + k * 1024); } while (0)
; #define PG8_MMA(ai, bj, At, Bt) do { __builtin_amdgcn_s_setprio(1); _Pragma("unroll") for (int m = 0; m < 4; ++m) _Pragma("unroll") for (int n = 0; n < 2; ++n) _Pragma("unroll") for (int k = 0; k < 2; ++k) \
;         acc[ai][bj][m][n] = __builtin_amdgcn_mfma_f32_16x16x32_bf16(Bt[n][k], At[m][k], acc[ai][bj][m][n], 0, 0, 0); __builtin_amdgcn_s_setprio(0); } while (0)
; #define PG8_WAIT_V(n) asm volatile("s_waitcnt vmcnt(" #n ")" ::: "memory")
; #define PG8_WAIT_L(n) asm volatile("s_waitcnt lgkmcnt(" #n ")" ::: "memory")
; #define PG8_BAR __builtin_amdgcn_s_barrier()
; #define PG8_SCHED __builtin_amdgcn_sched_barrier(0)
; template <class Epi, class Sched, bool ALIGN_EPI = false, bool SP2 = false>
; __device__ __forceinline__ void gemm_phase(PG8_LAS unsigned char* lds, const Gemm g, const Sched& S, const Epi& E) {
;     ...
;             PG8_LDB(B0, 0, 0); PG8_LDB(B1, 0, 1); PG8_SCHED; PG8_LDA(At, 0, 0); PG8_STAGE(PG8_SA(1, 1), a1 + hstep, voffA);
;             PG8_WAIT_V(8); PG8_WAIT_L(0); PG8_BAR; PG8_MMA(0, 0, At, B0); PG8_MMA(0, 1, At, B1); PG8_BAR; PG8_SCHED;
;             PG8_LDA(At, 0, 1); PG8_STAGE(PG8_SB(0, 0), b2, voffB); PG8_STAGE(PG8_SB(0, 1), b2 + hstep, voffB); PG8_STAGE(PG8_SA(0, 0), a2, voffA);
;             PG8_WAIT_V(8); PG8_WAIT_L(0); PG8_BAR; PG8_MMA(1, 0, At, B0); PG8_MMA(1, 1, At, B1); PG8_BAR; PG8_SCHED;
.LBB0_177:
	ds_read_b128 v[80:83], v171
	ds_read_b128 v[84:87], v171 offset:1024
	ds_read_b128 v[92:95], v171 offset:2048
	ds_read_b128 v[100:103], v171 offset:3072
	ds_read_b128 v[144:147], v206
	ds_read_b128 v[148:151], v206 offset:1024
	ds_read_b128 v[152:155], v206 offset:2048
	ds_read_b128 v[156:159], v206 offset:3072
	s_add_u32 s28, s72, 0xffea0080
	s_addc_u32 s29, s73, -1
	s_cmpk_eq_i32 s76, 0x54
	s_cselect_b32 s49, s69, s29
	s_cselect_b32 s48, s68, s28
	s_cselect_b32 s29, s71, s35
	s_cselect_b32 s28, s70, s34
	v_lshl_add_u64 v[234:235], s[72:73], 0, v[174:175]
	s_add_i32 m0, s40, 0xc000
	ds_read_b128 v[180:183], v207
	ds_read_b128 v[184:187], v207 offset:1024
	ds_read_b128 v[210:213], v207 offset:2048
	ds_read_b128 v[214:217], v207 offset:3072
	ds_read_b128 v[218:221], v207 offset:4096
	ds_read_b128 v[222:225], v207 offset:5120
	ds_read_b128 v[226:229], v207 offset:6144
	ds_read_b128 v[230:233], v207 offset:7168
	global_load_lds_dwordx4 v[234:235], off
	v_lshl_add_u64 v[234:235], s[72:73], 0, v[176:177]
	s_add_i32 m0, s40, 0xe000
	s_nop 0
	global_load_lds_dwordx4 v[234:235], off
	s_waitcnt vmcnt(8)
	s_waitcnt lgkmcnt(0)
	s_barrier
	s_setprio 1
	s_waitcnt lgkmcnt(0)
	v_mfma_f32_16x16x32_bf16 v[140:143], v[80:83], v[180:183], v[140:143]
	v_mfma_f32_16x16x32_bf16 v[140:143], v[84:87], v[184:187], v[140:143]
	v_mfma_f32_16x16x32_bf16 v[124:127], v[84:87], v[214:217], v[124:127]
	v_mfma_f32_16x16x32_bf16 v[124:127], v[80:83], v[210:213], v[124:127]
	v_mfma_f32_16x16x32_bf16 v[108:111], v[80:83], v[218:221], v[108:111]
	v_mfma_f32_16x16x32_bf16 v[108:111], v[84:87], v[222:225], v[108:111]
	v_mfma_f32_16x16x32_bf16 v[76:79], v[84:87], v[230:233], v[76:79]
	v_mfma_f32_16x16x32_bf16 v[76:79], v[80:83], v[226:229], v[76:79]
	v_mfma_f32_16x16x32_bf16 v[72:75], v[92:95], v[226:229], v[72:75]
	v_mfma_f32_16x16x32_bf16 v[72:75], v[100:103], v[230:233], v[72:75]
	v_mfma_f32_16x16x32_bf16 v[104:107], v[100:103], v[222:225], v[104:107]
	v_mfma_f32_16x16x32_bf16 v[104:107], v[92:95], v[218:221], v[104:107]
	v_mfma_f32_16x16x32_bf16 v[120:123], v[92:95], v[210:213], v[120:123]
	v_mfma_f32_16x16x32_bf16 v[120:123], v[100:103], v[214:217], v[120:123]
	v_mfma_f32_16x16x32_bf16 v[136:139], v[100:103], v[184:187], v[136:139]
	v_mfma_f32_16x16x32_bf16 v[136:139], v[92:95], v[180:183], v[136:139]
	s_setprio 0
	s_setprio 1
	v_mfma_f32_16x16x32_bf16 v[132:135], v[144:147], v[180:183], v[132:135]
	v_mfma_f32_16x16x32_bf16 v[132:135], v[148:151], v[184:187], v[132:135]
	v_mfma_f32_16x16x32_bf16 v[116:119], v[148:151], v[214:217], v[116:119]
	v_mfma_f32_16x16x32_bf16 v[116:119], v[144:147], v[210:213], v[116:119]
	v_mfma_f32_16x16x32_bf16 v[96:99], v[144:147], v[218:221], v[96:99]
	v_mfma_f32_16x16x32_bf16 v[96:99], v[148:151], v[222:225], v[96:99]
	v_mfma_f32_16x16x32_bf16 v[68:71], v[148:151], v[230:233], v[68:71]
	v_mfma_f32_16x16x32_bf16 v[68:71], v[144:147], v[226:229], v[68:71]
	v_mfma_f32_16x16x32_bf16 v[64:67], v[152:155], v[226:229], v[64:67]
	v_mfma_f32_16x16x32_bf16 v[64:67], v[156:159], v[230:233], v[64:67]
	v_mfma_f32_16x16x32_bf16 v[88:91], v[156:159], v[222:225], v[88:91]
	v_mfma_f32_16x16x32_bf16 v[88:91], v[152:155], v[218:221], v[88:91]
	v_mfma_f32_16x16x32_bf16 v[112:115], v[152:155], v[210:213], v[112:115]
	v_mfma_f32_16x16x32_bf16 v[112:115], v[156:159], v[214:217], v[112:115]
	s_setprio 2
	s_barrier
	v_mfma_f32_16x16x32_bf16 v[128:131], v[156:159], v[184:187], v[128:131]
	v_mfma_f32_16x16x32_bf16 v[128:131], v[152:155], v[180:183], v[128:131]
	s_setprio 0
	s_add_i32 s77, s61, s13
	v_lshl_add_u64 v[234:235], s[28:29], 0, v[160:161]
	s_mov_b32 m0, s77
	ds_read_b128 v[180:183], v207 offset:16384
	ds_read_b128 v[184:187], v207 offset:17408
	ds_read_b128 v[210:213], v207 offset:18432
	ds_read_b128 v[214:217], v207 offset:19456
	ds_read_b128 v[218:221], v207 offset:20480
	ds_read_b128 v[222:225], v207 offset:21504
	ds_read_b128 v[226:229], v207 offset:22528
	ds_read_b128 v[230:233], v207 offset:23552
	global_load_lds_dwordx4 v[234:235], off
	s_add_i32 m0, s77, 0x2000
	s_add_u32 s78, s28, 0x160000
	v_lshl_add_u64 v[236:237], s[28:29], 0, v[162:163]
	s_addc_u32 s79, s29, 0
	s_add_i32 s77, s62, s13
	global_load_lds_dwordx4 v[236:237], off
	v_lshl_add_u64 v[238:239], s[78:79], 0, v[160:161]
	s_mov_b32 m0, s77
	v_lshl_add_u64 v[240:241], s[48:49], 0, v[162:163]
	global_load_lds_dwordx4 v[238:239], off
	v_lshl_add_u64 v[238:239], s[78:79], 0, v[162:163]
	s_add_i32 m0, s77, 0x2000
	s_nop 0
	global_load_lds_dwordx4 v[238:239], off
	v_lshl_add_u64 v[238:239], s[48:49], 0, v[160:161]
	s_mov_b32 m0, s40
	s_nop 0
	global_load_lds_dwordx4 v[238:239], off
	s_mov_b32 m0, s41
	s_nop 0
	global_load_lds_dwordx4 v[240:241], off
	s_waitcnt vmcnt(8)
	s_waitcnt lgkmcnt(0)
	s_barrier
; #define PG8_STAGE(bufoff, gbase, voff) do { _Pragma("unroll") for (int _i = 0; _i < 2; ++_i) \
;         __builtin_amdgcn_global_load_lds((const unsigned*)((const char*)(gbase) + (voff)[_i]), (PG8_LAS unsigned*)(lds + (bufoff) + ldsw + _i * 8192), 16, 0, 0); } while (0)
; #define PG8_LDA(dst, b, h) do { _Pragma("unroll") for (int m = 0; m < 4; ++m) _Pragma("unroll") for (int k = 0; k < 2; ++k) dst[m][k] = *(const PG8_LAS bf16x8*)(lds + PG8_SA(b, h) + aoff + m * 2048 + k * 1024); } while (0)
; #define PG8_LDB(dst, b, h) do { _Pragma("unroll") for (int n = 0; n < 2; ++n) _Pragma("unroll") for (int k = 0; k < 2; ++k) dst[n][k] = *(const PG8_LAS bf16x8*)(lds + PG8_SB(b, h) + boff + n * 2048 + k * 1024); } while (0)
; #define PG8_MMA(ai, bj, At, Bt) do { __builtin_amdgcn_s_setprio(1); _Pragma("unroll") for (int m = 0; m < 4; ++m) _Pragma("unroll") for (int n = 0; n < 2; ++n) _Pragma("unroll") for (int k = 0; k < 2; ++k) \
;         acc[ai][bj][m][n] = __builtin_amdgcn_mfma_f32_16x16x32_bf16(Bt[n][k], At[m][k], acc[ai][bj][m][n], 0, 0, 0); __builtin_amdgcn_s_setprio(0); } while (0)
; #define PG8_WAIT_V(n) asm volatile("s_waitcnt vmcnt(" #n ")" ::: "memory")
; #define PG8_WAIT_L(n) asm volatile("s_waitcnt lgkmcnt(" #n ")" ::: "memory")
; #define PG8_BAR __builtin_amdgcn_s_barrier()
; #define PG8_SCHED __builtin_amdgcn_sched_barrier(0)
; template <class Epi, class Sched, bool ALIGN_EPI = false, bool SP2 = false>
; __device__ __forceinline__ void gemm_phase(PG8_LAS unsigned char* lds, const Gemm g, const Sched& S, const Epi& E) {
;     ...
;             PG8_WAIT_V(8); PG8_WAIT_L(0); PG8_BAR; PG8_MMA(1, 0, At, B0); PG8_MMA(1, 1, At, B1); PG8_BAR; PG8_SCHED;
;             PG8_LDB(B0, 1, 0); PG8_LDB(B1, 1, 1); PG8_SCHED; PG8_LDA(At, 1, 0); PG8_STAGE(PG8_SA(0, 1), a2 + hstep, voffA);
;             PG8_WAIT_V(8); PG8_WAIT_L(0); PG8_BAR; PG8_MMA(0, 0, At, B0); PG8_MMA(0, 1, At, B1); PG8_BAR; PG8_SCHED;
	s_setprio 1
	s_waitcnt lgkmcnt(0)
	v_mfma_f32_16x16x32_bf16 v[60:63], v[80:83], v[180:183], v[60:63]
	v_mfma_f32_16x16x32_bf16 v[60:63], v[84:87], v[184:187], v[60:63]
	v_mfma_f32_16x16x32_bf16 v[44:47], v[84:87], v[214:217], v[44:47]
	v_mfma_f32_16x16x32_bf16 v[44:47], v[80:83], v[210:213], v[44:47]
	v_mfma_f32_16x16x32_bf16 v[28:31], v[80:83], v[218:221], v[28:31]
	v_mfma_f32_16x16x32_bf16 v[28:31], v[84:87], v[222:225], v[28:31]
	v_mfma_f32_16x16x32_bf16 v[12:15], v[84:87], v[230:233], v[12:15]
	v_mfma_f32_16x16x32_bf16 v[12:15], v[80:83], v[226:229], v[12:15]
	v_mfma_f32_16x16x32_bf16 v[8:11], v[92:95], v[226:229], v[8:11]
	v_mfma_f32_16x16x32_bf16 v[8:11], v[100:103], v[230:233], v[8:11]
	v_mfma_f32_16x16x32_bf16 v[24:27], v[100:103], v[222:225], v[24:27]
	v_mfma_f32_16x16x32_bf16 v[24:27], v[92:95], v[218:221], v[24:27]
	v_mfma_f32_16x16x32_bf16 v[40:43], v[92:95], v[210:213], v[40:43]
	v_mfma_f32_16x16x32_bf16 v[40:43], v[100:103], v[214:217], v[40:43]
	v_mfma_f32_16x16x32_bf16 v[56:59], v[100:103], v[184:187], v[56:59]
	v_mfma_f32_16x16x32_bf16 v[56:59], v[92:95], v[180:183], v[56:59]
	s_setprio 0
	s_setprio 1
	v_mfma_f32_16x16x32_bf16 v[52:55], v[144:147], v[180:183], v[52:55]
	v_mfma_f32_16x16x32_bf16 v[52:55], v[148:151], v[184:187], v[52:55]
	v_mfma_f32_16x16x32_bf16 v[36:39], v[148:151], v[214:217], v[36:39]
	v_mfma_f32_16x16x32_bf16 v[36:39], v[144:147], v[210:213], v[36:39]
	v_mfma_f32_16x16x32_bf16 v[20:23], v[144:147], v[218:221], v[20:23]
	v_mfma_f32_16x16x32_bf16 v[20:23], v[148:151], v[222:225], v[20:23]
	v_mfma_f32_16x16x32_bf16 v[4:7], v[148:151], v[230:233], v[4:7]
	v_mfma_f32_16x16x32_bf16 v[4:7], v[144:147], v[226:229], v[4:7]
	v_mfma_f32_16x16x32_bf16 v[0:3], v[152:155], v[226:229], v[0:3]
	v_mfma_f32_16x16x32_bf16 v[0:3], v[156:159], v[230:233], v[0:3]
	v_mfma_f32_16x16x32_bf16 v[16:19], v[156:159], v[222:225], v[16:19]
	v_mfma_f32_16x16x32_bf16 v[16:19], v[152:155], v[218:221], v[16:19]
	v_mfma_f32_16x16x32_bf16 v[32:35], v[152:155], v[210:213], v[32:35]
	v_mfma_f32_16x16x32_bf16 v[32:35], v[156:159], v[214:217], v[32:35]
	s_setprio 2
	s_barrier
	v_mfma_f32_16x16x32_bf16 v[48:51], v[156:159], v[184:187], v[48:51]
	v_mfma_f32_16x16x32_bf16 v[48:51], v[152:155], v[180:183], v[48:51]
	s_setprio 0
	s_add_i32 s77, 0, 0x18000
	s_add_i32 s78, 0, 0x1c000
	v_add_u32_e32 v100, s77, v167
	v_add_u32_e32 v156, s78, v167
	ds_read_b128 v[80:83], v100
	ds_read_b128 v[84:87], v100 offset:1024
	ds_read_b128 v[92:95], v100 offset:2048
	ds_read_b128 v[100:103], v100 offset:3072
	ds_read_b128 v[144:147], v156
	ds_read_b128 v[148:151], v156 offset:1024
	ds_read_b128 v[152:155], v156 offset:2048
	ds_read_b128 v[156:159], v156 offset:3072
	s_add_u32 s48, s48, 0x160000
	s_addc_u32 s49, s49, 0
	s_mov_b32 m0, s44
	v_lshl_add_u64 v[242:243], s[48:49], 0, v[160:161]
	ds_read_b128 v[180:183], v207 offset:32768
	ds_read_b128 v[184:187], v207 offset:33792
	ds_read_b128 v[210:213], v207 offset:34816
	ds_read_b128 v[214:217], v207 offset:35840
	ds_read_b128 v[218:221], v207 offset:36864
	ds_read_b128 v[222:225], v207 offset:37888
	ds_read_b128 v[226:229], v207 offset:38912
	ds_read_b128 v[230:233], v207 offset:39936
	global_load_lds_dwordx4 v[242:243], off
	v_lshl_add_u64 v[242:243], s[48:49], 0, v[162:163]
	s_mov_b32 m0, s45
	s_nop 0
	global_load_lds_dwordx4 v[242:243], off
	s_waitcnt vmcnt(8)
	s_waitcnt lgkmcnt(0)
	s_barrier
	s_setprio 1
	s_waitcnt lgkmcnt(0)
	v_mfma_f32_16x16x32_bf16 v[140:143], v[80:83], v[180:183], v[140:143]
	v_mfma_f32_16x16x32_bf16 v[140:143], v[84:87], v[184:187], v[140:143]
	v_mfma_f32_16x16x32_bf16 v[124:127], v[84:87], v[214:217], v[124:127]
	v_mfma_f32_16x16x32_bf16 v[124:127], v[80:83], v[210:213], v[124:127]
	v_mfma_f32_16x16x32_bf16 v[108:111], v[80:83], v[218:221], v[108:111]
	v_mfma_f32_16x16x32_bf16 v[108:111], v[84:87], v[222:225], v[108:111]
	v_mfma_f32_16x16x32_bf16 v[76:79], v[84:87], v[230:233], v[76:79]
	v_mfma_f32_16x16x32_bf16 v[76:79], v[80:83], v[226:229], v[76:79]
	v_mfma_f32_16x16x32_bf16 v[72:75], v[92:95], v[226:229], v[72:75]
	v_mfma_f32_16x16x32_bf16 v[72:75], v[100:103], v[230:233], v[72:75]
	v_mfma_f32_16x16x32_bf16 v[104:107], v[100:103], v[222:225], v[104:107]
	v_mfma_f32_16x16x32_bf16 v[104:107], v[92:95], v[218:221], v[104:107]
	v_mfma_f32_16x16x32_bf16 v[120:123], v[92:95], v[210:213], v[120:123]
	v_mfma_f32_16x16x32_bf16 v[120:123], v[100:103], v[214:217], v[120:123]
	v_mfma_f32_16x16x32_bf16 v[136:139], v[100:103], v[184:187], v[136:139]
	v_mfma_f32_16x16x32_bf16 v[136:139], v[92:95], v[180:183], v[136:139]
	s_setprio 0
	s_setprio 1
	v_mfma_f32_16x16x32_bf16 v[132:135], v[144:147], v[180:183], v[132:135]
	v_mfma_f32_16x16x32_bf16 v[132:135], v[148:151], v[184:187], v[132:135]
	v_mfma_f32_16x16x32_bf16 v[116:119], v[148:151], v[214:217], v[116:119]
	v_mfma_f32_16x16x32_bf16 v[116:119], v[144:147], v[210:213], v[116:119]
	v_mfma_f32_16x16x32_bf16 v[96:99], v[144:147], v[218:221], v[96:99]
	v_mfma_f32_16x16x32_bf16 v[96:99], v[148:151], v[222:225], v[96:99]
	v_mfma_f32_16x16x32_bf16 v[68:71], v[148:151], v[230:233], v[68:71]
	v_mfma_f32_16x16x32_bf16 v[68:71], v[144:147], v[226:229], v[68:71]
	v_mfma_f32_16x16x32_bf16 v[64:67], v[152:155], v[226:229], v[64:67]
	v_mfma_f32_16x16x32_bf16 v[64:67], v[156:159], v[230:233], v[64:67]
	v_mfma_f32_16x16x32_bf16 v[88:91], v[156:159], v[222:225], v[88:91]
	v_mfma_f32_16x16x32_bf16 v[88:91], v[152:155], v[218:221], v[88:91]
	v_mfma_f32_16x16x32_bf16 v[112:115], v[152:155], v[210:213], v[112:115]
	v_mfma_f32_16x16x32_bf16 v[112:115], v[156:159], v[214:217], v[112:115]
	s_setprio 2
	s_barrier
; #define PG8_STAGE(bufoff, gbase, voff) do { _Pragma("unroll") for (int _i = 0; _i < 2; ++_i) \
;         __builtin_amdgcn_global_load_lds((const unsigned*)((const char*)(gbase) + (voff)[_i]), (PG8_LAS unsigned*)(lds + (bufoff) + ldsw + _i * 8192), 16, 0, 0); } while (0)
; #define PG8_LDA(dst, b, h) do { _Pragma("unroll") for (int m = 0; m < 4; ++m) _Pragma("unroll") for (int k = 0; k < 2; ++k) dst[m][k] = *(const PG8_LAS bf16x8*)(lds + PG8_SA(b, h) + aoff + m * 2048 + k * 1024); } while (0)
; #define PG8_MMA(ai, bj, At, Bt) do { __builtin_amdgcn_s_setprio(1); _Pragma("unroll") for (int m = 0; m < 4; ++m) _Pragma("unroll") for (int n = 0; n < 2; ++n) _Pragma("unroll") for (int k = 0; k < 2; ++k) \
;         acc[ai][bj][m][n] = __builtin_amdgcn_mfma_f32_16x16x32_bf16(Bt[n][k], At[m][k], acc[ai][bj][m][n], 0, 0, 0); __builtin_amdgcn_s_setprio(0); } while (0)
; #define PG8_WAIT_V(n) asm volatile("s_waitcnt vmcnt(" #n ")" ::: "memory")
; #define PG8_WAIT_L(n) asm volatile("s_waitcnt lgkmcnt(" #n ")" ::: "memory")
; #define PG8_BAR __builtin_amdgcn_s_barrier()
; #define PG8_SCHED __builtin_amdgcn_sched_barrier(0)
; template <class Epi, class Sched, bool ALIGN_EPI = false, bool SP2 = false>
; __device__ __forceinline__ void gemm_phase(PG8_LAS unsigned char* lds, const Gemm g, const Sched& S, const Epi& E) {
;     ...
;         for (int t = 0; t < nt; t += 2) {
;     ...
;             PG8_WAIT_V(8); PG8_WAIT_L(0); PG8_BAR; PG8_MMA(0, 0, At, B0); PG8_MMA(0, 1, At, B1); PG8_BAR; PG8_SCHED;
;             PG8_LDA(At, 1, 1); PG8_STAGE(PG8_SB(1, 0), b3, voffB); PG8_STAGE(PG8_SB(1, 1), b3 + hstep, voffB); PG8_STAGE(PG8_SA(1, 0), a3, voffA);
;             PG8_WAIT_V(8); PG8_WAIT_L(0); PG8_BAR; PG8_MMA(1, 0, At, B0); PG8_MMA(1, 1, At, B1); PG8_BAR; PG8_SCHED;
	v_mfma_f32_16x16x32_bf16 v[128:131], v[156:159], v[184:187], v[128:131]
	v_mfma_f32_16x16x32_bf16 v[128:131], v[152:155], v[180:183], v[128:131]
	s_setprio 0
	s_add_i32 s48, s77, s13
	v_lshl_add_u64 v[234:235], v[234:235], 0, s[50:51]
	s_mov_b32 m0, s48
	ds_read_b128 v[180:183], v207 offset:49152
	ds_read_b128 v[184:187], v207 offset:50176
	ds_read_b128 v[210:213], v207 offset:51200
	ds_read_b128 v[214:217], v207 offset:52224
	ds_read_b128 v[218:221], v207 offset:53248
	ds_read_b128 v[222:225], v207 offset:54272
	ds_read_b128 v[226:229], v207 offset:55296
	ds_read_b128 v[230:233], v207 offset:56320
	global_load_lds_dwordx4 v[234:235], off
	s_add_i32 m0, s48, 0x2000
	s_add_u32 s28, s28, 0x160080
	v_lshl_add_u64 v[234:235], v[236:237], 0, s[50:51]
	s_addc_u32 s29, s29, 0
	s_add_i32 s48, s78, s13
	global_load_lds_dwordx4 v[234:235], off
	v_lshl_add_u64 v[234:235], s[28:29], 0, v[160:161]
	s_mov_b32 m0, s48
	s_nop 0
	global_load_lds_dwordx4 v[234:235], off
	v_lshl_add_u64 v[234:235], s[28:29], 0, v[162:163]
	s_add_i32 m0, s48, 0x2000
	s_nop 0
	global_load_lds_dwordx4 v[234:235], off
	v_lshl_add_u64 v[234:235], v[238:239], 0, s[50:51]
	s_mov_b32 m0, s56
	s_nop 0
	global_load_lds_dwordx4 v[234:235], off
	v_lshl_add_u64 v[234:235], v[240:241], 0, s[50:51]
	s_mov_b32 m0, s57
	s_nop 0
	global_load_lds_dwordx4 v[234:235], off
	s_waitcnt vmcnt(8)
	s_waitcnt lgkmcnt(0)
	s_barrier
	s_setprio 1
	s_waitcnt lgkmcnt(0)
	v_mfma_f32_16x16x32_bf16 v[60:63], v[80:83], v[180:183], v[60:63]
	v_mfma_f32_16x16x32_bf16 v[60:63], v[84:87], v[184:187], v[60:63]
	v_mfma_f32_16x16x32_bf16 v[44:47], v[84:87], v[214:217], v[44:47]
	v_mfma_f32_16x16x32_bf16 v[44:47], v[80:83], v[210:213], v[44:47]
	v_mfma_f32_16x16x32_bf16 v[28:31], v[80:83], v[218:221], v[28:31]
	v_mfma_f32_16x16x32_bf16 v[28:31], v[84:87], v[222:225], v[28:31]
	v_mfma_f32_16x16x32_bf16 v[12:15], v[84:87], v[230:233], v[12:15]
	v_mfma_f32_16x16x32_bf16 v[12:15], v[80:83], v[226:229], v[12:15]
	v_mfma_f32_16x16x32_bf16 v[8:11], v[92:95], v[226:229], v[8:11]
	v_mfma_f32_16x16x32_bf16 v[8:11], v[100:103], v[230:233], v[8:11]
	v_mfma_f32_16x16x32_bf16 v[24:27], v[100:103], v[222:225], v[24:27]
	v_mfma_f32_16x16x32_bf16 v[24:27], v[92:95], v[218:221], v[24:27]
	v_mfma_f32_16x16x32_bf16 v[40:43], v[92:95], v[210:213], v[40:43]
	v_mfma_f32_16x16x32_bf16 v[40:43], v[100:103], v[214:217], v[40:43]
	v_mfma_f32_16x16x32_bf16 v[56:59], v[100:103], v[184:187], v[56:59]
	v_mfma_f32_16x16x32_bf16 v[56:59], v[92:95], v[180:183], v[56:59]
	s_setprio 0
	s_setprio 1
	v_mfma_f32_16x16x32_bf16 v[52:55], v[144:147], v[180:183], v[52:55]
	v_mfma_f32_16x16x32_bf16 v[52:55], v[148:151], v[184:187], v[52:55]
	v_mfma_f32_16x16x32_bf16 v[36:39], v[148:151], v[214:217], v[36:39]
	v_mfma_f32_16x16x32_bf16 v[36:39], v[144:147], v[210:213], v[36:39]
	v_mfma_f32_16x16x32_bf16 v[20:23], v[144:147], v[218:221], v[20:23]
	v_mfma_f32_16x16x32_bf16 v[20:23], v[148:151], v[222:225], v[20:23]
	v_mfma_f32_16x16x32_bf16 v[4:7], v[148:151], v[230:233], v[4:7]
	v_mfma_f32_16x16x32_bf16 v[4:7], v[144:147], v[226:229], v[4:7]
	v_mfma_f32_16x16x32_bf16 v[0:3], v[152:155], v[226:229], v[0:3]
	v_mfma_f32_16x16x32_bf16 v[0:3], v[156:159], v[230:233], v[0:3]
	v_mfma_f32_16x16x32_bf16 v[16:19], v[156:159], v[222:225], v[16:19]
	v_mfma_f32_16x16x32_bf16 v[16:19], v[152:155], v[218:221], v[16:19]
	v_mfma_f32_16x16x32_bf16 v[32:35], v[152:155], v[210:213], v[32:35]
	v_mfma_f32_16x16x32_bf16 v[32:35], v[156:159], v[214:217], v[32:35]
	s_setprio 2
	s_barrier
	v_mfma_f32_16x16x32_bf16 v[48:51], v[156:159], v[184:187], v[48:51]
	v_mfma_f32_16x16x32_bf16 v[48:51], v[152:155], v[180:183], v[48:51]
	s_setprio 0
	s_add_i32 s76, s76, 2
	s_add_u32 s72, s72, 0x100
	s_addc_u32 s73, s73, 0
	s_add_u32 s34, s34, 0x100
	s_addc_u32 s35, s35, 0
	s_cmpk_gt_u32 s76, 0x55
	s_cbranch_scc0 .LBB0_177
	s_and_b64 vcc, exec, s[52:53]
	s_cbranch_vccz .LBB0_180
	s_barrier

; #define PG8_STAGE(bufoff, gbase, voff) do { _Pragma("unroll") for (int _i = 0; _i < 2; ++_i) \
;         __builtin_amdgcn_global_load_lds((const unsigned*)((const char*)(gbase) + (voff)[_i]), (PG8_LAS unsigned*)(lds + (bufoff) + ldsw + _i * 8192), 16, 0, 0); } while (0)
; #define PG8_LDA(dst, b, h) do { _Pragma("unroll") for (int m = 0; m < 4; ++m) _Pragma("unroll") for (int k = 0; k < 2; ++k) dst[m][k] = *(const PG8_LAS bf16x8*)(lds + PG8_SA(b, h) + aoff + m * 2048 + k * 1024); } while (0)
; #define PG8_LDB(dst, b, h) do { _Pragma("unroll") for (int n = 0; n < 2; ++n) _Pragma("unroll") for (int k = 0; k < 2; ++k) dst[n][k] = *(const PG8_LAS bf16x8*)(lds + PG8_SB(b, h) + boff + n * 2048 + k * 1024); } while (0)
; #define PG8_MMA(ai, bj, At, Bt) do { __builtin_amdgcn_s_setprio(1); _Pragma("unroll") for (int m = 0; m < 4; ++m) _Pragma("unroll") for (int n = 0; n < 2; ++n) _Pragma("unroll") for (int k = 0; k < 2; ++k) \
;         acc[ai][bj][m][n] = __builtin_amdgcn_mfma_f32_16x16x32_bf16(Bt[n][k], At[m][k], acc[ai][bj][m][n], 0, 0, 0); __builtin_amdgcn_s_setprio(0); } while (0)
; #define PG8_WAIT_V(n) asm volatile("s_waitcnt vmcnt(" #n ")" ::: "memory")
; #define PG8_WAIT_L(n) asm volatile("s_waitcnt lgkmcnt(" #n ")" ::: "memory")
; #define PG8_BAR __builtin_amdgcn_s_barrier()
; #define PG8_SCHED __builtin_amdgcn_sched_barrier(0)
; template <class Epi, class Sched, bool ALIGN_EPI = false, bool SP2 = false>
; __device__ __forceinline__ void gemm_phase(PG8_LAS unsigned char* lds, const Gemm g, const Sched& S, const Epi& E) {
;     ...
;         for (int t = 0; t < nt; t += 2) {
;             const bool last = (t == nt - 2);
;             const char* a1 = cA + (size_t)(t + 1) * kstep;
;             const char* a2 = last ? nA : cA + (size_t)(t + 2) * kstep; const char* b2 = last ? nB : cB + (size_t)(t + 2) * kstep;
;             const char* a3 = a2 + kstep; const char* b3 = b2 + kstep;
;             if (last && has_next) S.a_ready(nxt);
;             if constexpr (SP2) {
;             PG8_LDB(B0, 0, 0); PG8_LDB(B1, 0, 1); PG8_SCHED; PG8_LDA(At, 0, 0); PG8_STAGE(PG8_SA(1, 1), a1 + hstep, voffA);
;             PG8_WAIT_V(8); PG8_WAIT_L(0); PG8_BAR; PG8_MMA(0, 0, At, B0); PG8_MMA(0, 1, At, B1); PG8_BAR; PG8_SCHED;
;             PG8_LDA(At, 0, 1); PG8_STAGE(PG8_SB(0, 0), b2, voffB); PG8_STAGE(PG8_SB(0, 1), b2 + hstep, voffB); PG8_STAGE(PG8_SA(0, 0), a2, voffA);
.LBB0_231:
	ds_read_b128 v[142:145], v153
	ds_read_b128 v[146:149], v153 offset:1024
	ds_read_b128 v[174:177], v153 offset:2048
	ds_read_b128 v[178:181], v153 offset:3072
	ds_read_b128 v[182:185], v154
	ds_read_b128 v[206:209], v154 offset:1024
	ds_read_b128 v[210:213], v154 offset:2048
	ds_read_b128 v[214:217], v154 offset:3072
	s_add_u32 s28, s84, 0xfff80080
	s_addc_u32 s29, s85, -1
	s_cmp_eq_u32 s97, 28
	s_cselect_b32 s49, s34, s29
	s_cselect_b32 s48, s35, s28
	s_cselect_b32 s29, s75, s96
	s_cselect_b32 s28, s77, s95
	v_lshl_add_u64 v[158:159], s[84:85], 0, v[134:135]
	s_add_i32 m0, s56, 0xc000
	ds_read_b128 v[218:221], v155
	ds_read_b128 v[222:225], v155 offset:1024
	ds_read_b128 v[226:229], v155 offset:2048
	ds_read_b128 v[230:233], v155 offset:3072
	ds_read_b128 v[234:237], v155 offset:4096
	ds_read_b128 v[238:241], v155 offset:5120
	ds_read_b128 v[242:245], v155 offset:6144
	ds_read_b128 v[246:249], v155 offset:7168
	global_load_lds_dwordx4 v[158:159], off
	v_lshl_add_u64 v[158:159], s[84:85], 0, v[136:137]
	s_add_i32 m0, s56, 0xe000
	s_nop 0
	global_load_lds_dwordx4 v[158:159], off
	s_waitcnt vmcnt(8)
	s_waitcnt lgkmcnt(0)
	s_barrier
	s_setprio 1
	s_waitcnt lgkmcnt(0)
	v_mfma_f32_16x16x32_bf16 v[124:127], v[142:145], v[218:221], v[124:127]
	v_mfma_f32_16x16x32_bf16 v[124:127], v[146:149], v[222:225], v[124:127]
	v_mfma_f32_16x16x32_bf16 v[108:111], v[146:149], v[230:233], v[108:111]
	v_mfma_f32_16x16x32_bf16 v[108:111], v[142:145], v[226:229], v[108:111]
	v_mfma_f32_16x16x32_bf16 v[92:95], v[142:145], v[234:237], v[92:95]
	v_mfma_f32_16x16x32_bf16 v[92:95], v[146:149], v[238:241], v[92:95]
	v_mfma_f32_16x16x32_bf16 v[76:79], v[146:149], v[246:249], v[76:79]
	v_mfma_f32_16x16x32_bf16 v[76:79], v[142:145], v[242:245], v[76:79]
	v_mfma_f32_16x16x32_bf16 v[72:75], v[174:177], v[242:245], v[72:75]
	v_mfma_f32_16x16x32_bf16 v[72:75], v[178:181], v[246:249], v[72:75]
	v_mfma_f32_16x16x32_bf16 v[88:91], v[178:181], v[238:241], v[88:91]
	v_mfma_f32_16x16x32_bf16 v[88:91], v[174:177], v[234:237], v[88:91]
	v_mfma_f32_16x16x32_bf16 v[104:107], v[174:177], v[226:229], v[104:107]
	v_mfma_f32_16x16x32_bf16 v[104:107], v[178:181], v[230:233], v[104:107]
	v_mfma_f32_16x16x32_bf16 v[120:123], v[178:181], v[222:225], v[120:123]
	v_mfma_f32_16x16x32_bf16 v[120:123], v[174:177], v[218:221], v[120:123]
	s_setprio 0
	s_setprio 1
	v_mfma_f32_16x16x32_bf16 v[116:119], v[182:185], v[218:221], v[116:119]
	v_mfma_f32_16x16x32_bf16 v[116:119], v[206:209], v[222:225], v[116:119]
	v_mfma_f32_16x16x32_bf16 v[100:103], v[206:209], v[230:233], v[100:103]
	v_mfma_f32_16x16x32_bf16 v[100:103], v[182:185], v[226:229], v[100:103]
	v_mfma_f32_16x16x32_bf16 v[84:87], v[182:185], v[234:237], v[84:87]
	v_mfma_f32_16x16x32_bf16 v[84:87], v[206:209], v[238:241], v[84:87]
	v_mfma_f32_16x16x32_bf16 v[68:71], v[206:209], v[246:249], v[68:71]
	v_mfma_f32_16x16x32_bf16 v[68:71], v[182:185], v[242:245], v[68:71]
	v_mfma_f32_16x16x32_bf16 v[64:67], v[210:213], v[242:245], v[64:67]
	v_mfma_f32_16x16x32_bf16 v[64:67], v[214:217], v[246:249], v[64:67]
	v_mfma_f32_16x16x32_bf16 v[80:83], v[214:217], v[238:241], v[80:83]
	v_mfma_f32_16x16x32_bf16 v[80:83], v[210:213], v[234:237], v[80:83]
	v_mfma_f32_16x16x32_bf16 v[96:99], v[210:213], v[226:229], v[96:99]
	v_mfma_f32_16x16x32_bf16 v[96:99], v[214:217], v[230:233], v[96:99]
	s_setprio 2
	s_barrier
	v_mfma_f32_16x16x32_bf16 v[112:115], v[214:217], v[222:225], v[112:115]
	v_mfma_f32_16x16x32_bf16 v[112:115], v[210:213], v[218:221], v[112:115]
	s_setprio 0
	s_add_i32 vcc_lo, s83, s13
	v_lshl_add_u64 v[158:159], s[28:29], 0, v[166:167]
	s_mov_b32 m0, vcc_lo
	ds_read_b128 v[218:221], v155 offset:16384
	ds_read_b128 v[222:225], v155 offset:17408
	ds_read_b128 v[226:229], v155 offset:18432
	ds_read_b128 v[230:233], v155 offset:19456
	ds_read_b128 v[234:237], v155 offset:20480
	ds_read_b128 v[238:241], v155 offset:21504
	ds_read_b128 v[242:245], v155 offset:22528
	ds_read_b128 v[246:249], v155 offset:23552
	global_load_lds_dwordx4 v[158:159], off
	s_add_i32 m0, vcc_lo, 0x2000
	s_add_u32 vcc_lo, s28, 0x80000
	v_lshl_add_u64 v[186:187], s[28:29], 0, v[170:171]
	s_addc_u32 vcc_hi, s29, 0
	s_add_i32 s44, s90, s13
	global_load_lds_dwordx4 v[186:187], off
	v_lshl_add_u64 v[250:251], vcc, 0, v[166:167]
	s_mov_b32 m0, s44
	v_lshl_add_u64 v[252:253], s[48:49], 0, v[168:169]
	global_load_lds_dwordx4 v[250:251], off
	v_lshl_add_u64 v[250:251], vcc, 0, v[170:171]
	s_add_i32 m0, s44, 0x2000
	s_nop 0
	global_load_lds_dwordx4 v[250:251], off
	v_lshl_add_u64 v[250:251], s[48:49], 0, v[164:165]
	s_mov_b32 m0, s56
	s_nop 0
	global_load_lds_dwordx4 v[250:251], off
	s_mov_b32 m0, s57
	s_nop 0
	global_load_lds_dwordx4 v[252:253], off
	s_waitcnt vmcnt(8)
	s_waitcnt lgkmcnt(0)
	s_barrier
; #define PG8_STAGE(bufoff, gbase, voff) do { _Pragma("unroll") for (int _i = 0; _i < 2; ++_i) \
;         __builtin_amdgcn_global_load_lds((const unsigned*)((const char*)(gbase) + (voff)[_i]), (PG8_LAS unsigned*)(lds + (bufoff) + ldsw + _i * 8192), 16, 0, 0); } while (0)
; #define PG8_LDA(dst, b, h) do { _Pragma("unroll") for (int m = 0; m < 4; ++m) _Pragma("unroll") for (int k = 0; k < 2; ++k) dst[m][k] = *(const PG8_LAS bf16x8*)(lds + PG8_SA(b, h) + aoff + m * 2048 + k * 1024); } while (0)
; #define PG8_LDB(dst, b, h) do { _Pragma("unroll") for (int n = 0; n < 2; ++n) _Pragma("unroll") for (int k = 0; k < 2; ++k) dst[n][k] = *(const PG8_LAS bf16x8*)(lds + PG8_SB(b, h) + boff + n * 2048 + k * 1024); } while (0)
; #define PG8_MMA(ai, bj, At, Bt) do { __builtin_amdgcn_s_setprio(1); _Pragma("unroll") for (int m = 0; m < 4; ++m) _Pragma("unroll") for (int n = 0; n < 2; ++n) _Pragma("unroll") for (int k = 0; k < 2; ++k) \
;         acc[ai][bj][m][n] = __builtin_amdgcn_mfma_f32_16x16x32_bf16(Bt[n][k], At[m][k], acc[ai][bj][m][n], 0, 0, 0); __builtin_amdgcn_s_setprio(0); } while (0)
; #define PG8_WAIT_V(n) asm volatile("s_waitcnt vmcnt(" #n ")" ::: "memory")
; #define PG8_WAIT_L(n) asm volatile("s_waitcnt lgkmcnt(" #n ")" ::: "memory")
; #define PG8_BAR __builtin_amdgcn_s_barrier()
; #define PG8_SCHED __builtin_amdgcn_sched_barrier(0)
; template <class Epi, class Sched, bool ALIGN_EPI = false, bool SP2 = false>
; __device__ __forceinline__ void gemm_phase(PG8_LAS unsigned char* lds, const Gemm g, const Sched& S, const Epi& E) {
;     ...
;             PG8_WAIT_V(8); PG8_WAIT_L(0); PG8_BAR; PG8_MMA(1, 0, At, B0); PG8_MMA(1, 1, At, B1); PG8_BAR; PG8_SCHED;
;             PG8_LDB(B0, 1, 0); PG8_LDB(B1, 1, 1); PG8_SCHED; PG8_LDA(At, 1, 0); PG8_STAGE(PG8_SA(0, 1), a2 + hstep, voffA);
;             PG8_WAIT_V(8); PG8_WAIT_L(0); PG8_BAR; PG8_MMA(0, 0, At, B0); PG8_MMA(0, 1, At, B1); PG8_BAR; PG8_SCHED;
	s_setprio 1
	s_waitcnt lgkmcnt(0)
	v_mfma_f32_16x16x32_bf16 v[60:63], v[142:145], v[218:221], v[60:63]
	v_mfma_f32_16x16x32_bf16 v[60:63], v[146:149], v[222:225], v[60:63]
	v_mfma_f32_16x16x32_bf16 v[44:47], v[146:149], v[230:233], v[44:47]
	v_mfma_f32_16x16x32_bf16 v[44:47], v[142:145], v[226:229], v[44:47]
	v_mfma_f32_16x16x32_bf16 v[28:31], v[142:145], v[234:237], v[28:31]
	v_mfma_f32_16x16x32_bf16 v[28:31], v[146:149], v[238:241], v[28:31]
	v_mfma_f32_16x16x32_bf16 v[12:15], v[146:149], v[246:249], v[12:15]
	v_mfma_f32_16x16x32_bf16 v[12:15], v[142:145], v[242:245], v[12:15]
	v_mfma_f32_16x16x32_bf16 v[8:11], v[174:177], v[242:245], v[8:11]
	v_mfma_f32_16x16x32_bf16 v[8:11], v[178:181], v[246:249], v[8:11]
	v_mfma_f32_16x16x32_bf16 v[24:27], v[178:181], v[238:241], v[24:27]
	v_mfma_f32_16x16x32_bf16 v[24:27], v[174:177], v[234:237], v[24:27]
	v_mfma_f32_16x16x32_bf16 v[40:43], v[174:177], v[226:229], v[40:43]
	v_mfma_f32_16x16x32_bf16 v[40:43], v[178:181], v[230:233], v[40:43]
	v_mfma_f32_16x16x32_bf16 v[56:59], v[178:181], v[222:225], v[56:59]
	v_mfma_f32_16x16x32_bf16 v[56:59], v[174:177], v[218:221], v[56:59]
	s_setprio 0
	s_setprio 1
	v_mfma_f32_16x16x32_bf16 v[52:55], v[182:185], v[218:221], v[52:55]
	v_mfma_f32_16x16x32_bf16 v[52:55], v[206:209], v[222:225], v[52:55]
	v_mfma_f32_16x16x32_bf16 v[36:39], v[206:209], v[230:233], v[36:39]
	v_mfma_f32_16x16x32_bf16 v[36:39], v[182:185], v[226:229], v[36:39]
	v_mfma_f32_16x16x32_bf16 v[20:23], v[182:185], v[234:237], v[20:23]
	v_mfma_f32_16x16x32_bf16 v[20:23], v[206:209], v[238:241], v[20:23]
	v_mfma_f32_16x16x32_bf16 v[4:7], v[206:209], v[246:249], v[4:7]
	v_mfma_f32_16x16x32_bf16 v[4:7], v[182:185], v[242:245], v[4:7]
	v_mfma_f32_16x16x32_bf16 v[0:3], v[210:213], v[242:245], v[0:3]
	v_mfma_f32_16x16x32_bf16 v[0:3], v[214:217], v[246:249], v[0:3]
	v_mfma_f32_16x16x32_bf16 v[16:19], v[214:217], v[238:241], v[16:19]
	v_mfma_f32_16x16x32_bf16 v[16:19], v[210:213], v[234:237], v[16:19]
	v_mfma_f32_16x16x32_bf16 v[32:35], v[210:213], v[226:229], v[32:35]
	v_mfma_f32_16x16x32_bf16 v[32:35], v[214:217], v[230:233], v[32:35]
	s_setprio 2
	s_barrier
	v_mfma_f32_16x16x32_bf16 v[48:51], v[214:217], v[222:225], v[48:51]
	v_mfma_f32_16x16x32_bf16 v[48:51], v[210:213], v[218:221], v[48:51]
	s_setprio 0
	s_add_i32 s44, 0, 0x18000
	v_add_u32_e32 v161, s44, v151
	s_add_i32 s45, 0, 0x1c000
	ds_read_b128 v[142:145], v161
	ds_read_b128 v[146:149], v161 offset:1024
	ds_read_b128 v[174:177], v161 offset:2048
	ds_read_b128 v[178:181], v161 offset:3072
	v_add_u32_e32 v161, s45, v151
	ds_read_b128 v[182:185], v161
	ds_read_b128 v[206:209], v161 offset:1024
	ds_read_b128 v[210:213], v161 offset:2048
	ds_read_b128 v[214:217], v161 offset:3072
	s_add_u32 s48, s48, 0x80000
	s_addc_u32 s49, s49, 0
	s_mov_b32 m0, s60
	v_lshl_add_u64 v[200:201], s[48:49], 0, v[164:165]
	ds_read_b128 v[218:221], v155 offset:32768
	ds_read_b128 v[222:225], v155 offset:33792
	ds_read_b128 v[226:229], v155 offset:34816
	ds_read_b128 v[230:233], v155 offset:35840
	ds_read_b128 v[234:237], v155 offset:36864
	ds_read_b128 v[238:241], v155 offset:37888
	ds_read_b128 v[242:245], v155 offset:38912
	ds_read_b128 v[246:249], v155 offset:39936
	global_load_lds_dwordx4 v[200:201], off
	v_lshl_add_u64 v[200:201], s[48:49], 0, v[168:169]
	s_mov_b32 m0, s61
	s_nop 0
	global_load_lds_dwordx4 v[200:201], off
	s_waitcnt vmcnt(8)
	s_waitcnt lgkmcnt(0)
	s_barrier
	s_setprio 1
	s_waitcnt lgkmcnt(0)
	v_mfma_f32_16x16x32_bf16 v[124:127], v[142:145], v[218:221], v[124:127]
	v_mfma_f32_16x16x32_bf16 v[124:127], v[146:149], v[222:225], v[124:127]
	v_mfma_f32_16x16x32_bf16 v[108:111], v[146:149], v[230:233], v[108:111]
	v_mfma_f32_16x16x32_bf16 v[108:111], v[142:145], v[226:229], v[108:111]
	v_mfma_f32_16x16x32_bf16 v[92:95], v[142:145], v[234:237], v[92:95]
	v_mfma_f32_16x16x32_bf16 v[92:95], v[146:149], v[238:241], v[92:95]
	v_mfma_f32_16x16x32_bf16 v[76:79], v[146:149], v[246:249], v[76:79]
	v_mfma_f32_16x16x32_bf16 v[76:79], v[142:145], v[242:245], v[76:79]
	v_mfma_f32_16x16x32_bf16 v[72:75], v[174:177], v[242:245], v[72:75]
	v_mfma_f32_16x16x32_bf16 v[72:75], v[178:181], v[246:249], v[72:75]
	v_mfma_f32_16x16x32_bf16 v[88:91], v[178:181], v[238:241], v[88:91]
	v_mfma_f32_16x16x32_bf16 v[88:91], v[174:177], v[234:237], v[88:91]
	v_mfma_f32_16x16x32_bf16 v[104:107], v[174:177], v[226:229], v[104:107]
	v_mfma_f32_16x16x32_bf16 v[104:107], v[178:181], v[230:233], v[104:107]
	v_mfma_f32_16x16x32_bf16 v[120:123], v[178:181], v[222:225], v[120:123]
	v_mfma_f32_16x16x32_bf16 v[120:123], v[174:177], v[218:221], v[120:123]
	s_setprio 0
	s_setprio 1
	v_mfma_f32_16x16x32_bf16 v[116:119], v[182:185], v[218:221], v[116:119]
	v_mfma_f32_16x16x32_bf16 v[116:119], v[206:209], v[222:225], v[116:119]
	v_mfma_f32_16x16x32_bf16 v[100:103], v[206:209], v[230:233], v[100:103]
	v_mfma_f32_16x16x32_bf16 v[100:103], v[182:185], v[226:229], v[100:103]
	v_mfma_f32_16x16x32_bf16 v[84:87], v[182:185], v[234:237], v[84:87]
	v_mfma_f32_16x16x32_bf16 v[84:87], v[206:209], v[238:241], v[84:87]
	v_mfma_f32_16x16x32_bf16 v[68:71], v[206:209], v[246:249], v[68:71]
	v_mfma_f32_16x16x32_bf16 v[68:71], v[182:185], v[242:245], v[68:71]
	v_mfma_f32_16x16x32_bf16 v[64:67], v[210:213], v[242:245], v[64:67]
	v_mfma_f32_16x16x32_bf16 v[64:67], v[214:217], v[246:249], v[64:67]
	v_mfma_f32_16x16x32_bf16 v[80:83], v[214:217], v[238:241], v[80:83]
	v_mfma_f32_16x16x32_bf16 v[80:83], v[210:213], v[234:237], v[80:83]
	v_mfma_f32_16x16x32_bf16 v[96:99], v[210:213], v[226:229], v[96:99]
	v_mfma_f32_16x16x32_bf16 v[96:99], v[214:217], v[230:233], v[96:99]
	s_setprio 2
	s_barrier
; #define PG8_STAGE(bufoff, gbase, voff) do { _Pragma("unroll") for (int _i = 0; _i < 2; ++_i) \
;         __builtin_amdgcn_global_load_lds((const unsigned*)((const char*)(gbase) + (voff)[_i]), (PG8_LAS unsigned*)(lds + (bufoff) + ldsw + _i * 8192), 16, 0, 0); } while (0)
; #define PG8_LDA(dst, b, h) do { _Pragma("unroll") for (int m = 0; m < 4; ++m) _Pragma("unroll") for (int k = 0; k < 2; ++k) dst[m][k] = *(const PG8_LAS bf16x8*)(lds + PG8_SA(b, h) + aoff + m * 2048 + k * 1024); } while (0)
; #define PG8_MMA(ai, bj, At, Bt) do { __builtin_amdgcn_s_setprio(1); _Pragma("unroll") for (int m = 0; m < 4; ++m) _Pragma("unroll") for (int n = 0; n < 2; ++n) _Pragma("unroll") for (int k = 0; k < 2; ++k) \
;         acc[ai][bj][m][n] = __builtin_amdgcn_mfma_f32_16x16x32_bf16(Bt[n][k], At[m][k], acc[ai][bj][m][n], 0, 0, 0); __builtin_amdgcn_s_setprio(0); } while (0)
; #define PG8_WAIT_V(n) asm volatile("s_waitcnt vmcnt(" #n ")" ::: "memory")
; #define PG8_WAIT_L(n) asm volatile("s_waitcnt lgkmcnt(" #n ")" ::: "memory")
; #define PG8_BAR __builtin_amdgcn_s_barrier()
; #define PG8_SCHED __builtin_amdgcn_sched_barrier(0)
; template <class Epi, class Sched, bool ALIGN_EPI = false, bool SP2 = false>
; __device__ __forceinline__ void gemm_phase(PG8_LAS unsigned char* lds, const Gemm g, const Sched& S, const Epi& E) {
;     ...
;         for (int t = 0; t < nt; t += 2) {
;     ...
;             PG8_WAIT_V(8); PG8_WAIT_L(0); PG8_BAR; PG8_MMA(0, 0, At, B0); PG8_MMA(0, 1, At, B1); PG8_BAR; PG8_SCHED;
;             PG8_LDA(At, 1, 1); PG8_STAGE(PG8_SB(1, 0), b3, voffB); PG8_STAGE(PG8_SB(1, 1), b3 + hstep, voffB); PG8_STAGE(PG8_SA(1, 0), a3, voffA);
;             PG8_WAIT_V(8); PG8_WAIT_L(0); PG8_BAR; PG8_MMA(1, 0, At, B0); PG8_MMA(1, 1, At, B1); PG8_BAR; PG8_SCHED;
	v_mfma_f32_16x16x32_bf16 v[112:115], v[214:217], v[222:225], v[112:115]
	v_mfma_f32_16x16x32_bf16 v[112:115], v[210:213], v[218:221], v[112:115]
	s_setprio 0
	s_add_i32 s44, s44, s13
	v_lshl_add_u64 v[158:159], v[158:159], 0, s[52:53]
	s_mov_b32 m0, s44
	ds_read_b128 v[218:221], v155 offset:49152
	ds_read_b128 v[222:225], v155 offset:50176
	ds_read_b128 v[226:229], v155 offset:51200
	ds_read_b128 v[230:233], v155 offset:52224
	ds_read_b128 v[234:237], v155 offset:53248
	ds_read_b128 v[238:241], v155 offset:54272
	ds_read_b128 v[242:245], v155 offset:55296
	ds_read_b128 v[246:249], v155 offset:56320
	global_load_lds_dwordx4 v[158:159], off
	s_add_i32 m0, s44, 0x2000
	s_add_u32 s28, s28, 0x80080
	v_lshl_add_u64 v[158:159], v[186:187], 0, s[52:53]
	s_addc_u32 s29, s29, 0
	s_add_i32 s44, s45, s13
	global_load_lds_dwordx4 v[158:159], off
	v_lshl_add_u64 v[158:159], s[28:29], 0, v[166:167]
	s_mov_b32 m0, s44
	s_nop 0
	global_load_lds_dwordx4 v[158:159], off
	v_lshl_add_u64 v[158:159], s[28:29], 0, v[170:171]
	s_add_i32 m0, s44, 0x2000
	s_nop 0
	global_load_lds_dwordx4 v[158:159], off
	v_lshl_add_u64 v[158:159], v[250:251], 0, s[52:53]
	s_mov_b32 m0, s62
	s_nop 0
	global_load_lds_dwordx4 v[158:159], off
	v_lshl_add_u64 v[158:159], v[252:253], 0, s[52:53]
	s_mov_b32 m0, s63
	s_nop 0
	global_load_lds_dwordx4 v[158:159], off
	s_waitcnt vmcnt(8)
	s_waitcnt lgkmcnt(0)
	s_barrier
	s_setprio 1
	s_waitcnt lgkmcnt(0)
	v_mfma_f32_16x16x32_bf16 v[60:63], v[142:145], v[218:221], v[60:63]
	v_mfma_f32_16x16x32_bf16 v[60:63], v[146:149], v[222:225], v[60:63]
	v_mfma_f32_16x16x32_bf16 v[44:47], v[146:149], v[230:233], v[44:47]
	v_mfma_f32_16x16x32_bf16 v[44:47], v[142:145], v[226:229], v[44:47]
	v_mfma_f32_16x16x32_bf16 v[28:31], v[142:145], v[234:237], v[28:31]
	v_mfma_f32_16x16x32_bf16 v[28:31], v[146:149], v[238:241], v[28:31]
	v_mfma_f32_16x16x32_bf16 v[12:15], v[146:149], v[246:249], v[12:15]
	v_mfma_f32_16x16x32_bf16 v[12:15], v[142:145], v[242:245], v[12:15]
	v_mfma_f32_16x16x32_bf16 v[8:11], v[174:177], v[242:245], v[8:11]
	v_mfma_f32_16x16x32_bf16 v[8:11], v[178:181], v[246:249], v[8:11]
	v_mfma_f32_16x16x32_bf16 v[24:27], v[178:181], v[238:241], v[24:27]
	v_mfma_f32_16x16x32_bf16 v[24:27], v[174:177], v[234:237], v[24:27]
	v_mfma_f32_16x16x32_bf16 v[40:43], v[174:177], v[226:229], v[40:43]
	v_mfma_f32_16x16x32_bf16 v[40:43], v[178:181], v[230:233], v[40:43]
	v_mfma_f32_16x16x32_bf16 v[56:59], v[178:181], v[222:225], v[56:59]
	v_mfma_f32_16x16x32_bf16 v[56:59], v[174:177], v[218:221], v[56:59]
	s_setprio 0
	s_setprio 1
	v_mfma_f32_16x16x32_bf16 v[52:55], v[182:185], v[218:221], v[52:55]
	v_mfma_f32_16x16x32_bf16 v[52:55], v[206:209], v[222:225], v[52:55]
	v_mfma_f32_16x16x32_bf16 v[36:39], v[206:209], v[230:233], v[36:39]
	v_mfma_f32_16x16x32_bf16 v[36:39], v[182:185], v[226:229], v[36:39]
	v_mfma_f32_16x16x32_bf16 v[20:23], v[182:185], v[234:237], v[20:23]
	v_mfma_f32_16x16x32_bf16 v[20:23], v[206:209], v[238:241], v[20:23]
	v_mfma_f32_16x16x32_bf16 v[4:7], v[206:209], v[246:249], v[4:7]
	v_mfma_f32_16x16x32_bf16 v[4:7], v[182:185], v[242:245], v[4:7]
	v_mfma_f32_16x16x32_bf16 v[0:3], v[210:213], v[242:245], v[0:3]
	v_mfma_f32_16x16x32_bf16 v[0:3], v[214:217], v[246:249], v[0:3]
	v_mfma_f32_16x16x32_bf16 v[16:19], v[214:217], v[238:241], v[16:19]
	v_mfma_f32_16x16x32_bf16 v[16:19], v[210:213], v[234:237], v[16:19]
	v_mfma_f32_16x16x32_bf16 v[32:35], v[210:213], v[226:229], v[32:35]
	v_mfma_f32_16x16x32_bf16 v[32:35], v[214:217], v[230:233], v[32:35]
	s_setprio 2
	s_barrier
	v_mfma_f32_16x16x32_bf16 v[48:51], v[214:217], v[222:225], v[48:51]
	v_mfma_f32_16x16x32_bf16 v[48:51], v[210:213], v[218:221], v[48:51]
	s_setprio 0
	s_add_i32 s97, s97, 2
	s_add_u32 s84, s84, 0x100
	s_addc_u32 s85, s85, 0
	s_add_u32 s95, s95, 0x100
	s_addc_u32 s96, s96, 0
	s_cmp_gt_u32 s97, 29
	s_cbranch_scc0 .LBB0_231
	s_and_b64 vcc, exec, s[72:73]
	s_cbranch_vccz .LBB0_236
	s_barrier
	v_lshl_add_u32 v142, s82, 8, v150
	s_cmp_gt_i32 s94, 7
	s_mov_b64 s[28:29], -1
	s_cbranch_scc1 .LBB0_237

; #define PG8_STAGE(bufoff, gbase, voff) do { _Pragma("unroll") for (int _i = 0; _i < 2; ++_i) \
;         __builtin_amdgcn_global_load_lds((const unsigned*)((const char*)(gbase) + (voff)[_i]), (PG8_LAS unsigned*)(lds + (bufoff) + ldsw + _i * 8192), 16, 0, 0); } while (0)
; #define PG8_LDA(dst, b, h) do { _Pragma("unroll") for (int m = 0; m < 4; ++m) _Pragma("unroll") for (int k = 0; k < 2; ++k) dst[m][k] = *(const PG8_LAS bf16x8*)(lds + PG8_SA(b, h) + aoff + m * 2048 + k * 1024); } while (0)
; #define PG8_LDB(dst, b, h) do { _Pragma("unroll") for (int n = 0; n < 2; ++n) _Pragma("unroll") for (int k = 0; k < 2; ++k) dst[n][k] = *(const PG8_LAS bf16x8*)(lds + PG8_SB(b, h) + boff + n * 2048 + k * 1024); } while (0)
; #define PG8_MMA(ai, bj, At, Bt) do { __builtin_amdgcn_s_setprio(1); _Pragma("unroll") for (int m = 0; m < 4; ++m) _Pragma("unroll") for (int n = 0; n < 2; ++n) _Pragma("unroll") for (int k = 0; k < 2; ++k) \
;         acc[ai][bj][m][n] = __builtin_amdgcn_mfma_f32_16x16x32_bf16(Bt[n][k], At[m][k], acc[ai][bj][m][n], 0, 0, 0); __builtin_amdgcn_s_setprio(0); } while (0)
; #define PG8_WAIT_V(n) asm volatile("s_waitcnt vmcnt(" #n ")" ::: "memory")
; #define PG8_WAIT_L(n) asm volatile("s_waitcnt lgkmcnt(" #n ")" ::: "memory")
; #define PG8_BAR __builtin_amdgcn_s_barrier()
; #define PG8_SCHED __builtin_amdgcn_sched_barrier(0)
; template <class Epi, class Sched, bool ALIGN_EPI = false, bool SP2 = false>
; __device__ __forceinline__ void gemm_phase(PG8_LAS unsigned char* lds, const Gemm g, const Sched& S, const Epi& E) {
;     ...
;         for (int t = 0; t < nt; t += 2) {
;             const bool last = (t == nt - 2);
;             const char* a1 = cA + (size_t)(t + 1) * kstep;
;             const char* a2 = last ? nA : cA + (size_t)(t + 2) * kstep; const char* b2 = last ? nB : cB + (size_t)(t + 2) * kstep;
;             const char* a3 = a2 + kstep; const char* b3 = b2 + kstep;
;             if (last && has_next) S.a_ready(nxt);
;             if constexpr (SP2) {
;             PG8_LDB(B0, 0, 0); PG8_LDB(B1, 0, 1); PG8_SCHED; PG8_LDA(At, 0, 0); PG8_STAGE(PG8_SA(1, 1), a1 + hstep, voffA);
;             PG8_WAIT_V(8); PG8_WAIT_L(0); PG8_BAR; PG8_MMA(0, 0, At, B0); PG8_MMA(0, 1, At, B1); PG8_BAR; PG8_SCHED;
;             PG8_LDA(At, 0, 1); PG8_STAGE(PG8_SB(0, 0), b2, voffB); PG8_STAGE(PG8_SB(0, 1), b2 + hstep, voffB); PG8_STAGE(PG8_SA(0, 0), a2, voffA);
.LBB0_362:
	ds_read_b128 v[80:83], v171
	ds_read_b128 v[84:87], v171 offset:1024
	ds_read_b128 v[92:95], v171 offset:2048
	ds_read_b128 v[100:103], v171 offset:3072
	ds_read_b128 v[144:147], v186
	ds_read_b128 v[148:151], v186 offset:1024
	ds_read_b128 v[152:155], v186 offset:2048
	ds_read_b128 v[156:159], v186 offset:3072
	s_add_u32 s28, s74, 0xfff80080
	s_addc_u32 s29, s75, -1
	s_cmp_eq_u32 s77, 28
	s_cselect_b32 s49, s23, s29
	s_cselect_b32 s48, s34, s28
	s_cselect_b32 s29, s21, s76
	s_cselect_b32 s28, s35, s73
	v_lshl_add_u64 v[200:201], s[74:75], 0, v[172:173]
	s_add_i32 m0, s38, 0xc000
	ds_read_b128 v[178:181], v187
	ds_read_b128 v[182:185], v187 offset:1024
	ds_read_b128 v[206:209], v187 offset:2048
	ds_read_b128 v[210:213], v187 offset:3072
	ds_read_b128 v[214:217], v187 offset:4096
	ds_read_b128 v[218:221], v187 offset:5120
	ds_read_b128 v[222:225], v187 offset:6144
	ds_read_b128 v[226:229], v187 offset:7168
	global_load_lds_dwordx4 v[200:201], off
	v_lshl_add_u64 v[200:201], s[74:75], 0, v[174:175]
	s_add_i32 m0, s38, 0xe000
	s_nop 0
	global_load_lds_dwordx4 v[200:201], off
	s_waitcnt vmcnt(8)
	s_waitcnt lgkmcnt(0)
	s_barrier
	s_setprio 1
	s_waitcnt lgkmcnt(0)
	v_mfma_f32_16x16x32_bf16 v[140:143], v[80:83], v[178:181], v[140:143]
	v_mfma_f32_16x16x32_bf16 v[140:143], v[84:87], v[182:185], v[140:143]
	v_mfma_f32_16x16x32_bf16 v[124:127], v[84:87], v[210:213], v[124:127]
	v_mfma_f32_16x16x32_bf16 v[124:127], v[80:83], v[206:209], v[124:127]
	v_mfma_f32_16x16x32_bf16 v[108:111], v[80:83], v[214:217], v[108:111]
	v_mfma_f32_16x16x32_bf16 v[108:111], v[84:87], v[218:221], v[108:111]
	v_mfma_f32_16x16x32_bf16 v[76:79], v[84:87], v[226:229], v[76:79]
	v_mfma_f32_16x16x32_bf16 v[76:79], v[80:83], v[222:225], v[76:79]
	v_mfma_f32_16x16x32_bf16 v[72:75], v[92:95], v[222:225], v[72:75]
	v_mfma_f32_16x16x32_bf16 v[72:75], v[100:103], v[226:229], v[72:75]
	v_mfma_f32_16x16x32_bf16 v[104:107], v[100:103], v[218:221], v[104:107]
	v_mfma_f32_16x16x32_bf16 v[104:107], v[92:95], v[214:217], v[104:107]
	v_mfma_f32_16x16x32_bf16 v[120:123], v[92:95], v[206:209], v[120:123]
	v_mfma_f32_16x16x32_bf16 v[120:123], v[100:103], v[210:213], v[120:123]
	v_mfma_f32_16x16x32_bf16 v[136:139], v[100:103], v[182:185], v[136:139]
	v_mfma_f32_16x16x32_bf16 v[136:139], v[92:95], v[178:181], v[136:139]
	s_setprio 0
	s_setprio 1
	v_mfma_f32_16x16x32_bf16 v[132:135], v[144:147], v[178:181], v[132:135]
	v_mfma_f32_16x16x32_bf16 v[132:135], v[148:151], v[182:185], v[132:135]
	v_mfma_f32_16x16x32_bf16 v[116:119], v[148:151], v[210:213], v[116:119]
	v_mfma_f32_16x16x32_bf16 v[116:119], v[144:147], v[206:209], v[116:119]
	v_mfma_f32_16x16x32_bf16 v[96:99], v[144:147], v[214:217], v[96:99]
	v_mfma_f32_16x16x32_bf16 v[96:99], v[148:151], v[218:221], v[96:99]
	v_mfma_f32_16x16x32_bf16 v[68:71], v[148:151], v[226:229], v[68:71]
	v_mfma_f32_16x16x32_bf16 v[68:71], v[144:147], v[222:225], v[68:71]
	v_mfma_f32_16x16x32_bf16 v[64:67], v[152:155], v[222:225], v[64:67]
	v_mfma_f32_16x16x32_bf16 v[64:67], v[156:159], v[226:229], v[64:67]
	v_mfma_f32_16x16x32_bf16 v[88:91], v[156:159], v[218:221], v[88:91]
	v_mfma_f32_16x16x32_bf16 v[88:91], v[152:155], v[214:217], v[88:91]
	v_mfma_f32_16x16x32_bf16 v[112:115], v[152:155], v[206:209], v[112:115]
	v_mfma_f32_16x16x32_bf16 v[112:115], v[156:159], v[210:213], v[112:115]
	s_setprio 2
	s_barrier
	v_mfma_f32_16x16x32_bf16 v[128:131], v[156:159], v[182:185], v[128:131]
	v_mfma_f32_16x16x32_bf16 v[128:131], v[152:155], v[178:181], v[128:131]
	s_setprio 0
	s_add_i32 s44, s62, s13
	v_lshl_add_u64 v[200:201], s[28:29], 0, v[164:165]
	s_mov_b32 m0, s44
	ds_read_b128 v[178:181], v187 offset:16384
	ds_read_b128 v[182:185], v187 offset:17408
	ds_read_b128 v[206:209], v187 offset:18432
	ds_read_b128 v[210:213], v187 offset:19456
	ds_read_b128 v[214:217], v187 offset:20480
	ds_read_b128 v[218:221], v187 offset:21504
	ds_read_b128 v[222:225], v187 offset:22528
	ds_read_b128 v[226:229], v187 offset:23552
	global_load_lds_dwordx4 v[200:201], off
	s_add_i32 m0, s44, 0x2000
	s_add_u32 s78, s28, 0x80000
	v_lshl_add_u64 v[230:231], s[28:29], 0, v[168:169]
	s_addc_u32 s79, s29, 0
	s_add_i32 s44, s63, s13
	global_load_lds_dwordx4 v[230:231], off
	v_lshl_add_u64 v[232:233], s[78:79], 0, v[164:165]
	s_mov_b32 m0, s44
	v_lshl_add_u64 v[234:235], s[48:49], 0, v[168:169]
	global_load_lds_dwordx4 v[232:233], off
	v_lshl_add_u64 v[232:233], s[78:79], 0, v[168:169]
	s_add_i32 m0, s44, 0x2000
	s_nop 0
	global_load_lds_dwordx4 v[232:233], off
	v_lshl_add_u64 v[232:233], s[48:49], 0, v[164:165]
	s_mov_b32 m0, s38
	s_nop 0
	global_load_lds_dwordx4 v[232:233], off
	s_mov_b32 m0, s39
	s_nop 0
	global_load_lds_dwordx4 v[234:235], off
	s_waitcnt vmcnt(8)
	s_waitcnt lgkmcnt(0)
	s_barrier
; #define PG8_STAGE(bufoff, gbase, voff) do { _Pragma("unroll") for (int _i = 0; _i < 2; ++_i) \
;         __builtin_amdgcn_global_load_lds((const unsigned*)((const char*)(gbase) + (voff)[_i]), (PG8_LAS unsigned*)(lds + (bufoff) + ldsw + _i * 8192), 16, 0, 0); } while (0)
; #define PG8_LDA(dst, b, h) do { _Pragma("unroll") for (int m = 0; m < 4; ++m) _Pragma("unroll") for (int k = 0; k < 2; ++k) dst[m][k] = *(const PG8_LAS bf16x8*)(lds + PG8_SA(b, h) + aoff + m * 2048 + k * 1024); } while (0)
; #define PG8_LDB(dst, b, h) do { _Pragma("unroll") for (int n = 0; n < 2; ++n) _Pragma("unroll") for (int k = 0; k < 2; ++k) dst[n][k] = *(const PG8_LAS bf16x8*)(lds + PG8_SB(b, h) + boff + n * 2048 + k * 1024); } while (0)
; #define PG8_MMA(ai, bj, At, Bt) do { __builtin_amdgcn_s_setprio(1); _Pragma("unroll") for (int m = 0; m < 4; ++m) _Pragma("unroll") for (int n = 0; n < 2; ++n) _Pragma("unroll") for (int k = 0; k < 2; ++k) \
;         acc[ai][bj][m][n] = __builtin_amdgcn_mfma_f32_16x16x32_bf16(Bt[n][k], At[m][k], acc[ai][bj][m][n], 0, 0, 0); __builtin_amdgcn_s_setprio(0); } while (0)
; #define PG8_WAIT_V(n) asm volatile("s_waitcnt vmcnt(" #n ")" ::: "memory")
; #define PG8_WAIT_L(n) asm volatile("s_waitcnt lgkmcnt(" #n ")" ::: "memory")
; #define PG8_BAR __builtin_amdgcn_s_barrier()
; #define PG8_SCHED __builtin_amdgcn_sched_barrier(0)
; template <class Epi, class Sched, bool ALIGN_EPI = false, bool SP2 = false>
; __device__ __forceinline__ void gemm_phase(PG8_LAS unsigned char* lds, const Gemm g, const Sched& S, const Epi& E) {
;     ...
;             PG8_WAIT_V(8); PG8_WAIT_L(0); PG8_BAR; PG8_MMA(1, 0, At, B0); PG8_MMA(1, 1, At, B1); PG8_BAR; PG8_SCHED;
;             PG8_LDB(B0, 1, 0); PG8_LDB(B1, 1, 1); PG8_SCHED; PG8_LDA(At, 1, 0); PG8_STAGE(PG8_SA(0, 1), a2 + hstep, voffA);
;             PG8_WAIT_V(8); PG8_WAIT_L(0); PG8_BAR; PG8_MMA(0, 0, At, B0); PG8_MMA(0, 1, At, B1); PG8_BAR; PG8_SCHED;
	s_setprio 1
	s_waitcnt lgkmcnt(0)
	v_mfma_f32_16x16x32_bf16 v[60:63], v[80:83], v[178:181], v[60:63]
	v_mfma_f32_16x16x32_bf16 v[60:63], v[84:87], v[182:185], v[60:63]
	v_mfma_f32_16x16x32_bf16 v[44:47], v[84:87], v[210:213], v[44:47]
	v_mfma_f32_16x16x32_bf16 v[44:47], v[80:83], v[206:209], v[44:47]
	v_mfma_f32_16x16x32_bf16 v[28:31], v[80:83], v[214:217], v[28:31]
	v_mfma_f32_16x16x32_bf16 v[28:31], v[84:87], v[218:221], v[28:31]
	v_mfma_f32_16x16x32_bf16 v[12:15], v[84:87], v[226:229], v[12:15]
	v_mfma_f32_16x16x32_bf16 v[12:15], v[80:83], v[222:225], v[12:15]
	v_mfma_f32_16x16x32_bf16 v[8:11], v[92:95], v[222:225], v[8:11]
	v_mfma_f32_16x16x32_bf16 v[8:11], v[100:103], v[226:229], v[8:11]
	v_mfma_f32_16x16x32_bf16 v[24:27], v[100:103], v[218:221], v[24:27]
	v_mfma_f32_16x16x32_bf16 v[24:27], v[92:95], v[214:217], v[24:27]
	v_mfma_f32_16x16x32_bf16 v[40:43], v[92:95], v[206:209], v[40:43]
	v_mfma_f32_16x16x32_bf16 v[40:43], v[100:103], v[210:213], v[40:43]
	v_mfma_f32_16x16x32_bf16 v[56:59], v[100:103], v[182:185], v[56:59]
	v_mfma_f32_16x16x32_bf16 v[56:59], v[92:95], v[178:181], v[56:59]
	s_setprio 0
	s_setprio 1
	v_mfma_f32_16x16x32_bf16 v[52:55], v[144:147], v[178:181], v[52:55]
	v_mfma_f32_16x16x32_bf16 v[52:55], v[148:151], v[182:185], v[52:55]
	v_mfma_f32_16x16x32_bf16 v[36:39], v[148:151], v[210:213], v[36:39]
	v_mfma_f32_16x16x32_bf16 v[36:39], v[144:147], v[206:209], v[36:39]
	v_mfma_f32_16x16x32_bf16 v[20:23], v[144:147], v[214:217], v[20:23]
	v_mfma_f32_16x16x32_bf16 v[20:23], v[148:151], v[218:221], v[20:23]
	v_mfma_f32_16x16x32_bf16 v[4:7], v[148:151], v[226:229], v[4:7]
	v_mfma_f32_16x16x32_bf16 v[4:7], v[144:147], v[222:225], v[4:7]
	v_mfma_f32_16x16x32_bf16 v[0:3], v[152:155], v[222:225], v[0:3]
	v_mfma_f32_16x16x32_bf16 v[0:3], v[156:159], v[226:229], v[0:3]
	v_mfma_f32_16x16x32_bf16 v[16:19], v[156:159], v[218:221], v[16:19]
	v_mfma_f32_16x16x32_bf16 v[16:19], v[152:155], v[214:217], v[16:19]
	v_mfma_f32_16x16x32_bf16 v[32:35], v[152:155], v[206:209], v[32:35]
	v_mfma_f32_16x16x32_bf16 v[32:35], v[156:159], v[210:213], v[32:35]
	s_setprio 2
	s_barrier
	v_mfma_f32_16x16x32_bf16 v[48:51], v[156:159], v[182:185], v[48:51]
	v_mfma_f32_16x16x32_bf16 v[48:51], v[152:155], v[178:181], v[48:51]
	s_setprio 0
	s_add_i32 s44, 0, 0x18000
	s_add_i32 s45, 0, 0x1c000
	v_add_u32_e32 v100, s44, v163
	v_add_u32_e32 v156, s45, v163
	ds_read_b128 v[80:83], v100
	ds_read_b128 v[84:87], v100 offset:1024
	ds_read_b128 v[92:95], v100 offset:2048
	ds_read_b128 v[100:103], v100 offset:3072
	ds_read_b128 v[144:147], v156
	ds_read_b128 v[148:151], v156 offset:1024
	ds_read_b128 v[152:155], v156 offset:2048
	ds_read_b128 v[156:159], v156 offset:3072
	s_add_u32 s48, s48, 0x80000
	s_addc_u32 s49, s49, 0
	s_mov_b32 m0, s40
	v_lshl_add_u64 v[236:237], s[48:49], 0, v[164:165]
	ds_read_b128 v[178:181], v187 offset:32768
	ds_read_b128 v[182:185], v187 offset:33792
	ds_read_b128 v[206:209], v187 offset:34816
	ds_read_b128 v[210:213], v187 offset:35840
	ds_read_b128 v[214:217], v187 offset:36864
	ds_read_b128 v[218:221], v187 offset:37888
	ds_read_b128 v[222:225], v187 offset:38912
	ds_read_b128 v[226:229], v187 offset:39936
	global_load_lds_dwordx4 v[236:237], off
	v_lshl_add_u64 v[236:237], s[48:49], 0, v[168:169]
	s_mov_b32 m0, s41
	s_nop 0
	global_load_lds_dwordx4 v[236:237], off
	s_waitcnt vmcnt(8)
	s_waitcnt lgkmcnt(0)
	s_barrier
	s_setprio 1
	s_waitcnt lgkmcnt(0)
	v_mfma_f32_16x16x32_bf16 v[140:143], v[80:83], v[178:181], v[140:143]
	v_mfma_f32_16x16x32_bf16 v[140:143], v[84:87], v[182:185], v[140:143]
	v_mfma_f32_16x16x32_bf16 v[124:127], v[84:87], v[210:213], v[124:127]
	v_mfma_f32_16x16x32_bf16 v[124:127], v[80:83], v[206:209], v[124:127]
	v_mfma_f32_16x16x32_bf16 v[108:111], v[80:83], v[214:217], v[108:111]
	v_mfma_f32_16x16x32_bf16 v[108:111], v[84:87], v[218:221], v[108:111]
	v_mfma_f32_16x16x32_bf16 v[76:79], v[84:87], v[226:229], v[76:79]
	v_mfma_f32_16x16x32_bf16 v[76:79], v[80:83], v[222:225], v[76:79]
	v_mfma_f32_16x16x32_bf16 v[72:75], v[92:95], v[222:225], v[72:75]
	v_mfma_f32_16x16x32_bf16 v[72:75], v[100:103], v[226:229], v[72:75]
	v_mfma_f32_16x16x32_bf16 v[104:107], v[100:103], v[218:221], v[104:107]
	v_mfma_f32_16x16x32_bf16 v[104:107], v[92:95], v[214:217], v[104:107]
	v_mfma_f32_16x16x32_bf16 v[120:123], v[92:95], v[206:209], v[120:123]
	v_mfma_f32_16x16x32_bf16 v[120:123], v[100:103], v[210:213], v[120:123]
	v_mfma_f32_16x16x32_bf16 v[136:139], v[100:103], v[182:185], v[136:139]
	v_mfma_f32_16x16x32_bf16 v[136:139], v[92:95], v[178:181], v[136:139]
	s_setprio 0
	s_setprio 1
	v_mfma_f32_16x16x32_bf16 v[132:135], v[144:147], v[178:181], v[132:135]
	v_mfma_f32_16x16x32_bf16 v[132:135], v[148:151], v[182:185], v[132:135]
	v_mfma_f32_16x16x32_bf16 v[116:119], v[148:151], v[210:213], v[116:119]
	v_mfma_f32_16x16x32_bf16 v[116:119], v[144:147], v[206:209], v[116:119]
	v_mfma_f32_16x16x32_bf16 v[96:99], v[144:147], v[214:217], v[96:99]
	v_mfma_f32_16x16x32_bf16 v[96:99], v[148:151], v[218:221], v[96:99]
	v_mfma_f32_16x16x32_bf16 v[68:71], v[148:151], v[226:229], v[68:71]
	v_mfma_f32_16x16x32_bf16 v[68:71], v[144:147], v[222:225], v[68:71]
	v_mfma_f32_16x16x32_bf16 v[64:67], v[152:155], v[222:225], v[64:67]
	v_mfma_f32_16x16x32_bf16 v[64:67], v[156:159], v[226:229], v[64:67]
	v_mfma_f32_16x16x32_bf16 v[88:91], v[156:159], v[218:221], v[88:91]
	v_mfma_f32_16x16x32_bf16 v[88:91], v[152:155], v[214:217], v[88:91]
	v_mfma_f32_16x16x32_bf16 v[112:115], v[152:155], v[206:209], v[112:115]
	v_mfma_f32_16x16x32_bf16 v[112:115], v[156:159], v[210:213], v[112:115]
	s_setprio 2
	s_barrier
; #define PG8_STAGE(bufoff, gbase, voff) do { _Pragma("unroll") for (int _i = 0; _i < 2; ++_i) \
;         __builtin_amdgcn_global_load_lds((const unsigned*)((const char*)(gbase) + (voff)[_i]), (PG8_LAS unsigned*)(lds + (bufoff) + ldsw + _i * 8192), 16, 0, 0); } while (0)
; #define PG8_LDA(dst, b, h) do { _Pragma("unroll") for (int m = 0; m < 4; ++m) _Pragma("unroll") for (int k = 0; k < 2; ++k) dst[m][k] = *(const PG8_LAS bf16x8*)(lds + PG8_SA(b, h) + aoff + m * 2048 + k * 1024); } while (0)
; #define PG8_MMA(ai, bj, At, Bt) do { __builtin_amdgcn_s_setprio(1); _Pragma("unroll") for (int m = 0; m < 4; ++m) _Pragma("unroll") for (int n = 0; n < 2; ++n) _Pragma("unroll") for (int k = 0; k < 2; ++k) \
;         acc[ai][bj][m][n] = __builtin_amdgcn_mfma_f32_16x16x32_bf16(Bt[n][k], At[m][k], acc[ai][bj][m][n], 0, 0, 0); __builtin_amdgcn_s_setprio(0); } while (0)
; #define PG8_WAIT_V(n) asm volatile("s_waitcnt vmcnt(" #n ")" ::: "memory")
; #define PG8_WAIT_L(n) asm volatile("s_waitcnt lgkmcnt(" #n ")" ::: "memory")
; #define PG8_BAR __builtin_amdgcn_s_barrier()
; #define PG8_SCHED __builtin_amdgcn_sched_barrier(0)
; template <class Epi, class Sched, bool ALIGN_EPI = false, bool SP2 = false>
; __device__ __forceinline__ void gemm_phase(PG8_LAS unsigned char* lds, const Gemm g, const Sched& S, const Epi& E) {
;     ...
;         for (int t = 0; t < nt; t += 2) {
;     ...
;             PG8_WAIT_V(8); PG8_WAIT_L(0); PG8_BAR; PG8_MMA(0, 0, At, B0); PG8_MMA(0, 1, At, B1); PG8_BAR; PG8_SCHED;
;             PG8_LDA(At, 1, 1); PG8_STAGE(PG8_SB(1, 0), b3, voffB); PG8_STAGE(PG8_SB(1, 1), b3 + hstep, voffB); PG8_STAGE(PG8_SA(1, 0), a3, voffA);
;             PG8_WAIT_V(8); PG8_WAIT_L(0); PG8_BAR; PG8_MMA(1, 0, At, B0); PG8_MMA(1, 1, At, B1); PG8_BAR; PG8_SCHED;
	v_mfma_f32_16x16x32_bf16 v[128:131], v[156:159], v[182:185], v[128:131]
	v_mfma_f32_16x16x32_bf16 v[128:131], v[152:155], v[178:181], v[128:131]
	s_setprio 0
	s_add_i32 s44, s44, s13
	v_lshl_add_u64 v[200:201], v[200:201], 0, s[16:17]
	s_mov_b32 m0, s44
	ds_read_b128 v[178:181], v187 offset:49152
	ds_read_b128 v[182:185], v187 offset:50176
	ds_read_b128 v[206:209], v187 offset:51200
	ds_read_b128 v[210:213], v187 offset:52224
	ds_read_b128 v[214:217], v187 offset:53248
	ds_read_b128 v[218:221], v187 offset:54272
	ds_read_b128 v[222:225], v187 offset:55296
	ds_read_b128 v[226:229], v187 offset:56320
	global_load_lds_dwordx4 v[200:201], off
	s_add_i32 m0, s44, 0x2000
	s_add_u32 s28, s28, 0x80080
	v_lshl_add_u64 v[200:201], v[230:231], 0, s[16:17]
	s_addc_u32 s29, s29, 0
	s_add_i32 s44, s45, s13
	global_load_lds_dwordx4 v[200:201], off
	v_lshl_add_u64 v[200:201], s[28:29], 0, v[164:165]
	s_mov_b32 m0, s44
	s_nop 0
	global_load_lds_dwordx4 v[200:201], off
	v_lshl_add_u64 v[200:201], s[28:29], 0, v[168:169]
	s_add_i32 m0, s44, 0x2000
	s_nop 0
	global_load_lds_dwordx4 v[200:201], off
	v_lshl_add_u64 v[200:201], v[232:233], 0, s[16:17]
	s_mov_b32 m0, s56
	s_nop 0
	global_load_lds_dwordx4 v[200:201], off
	v_lshl_add_u64 v[200:201], v[234:235], 0, s[16:17]
	s_mov_b32 m0, s57
	s_nop 0
	global_load_lds_dwordx4 v[200:201], off
	s_waitcnt vmcnt(8)
	s_waitcnt lgkmcnt(0)
	s_barrier
	s_setprio 1
	s_waitcnt lgkmcnt(0)
	v_mfma_f32_16x16x32_bf16 v[60:63], v[80:83], v[178:181], v[60:63]
	v_mfma_f32_16x16x32_bf16 v[60:63], v[84:87], v[182:185], v[60:63]
	v_mfma_f32_16x16x32_bf16 v[44:47], v[84:87], v[210:213], v[44:47]
	v_mfma_f32_16x16x32_bf16 v[44:47], v[80:83], v[206:209], v[44:47]
	v_mfma_f32_16x16x32_bf16 v[28:31], v[80:83], v[214:217], v[28:31]
	v_mfma_f32_16x16x32_bf16 v[28:31], v[84:87], v[218:221], v[28:31]
	v_mfma_f32_16x16x32_bf16 v[12:15], v[84:87], v[226:229], v[12:15]
	v_mfma_f32_16x16x32_bf16 v[12:15], v[80:83], v[222:225], v[12:15]
	v_mfma_f32_16x16x32_bf16 v[8:11], v[92:95], v[222:225], v[8:11]
	v_mfma_f32_16x16x32_bf16 v[8:11], v[100:103], v[226:229], v[8:11]
	v_mfma_f32_16x16x32_bf16 v[24:27], v[100:103], v[218:221], v[24:27]
	v_mfma_f32_16x16x32_bf16 v[24:27], v[92:95], v[214:217], v[24:27]
	v_mfma_f32_16x16x32_bf16 v[40:43], v[92:95], v[206:209], v[40:43]
	v_mfma_f32_16x16x32_bf16 v[40:43], v[100:103], v[210:213], v[40:43]
	v_mfma_f32_16x16x32_bf16 v[56:59], v[100:103], v[182:185], v[56:59]
	v_mfma_f32_16x16x32_bf16 v[56:59], v[92:95], v[178:181], v[56:59]
	s_setprio 0
	s_setprio 1
	v_mfma_f32_16x16x32_bf16 v[52:55], v[144:147], v[178:181], v[52:55]
	v_mfma_f32_16x16x32_bf16 v[52:55], v[148:151], v[182:185], v[52:55]
	v_mfma_f32_16x16x32_bf16 v[36:39], v[148:151], v[210:213], v[36:39]
	v_mfma_f32_16x16x32_bf16 v[36:39], v[144:147], v[206:209], v[36:39]
	v_mfma_f32_16x16x32_bf16 v[20:23], v[144:147], v[214:217], v[20:23]
	v_mfma_f32_16x16x32_bf16 v[20:23], v[148:151], v[218:221], v[20:23]
	v_mfma_f32_16x16x32_bf16 v[4:7], v[148:151], v[226:229], v[4:7]
	v_mfma_f32_16x16x32_bf16 v[4:7], v[144:147], v[222:225], v[4:7]
	v_mfma_f32_16x16x32_bf16 v[0:3], v[152:155], v[222:225], v[0:3]
	v_mfma_f32_16x16x32_bf16 v[0:3], v[156:159], v[226:229], v[0:3]
	v_mfma_f32_16x16x32_bf16 v[16:19], v[156:159], v[218:221], v[16:19]
	v_mfma_f32_16x16x32_bf16 v[16:19], v[152:155], v[214:217], v[16:19]
	v_mfma_f32_16x16x32_bf16 v[32:35], v[152:155], v[206:209], v[32:35]
	v_mfma_f32_16x16x32_bf16 v[32:35], v[156:159], v[210:213], v[32:35]
	s_setprio 2
	s_barrier
	v_mfma_f32_16x16x32_bf16 v[48:51], v[156:159], v[182:185], v[48:51]
	v_mfma_f32_16x16x32_bf16 v[48:51], v[152:155], v[178:181], v[48:51]
	s_setprio 0
	s_add_i32 s77, s77, 2
	s_add_u32 s74, s74, 0x100
	s_addc_u32 s75, s75, 0
	s_add_u32 s73, s73, 0x100
	s_addc_u32 s76, s76, 0
	s_cmp_gt_u32 s77, 29
	s_cbranch_scc0 .LBB0_362
	s_and_b64 vcc, exec, s[18:19]
	s_cbranch_vccz .LBB0_365
	s_barrier

; #define PG8_STAGE(bufoff, gbase, voff) do { _Pragma("unroll") for (int _i = 0; _i < 2; ++_i) \
;         __builtin_amdgcn_global_load_lds((const unsigned*)((const char*)(gbase) + (voff)[_i]), (PG8_LAS unsigned*)(lds + (bufoff) + ldsw + _i * 8192), 16, 0, 0); } while (0)
; #define PG8_LDA(dst, b, h) do { _Pragma("unroll") for (int m = 0; m < 4; ++m) _Pragma("unroll") for (int k = 0; k < 2; ++k) dst[m][k] = *(const PG8_LAS bf16x8*)(lds + PG8_SA(b, h) + aoff + m * 2048 + k * 1024); } while (0)
; #define PG8_LDB(dst, b, h) do { _Pragma("unroll") for (int n = 0; n < 2; ++n) _Pragma("unroll") for (int k = 0; k < 2; ++k) dst[n][k] = *(const PG8_LAS bf16x8*)(lds + PG8_SB(b, h) + boff + n * 2048 + k * 1024); } while (0)
; #define PG8_MMA(ai, bj, At, Bt) do { __builtin_amdgcn_s_setprio(1); _Pragma("unroll") for (int m = 0; m < 4; ++m) _Pragma("unroll") for (int n = 0; n < 2; ++n) _Pragma("unroll") for (int k = 0; k < 2; ++k) \
;         acc[ai][bj][m][n] = __builtin_amdgcn_mfma_f32_16x16x32_bf16(Bt[n][k], At[m][k], acc[ai][bj][m][n], 0, 0, 0); __builtin_amdgcn_s_setprio(0); } while (0)
; #define PG8_WAIT_V(n) asm volatile("s_waitcnt vmcnt(" #n ")" ::: "memory")
; #define PG8_WAIT_L(n) asm volatile("s_waitcnt lgkmcnt(" #n ")" ::: "memory")
; #define PG8_BAR __builtin_amdgcn_s_barrier()
; #define PG8_SCHED __builtin_amdgcn_sched_barrier(0)
; template <class Epi, class Sched, bool ALIGN_EPI = false, bool SP2 = false>
; __device__ __forceinline__ void gemm_phase(PG8_LAS unsigned char* lds, const Gemm g, const Sched& S, const Epi& E) {
;     ...
;         for (int t = 0; t < nt; t += 2) {
;             const bool last = (t == nt - 2);
;             const char* a1 = cA + (size_t)(t + 1) * kstep;
;             const char* a2 = last ? nA : cA + (size_t)(t + 2) * kstep; const char* b2 = last ? nB : cB + (size_t)(t + 2) * kstep;
;             const char* a3 = a2 + kstep; const char* b3 = b2 + kstep;
;             if (last && has_next) S.a_ready(nxt);
;             if constexpr (SP2) {
;             PG8_LDB(B0, 0, 0); PG8_LDB(B1, 0, 1); PG8_SCHED; PG8_LDA(At, 0, 0); PG8_STAGE(PG8_SA(1, 1), a1 + hstep, voffA);
;             PG8_WAIT_V(8); PG8_WAIT_L(0); PG8_BAR; PG8_MMA(0, 0, At, B0); PG8_MMA(0, 1, At, B1); PG8_BAR; PG8_SCHED;
;             PG8_LDA(At, 0, 1); PG8_STAGE(PG8_SB(0, 0), b2, voffB); PG8_STAGE(PG8_SB(0, 1), b2 + hstep, voffB); PG8_STAGE(PG8_SA(0, 0), a2, voffA);
.LBB0_416:
	ds_read_b128 v[136:139], v156
	ds_read_b128 v[140:143], v156 offset:1024
	ds_read_b128 v[172:175], v156 offset:2048
	ds_read_b128 v[176:179], v156 offset:3072
	ds_read_b128 v[180:183], v157
	ds_read_b128 v[184:187], v157 offset:1024
	ds_read_b128 v[206:209], v157 offset:2048
	ds_read_b128 v[210:213], v157 offset:3072
	s_add_u32 s28, s68, 0xfff80080
	s_addc_u32 s29, s69, -1
	s_cmp_eq_u32 s79, 28
	s_cselect_b32 s49, s34, s29
	s_cselect_b32 s48, s35, s28
	s_cselect_b32 s29, s23, s78
	s_cselect_b32 s28, s63, s77
	v_lshl_add_u64 v[200:201], s[68:69], 0, v[128:129]
	s_add_i32 m0, s15, 0xc000
	ds_read_b128 v[214:217], v158
	ds_read_b128 v[218:221], v158 offset:1024
	ds_read_b128 v[222:225], v158 offset:2048
	ds_read_b128 v[226:229], v158 offset:3072
	ds_read_b128 v[230:233], v158 offset:4096
	ds_read_b128 v[234:237], v158 offset:5120
	ds_read_b128 v[238:241], v158 offset:6144
	ds_read_b128 v[242:245], v158 offset:7168
	global_load_lds_dwordx4 v[200:201], off
	v_lshl_add_u64 v[200:201], s[68:69], 0, v[130:131]
	s_add_i32 m0, s15, 0xe000
	s_nop 0
	global_load_lds_dwordx4 v[200:201], off
	s_waitcnt vmcnt(8)
	s_waitcnt lgkmcnt(0)
	s_barrier
	s_setprio 1
	s_waitcnt lgkmcnt(0)
	v_mfma_f32_16x16x32_bf16 v[124:127], v[136:139], v[214:217], v[124:127]
	v_mfma_f32_16x16x32_bf16 v[124:127], v[140:143], v[218:221], v[124:127]
	v_mfma_f32_16x16x32_bf16 v[108:111], v[140:143], v[226:229], v[108:111]
	v_mfma_f32_16x16x32_bf16 v[108:111], v[136:139], v[222:225], v[108:111]
	v_mfma_f32_16x16x32_bf16 v[96:99], v[136:139], v[230:233], v[96:99]
	v_mfma_f32_16x16x32_bf16 v[96:99], v[140:143], v[234:237], v[96:99]
	v_mfma_f32_16x16x32_bf16 v[80:83], v[140:143], v[242:245], v[80:83]
	v_mfma_f32_16x16x32_bf16 v[80:83], v[136:139], v[238:241], v[80:83]
	v_mfma_f32_16x16x32_bf16 v[72:75], v[172:175], v[238:241], v[72:75]
	v_mfma_f32_16x16x32_bf16 v[72:75], v[176:179], v[242:245], v[72:75]
	v_mfma_f32_16x16x32_bf16 v[88:91], v[176:179], v[234:237], v[88:91]
	v_mfma_f32_16x16x32_bf16 v[88:91], v[172:175], v[230:233], v[88:91]
	v_mfma_f32_16x16x32_bf16 v[104:107], v[172:175], v[222:225], v[104:107]
	v_mfma_f32_16x16x32_bf16 v[104:107], v[176:179], v[226:229], v[104:107]
	v_mfma_f32_16x16x32_bf16 v[120:123], v[176:179], v[218:221], v[120:123]
	v_mfma_f32_16x16x32_bf16 v[120:123], v[172:175], v[214:217], v[120:123]
	s_setprio 0
	s_setprio 1
	v_mfma_f32_16x16x32_bf16 v[116:119], v[180:183], v[214:217], v[116:119]
	v_mfma_f32_16x16x32_bf16 v[116:119], v[184:187], v[218:221], v[116:119]
	v_mfma_f32_16x16x32_bf16 v[100:103], v[184:187], v[226:229], v[100:103]
	v_mfma_f32_16x16x32_bf16 v[100:103], v[180:183], v[222:225], v[100:103]
	v_mfma_f32_16x16x32_bf16 v[84:87], v[180:183], v[230:233], v[84:87]
	v_mfma_f32_16x16x32_bf16 v[84:87], v[184:187], v[234:237], v[84:87]
	v_mfma_f32_16x16x32_bf16 v[68:71], v[184:187], v[242:245], v[68:71]
	v_mfma_f32_16x16x32_bf16 v[68:71], v[180:183], v[238:241], v[68:71]
	v_mfma_f32_16x16x32_bf16 v[64:67], v[206:209], v[238:241], v[64:67]
	v_mfma_f32_16x16x32_bf16 v[64:67], v[210:213], v[242:245], v[64:67]
	v_mfma_f32_16x16x32_bf16 v[76:79], v[210:213], v[234:237], v[76:79]
	v_mfma_f32_16x16x32_bf16 v[76:79], v[206:209], v[230:233], v[76:79]
	v_mfma_f32_16x16x32_bf16 v[92:95], v[206:209], v[222:225], v[92:95]
	v_mfma_f32_16x16x32_bf16 v[92:95], v[210:213], v[226:229], v[92:95]
	s_setprio 2
	s_barrier
	v_mfma_f32_16x16x32_bf16 v[112:115], v[210:213], v[218:221], v[112:115]
	v_mfma_f32_16x16x32_bf16 v[112:115], v[206:209], v[214:217], v[112:115]
	s_setprio 0
	s_add_i32 s44, s72, s39
	v_lshl_add_u64 v[200:201], s[28:29], 0, v[166:167]
	s_mov_b32 m0, s44
	ds_read_b128 v[214:217], v158 offset:16384
	ds_read_b128 v[218:221], v158 offset:17408
	ds_read_b128 v[222:225], v158 offset:18432
	ds_read_b128 v[226:229], v158 offset:19456
	ds_read_b128 v[230:233], v158 offset:20480
	ds_read_b128 v[234:237], v158 offset:21504
	ds_read_b128 v[238:241], v158 offset:22528
	ds_read_b128 v[242:245], v158 offset:23552
	global_load_lds_dwordx4 v[200:201], off
	s_add_i32 m0, s44, 0x2000
	s_add_u32 s80, s28, 0x80000
	v_lshl_add_u64 v[246:247], s[28:29], 0, v[170:171]
	s_addc_u32 s81, s29, 0
	s_add_i32 s44, s73, s39
	global_load_lds_dwordx4 v[246:247], off
	v_lshl_add_u64 v[248:249], s[80:81], 0, v[166:167]
	s_mov_b32 m0, s44
	v_lshl_add_u64 v[250:251], s[48:49], 0, v[168:169]
	global_load_lds_dwordx4 v[248:249], off
	v_lshl_add_u64 v[248:249], s[80:81], 0, v[170:171]
	s_add_i32 m0, s44, 0x2000
	s_nop 0
	global_load_lds_dwordx4 v[248:249], off
	v_lshl_add_u64 v[248:249], s[48:49], 0, v[164:165]
	s_mov_b32 m0, s15
	s_nop 0
	global_load_lds_dwordx4 v[248:249], off
	s_mov_b32 m0, s41
	s_nop 0
	global_load_lds_dwordx4 v[250:251], off
	s_waitcnt vmcnt(8)
	s_waitcnt lgkmcnt(0)
	s_barrier
; #define PG8_STAGE(bufoff, gbase, voff) do { _Pragma("unroll") for (int _i = 0; _i < 2; ++_i) \
;         __builtin_amdgcn_global_load_lds((const unsigned*)((const char*)(gbase) + (voff)[_i]), (PG8_LAS unsigned*)(lds + (bufoff) + ldsw + _i * 8192), 16, 0, 0); } while (0)
; #define PG8_LDA(dst, b, h) do { _Pragma("unroll") for (int m = 0; m < 4; ++m) _Pragma("unroll") for (int k = 0; k < 2; ++k) dst[m][k] = *(const PG8_LAS bf16x8*)(lds + PG8_SA(b, h) + aoff + m * 2048 + k * 1024); } while (0)
; #define PG8_LDB(dst, b, h) do { _Pragma("unroll") for (int n = 0; n < 2; ++n) _Pragma("unroll") for (int k = 0; k < 2; ++k) dst[n][k] = *(const PG8_LAS bf16x8*)(lds + PG8_SB(b, h) + boff + n * 2048 + k * 1024); } while (0)
; #define PG8_MMA(ai, bj, At, Bt) do { __builtin_amdgcn_s_setprio(1); _Pragma("unroll") for (int m = 0; m < 4; ++m) _Pragma("unroll") for (int n = 0; n < 2; ++n) _Pragma("unroll") for (int k = 0; k < 2; ++k) \
;         acc[ai][bj][m][n] = __builtin_amdgcn_mfma_f32_16x16x32_bf16(Bt[n][k], At[m][k], acc[ai][bj][m][n], 0, 0, 0); __builtin_amdgcn_s_setprio(0); } while (0)
; #define PG8_WAIT_V(n) asm volatile("s_waitcnt vmcnt(" #n ")" ::: "memory")
; #define PG8_WAIT_L(n) asm volatile("s_waitcnt lgkmcnt(" #n ")" ::: "memory")
; #define PG8_BAR __builtin_amdgcn_s_barrier()
; #define PG8_SCHED __builtin_amdgcn_sched_barrier(0)
; template <class Epi, class Sched, bool ALIGN_EPI = false, bool SP2 = false>
; __device__ __forceinline__ void gemm_phase(PG8_LAS unsigned char* lds, const Gemm g, const Sched& S, const Epi& E) {
;     ...
;             PG8_WAIT_V(8); PG8_WAIT_L(0); PG8_BAR; PG8_MMA(1, 0, At, B0); PG8_MMA(1, 1, At, B1); PG8_BAR; PG8_SCHED;
;             PG8_LDB(B0, 1, 0); PG8_LDB(B1, 1, 1); PG8_SCHED; PG8_LDA(At, 1, 0); PG8_STAGE(PG8_SA(0, 1), a2 + hstep, voffA);
;             PG8_WAIT_V(8); PG8_WAIT_L(0); PG8_BAR; PG8_MMA(0, 0, At, B0); PG8_MMA(0, 1, At, B1); PG8_BAR; PG8_SCHED;
	s_setprio 1
	s_waitcnt lgkmcnt(0)
	v_mfma_f32_16x16x32_bf16 v[60:63], v[136:139], v[214:217], v[60:63]
	v_mfma_f32_16x16x32_bf16 v[60:63], v[140:143], v[218:221], v[60:63]
	v_mfma_f32_16x16x32_bf16 v[48:51], v[140:143], v[226:229], v[48:51]
	v_mfma_f32_16x16x32_bf16 v[48:51], v[136:139], v[222:225], v[48:51]
	v_mfma_f32_16x16x32_bf16 v[32:35], v[136:139], v[230:233], v[32:35]
	v_mfma_f32_16x16x32_bf16 v[32:35], v[140:143], v[234:237], v[32:35]
	v_mfma_f32_16x16x32_bf16 v[12:15], v[140:143], v[242:245], v[12:15]
	v_mfma_f32_16x16x32_bf16 v[12:15], v[136:139], v[238:241], v[12:15]
	v_mfma_f32_16x16x32_bf16 v[8:11], v[172:175], v[238:241], v[8:11]
	v_mfma_f32_16x16x32_bf16 v[8:11], v[176:179], v[242:245], v[8:11]
	v_mfma_f32_16x16x32_bf16 v[24:27], v[176:179], v[234:237], v[24:27]
	v_mfma_f32_16x16x32_bf16 v[24:27], v[172:175], v[230:233], v[24:27]
	v_mfma_f32_16x16x32_bf16 v[40:43], v[172:175], v[222:225], v[40:43]
	v_mfma_f32_16x16x32_bf16 v[40:43], v[176:179], v[226:229], v[40:43]
	v_mfma_f32_16x16x32_bf16 v[56:59], v[176:179], v[218:221], v[56:59]
	v_mfma_f32_16x16x32_bf16 v[56:59], v[172:175], v[214:217], v[56:59]
	s_setprio 0
	s_setprio 1
	v_mfma_f32_16x16x32_bf16 v[52:55], v[180:183], v[214:217], v[52:55]
	v_mfma_f32_16x16x32_bf16 v[52:55], v[184:187], v[218:221], v[52:55]
	v_mfma_f32_16x16x32_bf16 v[36:39], v[184:187], v[226:229], v[36:39]
	v_mfma_f32_16x16x32_bf16 v[36:39], v[180:183], v[222:225], v[36:39]
	v_mfma_f32_16x16x32_bf16 v[20:23], v[180:183], v[230:233], v[20:23]
	v_mfma_f32_16x16x32_bf16 v[20:23], v[184:187], v[234:237], v[20:23]
	v_mfma_f32_16x16x32_bf16 v[4:7], v[184:187], v[242:245], v[4:7]
	v_mfma_f32_16x16x32_bf16 v[4:7], v[180:183], v[238:241], v[4:7]
	v_mfma_f32_16x16x32_bf16 v[0:3], v[206:209], v[238:241], v[0:3]
	v_mfma_f32_16x16x32_bf16 v[0:3], v[210:213], v[242:245], v[0:3]
	v_mfma_f32_16x16x32_bf16 v[16:19], v[210:213], v[234:237], v[16:19]
	v_mfma_f32_16x16x32_bf16 v[16:19], v[206:209], v[230:233], v[16:19]
	v_mfma_f32_16x16x32_bf16 v[28:31], v[206:209], v[222:225], v[28:31]
	v_mfma_f32_16x16x32_bf16 v[28:31], v[210:213], v[226:229], v[28:31]
	s_setprio 2
	s_barrier
	v_mfma_f32_16x16x32_bf16 v[44:47], v[210:213], v[218:221], v[44:47]
	v_mfma_f32_16x16x32_bf16 v[44:47], v[206:209], v[214:217], v[44:47]
	s_setprio 0
	s_add_i32 s44, 0, 0x18000
	v_add_u32_e32 v144, s44, v146
	s_add_i32 s45, 0, 0x1c000
	ds_read_b128 v[136:139], v144
	ds_read_b128 v[140:143], v144 offset:1024
	ds_read_b128 v[172:175], v144 offset:2048
	ds_read_b128 v[176:179], v144 offset:3072
	v_add_u32_e32 v144, s45, v146
	ds_read_b128 v[180:183], v144
	ds_read_b128 v[184:187], v144 offset:1024
	ds_read_b128 v[206:209], v144 offset:2048
	ds_read_b128 v[210:213], v144 offset:3072
	s_add_u32 s48, s48, 0x80000
	s_addc_u32 s49, s49, 0
	s_mov_b32 m0, s56
	v_lshl_add_u64 v[252:253], s[48:49], 0, v[164:165]
	ds_read_b128 v[214:217], v158 offset:32768
	ds_read_b128 v[218:221], v158 offset:33792
	ds_read_b128 v[222:225], v158 offset:34816
	ds_read_b128 v[226:229], v158 offset:35840
	ds_read_b128 v[230:233], v158 offset:36864
	ds_read_b128 v[234:237], v158 offset:37888
	ds_read_b128 v[238:241], v158 offset:38912
	ds_read_b128 v[242:245], v158 offset:39936
	global_load_lds_dwordx4 v[252:253], off
	v_lshl_add_u64 v[252:253], s[48:49], 0, v[168:169]
	s_mov_b32 m0, s57
	s_nop 0
	global_load_lds_dwordx4 v[252:253], off
	s_waitcnt vmcnt(8)
	s_waitcnt lgkmcnt(0)
	s_barrier
	s_setprio 1
	s_waitcnt lgkmcnt(0)
	v_mfma_f32_16x16x32_bf16 v[124:127], v[136:139], v[214:217], v[124:127]
	v_mfma_f32_16x16x32_bf16 v[124:127], v[140:143], v[218:221], v[124:127]
	v_mfma_f32_16x16x32_bf16 v[108:111], v[140:143], v[226:229], v[108:111]
	v_mfma_f32_16x16x32_bf16 v[108:111], v[136:139], v[222:225], v[108:111]
	v_mfma_f32_16x16x32_bf16 v[96:99], v[136:139], v[230:233], v[96:99]
	v_mfma_f32_16x16x32_bf16 v[96:99], v[140:143], v[234:237], v[96:99]
	v_mfma_f32_16x16x32_bf16 v[80:83], v[140:143], v[242:245], v[80:83]
	v_mfma_f32_16x16x32_bf16 v[80:83], v[136:139], v[238:241], v[80:83]
	v_mfma_f32_16x16x32_bf16 v[72:75], v[172:175], v[238:241], v[72:75]
	v_mfma_f32_16x16x32_bf16 v[72:75], v[176:179], v[242:245], v[72:75]
	v_mfma_f32_16x16x32_bf16 v[88:91], v[176:179], v[234:237], v[88:91]
	v_mfma_f32_16x16x32_bf16 v[88:91], v[172:175], v[230:233], v[88:91]
	v_mfma_f32_16x16x32_bf16 v[104:107], v[172:175], v[222:225], v[104:107]
	v_mfma_f32_16x16x32_bf16 v[104:107], v[176:179], v[226:229], v[104:107]
	v_mfma_f32_16x16x32_bf16 v[120:123], v[176:179], v[218:221], v[120:123]
	v_mfma_f32_16x16x32_bf16 v[120:123], v[172:175], v[214:217], v[120:123]
	s_setprio 0
	s_setprio 1
	v_mfma_f32_16x16x32_bf16 v[116:119], v[180:183], v[214:217], v[116:119]
	v_mfma_f32_16x16x32_bf16 v[116:119], v[184:187], v[218:221], v[116:119]
	v_mfma_f32_16x16x32_bf16 v[100:103], v[184:187], v[226:229], v[100:103]
	v_mfma_f32_16x16x32_bf16 v[100:103], v[180:183], v[222:225], v[100:103]
	v_mfma_f32_16x16x32_bf16 v[84:87], v[180:183], v[230:233], v[84:87]
	v_mfma_f32_16x16x32_bf16 v[84:87], v[184:187], v[234:237], v[84:87]
	v_mfma_f32_16x16x32_bf16 v[68:71], v[184:187], v[242:245], v[68:71]
	v_mfma_f32_16x16x32_bf16 v[68:71], v[180:183], v[238:241], v[68:71]
	v_mfma_f32_16x16x32_bf16 v[64:67], v[206:209], v[238:241], v[64:67]
	v_mfma_f32_16x16x32_bf16 v[64:67], v[210:213], v[242:245], v[64:67]
	v_mfma_f32_16x16x32_bf16 v[76:79], v[210:213], v[234:237], v[76:79]
	v_mfma_f32_16x16x32_bf16 v[76:79], v[206:209], v[230:233], v[76:79]
	v_mfma_f32_16x16x32_bf16 v[92:95], v[206:209], v[222:225], v[92:95]
	v_mfma_f32_16x16x32_bf16 v[92:95], v[210:213], v[226:229], v[92:95]
	s_setprio 2
	s_barrier
; #define PG8_STAGE(bufoff, gbase, voff) do { _Pragma("unroll") for (int _i = 0; _i < 2; ++_i) \
;         __builtin_amdgcn_global_load_lds((const unsigned*)((const char*)(gbase) + (voff)[_i]), (PG8_LAS unsigned*)(lds + (bufoff) + ldsw + _i * 8192), 16, 0, 0); } while (0)
; #define PG8_LDA(dst, b, h) do { _Pragma("unroll") for (int m = 0; m < 4; ++m) _Pragma("unroll") for (int k = 0; k < 2; ++k) dst[m][k] = *(const PG8_LAS bf16x8*)(lds + PG8_SA(b, h) + aoff + m * 2048 + k * 1024); } while (0)
; #define PG8_MMA(ai, bj, At, Bt) do { __builtin_amdgcn_s_setprio(1); _Pragma("unroll") for (int m = 0; m < 4; ++m) _Pragma("unroll") for (int n = 0; n < 2; ++n) _Pragma("unroll") for (int k = 0; k < 2; ++k) \
;         acc[ai][bj][m][n] = __builtin_amdgcn_mfma_f32_16x16x32_bf16(Bt[n][k], At[m][k], acc[ai][bj][m][n], 0, 0, 0); __builtin_amdgcn_s_setprio(0); } while (0)
; #define PG8_WAIT_V(n) asm volatile("s_waitcnt vmcnt(" #n ")" ::: "memory")
; #define PG8_WAIT_L(n) asm volatile("s_waitcnt lgkmcnt(" #n ")" ::: "memory")
; #define PG8_BAR __builtin_amdgcn_s_barrier()
; #define PG8_SCHED __builtin_amdgcn_sched_barrier(0)
; template <class Epi, class Sched, bool ALIGN_EPI = false, bool SP2 = false>
; __device__ __forceinline__ void gemm_phase(PG8_LAS unsigned char* lds, const Gemm g, const Sched& S, const Epi& E) {
;     ...
;         for (int t = 0; t < nt; t += 2) {
;     ...
;             PG8_WAIT_V(8); PG8_WAIT_L(0); PG8_BAR; PG8_MMA(0, 0, At, B0); PG8_MMA(0, 1, At, B1); PG8_BAR; PG8_SCHED;
;             PG8_LDA(At, 1, 1); PG8_STAGE(PG8_SB(1, 0), b3, voffB); PG8_STAGE(PG8_SB(1, 1), b3 + hstep, voffB); PG8_STAGE(PG8_SA(1, 0), a3, voffA);
;             PG8_WAIT_V(8); PG8_WAIT_L(0); PG8_BAR; PG8_MMA(1, 0, At, B0); PG8_MMA(1, 1, At, B1); PG8_BAR; PG8_SCHED;
	v_mfma_f32_16x16x32_bf16 v[112:115], v[210:213], v[218:221], v[112:115]
	v_mfma_f32_16x16x32_bf16 v[112:115], v[206:209], v[214:217], v[112:115]
	s_setprio 0
	s_add_i32 s44, s44, s39
	v_lshl_add_u64 v[200:201], v[200:201], 0, s[18:19]
	s_mov_b32 m0, s44
	ds_read_b128 v[214:217], v158 offset:49152
	ds_read_b128 v[218:221], v158 offset:50176
	ds_read_b128 v[222:225], v158 offset:51200
	ds_read_b128 v[226:229], v158 offset:52224
	ds_read_b128 v[230:233], v158 offset:53248
	ds_read_b128 v[234:237], v158 offset:54272
	ds_read_b128 v[238:241], v158 offset:55296
	ds_read_b128 v[242:245], v158 offset:56320
	global_load_lds_dwordx4 v[200:201], off
	s_add_i32 m0, s44, 0x2000
	s_add_u32 s28, s28, 0x80080
	v_lshl_add_u64 v[200:201], v[246:247], 0, s[18:19]
	s_addc_u32 s29, s29, 0
	s_add_i32 s44, s45, s39
	global_load_lds_dwordx4 v[200:201], off
	v_lshl_add_u64 v[200:201], s[28:29], 0, v[166:167]
	s_mov_b32 m0, s44
	s_nop 0
	global_load_lds_dwordx4 v[200:201], off
	v_lshl_add_u64 v[200:201], s[28:29], 0, v[170:171]
	s_add_i32 m0, s44, 0x2000
	s_nop 0
	global_load_lds_dwordx4 v[200:201], off
	v_lshl_add_u64 v[200:201], v[248:249], 0, s[18:19]
	s_mov_b32 m0, s70
	s_nop 0
	global_load_lds_dwordx4 v[200:201], off
	v_lshl_add_u64 v[200:201], v[250:251], 0, s[18:19]
	s_mov_b32 m0, s71
	s_nop 0
	global_load_lds_dwordx4 v[200:201], off
	s_waitcnt vmcnt(8)
	s_waitcnt lgkmcnt(0)
	s_barrier
	s_setprio 1
	s_waitcnt lgkmcnt(0)
	v_mfma_f32_16x16x32_bf16 v[60:63], v[136:139], v[214:217], v[60:63]
	v_mfma_f32_16x16x32_bf16 v[60:63], v[140:143], v[218:221], v[60:63]
	v_mfma_f32_16x16x32_bf16 v[48:51], v[140:143], v[226:229], v[48:51]
	v_mfma_f32_16x16x32_bf16 v[48:51], v[136:139], v[222:225], v[48:51]
	v_mfma_f32_16x16x32_bf16 v[32:35], v[136:139], v[230:233], v[32:35]
	v_mfma_f32_16x16x32_bf16 v[32:35], v[140:143], v[234:237], v[32:35]
	v_mfma_f32_16x16x32_bf16 v[12:15], v[140:143], v[242:245], v[12:15]
	v_mfma_f32_16x16x32_bf16 v[12:15], v[136:139], v[238:241], v[12:15]
	v_mfma_f32_16x16x32_bf16 v[8:11], v[172:175], v[238:241], v[8:11]
	v_mfma_f32_16x16x32_bf16 v[8:11], v[176:179], v[242:245], v[8:11]
	v_mfma_f32_16x16x32_bf16 v[24:27], v[176:179], v[234:237], v[24:27]
	v_mfma_f32_16x16x32_bf16 v[24:27], v[172:175], v[230:233], v[24:27]
	v_mfma_f32_16x16x32_bf16 v[40:43], v[172:175], v[222:225], v[40:43]
	v_mfma_f32_16x16x32_bf16 v[40:43], v[176:179], v[226:229], v[40:43]
	v_mfma_f32_16x16x32_bf16 v[56:59], v[176:179], v[218:221], v[56:59]
	v_mfma_f32_16x16x32_bf16 v[56:59], v[172:175], v[214:217], v[56:59]
	s_setprio 0
	s_setprio 1
	v_mfma_f32_16x16x32_bf16 v[52:55], v[180:183], v[214:217], v[52:55]
	v_mfma_f32_16x16x32_bf16 v[52:55], v[184:187], v[218:221], v[52:55]
	v_mfma_f32_16x16x32_bf16 v[36:39], v[184:187], v[226:229], v[36:39]
	v_mfma_f32_16x16x32_bf16 v[36:39], v[180:183], v[222:225], v[36:39]
	v_mfma_f32_16x16x32_bf16 v[20:23], v[180:183], v[230:233], v[20:23]
	v_mfma_f32_16x16x32_bf16 v[20:23], v[184:187], v[234:237], v[20:23]
	v_mfma_f32_16x16x32_bf16 v[4:7], v[184:187], v[242:245], v[4:7]
	v_mfma_f32_16x16x32_bf16 v[4:7], v[180:183], v[238:241], v[4:7]
	v_mfma_f32_16x16x32_bf16 v[0:3], v[206:209], v[238:241], v[0:3]
	v_mfma_f32_16x16x32_bf16 v[0:3], v[210:213], v[242:245], v[0:3]
	v_mfma_f32_16x16x32_bf16 v[16:19], v[210:213], v[234:237], v[16:19]
	v_mfma_f32_16x16x32_bf16 v[16:19], v[206:209], v[230:233], v[16:19]
	v_mfma_f32_16x16x32_bf16 v[28:31], v[206:209], v[222:225], v[28:31]
	v_mfma_f32_16x16x32_bf16 v[28:31], v[210:213], v[226:229], v[28:31]
	s_setprio 2
	s_barrier
	v_mfma_f32_16x16x32_bf16 v[44:47], v[210:213], v[218:221], v[44:47]
	v_mfma_f32_16x16x32_bf16 v[44:47], v[206:209], v[214:217], v[44:47]
	s_setprio 0
	s_add_i32 s79, s79, 2
	s_add_u32 s68, s68, 0x100
	s_addc_u32 s69, s69, 0
	s_add_u32 s77, s77, 0x100
	s_addc_u32 s78, s78, 0
	s_cmp_gt_u32 s79, 29
	s_cbranch_scc0 .LBB0_416
	s_and_b64 vcc, exec, s[20:21]
	s_cbranch_vccz .LBB0_419
	s_barrier

; #define PG8_STAGE(bufoff, gbase, voff) do { _Pragma("unroll") for (int _i = 0; _i < 2; ++_i) \
;         __builtin_amdgcn_global_load_lds((const unsigned*)((const char*)(gbase) + (voff)[_i]), (PG8_LAS unsigned*)(lds + (bufoff) + ldsw + _i * 8192), 16, 0, 0); } while (0)
; #define PG8_LDA(dst, b, h) do { _Pragma("unroll") for (int m = 0; m < 4; ++m) _Pragma("unroll") for (int k = 0; k < 2; ++k) dst[m][k] = *(const PG8_LAS bf16x8*)(lds + PG8_SA(b, h) + aoff + m * 2048 + k * 1024); } while (0)
; #define PG8_LDB(dst, b, h) do { _Pragma("unroll") for (int n = 0; n < 2; ++n) _Pragma("unroll") for (int k = 0; k < 2; ++k) dst[n][k] = *(const PG8_LAS bf16x8*)(lds + PG8_SB(b, h) + boff + n * 2048 + k * 1024); } while (0)
; #define PG8_MMA(ai, bj, At, Bt) do { __builtin_amdgcn_s_setprio(1); _Pragma("unroll") for (int m = 0; m < 4; ++m) _Pragma("unroll") for (int n = 0; n < 2; ++n) _Pragma("unroll") for (int k = 0; k < 2; ++k) \
;         acc[ai][bj][m][n] = __builtin_amdgcn_mfma_f32_16x16x32_bf16(Bt[n][k], At[m][k], acc[ai][bj][m][n], 0, 0, 0); __builtin_amdgcn_s_setprio(0); } while (0)
; #define PG8_WAIT_V(n) asm volatile("s_waitcnt vmcnt(" #n ")" ::: "memory")
; #define PG8_WAIT_L(n) asm volatile("s_waitcnt lgkmcnt(" #n ")" ::: "memory")
; #define PG8_BAR __builtin_amdgcn_s_barrier()
; #define PG8_SCHED __builtin_amdgcn_sched_barrier(0)
; template <class Epi, class Sched, bool ALIGN_EPI = false, bool SP2 = false>
; __device__ __forceinline__ void gemm_phase(PG8_LAS unsigned char* lds, const Gemm g, const Sched& S, const Epi& E) {
;     ...
;         for (int t = 0; t < nt; t += 2) {
;             const bool last = (t == nt - 2);
;             const char* a1 = cA + (size_t)(t + 1) * kstep;
;             const char* a2 = last ? nA : cA + (size_t)(t + 2) * kstep; const char* b2 = last ? nB : cB + (size_t)(t + 2) * kstep;
;             const char* a3 = a2 + kstep; const char* b3 = b2 + kstep;
;             if (last && has_next) S.a_ready(nxt);
;             if constexpr (SP2) {
;             PG8_LDB(B0, 0, 0); PG8_LDB(B1, 0, 1); PG8_SCHED; PG8_LDA(At, 0, 0); PG8_STAGE(PG8_SA(1, 1), a1 + hstep, voffA);
;             PG8_WAIT_V(8); PG8_WAIT_L(0); PG8_BAR; PG8_MMA(0, 0, At, B0); PG8_MMA(0, 1, At, B1); PG8_BAR; PG8_SCHED;
;             PG8_LDA(At, 0, 1); PG8_STAGE(PG8_SB(0, 0), b2, voffB); PG8_STAGE(PG8_SB(0, 1), b2 + hstep, voffB); PG8_STAGE(PG8_SA(0, 0), a2, voffA);
.LBB0_482:
	ds_read_b128 v[76:79], v171
	ds_read_b128 v[84:87], v171 offset:1024
	ds_read_b128 v[92:95], v171 offset:2048
	ds_read_b128 v[96:99], v171 offset:3072
	ds_read_b128 v[144:147], v186
	ds_read_b128 v[148:151], v186 offset:1024
	ds_read_b128 v[152:155], v186 offset:2048
	ds_read_b128 v[156:159], v186 offset:3072
	s_add_u32 s28, s64, 0xffea0080
	s_addc_u32 s29, s65, -1
	s_cmpk_eq_i32 s77, 0x54
	s_cselect_b32 s49, s39, s29
	s_cselect_b32 s48, s38, s28
	s_cselect_b32 s29, s63, s35
	s_cselect_b32 s28, s62, s34
	v_lshl_add_u64 v[200:201], s[64:65], 0, v[172:173]
	s_add_i32 m0, s56, 0xc000
	ds_read_b128 v[178:181], v187
	ds_read_b128 v[182:185], v187 offset:1024
	ds_read_b128 v[206:209], v187 offset:2048
	ds_read_b128 v[210:213], v187 offset:3072
	ds_read_b128 v[214:217], v187 offset:4096
	ds_read_b128 v[218:221], v187 offset:5120
	ds_read_b128 v[222:225], v187 offset:6144
	ds_read_b128 v[226:229], v187 offset:7168
	global_load_lds_dwordx4 v[200:201], off
	v_lshl_add_u64 v[200:201], s[64:65], 0, v[174:175]
	s_add_i32 m0, s56, 0xe000
	s_nop 0
	global_load_lds_dwordx4 v[200:201], off
	s_waitcnt vmcnt(8)
	s_waitcnt lgkmcnt(0)
	s_barrier
	s_setprio 1
	s_waitcnt lgkmcnt(0)
	v_mfma_f32_16x16x32_bf16 v[140:143], v[76:79], v[178:181], v[140:143]
	v_mfma_f32_16x16x32_bf16 v[140:143], v[84:87], v[182:185], v[140:143]
	v_mfma_f32_16x16x32_bf16 v[124:127], v[84:87], v[210:213], v[124:127]
	v_mfma_f32_16x16x32_bf16 v[124:127], v[76:79], v[206:209], v[124:127]
	v_mfma_f32_16x16x32_bf16 v[108:111], v[76:79], v[214:217], v[108:111]
	v_mfma_f32_16x16x32_bf16 v[108:111], v[84:87], v[218:221], v[108:111]
	v_mfma_f32_16x16x32_bf16 v[80:83], v[84:87], v[226:229], v[80:83]
	v_mfma_f32_16x16x32_bf16 v[80:83], v[76:79], v[222:225], v[80:83]
	v_mfma_f32_16x16x32_bf16 v[72:75], v[92:95], v[222:225], v[72:75]
	v_mfma_f32_16x16x32_bf16 v[72:75], v[96:99], v[226:229], v[72:75]
	v_mfma_f32_16x16x32_bf16 v[104:107], v[96:99], v[218:221], v[104:107]
	v_mfma_f32_16x16x32_bf16 v[104:107], v[92:95], v[214:217], v[104:107]
	v_mfma_f32_16x16x32_bf16 v[120:123], v[92:95], v[206:209], v[120:123]
	v_mfma_f32_16x16x32_bf16 v[120:123], v[96:99], v[210:213], v[120:123]
	v_mfma_f32_16x16x32_bf16 v[136:139], v[96:99], v[182:185], v[136:139]
	v_mfma_f32_16x16x32_bf16 v[136:139], v[92:95], v[178:181], v[136:139]
	s_setprio 0
	s_setprio 1
	v_mfma_f32_16x16x32_bf16 v[132:135], v[144:147], v[178:181], v[132:135]
	v_mfma_f32_16x16x32_bf16 v[132:135], v[148:151], v[182:185], v[132:135]
	v_mfma_f32_16x16x32_bf16 v[116:119], v[148:151], v[210:213], v[116:119]
	v_mfma_f32_16x16x32_bf16 v[116:119], v[144:147], v[206:209], v[116:119]
	v_mfma_f32_16x16x32_bf16 v[100:103], v[144:147], v[214:217], v[100:103]
	v_mfma_f32_16x16x32_bf16 v[100:103], v[148:151], v[218:221], v[100:103]
	v_mfma_f32_16x16x32_bf16 v[68:71], v[148:151], v[226:229], v[68:71]
	v_mfma_f32_16x16x32_bf16 v[68:71], v[144:147], v[222:225], v[68:71]
	v_mfma_f32_16x16x32_bf16 v[64:67], v[152:155], v[222:225], v[64:67]
	v_mfma_f32_16x16x32_bf16 v[64:67], v[156:159], v[226:229], v[64:67]
	v_mfma_f32_16x16x32_bf16 v[88:91], v[156:159], v[218:221], v[88:91]
	v_mfma_f32_16x16x32_bf16 v[88:91], v[152:155], v[214:217], v[88:91]
	v_mfma_f32_16x16x32_bf16 v[112:115], v[152:155], v[206:209], v[112:115]
	v_mfma_f32_16x16x32_bf16 v[112:115], v[156:159], v[210:213], v[112:115]
	s_setprio 2
	s_barrier
	v_mfma_f32_16x16x32_bf16 v[128:131], v[156:159], v[182:185], v[128:131]
	v_mfma_f32_16x16x32_bf16 v[128:131], v[152:155], v[178:181], v[128:131]
	s_setprio 0
	s_add_i32 s44, s70, s41
	v_lshl_add_u64 v[200:201], s[28:29], 0, v[160:161]
	s_mov_b32 m0, s44
	ds_read_b128 v[178:181], v187 offset:16384
	ds_read_b128 v[182:185], v187 offset:17408
	ds_read_b128 v[206:209], v187 offset:18432
	ds_read_b128 v[210:213], v187 offset:19456
	ds_read_b128 v[214:217], v187 offset:20480
	ds_read_b128 v[218:221], v187 offset:21504
	ds_read_b128 v[222:225], v187 offset:22528
	ds_read_b128 v[226:229], v187 offset:23552
	global_load_lds_dwordx4 v[200:201], off
	s_add_i32 m0, s44, 0x2000
	s_add_u32 s78, s28, 0x160000
	v_lshl_add_u64 v[230:231], s[28:29], 0, v[162:163]
	s_addc_u32 s79, s29, 0
	s_add_i32 s44, s71, s41
	global_load_lds_dwordx4 v[230:231], off
	v_lshl_add_u64 v[232:233], s[78:79], 0, v[160:161]
	s_mov_b32 m0, s44
	v_lshl_add_u64 v[234:235], s[48:49], 0, v[162:163]
	global_load_lds_dwordx4 v[232:233], off
	v_lshl_add_u64 v[232:233], s[78:79], 0, v[162:163]
	s_add_i32 m0, s44, 0x2000
	s_nop 0
	global_load_lds_dwordx4 v[232:233], off
	v_lshl_add_u64 v[232:233], s[48:49], 0, v[160:161]
	s_mov_b32 m0, s56
	s_nop 0
	global_load_lds_dwordx4 v[232:233], off
	s_mov_b32 m0, s57
	s_nop 0
	global_load_lds_dwordx4 v[234:235], off
	s_waitcnt vmcnt(8)
	s_waitcnt lgkmcnt(0)
	s_barrier
; #define PG8_STAGE(bufoff, gbase, voff) do { _Pragma("unroll") for (int _i = 0; _i < 2; ++_i) \
;         __builtin_amdgcn_global_load_lds((const unsigned*)((const char*)(gbase) + (voff)[_i]), (PG8_LAS unsigned*)(lds + (bufoff) + ldsw + _i * 8192), 16, 0, 0); } while (0)
; #define PG8_LDA(dst, b, h) do { _Pragma("unroll") for (int m = 0; m < 4; ++m) _Pragma("unroll") for (int k = 0; k < 2; ++k) dst[m][k] = *(const PG8_LAS bf16x8*)(lds + PG8_SA(b, h) + aoff + m * 2048 + k * 1024); } while (0)
; #define PG8_LDB(dst, b, h) do { _Pragma("unroll") for (int n = 0; n < 2; ++n) _Pragma("unroll") for (int k = 0; k < 2; ++k) dst[n][k] = *(const PG8_LAS bf16x8*)(lds + PG8_SB(b, h) + boff + n * 2048 + k * 1024); } while (0)
; #define PG8_MMA(ai, bj, At, Bt) do { __builtin_amdgcn_s_setprio(1); _Pragma("unroll") for (int m = 0; m < 4; ++m) _Pragma("unroll") for (int n = 0; n < 2; ++n) _Pragma("unroll") for (int k = 0; k < 2; ++k) \
;         acc[ai][bj][m][n] = __builtin_amdgcn_mfma_f32_16x16x32_bf16(Bt[n][k], At[m][k], acc[ai][bj][m][n], 0, 0, 0); __builtin_amdgcn_s_setprio(0); } while (0)
; #define PG8_WAIT_V(n) asm volatile("s_waitcnt vmcnt(" #n ")" ::: "memory")
; #define PG8_WAIT_L(n) asm volatile("s_waitcnt lgkmcnt(" #n ")" ::: "memory")
; #define PG8_BAR __builtin_amdgcn_s_barrier()
; #define PG8_SCHED __builtin_amdgcn_sched_barrier(0)
; template <class Epi, class Sched, bool ALIGN_EPI = false, bool SP2 = false>
; __device__ __forceinline__ void gemm_phase(PG8_LAS unsigned char* lds, const Gemm g, const Sched& S, const Epi& E) {
;     ...
;             PG8_WAIT_V(8); PG8_WAIT_L(0); PG8_BAR; PG8_MMA(1, 0, At, B0); PG8_MMA(1, 1, At, B1); PG8_BAR; PG8_SCHED;
;             PG8_LDB(B0, 1, 0); PG8_LDB(B1, 1, 1); PG8_SCHED; PG8_LDA(At, 1, 0); PG8_STAGE(PG8_SA(0, 1), a2 + hstep, voffA);
;             PG8_WAIT_V(8); PG8_WAIT_L(0); PG8_BAR; PG8_MMA(0, 0, At, B0); PG8_MMA(0, 1, At, B1); PG8_BAR; PG8_SCHED;
	s_setprio 1
	s_waitcnt lgkmcnt(0)
	v_mfma_f32_16x16x32_bf16 v[60:63], v[76:79], v[178:181], v[60:63]
	v_mfma_f32_16x16x32_bf16 v[60:63], v[84:87], v[182:185], v[60:63]
	v_mfma_f32_16x16x32_bf16 v[44:47], v[84:87], v[210:213], v[44:47]
	v_mfma_f32_16x16x32_bf16 v[44:47], v[76:79], v[206:209], v[44:47]
	v_mfma_f32_16x16x32_bf16 v[28:31], v[76:79], v[214:217], v[28:31]
	v_mfma_f32_16x16x32_bf16 v[28:31], v[84:87], v[218:221], v[28:31]
	v_mfma_f32_16x16x32_bf16 v[12:15], v[84:87], v[226:229], v[12:15]
	v_mfma_f32_16x16x32_bf16 v[12:15], v[76:79], v[222:225], v[12:15]
	v_mfma_f32_16x16x32_bf16 v[8:11], v[92:95], v[222:225], v[8:11]
	v_mfma_f32_16x16x32_bf16 v[8:11], v[96:99], v[226:229], v[8:11]
	v_mfma_f32_16x16x32_bf16 v[24:27], v[96:99], v[218:221], v[24:27]
	v_mfma_f32_16x16x32_bf16 v[24:27], v[92:95], v[214:217], v[24:27]
	v_mfma_f32_16x16x32_bf16 v[40:43], v[92:95], v[206:209], v[40:43]
	v_mfma_f32_16x16x32_bf16 v[40:43], v[96:99], v[210:213], v[40:43]
	v_mfma_f32_16x16x32_bf16 v[56:59], v[96:99], v[182:185], v[56:59]
	v_mfma_f32_16x16x32_bf16 v[56:59], v[92:95], v[178:181], v[56:59]
	s_setprio 0
	s_setprio 1
	v_mfma_f32_16x16x32_bf16 v[52:55], v[144:147], v[178:181], v[52:55]
	v_mfma_f32_16x16x32_bf16 v[52:55], v[148:151], v[182:185], v[52:55]
	v_mfma_f32_16x16x32_bf16 v[36:39], v[148:151], v[210:213], v[36:39]
	v_mfma_f32_16x16x32_bf16 v[36:39], v[144:147], v[206:209], v[36:39]
	v_mfma_f32_16x16x32_bf16 v[20:23], v[144:147], v[214:217], v[20:23]
	v_mfma_f32_16x16x32_bf16 v[20:23], v[148:151], v[218:221], v[20:23]
	v_mfma_f32_16x16x32_bf16 v[4:7], v[148:151], v[226:229], v[4:7]
	v_mfma_f32_16x16x32_bf16 v[4:7], v[144:147], v[222:225], v[4:7]
	v_mfma_f32_16x16x32_bf16 v[0:3], v[152:155], v[222:225], v[0:3]
	v_mfma_f32_16x16x32_bf16 v[0:3], v[156:159], v[226:229], v[0:3]
	v_mfma_f32_16x16x32_bf16 v[16:19], v[156:159], v[218:221], v[16:19]
	v_mfma_f32_16x16x32_bf16 v[16:19], v[152:155], v[214:217], v[16:19]
	v_mfma_f32_16x16x32_bf16 v[32:35], v[152:155], v[206:209], v[32:35]
	v_mfma_f32_16x16x32_bf16 v[32:35], v[156:159], v[210:213], v[32:35]
	s_setprio 2
	s_barrier
	v_mfma_f32_16x16x32_bf16 v[48:51], v[156:159], v[182:185], v[48:51]
	v_mfma_f32_16x16x32_bf16 v[48:51], v[152:155], v[178:181], v[48:51]
	s_setprio 0
	s_add_i32 s44, 0, 0x18000
	s_add_i32 s45, 0, 0x1c000
	v_add_u32_e32 v96, s44, v167
	v_add_u32_e32 v156, s45, v167
	ds_read_b128 v[76:79], v96
	ds_read_b128 v[84:87], v96 offset:1024
	ds_read_b128 v[92:95], v96 offset:2048
	ds_read_b128 v[96:99], v96 offset:3072
	ds_read_b128 v[144:147], v156
	ds_read_b128 v[148:151], v156 offset:1024
	ds_read_b128 v[152:155], v156 offset:2048
	ds_read_b128 v[156:159], v156 offset:3072
	s_add_u32 s48, s48, 0x160000
	s_addc_u32 s49, s49, 0
	s_mov_b32 m0, s61
	v_lshl_add_u64 v[236:237], s[48:49], 0, v[160:161]
	ds_read_b128 v[178:181], v187 offset:32768
	ds_read_b128 v[182:185], v187 offset:33792
	ds_read_b128 v[206:209], v187 offset:34816
	ds_read_b128 v[210:213], v187 offset:35840
	ds_read_b128 v[214:217], v187 offset:36864
	ds_read_b128 v[218:221], v187 offset:37888
	ds_read_b128 v[222:225], v187 offset:38912
	ds_read_b128 v[226:229], v187 offset:39936
	global_load_lds_dwordx4 v[236:237], off
	v_lshl_add_u64 v[236:237], s[48:49], 0, v[162:163]
	s_mov_b32 m0, s66
	s_nop 0
	global_load_lds_dwordx4 v[236:237], off
	s_waitcnt vmcnt(8)
	s_waitcnt lgkmcnt(0)
	s_barrier
	s_setprio 1
	s_waitcnt lgkmcnt(0)
	v_mfma_f32_16x16x32_bf16 v[140:143], v[76:79], v[178:181], v[140:143]
	v_mfma_f32_16x16x32_bf16 v[140:143], v[84:87], v[182:185], v[140:143]
	v_mfma_f32_16x16x32_bf16 v[124:127], v[84:87], v[210:213], v[124:127]
	v_mfma_f32_16x16x32_bf16 v[124:127], v[76:79], v[206:209], v[124:127]
	v_mfma_f32_16x16x32_bf16 v[108:111], v[76:79], v[214:217], v[108:111]
	v_mfma_f32_16x16x32_bf16 v[108:111], v[84:87], v[218:221], v[108:111]
	v_mfma_f32_16x16x32_bf16 v[80:83], v[84:87], v[226:229], v[80:83]
	v_mfma_f32_16x16x32_bf16 v[80:83], v[76:79], v[222:225], v[80:83]
	v_mfma_f32_16x16x32_bf16 v[72:75], v[92:95], v[222:225], v[72:75]
	v_mfma_f32_16x16x32_bf16 v[72:75], v[96:99], v[226:229], v[72:75]
	v_mfma_f32_16x16x32_bf16 v[104:107], v[96:99], v[218:221], v[104:107]
	v_mfma_f32_16x16x32_bf16 v[104:107], v[92:95], v[214:217], v[104:107]
	v_mfma_f32_16x16x32_bf16 v[120:123], v[92:95], v[206:209], v[120:123]
	v_mfma_f32_16x16x32_bf16 v[120:123], v[96:99], v[210:213], v[120:123]
	v_mfma_f32_16x16x32_bf16 v[136:139], v[96:99], v[182:185], v[136:139]
	v_mfma_f32_16x16x32_bf16 v[136:139], v[92:95], v[178:181], v[136:139]
	s_setprio 0
	s_setprio 1
	v_mfma_f32_16x16x32_bf16 v[132:135], v[144:147], v[178:181], v[132:135]
	v_mfma_f32_16x16x32_bf16 v[132:135], v[148:151], v[182:185], v[132:135]
	v_mfma_f32_16x16x32_bf16 v[116:119], v[148:151], v[210:213], v[116:119]
	v_mfma_f32_16x16x32_bf16 v[116:119], v[144:147], v[206:209], v[116:119]
	v_mfma_f32_16x16x32_bf16 v[100:103], v[144:147], v[214:217], v[100:103]
	v_mfma_f32_16x16x32_bf16 v[100:103], v[148:151], v[218:221], v[100:103]
	v_mfma_f32_16x16x32_bf16 v[68:71], v[148:151], v[226:229], v[68:71]
	v_mfma_f32_16x16x32_bf16 v[68:71], v[144:147], v[222:225], v[68:71]
	v_mfma_f32_16x16x32_bf16 v[64:67], v[152:155], v[222:225], v[64:67]
	v_mfma_f32_16x16x32_bf16 v[64:67], v[156:159], v[226:229], v[64:67]
	v_mfma_f32_16x16x32_bf16 v[88:91], v[156:159], v[218:221], v[88:91]
	v_mfma_f32_16x16x32_bf16 v[88:91], v[152:155], v[214:217], v[88:91]
	v_mfma_f32_16x16x32_bf16 v[112:115], v[152:155], v[206:209], v[112:115]
	v_mfma_f32_16x16x32_bf16 v[112:115], v[156:159], v[210:213], v[112:115]
	s_setprio 2
	s_barrier
; #define PG8_STAGE(bufoff, gbase, voff) do { _Pragma("unroll") for (int _i = 0; _i < 2; ++_i) \
;         __builtin_amdgcn_global_load_lds((const unsigned*)((const char*)(gbase) + (voff)[_i]), (PG8_LAS unsigned*)(lds + (bufoff) + ldsw + _i * 8192), 16, 0, 0); } while (0)
; #define PG8_LDA(dst, b, h) do { _Pragma("unroll") for (int m = 0; m < 4; ++m) _Pragma("unroll") for (int k = 0; k < 2; ++k) dst[m][k] = *(const PG8_LAS bf16x8*)(lds + PG8_SA(b, h) + aoff + m * 2048 + k * 1024); } while (0)
; #define PG8_MMA(ai, bj, At, Bt) do { __builtin_amdgcn_s_setprio(1); _Pragma("unroll") for (int m = 0; m < 4; ++m) _Pragma("unroll") for (int n = 0; n < 2; ++n) _Pragma("unroll") for (int k = 0; k < 2; ++k) \
;         acc[ai][bj][m][n] = __builtin_amdgcn_mfma_f32_16x16x32_bf16(Bt[n][k], At[m][k], acc[ai][bj][m][n], 0, 0, 0); __builtin_amdgcn_s_setprio(0); } while (0)
; #define PG8_WAIT_V(n) asm volatile("s_waitcnt vmcnt(" #n ")" ::: "memory")
; #define PG8_WAIT_L(n) asm volatile("s_waitcnt lgkmcnt(" #n ")" ::: "memory")
; #define PG8_BAR __builtin_amdgcn_s_barrier()
; #define PG8_SCHED __builtin_amdgcn_sched_barrier(0)
; template <class Epi, class Sched, bool ALIGN_EPI = false, bool SP2 = false>
; __device__ __forceinline__ void gemm_phase(PG8_LAS unsigned char* lds, const Gemm g, const Sched& S, const Epi& E) {
;     ...
;         for (int t = 0; t < nt; t += 2) {
;     ...
;             PG8_WAIT_V(8); PG8_WAIT_L(0); PG8_BAR; PG8_MMA(0, 0, At, B0); PG8_MMA(0, 1, At, B1); PG8_BAR; PG8_SCHED;
;             PG8_LDA(At, 1, 1); PG8_STAGE(PG8_SB(1, 0), b3, voffB); PG8_STAGE(PG8_SB(1, 1), b3 + hstep, voffB); PG8_STAGE(PG8_SA(1, 0), a3, voffA);
;             PG8_WAIT_V(8); PG8_WAIT_L(0); PG8_BAR; PG8_MMA(1, 0, At, B0); PG8_MMA(1, 1, At, B1); PG8_BAR; PG8_SCHED;
	v_mfma_f32_16x16x32_bf16 v[128:131], v[156:159], v[182:185], v[128:131]
	v_mfma_f32_16x16x32_bf16 v[128:131], v[152:155], v[178:181], v[128:131]
	s_setprio 0
	s_add_i32 s44, s44, s41
	v_lshl_add_u64 v[200:201], v[200:201], 0, s[20:21]
	s_mov_b32 m0, s44
	ds_read_b128 v[178:181], v187 offset:49152
	ds_read_b128 v[182:185], v187 offset:50176
	ds_read_b128 v[206:209], v187 offset:51200
	ds_read_b128 v[210:213], v187 offset:52224
	ds_read_b128 v[214:217], v187 offset:53248
	ds_read_b128 v[218:221], v187 offset:54272
	ds_read_b128 v[222:225], v187 offset:55296
	ds_read_b128 v[226:229], v187 offset:56320
	global_load_lds_dwordx4 v[200:201], off
	s_add_i32 m0, s44, 0x2000
	s_add_u32 s28, s28, 0x160080
	v_lshl_add_u64 v[200:201], v[230:231], 0, s[20:21]
	s_addc_u32 s29, s29, 0
	s_add_i32 s44, s45, s41
	global_load_lds_dwordx4 v[200:201], off
	v_lshl_add_u64 v[200:201], s[28:29], 0, v[160:161]
	s_mov_b32 m0, s44
	s_nop 0
	global_load_lds_dwordx4 v[200:201], off
	v_lshl_add_u64 v[200:201], s[28:29], 0, v[162:163]
	s_add_i32 m0, s44, 0x2000
	s_nop 0
	global_load_lds_dwordx4 v[200:201], off
	v_lshl_add_u64 v[200:201], v[232:233], 0, s[20:21]
	s_mov_b32 m0, s67
	s_nop 0
	global_load_lds_dwordx4 v[200:201], off
	v_lshl_add_u64 v[200:201], v[234:235], 0, s[20:21]
	s_mov_b32 m0, s68
	s_nop 0
	global_load_lds_dwordx4 v[200:201], off
	s_waitcnt vmcnt(8)
	s_waitcnt lgkmcnt(0)
	s_barrier
	s_setprio 1
	s_waitcnt lgkmcnt(0)
	v_mfma_f32_16x16x32_bf16 v[60:63], v[76:79], v[178:181], v[60:63]
	v_mfma_f32_16x16x32_bf16 v[60:63], v[84:87], v[182:185], v[60:63]
	v_mfma_f32_16x16x32_bf16 v[44:47], v[84:87], v[210:213], v[44:47]
	v_mfma_f32_16x16x32_bf16 v[44:47], v[76:79], v[206:209], v[44:47]
	v_mfma_f32_16x16x32_bf16 v[28:31], v[76:79], v[214:217], v[28:31]
	v_mfma_f32_16x16x32_bf16 v[28:31], v[84:87], v[218:221], v[28:31]
	v_mfma_f32_16x16x32_bf16 v[12:15], v[84:87], v[226:229], v[12:15]
	v_mfma_f32_16x16x32_bf16 v[12:15], v[76:79], v[222:225], v[12:15]
	v_mfma_f32_16x16x32_bf16 v[8:11], v[92:95], v[222:225], v[8:11]
	v_mfma_f32_16x16x32_bf16 v[8:11], v[96:99], v[226:229], v[8:11]
	v_mfma_f32_16x16x32_bf16 v[24:27], v[96:99], v[218:221], v[24:27]
	v_mfma_f32_16x16x32_bf16 v[24:27], v[92:95], v[214:217], v[24:27]
	v_mfma_f32_16x16x32_bf16 v[40:43], v[92:95], v[206:209], v[40:43]
	v_mfma_f32_16x16x32_bf16 v[40:43], v[96:99], v[210:213], v[40:43]
	v_mfma_f32_16x16x32_bf16 v[56:59], v[96:99], v[182:185], v[56:59]
	v_mfma_f32_16x16x32_bf16 v[56:59], v[92:95], v[178:181], v[56:59]
	s_setprio 0
	s_setprio 1
	v_mfma_f32_16x16x32_bf16 v[52:55], v[144:147], v[178:181], v[52:55]
	v_mfma_f32_16x16x32_bf16 v[52:55], v[148:151], v[182:185], v[52:55]
	v_mfma_f32_16x16x32_bf16 v[36:39], v[148:151], v[210:213], v[36:39]
	v_mfma_f32_16x16x32_bf16 v[36:39], v[144:147], v[206:209], v[36:39]
	v_mfma_f32_16x16x32_bf16 v[20:23], v[144:147], v[214:217], v[20:23]
	v_mfma_f32_16x16x32_bf16 v[20:23], v[148:151], v[218:221], v[20:23]
	v_mfma_f32_16x16x32_bf16 v[4:7], v[148:151], v[226:229], v[4:7]
	v_mfma_f32_16x16x32_bf16 v[4:7], v[144:147], v[222:225], v[4:7]
	v_mfma_f32_16x16x32_bf16 v[0:3], v[152:155], v[222:225], v[0:3]
	v_mfma_f32_16x16x32_bf16 v[0:3], v[156:159], v[226:229], v[0:3]
	v_mfma_f32_16x16x32_bf16 v[16:19], v[156:159], v[218:221], v[16:19]
	v_mfma_f32_16x16x32_bf16 v[16:19], v[152:155], v[214:217], v[16:19]
	v_mfma_f32_16x16x32_bf16 v[32:35], v[152:155], v[206:209], v[32:35]
	v_mfma_f32_16x16x32_bf16 v[32:35], v[156:159], v[210:213], v[32:35]
	s_setprio 2
	s_barrier
	v_mfma_f32_16x16x32_bf16 v[48:51], v[156:159], v[182:185], v[48:51]
	v_mfma_f32_16x16x32_bf16 v[48:51], v[152:155], v[178:181], v[48:51]
	s_setprio 0
	s_add_i32 s77, s77, 2
	s_add_u32 s64, s64, 0x100
	s_addc_u32 s65, s65, 0
	s_add_u32 s34, s34, 0x100
	s_addc_u32 s35, s35, 0
	s_cmpk_gt_u32 s77, 0x55
	s_cbranch_scc0 .LBB0_482
	s_and_b64 vcc, exec, s[22:23]
	s_cbranch_vccz .LBB0_485
	s_barrier

; #define PG8_STAGE(bufoff, gbase, voff) do { _Pragma("unroll") for (int _i = 0; _i < 2; ++_i) \
;         __builtin_amdgcn_global_load_lds((const unsigned*)((const char*)(gbase) + (voff)[_i]), (PG8_LAS unsigned*)(lds + (bufoff) + ldsw + _i * 8192), 16, 0, 0); } while (0)
; #define PG8_LDA(dst, b, h) do { _Pragma("unroll") for (int m = 0; m < 4; ++m) _Pragma("unroll") for (int k = 0; k < 2; ++k) dst[m][k] = *(const PG8_LAS bf16x8*)(lds + PG8_SA(b, h) + aoff + m * 2048 + k * 1024); } while (0)
; #define PG8_LDB(dst, b, h) do { _Pragma("unroll") for (int n = 0; n < 2; ++n) _Pragma("unroll") for (int k = 0; k < 2; ++k) dst[n][k] = *(const PG8_LAS bf16x8*)(lds + PG8_SB(b, h) + boff + n * 2048 + k * 1024); } while (0)
; #define PG8_MMA(ai, bj, At, Bt) do { __builtin_amdgcn_s_setprio(1); _Pragma("unroll") for (int m = 0; m < 4; ++m) _Pragma("unroll") for (int n = 0; n < 2; ++n) _Pragma("unroll") for (int k = 0; k < 2; ++k) \
;         acc[ai][bj][m][n] = __builtin_amdgcn_mfma_f32_16x16x32_bf16(Bt[n][k], At[m][k], acc[ai][bj][m][n], 0, 0, 0); __builtin_amdgcn_s_setprio(0); } while (0)
; #define PG8_WAIT_V(n) asm volatile("s_waitcnt vmcnt(" #n ")" ::: "memory")
; #define PG8_WAIT_L(n) asm volatile("s_waitcnt lgkmcnt(" #n ")" ::: "memory")
; #define PG8_BAR __builtin_amdgcn_s_barrier()
; #define PG8_SCHED __builtin_amdgcn_sched_barrier(0)
; template <class Epi, class Sched, bool ALIGN_EPI = false, bool SP2 = false>
; __device__ __forceinline__ void gemm_phase(PG8_LAS unsigned char* lds, const Gemm g, const Sched& S, const Epi& E) {
;     ...
;         for (int t = 0; t < nt; t += 2) {
;             const bool last = (t == nt - 2);
;             const char* a1 = cA + (size_t)(t + 1) * kstep;
;             const char* a2 = last ? nA : cA + (size_t)(t + 2) * kstep; const char* b2 = last ? nB : cB + (size_t)(t + 2) * kstep;
;             const char* a3 = a2 + kstep; const char* b3 = b2 + kstep;
;             if (last && has_next) S.a_ready(nxt);
;             if constexpr (SP2) {
;             PG8_LDB(B0, 0, 0); PG8_LDB(B1, 0, 1); PG8_SCHED; PG8_LDA(At, 0, 0); PG8_STAGE(PG8_SA(1, 1), a1 + hstep, voffA);
;             PG8_WAIT_V(8); PG8_WAIT_L(0); PG8_BAR; PG8_MMA(0, 0, At, B0); PG8_MMA(0, 1, At, B1); PG8_BAR; PG8_SCHED;
;             PG8_LDA(At, 0, 1); PG8_STAGE(PG8_SB(0, 0), b2, voffB); PG8_STAGE(PG8_SB(0, 1), b2 + hstep, voffB); PG8_STAGE(PG8_SA(0, 0), a2, voffA);
.LBB0_536:
	ds_read_b128 v[136:139], v156
	ds_read_b128 v[140:143], v156 offset:1024
	ds_read_b128 v[172:175], v156 offset:2048
	ds_read_b128 v[176:179], v156 offset:3072
	ds_read_b128 v[180:183], v157
	ds_read_b128 v[184:187], v157 offset:1024
	ds_read_b128 v[206:209], v157 offset:2048
	ds_read_b128 v[210:213], v157 offset:3072
	s_add_u32 s28, s66, 0xfff80080
	s_addc_u32 s29, s67, -1
	s_cmp_eq_u32 s79, 28
	s_cselect_b32 s49, s34, s29
	s_cselect_b32 s48, s35, s28
	s_cselect_b32 s29, s23, s78
	s_cselect_b32 s28, s39, s77
	v_lshl_add_u64 v[200:201], s[66:67], 0, v[128:129]
	s_add_i32 m0, s11, 0xc000
	ds_read_b128 v[214:217], v158
	ds_read_b128 v[218:221], v158 offset:1024
	ds_read_b128 v[222:225], v158 offset:2048
	ds_read_b128 v[226:229], v158 offset:3072
	ds_read_b128 v[230:233], v158 offset:4096
	ds_read_b128 v[234:237], v158 offset:5120
	ds_read_b128 v[238:241], v158 offset:6144
	ds_read_b128 v[242:245], v158 offset:7168
	global_load_lds_dwordx4 v[200:201], off
	v_lshl_add_u64 v[200:201], s[66:67], 0, v[130:131]
	s_add_i32 m0, s11, 0xe000
	s_nop 0
	global_load_lds_dwordx4 v[200:201], off
	s_waitcnt vmcnt(8)
	s_waitcnt lgkmcnt(0)
	s_barrier
	s_setprio 1
	s_waitcnt lgkmcnt(0)
	v_mfma_f32_16x16x32_bf16 v[124:127], v[136:139], v[214:217], v[124:127]
	v_mfma_f32_16x16x32_bf16 v[124:127], v[140:143], v[218:221], v[124:127]
	v_mfma_f32_16x16x32_bf16 v[108:111], v[140:143], v[226:229], v[108:111]
	v_mfma_f32_16x16x32_bf16 v[108:111], v[136:139], v[222:225], v[108:111]
	v_mfma_f32_16x16x32_bf16 v[96:99], v[136:139], v[230:233], v[96:99]
	v_mfma_f32_16x16x32_bf16 v[96:99], v[140:143], v[234:237], v[96:99]
	v_mfma_f32_16x16x32_bf16 v[80:83], v[140:143], v[242:245], v[80:83]
	v_mfma_f32_16x16x32_bf16 v[80:83], v[136:139], v[238:241], v[80:83]
	v_mfma_f32_16x16x32_bf16 v[72:75], v[172:175], v[238:241], v[72:75]
	v_mfma_f32_16x16x32_bf16 v[72:75], v[176:179], v[242:245], v[72:75]
	v_mfma_f32_16x16x32_bf16 v[88:91], v[176:179], v[234:237], v[88:91]
	v_mfma_f32_16x16x32_bf16 v[88:91], v[172:175], v[230:233], v[88:91]
	v_mfma_f32_16x16x32_bf16 v[104:107], v[172:175], v[222:225], v[104:107]
	v_mfma_f32_16x16x32_bf16 v[104:107], v[176:179], v[226:229], v[104:107]
	v_mfma_f32_16x16x32_bf16 v[120:123], v[176:179], v[218:221], v[120:123]
	v_mfma_f32_16x16x32_bf16 v[120:123], v[172:175], v[214:217], v[120:123]
	s_setprio 0
	s_setprio 1
	v_mfma_f32_16x16x32_bf16 v[116:119], v[180:183], v[214:217], v[116:119]
	v_mfma_f32_16x16x32_bf16 v[116:119], v[184:187], v[218:221], v[116:119]
	v_mfma_f32_16x16x32_bf16 v[100:103], v[184:187], v[226:229], v[100:103]
	v_mfma_f32_16x16x32_bf16 v[100:103], v[180:183], v[222:225], v[100:103]
	v_mfma_f32_16x16x32_bf16 v[84:87], v[180:183], v[230:233], v[84:87]
	v_mfma_f32_16x16x32_bf16 v[84:87], v[184:187], v[234:237], v[84:87]
	v_mfma_f32_16x16x32_bf16 v[68:71], v[184:187], v[242:245], v[68:71]
	v_mfma_f32_16x16x32_bf16 v[68:71], v[180:183], v[238:241], v[68:71]
	v_mfma_f32_16x16x32_bf16 v[64:67], v[206:209], v[238:241], v[64:67]
	v_mfma_f32_16x16x32_bf16 v[64:67], v[210:213], v[242:245], v[64:67]
	v_mfma_f32_16x16x32_bf16 v[76:79], v[210:213], v[234:237], v[76:79]
	v_mfma_f32_16x16x32_bf16 v[76:79], v[206:209], v[230:233], v[76:79]
	v_mfma_f32_16x16x32_bf16 v[92:95], v[206:209], v[222:225], v[92:95]
	v_mfma_f32_16x16x32_bf16 v[92:95], v[210:213], v[226:229], v[92:95]
	s_setprio 2
	s_barrier
	v_mfma_f32_16x16x32_bf16 v[112:115], v[210:213], v[218:221], v[112:115]
	v_mfma_f32_16x16x32_bf16 v[112:115], v[206:209], v[214:217], v[112:115]
	s_setprio 0
	s_add_i32 s44, s72, s41
	v_lshl_add_u64 v[200:201], s[28:29], 0, v[166:167]
	s_mov_b32 m0, s44
	ds_read_b128 v[214:217], v158 offset:16384
	ds_read_b128 v[218:221], v158 offset:17408
	ds_read_b128 v[222:225], v158 offset:18432
	ds_read_b128 v[226:229], v158 offset:19456
	ds_read_b128 v[230:233], v158 offset:20480
	ds_read_b128 v[234:237], v158 offset:21504
	ds_read_b128 v[238:241], v158 offset:22528
	ds_read_b128 v[242:245], v158 offset:23552
	global_load_lds_dwordx4 v[200:201], off
	s_add_i32 m0, s44, 0x2000
	s_add_u32 s80, s28, 0x80000
	v_lshl_add_u64 v[246:247], s[28:29], 0, v[170:171]
	s_addc_u32 s81, s29, 0
	s_add_i32 s44, s73, s41
	global_load_lds_dwordx4 v[246:247], off
	v_lshl_add_u64 v[248:249], s[80:81], 0, v[166:167]
	s_mov_b32 m0, s44
	v_lshl_add_u64 v[250:251], s[48:49], 0, v[168:169]
	global_load_lds_dwordx4 v[248:249], off
	v_lshl_add_u64 v[248:249], s[80:81], 0, v[170:171]
	s_add_i32 m0, s44, 0x2000
	s_nop 0
	global_load_lds_dwordx4 v[248:249], off
	v_lshl_add_u64 v[248:249], s[48:49], 0, v[164:165]
	s_mov_b32 m0, s11
	s_nop 0
	global_load_lds_dwordx4 v[248:249], off
	s_mov_b32 m0, s57
	s_nop 0
	global_load_lds_dwordx4 v[250:251], off
	s_waitcnt vmcnt(8)
	s_waitcnt lgkmcnt(0)
	s_barrier
; #define PG8_STAGE(bufoff, gbase, voff) do { _Pragma("unroll") for (int _i = 0; _i < 2; ++_i) \
;         __builtin_amdgcn_global_load_lds((const unsigned*)((const char*)(gbase) + (voff)[_i]), (PG8_LAS unsigned*)(lds + (bufoff) + ldsw + _i * 8192), 16, 0, 0); } while (0)
; #define PG8_LDA(dst, b, h) do { _Pragma("unroll") for (int m = 0; m < 4; ++m) _Pragma("unroll") for (int k = 0; k < 2; ++k) dst[m][k] = *(const PG8_LAS bf16x8*)(lds + PG8_SA(b, h) + aoff + m * 2048 + k * 1024); } while (0)
; #define PG8_LDB(dst, b, h) do { _Pragma("unroll") for (int n = 0; n < 2; ++n) _Pragma("unroll") for (int k = 0; k < 2; ++k) dst[n][k] = *(const PG8_LAS bf16x8*)(lds + PG8_SB(b, h) + boff + n * 2048 + k * 1024); } while (0)
; #define PG8_MMA(ai, bj, At, Bt) do { __builtin_amdgcn_s_setprio(1); _Pragma("unroll") for (int m = 0; m < 4; ++m) _Pragma("unroll") for (int n = 0; n < 2; ++n) _Pragma("unroll") for (int k = 0; k < 2; ++k) \
;         acc[ai][bj][m][n] = __builtin_amdgcn_mfma_f32_16x16x32_bf16(Bt[n][k], At[m][k], acc[ai][bj][m][n], 0, 0, 0); __builtin_amdgcn_s_setprio(0); } while (0)
; #define PG8_WAIT_V(n) asm volatile("s_waitcnt vmcnt(" #n ")" ::: "memory")
; #define PG8_WAIT_L(n) asm volatile("s_waitcnt lgkmcnt(" #n ")" ::: "memory")
; #define PG8_BAR __builtin_amdgcn_s_barrier()
; #define PG8_SCHED __builtin_amdgcn_sched_barrier(0)
; template <class Epi, class Sched, bool ALIGN_EPI = false, bool SP2 = false>
; __device__ __forceinline__ void gemm_phase(PG8_LAS unsigned char* lds, const Gemm g, const Sched& S, const Epi& E) {
;     ...
;             PG8_WAIT_V(8); PG8_WAIT_L(0); PG8_BAR; PG8_MMA(1, 0, At, B0); PG8_MMA(1, 1, At, B1); PG8_BAR; PG8_SCHED;
;             PG8_LDB(B0, 1, 0); PG8_LDB(B1, 1, 1); PG8_SCHED; PG8_LDA(At, 1, 0); PG8_STAGE(PG8_SA(0, 1), a2 + hstep, voffA);
;             PG8_WAIT_V(8); PG8_WAIT_L(0); PG8_BAR; PG8_MMA(0, 0, At, B0); PG8_MMA(0, 1, At, B1); PG8_BAR; PG8_SCHED;
	s_setprio 1
	s_waitcnt lgkmcnt(0)
	v_mfma_f32_16x16x32_bf16 v[60:63], v[136:139], v[214:217], v[60:63]
	v_mfma_f32_16x16x32_bf16 v[60:63], v[140:143], v[218:221], v[60:63]
	v_mfma_f32_16x16x32_bf16 v[48:51], v[140:143], v[226:229], v[48:51]
	v_mfma_f32_16x16x32_bf16 v[48:51], v[136:139], v[222:225], v[48:51]
	v_mfma_f32_16x16x32_bf16 v[32:35], v[136:139], v[230:233], v[32:35]
	v_mfma_f32_16x16x32_bf16 v[32:35], v[140:143], v[234:237], v[32:35]
	v_mfma_f32_16x16x32_bf16 v[12:15], v[140:143], v[242:245], v[12:15]
	v_mfma_f32_16x16x32_bf16 v[12:15], v[136:139], v[238:241], v[12:15]
	v_mfma_f32_16x16x32_bf16 v[8:11], v[172:175], v[238:241], v[8:11]
	v_mfma_f32_16x16x32_bf16 v[8:11], v[176:179], v[242:245], v[8:11]
	v_mfma_f32_16x16x32_bf16 v[24:27], v[176:179], v[234:237], v[24:27]
	v_mfma_f32_16x16x32_bf16 v[24:27], v[172:175], v[230:233], v[24:27]
	v_mfma_f32_16x16x32_bf16 v[40:43], v[172:175], v[222:225], v[40:43]
	v_mfma_f32_16x16x32_bf16 v[40:43], v[176:179], v[226:229], v[40:43]
	v_mfma_f32_16x16x32_bf16 v[56:59], v[176:179], v[218:221], v[56:59]
	v_mfma_f32_16x16x32_bf16 v[56:59], v[172:175], v[214:217], v[56:59]
	s_setprio 0
	s_setprio 1
	v_mfma_f32_16x16x32_bf16 v[52:55], v[180:183], v[214:217], v[52:55]
	v_mfma_f32_16x16x32_bf16 v[52:55], v[184:187], v[218:221], v[52:55]
	v_mfma_f32_16x16x32_bf16 v[36:39], v[184:187], v[226:229], v[36:39]
	v_mfma_f32_16x16x32_bf16 v[36:39], v[180:183], v[222:225], v[36:39]
	v_mfma_f32_16x16x32_bf16 v[20:23], v[180:183], v[230:233], v[20:23]
	v_mfma_f32_16x16x32_bf16 v[20:23], v[184:187], v[234:237], v[20:23]
	v_mfma_f32_16x16x32_bf16 v[4:7], v[184:187], v[242:245], v[4:7]
	v_mfma_f32_16x16x32_bf16 v[4:7], v[180:183], v[238:241], v[4:7]
	v_mfma_f32_16x16x32_bf16 v[0:3], v[206:209], v[238:241], v[0:3]
	v_mfma_f32_16x16x32_bf16 v[0:3], v[210:213], v[242:245], v[0:3]
	v_mfma_f32_16x16x32_bf16 v[16:19], v[210:213], v[234:237], v[16:19]
	v_mfma_f32_16x16x32_bf16 v[16:19], v[206:209], v[230:233], v[16:19]
	v_mfma_f32_16x16x32_bf16 v[28:31], v[206:209], v[222:225], v[28:31]
	v_mfma_f32_16x16x32_bf16 v[28:31], v[210:213], v[226:229], v[28:31]
	s_setprio 2
	s_barrier
	v_mfma_f32_16x16x32_bf16 v[44:47], v[210:213], v[218:221], v[44:47]
	v_mfma_f32_16x16x32_bf16 v[44:47], v[206:209], v[214:217], v[44:47]
	s_setprio 0
	s_add_i32 s44, 0, 0x18000
	v_add_u32_e32 v144, s44, v146
	s_add_i32 s45, 0, 0x1c000
	ds_read_b128 v[136:139], v144
	ds_read_b128 v[140:143], v144 offset:1024
	ds_read_b128 v[172:175], v144 offset:2048
	ds_read_b128 v[176:179], v144 offset:3072
	v_add_u32_e32 v144, s45, v146
	ds_read_b128 v[180:183], v144
	ds_read_b128 v[184:187], v144 offset:1024
	ds_read_b128 v[206:209], v144 offset:2048
	ds_read_b128 v[210:213], v144 offset:3072
	s_add_u32 s48, s48, 0x80000
	s_addc_u32 s49, s49, 0
	s_mov_b32 m0, s61
	v_lshl_add_u64 v[252:253], s[48:49], 0, v[164:165]
	ds_read_b128 v[214:217], v158 offset:32768
	ds_read_b128 v[218:221], v158 offset:33792
	ds_read_b128 v[222:225], v158 offset:34816
	ds_read_b128 v[226:229], v158 offset:35840
	ds_read_b128 v[230:233], v158 offset:36864
	ds_read_b128 v[234:237], v158 offset:37888
	ds_read_b128 v[238:241], v158 offset:38912
	ds_read_b128 v[242:245], v158 offset:39936
	global_load_lds_dwordx4 v[252:253], off
	v_lshl_add_u64 v[252:253], s[48:49], 0, v[168:169]
	s_mov_b32 m0, s68
	s_nop 0
	global_load_lds_dwordx4 v[252:253], off
	s_waitcnt vmcnt(8)
	s_waitcnt lgkmcnt(0)
	s_barrier
	s_setprio 1
	s_waitcnt lgkmcnt(0)
	v_mfma_f32_16x16x32_bf16 v[124:127], v[136:139], v[214:217], v[124:127]
	v_mfma_f32_16x16x32_bf16 v[124:127], v[140:143], v[218:221], v[124:127]
	v_mfma_f32_16x16x32_bf16 v[108:111], v[140:143], v[226:229], v[108:111]
	v_mfma_f32_16x16x32_bf16 v[108:111], v[136:139], v[222:225], v[108:111]
	v_mfma_f32_16x16x32_bf16 v[96:99], v[136:139], v[230:233], v[96:99]
	v_mfma_f32_16x16x32_bf16 v[96:99], v[140:143], v[234:237], v[96:99]
	v_mfma_f32_16x16x32_bf16 v[80:83], v[140:143], v[242:245], v[80:83]
	v_mfma_f32_16x16x32_bf16 v[80:83], v[136:139], v[238:241], v[80:83]
	v_mfma_f32_16x16x32_bf16 v[72:75], v[172:175], v[238:241], v[72:75]
	v_mfma_f32_16x16x32_bf16 v[72:75], v[176:179], v[242:245], v[72:75]
	v_mfma_f32_16x16x32_bf16 v[88:91], v[176:179], v[234:237], v[88:91]
	v_mfma_f32_16x16x32_bf16 v[88:91], v[172:175], v[230:233], v[88:91]
	v_mfma_f32_16x16x32_bf16 v[104:107], v[172:175], v[222:225], v[104:107]
	v_mfma_f32_16x16x32_bf16 v[104:107], v[176:179], v[226:229], v[104:107]
	v_mfma_f32_16x16x32_bf16 v[120:123], v[176:179], v[218:221], v[120:123]
	v_mfma_f32_16x16x32_bf16 v[120:123], v[172:175], v[214:217], v[120:123]
	s_setprio 0
	s_setprio 1
	v_mfma_f32_16x16x32_bf16 v[116:119], v[180:183], v[214:217], v[116:119]
	v_mfma_f32_16x16x32_bf16 v[116:119], v[184:187], v[218:221], v[116:119]
	v_mfma_f32_16x16x32_bf16 v[100:103], v[184:187], v[226:229], v[100:103]
	v_mfma_f32_16x16x32_bf16 v[100:103], v[180:183], v[222:225], v[100:103]
	v_mfma_f32_16x16x32_bf16 v[84:87], v[180:183], v[230:233], v[84:87]
	v_mfma_f32_16x16x32_bf16 v[84:87], v[184:187], v[234:237], v[84:87]
	v_mfma_f32_16x16x32_bf16 v[68:71], v[184:187], v[242:245], v[68:71]
	v_mfma_f32_16x16x32_bf16 v[68:71], v[180:183], v[238:241], v[68:71]
	v_mfma_f32_16x16x32_bf16 v[64:67], v[206:209], v[238:241], v[64:67]
	v_mfma_f32_16x16x32_bf16 v[64:67], v[210:213], v[242:245], v[64:67]
	v_mfma_f32_16x16x32_bf16 v[76:79], v[210:213], v[234:237], v[76:79]
	v_mfma_f32_16x16x32_bf16 v[76:79], v[206:209], v[230:233], v[76:79]
	v_mfma_f32_16x16x32_bf16 v[92:95], v[206:209], v[222:225], v[92:95]
	v_mfma_f32_16x16x32_bf16 v[92:95], v[210:213], v[226:229], v[92:95]
	s_setprio 2
	s_barrier
; #define PG8_STAGE(bufoff, gbase, voff) do { _Pragma("unroll") for (int _i = 0; _i < 2; ++_i) \
;         __builtin_amdgcn_global_load_lds((const unsigned*)((const char*)(gbase) + (voff)[_i]), (PG8_LAS unsigned*)(lds + (bufoff) + ldsw + _i * 8192), 16, 0, 0); } while (0)
; #define PG8_LDA(dst, b, h) do { _Pragma("unroll") for (int m = 0; m < 4; ++m) _Pragma("unroll") for (int k = 0; k < 2; ++k) dst[m][k] = *(const PG8_LAS bf16x8*)(lds + PG8_SA(b, h) + aoff + m * 2048 + k * 1024); } while (0)
; #define PG8_MMA(ai, bj, At, Bt) do { __builtin_amdgcn_s_setprio(1); _Pragma("unroll") for (int m = 0; m < 4; ++m) _Pragma("unroll") for (int n = 0; n < 2; ++n) _Pragma("unroll") for (int k = 0; k < 2; ++k) \
;         acc[ai][bj][m][n] = __builtin_amdgcn_mfma_f32_16x16x32_bf16(Bt[n][k], At[m][k], acc[ai][bj][m][n], 0, 0, 0); __builtin_amdgcn_s_setprio(0); } while (0)
; #define PG8_WAIT_V(n) asm volatile("s_waitcnt vmcnt(" #n ")" ::: "memory")
; #define PG8_WAIT_L(n) asm volatile("s_waitcnt lgkmcnt(" #n ")" ::: "memory")
; #define PG8_BAR __builtin_amdgcn_s_barrier()
; #define PG8_SCHED __builtin_amdgcn_sched_barrier(0)
; template <class Epi, class Sched, bool ALIGN_EPI = false, bool SP2 = false>
; __device__ __forceinline__ void gemm_phase(PG8_LAS unsigned char* lds, const Gemm g, const Sched& S, const Epi& E) {
;     ...
;         for (int t = 0; t < nt; t += 2) {
;     ...
;             PG8_WAIT_V(8); PG8_WAIT_L(0); PG8_BAR; PG8_MMA(0, 0, At, B0); PG8_MMA(0, 1, At, B1); PG8_BAR; PG8_SCHED;
;             PG8_LDA(At, 1, 1); PG8_STAGE(PG8_SB(1, 0), b3, voffB); PG8_STAGE(PG8_SB(1, 1), b3 + hstep, voffB); PG8_STAGE(PG8_SA(1, 0), a3, voffA);
;             PG8_WAIT_V(8); PG8_WAIT_L(0); PG8_BAR; PG8_MMA(1, 0, At, B0); PG8_MMA(1, 1, At, B1); PG8_BAR; PG8_SCHED;
	v_mfma_f32_16x16x32_bf16 v[112:115], v[210:213], v[218:221], v[112:115]
	v_mfma_f32_16x16x32_bf16 v[112:115], v[206:209], v[214:217], v[112:115]
	s_setprio 0
	s_add_i32 s44, s44, s41
	v_lshl_add_u64 v[200:201], v[200:201], 0, s[18:19]
	s_mov_b32 m0, s44
	ds_read_b128 v[214:217], v158 offset:49152
	ds_read_b128 v[218:221], v158 offset:50176
	ds_read_b128 v[222:225], v158 offset:51200
	ds_read_b128 v[226:229], v158 offset:52224
	ds_read_b128 v[230:233], v158 offset:53248
	ds_read_b128 v[234:237], v158 offset:54272
	ds_read_b128 v[238:241], v158 offset:55296
	ds_read_b128 v[242:245], v158 offset:56320
	global_load_lds_dwordx4 v[200:201], off
	s_add_i32 m0, s44, 0x2000
	s_add_u32 s28, s28, 0x80080
	v_lshl_add_u64 v[200:201], v[246:247], 0, s[18:19]
	s_addc_u32 s29, s29, 0
	s_add_i32 s44, s45, s41
	global_load_lds_dwordx4 v[200:201], off
	v_lshl_add_u64 v[200:201], s[28:29], 0, v[166:167]
	s_mov_b32 m0, s44
	s_nop 0
	global_load_lds_dwordx4 v[200:201], off
	v_lshl_add_u64 v[200:201], s[28:29], 0, v[170:171]
	s_add_i32 m0, s44, 0x2000
	s_nop 0
	global_load_lds_dwordx4 v[200:201], off
	v_lshl_add_u64 v[200:201], v[248:249], 0, s[18:19]
	s_mov_b32 m0, s70
	s_nop 0
	global_load_lds_dwordx4 v[200:201], off
	v_lshl_add_u64 v[200:201], v[250:251], 0, s[18:19]
	s_mov_b32 m0, s71
	s_nop 0
	global_load_lds_dwordx4 v[200:201], off
	s_waitcnt vmcnt(8)
	s_waitcnt lgkmcnt(0)
	s_barrier
	s_setprio 1
	s_waitcnt lgkmcnt(0)
	v_mfma_f32_16x16x32_bf16 v[60:63], v[136:139], v[214:217], v[60:63]
	v_mfma_f32_16x16x32_bf16 v[60:63], v[140:143], v[218:221], v[60:63]
	v_mfma_f32_16x16x32_bf16 v[48:51], v[140:143], v[226:229], v[48:51]
	v_mfma_f32_16x16x32_bf16 v[48:51], v[136:139], v[222:225], v[48:51]
	v_mfma_f32_16x16x32_bf16 v[32:35], v[136:139], v[230:233], v[32:35]
	v_mfma_f32_16x16x32_bf16 v[32:35], v[140:143], v[234:237], v[32:35]
	v_mfma_f32_16x16x32_bf16 v[12:15], v[140:143], v[242:245], v[12:15]
	v_mfma_f32_16x16x32_bf16 v[12:15], v[136:139], v[238:241], v[12:15]
	v_mfma_f32_16x16x32_bf16 v[8:11], v[172:175], v[238:241], v[8:11]
	v_mfma_f32_16x16x32_bf16 v[8:11], v[176:179], v[242:245], v[8:11]
	v_mfma_f32_16x16x32_bf16 v[24:27], v[176:179], v[234:237], v[24:27]
	v_mfma_f32_16x16x32_bf16 v[24:27], v[172:175], v[230:233], v[24:27]
	v_mfma_f32_16x16x32_bf16 v[40:43], v[172:175], v[222:225], v[40:43]
	v_mfma_f32_16x16x32_bf16 v[40:43], v[176:179], v[226:229], v[40:43]
	v_mfma_f32_16x16x32_bf16 v[56:59], v[176:179], v[218:221], v[56:59]
	v_mfma_f32_16x16x32_bf16 v[56:59], v[172:175], v[214:217], v[56:59]
	s_setprio 0
	s_setprio 1
	v_mfma_f32_16x16x32_bf16 v[52:55], v[180:183], v[214:217], v[52:55]
	v_mfma_f32_16x16x32_bf16 v[52:55], v[184:187], v[218:221], v[52:55]
	v_mfma_f32_16x16x32_bf16 v[36:39], v[184:187], v[226:229], v[36:39]
	v_mfma_f32_16x16x32_bf16 v[36:39], v[180:183], v[222:225], v[36:39]
	v_mfma_f32_16x16x32_bf16 v[20:23], v[180:183], v[230:233], v[20:23]
	v_mfma_f32_16x16x32_bf16 v[20:23], v[184:187], v[234:237], v[20:23]
	v_mfma_f32_16x16x32_bf16 v[4:7], v[184:187], v[242:245], v[4:7]
	v_mfma_f32_16x16x32_bf16 v[4:7], v[180:183], v[238:241], v[4:7]
	v_mfma_f32_16x16x32_bf16 v[0:3], v[206:209], v[238:241], v[0:3]
	v_mfma_f32_16x16x32_bf16 v[0:3], v[210:213], v[242:245], v[0:3]
	v_mfma_f32_16x16x32_bf16 v[16:19], v[210:213], v[234:237], v[16:19]
	v_mfma_f32_16x16x32_bf16 v[16:19], v[206:209], v[230:233], v[16:19]
	v_mfma_f32_16x16x32_bf16 v[28:31], v[206:209], v[222:225], v[28:31]
	v_mfma_f32_16x16x32_bf16 v[28:31], v[210:213], v[226:229], v[28:31]
	s_setprio 2
	s_barrier
	v_mfma_f32_16x16x32_bf16 v[44:47], v[210:213], v[218:221], v[44:47]
	v_mfma_f32_16x16x32_bf16 v[44:47], v[206:209], v[214:217], v[44:47]
	s_setprio 0
	s_add_i32 s79, s79, 2
	s_add_u32 s66, s66, 0x100
	s_addc_u32 s67, s67, 0
	s_add_u32 s77, s77, 0x100
	s_addc_u32 s78, s78, 0
	s_cmp_gt_u32 s79, 29
	s_cbranch_scc0 .LBB0_536
	s_and_b64 vcc, exec, s[20:21]
	s_cbranch_vccz .LBB0_539
	s_barrier

; #define PG8_STAGE(bufoff, gbase, voff) do { _Pragma("unroll") for (int _i = 0; _i < 2; ++_i) \
;         __builtin_amdgcn_global_load_lds((const unsigned*)((const char*)(gbase) + (voff)[_i]), (PG8_LAS unsigned*)(lds + (bufoff) + ldsw + _i * 8192), 16, 0, 0); } while (0)
; #define PG8_LDA(dst, b, h) do { _Pragma("unroll") for (int m = 0; m < 4; ++m) _Pragma("unroll") for (int k = 0; k < 2; ++k) dst[m][k] = *(const PG8_LAS bf16x8*)(lds + PG8_SA(b, h) + aoff + m * 2048 + k * 1024); } while (0)
; #define PG8_LDB(dst, b, h) do { _Pragma("unroll") for (int n = 0; n < 2; ++n) _Pragma("unroll") for (int k = 0; k < 2; ++k) dst[n][k] = *(const PG8_LAS bf16x8*)(lds + PG8_SB(b, h) + boff + n * 2048 + k * 1024); } while (0)
; #define PG8_MMA(ai, bj, At, Bt) do { __builtin_amdgcn_s_setprio(1); _Pragma("unroll") for (int m = 0; m < 4; ++m) _Pragma("unroll") for (int n = 0; n < 2; ++n) _Pragma("unroll") for (int k = 0; k < 2; ++k) \
;         acc[ai][bj][m][n] = __builtin_amdgcn_mfma_f32_16x16x32_bf16(Bt[n][k], At[m][k], acc[ai][bj][m][n], 0, 0, 0); __builtin_amdgcn_s_setprio(0); } while (0)
; #define PG8_WAIT_V(n) asm volatile("s_waitcnt vmcnt(" #n ")" ::: "memory")
; #define PG8_WAIT_L(n) asm volatile("s_waitcnt lgkmcnt(" #n ")" ::: "memory")
; #define PG8_BAR __builtin_amdgcn_s_barrier()
; #define PG8_SCHED __builtin_amdgcn_sched_barrier(0)
; template <class Epi, class Sched, bool ALIGN_EPI = false, bool SP2 = false>
; __device__ __forceinline__ void gemm_phase(PG8_LAS unsigned char* lds, const Gemm g, const Sched& S, const Epi& E) {
;     ...
;         for (int t = 0; t < nt; t += 2) {
;             const bool last = (t == nt - 2);
;             const char* a1 = cA + (size_t)(t + 1) * kstep;
;             const char* a2 = last ? nA : cA + (size_t)(t + 2) * kstep; const char* b2 = last ? nB : cB + (size_t)(t + 2) * kstep;
;             const char* a3 = a2 + kstep; const char* b3 = b2 + kstep;
;             if (last && has_next) S.a_ready(nxt);
;             if constexpr (SP2) {
;             PG8_LDB(B0, 0, 0); PG8_LDB(B1, 0, 1); PG8_SCHED; PG8_LDA(At, 0, 0); PG8_STAGE(PG8_SA(1, 1), a1 + hstep, voffA);
;             PG8_WAIT_V(8); PG8_WAIT_L(0); PG8_BAR; PG8_MMA(0, 0, At, B0); PG8_MMA(0, 1, At, B1); PG8_BAR; PG8_SCHED;
;             PG8_LDA(At, 0, 1); PG8_STAGE(PG8_SB(0, 0), b2, voffB); PG8_STAGE(PG8_SB(0, 1), b2 + hstep, voffB); PG8_STAGE(PG8_SA(0, 0), a2, voffA);
.LBB0_602:
	ds_read_b128 v[76:79], v171
	ds_read_b128 v[84:87], v171 offset:1024
	ds_read_b128 v[92:95], v171 offset:2048
	ds_read_b128 v[96:99], v171 offset:3072
	ds_read_b128 v[144:147], v186
	ds_read_b128 v[148:151], v186 offset:1024
	ds_read_b128 v[152:155], v186 offset:2048
	ds_read_b128 v[156:159], v186 offset:3072
	s_add_u32 s28, s62, 0xffea0080
	s_addc_u32 s29, s63, -1
	s_cmpk_eq_i32 s77, 0x54
	s_cselect_b32 s49, s39, s29
	s_cselect_b32 s48, s38, s28
	s_cselect_b32 s29, s41, s35
	s_cselect_b32 s28, s40, s34
	v_lshl_add_u64 v[200:201], s[62:63], 0, v[172:173]
	s_add_i32 m0, s61, 0xc000
	ds_read_b128 v[178:181], v187
	ds_read_b128 v[182:185], v187 offset:1024
	ds_read_b128 v[206:209], v187 offset:2048
	ds_read_b128 v[210:213], v187 offset:3072
	ds_read_b128 v[214:217], v187 offset:4096
	ds_read_b128 v[218:221], v187 offset:5120
	ds_read_b128 v[222:225], v187 offset:6144
	ds_read_b128 v[226:229], v187 offset:7168
	global_load_lds_dwordx4 v[200:201], off
	v_lshl_add_u64 v[200:201], s[62:63], 0, v[174:175]
	s_add_i32 m0, s61, 0xe000
	s_nop 0
	global_load_lds_dwordx4 v[200:201], off
	s_waitcnt vmcnt(8)
	s_waitcnt lgkmcnt(0)
	s_barrier
	s_setprio 1
	s_waitcnt lgkmcnt(0)
	v_mfma_f32_16x16x32_bf16 v[140:143], v[76:79], v[178:181], v[140:143]
	v_mfma_f32_16x16x32_bf16 v[140:143], v[84:87], v[182:185], v[140:143]
	v_mfma_f32_16x16x32_bf16 v[124:127], v[84:87], v[210:213], v[124:127]
	v_mfma_f32_16x16x32_bf16 v[124:127], v[76:79], v[206:209], v[124:127]
	v_mfma_f32_16x16x32_bf16 v[108:111], v[76:79], v[214:217], v[108:111]
	v_mfma_f32_16x16x32_bf16 v[108:111], v[84:87], v[218:221], v[108:111]
	v_mfma_f32_16x16x32_bf16 v[80:83], v[84:87], v[226:229], v[80:83]
	v_mfma_f32_16x16x32_bf16 v[80:83], v[76:79], v[222:225], v[80:83]
	v_mfma_f32_16x16x32_bf16 v[72:75], v[92:95], v[222:225], v[72:75]
	v_mfma_f32_16x16x32_bf16 v[72:75], v[96:99], v[226:229], v[72:75]
	v_mfma_f32_16x16x32_bf16 v[104:107], v[96:99], v[218:221], v[104:107]
	v_mfma_f32_16x16x32_bf16 v[104:107], v[92:95], v[214:217], v[104:107]
	v_mfma_f32_16x16x32_bf16 v[120:123], v[92:95], v[206:209], v[120:123]
	v_mfma_f32_16x16x32_bf16 v[120:123], v[96:99], v[210:213], v[120:123]
	v_mfma_f32_16x16x32_bf16 v[136:139], v[96:99], v[182:185], v[136:139]
	v_mfma_f32_16x16x32_bf16 v[136:139], v[92:95], v[178:181], v[136:139]
	s_setprio 0
	s_setprio 1
	v_mfma_f32_16x16x32_bf16 v[132:135], v[144:147], v[178:181], v[132:135]
	v_mfma_f32_16x16x32_bf16 v[132:135], v[148:151], v[182:185], v[132:135]
	v_mfma_f32_16x16x32_bf16 v[116:119], v[148:151], v[210:213], v[116:119]
	v_mfma_f32_16x16x32_bf16 v[116:119], v[144:147], v[206:209], v[116:119]
	v_mfma_f32_16x16x32_bf16 v[100:103], v[144:147], v[214:217], v[100:103]
	v_mfma_f32_16x16x32_bf16 v[100:103], v[148:151], v[218:221], v[100:103]
	v_mfma_f32_16x16x32_bf16 v[68:71], v[148:151], v[226:229], v[68:71]
	v_mfma_f32_16x16x32_bf16 v[68:71], v[144:147], v[222:225], v[68:71]
	v_mfma_f32_16x16x32_bf16 v[64:67], v[152:155], v[222:225], v[64:67]
	v_mfma_f32_16x16x32_bf16 v[64:67], v[156:159], v[226:229], v[64:67]
	v_mfma_f32_16x16x32_bf16 v[88:91], v[156:159], v[218:221], v[88:91]
	v_mfma_f32_16x16x32_bf16 v[88:91], v[152:155], v[214:217], v[88:91]
	v_mfma_f32_16x16x32_bf16 v[112:115], v[152:155], v[206:209], v[112:115]
	v_mfma_f32_16x16x32_bf16 v[112:115], v[156:159], v[210:213], v[112:115]
	s_setprio 2
	s_barrier
	v_mfma_f32_16x16x32_bf16 v[128:131], v[156:159], v[182:185], v[128:131]
	v_mfma_f32_16x16x32_bf16 v[128:131], v[152:155], v[178:181], v[128:131]
	s_setprio 0
	s_add_i32 s44, s70, s57
	v_lshl_add_u64 v[200:201], s[28:29], 0, v[160:161]
	s_mov_b32 m0, s44
	ds_read_b128 v[178:181], v187 offset:16384
	ds_read_b128 v[182:185], v187 offset:17408
	ds_read_b128 v[206:209], v187 offset:18432
	ds_read_b128 v[210:213], v187 offset:19456
	ds_read_b128 v[214:217], v187 offset:20480
	ds_read_b128 v[218:221], v187 offset:21504
	ds_read_b128 v[222:225], v187 offset:22528
	ds_read_b128 v[226:229], v187 offset:23552
	global_load_lds_dwordx4 v[200:201], off
	s_add_i32 m0, s44, 0x2000
	s_add_u32 s78, s28, 0x160000
	v_lshl_add_u64 v[230:231], s[28:29], 0, v[162:163]
	s_addc_u32 s79, s29, 0
	s_add_i32 s44, s71, s57
	global_load_lds_dwordx4 v[230:231], off
	v_lshl_add_u64 v[232:233], s[78:79], 0, v[160:161]
	s_mov_b32 m0, s44
	v_lshl_add_u64 v[234:235], s[48:49], 0, v[162:163]
	global_load_lds_dwordx4 v[232:233], off
	v_lshl_add_u64 v[232:233], s[78:79], 0, v[162:163]
	s_add_i32 m0, s44, 0x2000
	s_nop 0
	global_load_lds_dwordx4 v[232:233], off
	v_lshl_add_u64 v[232:233], s[48:49], 0, v[160:161]
	s_mov_b32 m0, s61
	s_nop 0
	global_load_lds_dwordx4 v[232:233], off
	s_mov_b32 m0, s64
	s_nop 0
	global_load_lds_dwordx4 v[234:235], off
	s_waitcnt vmcnt(8)
	s_waitcnt lgkmcnt(0)
	s_barrier
; #define PG8_STAGE(bufoff, gbase, voff) do { _Pragma("unroll") for (int _i = 0; _i < 2; ++_i) \
;         __builtin_amdgcn_global_load_lds((const unsigned*)((const char*)(gbase) + (voff)[_i]), (PG8_LAS unsigned*)(lds + (bufoff) + ldsw + _i * 8192), 16, 0, 0); } while (0)
; #define PG8_LDA(dst, b, h) do { _Pragma("unroll") for (int m = 0; m < 4; ++m) _Pragma("unroll") for (int k = 0; k < 2; ++k) dst[m][k] = *(const PG8_LAS bf16x8*)(lds + PG8_SA(b, h) + aoff + m * 2048 + k * 1024); } while (0)
; #define PG8_LDB(dst, b, h) do { _Pragma("unroll") for (int n = 0; n < 2; ++n) _Pragma("unroll") for (int k = 0; k < 2; ++k) dst[n][k] = *(const PG8_LAS bf16x8*)(lds + PG8_SB(b, h) + boff + n * 2048 + k * 1024); } while (0)
; #define PG8_MMA(ai, bj, At, Bt) do { __builtin_amdgcn_s_setprio(1); _Pragma("unroll") for (int m = 0; m < 4; ++m) _Pragma("unroll") for (int n = 0; n < 2; ++n) _Pragma("unroll") for (int k = 0; k < 2; ++k) \
;         acc[ai][bj][m][n] = __builtin_amdgcn_mfma_f32_16x16x32_bf16(Bt[n][k], At[m][k], acc[ai][bj][m][n], 0, 0, 0); __builtin_amdgcn_s_setprio(0); } while (0)
; #define PG8_WAIT_V(n) asm volatile("s_waitcnt vmcnt(" #n ")" ::: "memory")
; #define PG8_WAIT_L(n) asm volatile("s_waitcnt lgkmcnt(" #n ")" ::: "memory")
; #define PG8_BAR __builtin_amdgcn_s_barrier()
; #define PG8_SCHED __builtin_amdgcn_sched_barrier(0)
; template <class Epi, class Sched, bool ALIGN_EPI = false, bool SP2 = false>
; __device__ __forceinline__ void gemm_phase(PG8_LAS unsigned char* lds, const Gemm g, const Sched& S, const Epi& E) {
;     ...
;             PG8_WAIT_V(8); PG8_WAIT_L(0); PG8_BAR; PG8_MMA(1, 0, At, B0); PG8_MMA(1, 1, At, B1); PG8_BAR; PG8_SCHED;
;             PG8_LDB(B0, 1, 0); PG8_LDB(B1, 1, 1); PG8_SCHED; PG8_LDA(At, 1, 0); PG8_STAGE(PG8_SA(0, 1), a2 + hstep, voffA);
;             PG8_WAIT_V(8); PG8_WAIT_L(0); PG8_BAR; PG8_MMA(0, 0, At, B0); PG8_MMA(0, 1, At, B1); PG8_BAR; PG8_SCHED;
	s_setprio 1
	s_waitcnt lgkmcnt(0)
	v_mfma_f32_16x16x32_bf16 v[60:63], v[76:79], v[178:181], v[60:63]
	v_mfma_f32_16x16x32_bf16 v[60:63], v[84:87], v[182:185], v[60:63]
	v_mfma_f32_16x16x32_bf16 v[44:47], v[84:87], v[210:213], v[44:47]
	v_mfma_f32_16x16x32_bf16 v[44:47], v[76:79], v[206:209], v[44:47]
	v_mfma_f32_16x16x32_bf16 v[28:31], v[76:79], v[214:217], v[28:31]
	v_mfma_f32_16x16x32_bf16 v[28:31], v[84:87], v[218:221], v[28:31]
	v_mfma_f32_16x16x32_bf16 v[12:15], v[84:87], v[226:229], v[12:15]
	v_mfma_f32_16x16x32_bf16 v[12:15], v[76:79], v[222:225], v[12:15]
	v_mfma_f32_16x16x32_bf16 v[8:11], v[92:95], v[222:225], v[8:11]
	v_mfma_f32_16x16x32_bf16 v[8:11], v[96:99], v[226:229], v[8:11]
	v_mfma_f32_16x16x32_bf16 v[24:27], v[96:99], v[218:221], v[24:27]
	v_mfma_f32_16x16x32_bf16 v[24:27], v[92:95], v[214:217], v[24:27]
	v_mfma_f32_16x16x32_bf16 v[40:43], v[92:95], v[206:209], v[40:43]
	v_mfma_f32_16x16x32_bf16 v[40:43], v[96:99], v[210:213], v[40:43]
	v_mfma_f32_16x16x32_bf16 v[56:59], v[96:99], v[182:185], v[56:59]
	v_mfma_f32_16x16x32_bf16 v[56:59], v[92:95], v[178:181], v[56:59]
	s_setprio 0
	s_setprio 1
	v_mfma_f32_16x16x32_bf16 v[52:55], v[144:147], v[178:181], v[52:55]
	v_mfma_f32_16x16x32_bf16 v[52:55], v[148:151], v[182:185], v[52:55]
	v_mfma_f32_16x16x32_bf16 v[36:39], v[148:151], v[210:213], v[36:39]
	v_mfma_f32_16x16x32_bf16 v[36:39], v[144:147], v[206:209], v[36:39]
	v_mfma_f32_16x16x32_bf16 v[20:23], v[144:147], v[214:217], v[20:23]
	v_mfma_f32_16x16x32_bf16 v[20:23], v[148:151], v[218:221], v[20:23]
	v_mfma_f32_16x16x32_bf16 v[4:7], v[148:151], v[226:229], v[4:7]
	v_mfma_f32_16x16x32_bf16 v[4:7], v[144:147], v[222:225], v[4:7]
	v_mfma_f32_16x16x32_bf16 v[0:3], v[152:155], v[222:225], v[0:3]
	v_mfma_f32_16x16x32_bf16 v[0:3], v[156:159], v[226:229], v[0:3]
	v_mfma_f32_16x16x32_bf16 v[16:19], v[156:159], v[218:221], v[16:19]
	v_mfma_f32_16x16x32_bf16 v[16:19], v[152:155], v[214:217], v[16:19]
	v_mfma_f32_16x16x32_bf16 v[32:35], v[152:155], v[206:209], v[32:35]
	v_mfma_f32_16x16x32_bf16 v[32:35], v[156:159], v[210:213], v[32:35]
	s_setprio 2
	s_barrier
	v_mfma_f32_16x16x32_bf16 v[48:51], v[156:159], v[182:185], v[48:51]
	v_mfma_f32_16x16x32_bf16 v[48:51], v[152:155], v[178:181], v[48:51]
	s_setprio 0
	s_add_i32 s44, 0, 0x18000
	s_add_i32 s45, 0, 0x1c000
	v_add_u32_e32 v96, s44, v167
	v_add_u32_e32 v156, s45, v167
	ds_read_b128 v[76:79], v96
	ds_read_b128 v[84:87], v96 offset:1024
	ds_read_b128 v[92:95], v96 offset:2048
	ds_read_b128 v[96:99], v96 offset:3072
	ds_read_b128 v[144:147], v156
	ds_read_b128 v[148:151], v156 offset:1024
	ds_read_b128 v[152:155], v156 offset:2048
	ds_read_b128 v[156:159], v156 offset:3072
	s_add_u32 s48, s48, 0x160000
	s_addc_u32 s49, s49, 0
	s_mov_b32 m0, s65
	v_lshl_add_u64 v[236:237], s[48:49], 0, v[160:161]
	ds_read_b128 v[178:181], v187 offset:32768
	ds_read_b128 v[182:185], v187 offset:33792
	ds_read_b128 v[206:209], v187 offset:34816
	ds_read_b128 v[210:213], v187 offset:35840
	ds_read_b128 v[214:217], v187 offset:36864
	ds_read_b128 v[218:221], v187 offset:37888
	ds_read_b128 v[222:225], v187 offset:38912
	ds_read_b128 v[226:229], v187 offset:39936
	global_load_lds_dwordx4 v[236:237], off
	v_lshl_add_u64 v[236:237], s[48:49], 0, v[162:163]
	s_mov_b32 m0, s66
	s_nop 0
	global_load_lds_dwordx4 v[236:237], off
	s_waitcnt vmcnt(8)
	s_waitcnt lgkmcnt(0)
	s_barrier
	s_setprio 1
	s_waitcnt lgkmcnt(0)
	v_mfma_f32_16x16x32_bf16 v[140:143], v[76:79], v[178:181], v[140:143]
	v_mfma_f32_16x16x32_bf16 v[140:143], v[84:87], v[182:185], v[140:143]
	v_mfma_f32_16x16x32_bf16 v[124:127], v[84:87], v[210:213], v[124:127]
	v_mfma_f32_16x16x32_bf16 v[124:127], v[76:79], v[206:209], v[124:127]
	v_mfma_f32_16x16x32_bf16 v[108:111], v[76:79], v[214:217], v[108:111]
	v_mfma_f32_16x16x32_bf16 v[108:111], v[84:87], v[218:221], v[108:111]
	v_mfma_f32_16x16x32_bf16 v[80:83], v[84:87], v[226:229], v[80:83]
	v_mfma_f32_16x16x32_bf16 v[80:83], v[76:79], v[222:225], v[80:83]
	v_mfma_f32_16x16x32_bf16 v[72:75], v[92:95], v[222:225], v[72:75]
	v_mfma_f32_16x16x32_bf16 v[72:75], v[96:99], v[226:229], v[72:75]
	v_mfma_f32_16x16x32_bf16 v[104:107], v[96:99], v[218:221], v[104:107]
	v_mfma_f32_16x16x32_bf16 v[104:107], v[92:95], v[214:217], v[104:107]
	v_mfma_f32_16x16x32_bf16 v[120:123], v[92:95], v[206:209], v[120:123]
	v_mfma_f32_16x16x32_bf16 v[120:123], v[96:99], v[210:213], v[120:123]
	v_mfma_f32_16x16x32_bf16 v[136:139], v[96:99], v[182:185], v[136:139]
	v_mfma_f32_16x16x32_bf16 v[136:139], v[92:95], v[178:181], v[136:139]
	s_setprio 0
	s_setprio 1
	v_mfma_f32_16x16x32_bf16 v[132:135], v[144:147], v[178:181], v[132:135]
	v_mfma_f32_16x16x32_bf16 v[132:135], v[148:151], v[182:185], v[132:135]
	v_mfma_f32_16x16x32_bf16 v[116:119], v[148:151], v[210:213], v[116:119]
	v_mfma_f32_16x16x32_bf16 v[116:119], v[144:147], v[206:209], v[116:119]
	v_mfma_f32_16x16x32_bf16 v[100:103], v[144:147], v[214:217], v[100:103]
	v_mfma_f32_16x16x32_bf16 v[100:103], v[148:151], v[218:221], v[100:103]
	v_mfma_f32_16x16x32_bf16 v[68:71], v[148:151], v[226:229], v[68:71]
	v_mfma_f32_16x16x32_bf16 v[68:71], v[144:147], v[222:225], v[68:71]
	v_mfma_f32_16x16x32_bf16 v[64:67], v[152:155], v[222:225], v[64:67]
	v_mfma_f32_16x16x32_bf16 v[64:67], v[156:159], v[226:229], v[64:67]
	v_mfma_f32_16x16x32_bf16 v[88:91], v[156:159], v[218:221], v[88:91]
	v_mfma_f32_16x16x32_bf16 v[88:91], v[152:155], v[214:217], v[88:91]
	v_mfma_f32_16x16x32_bf16 v[112:115], v[152:155], v[206:209], v[112:115]
	v_mfma_f32_16x16x32_bf16 v[112:115], v[156:159], v[210:213], v[112:115]
	s_setprio 2
	s_barrier
; #define PG8_STAGE(bufoff, gbase, voff) do { _Pragma("unroll") for (int _i = 0; _i < 2; ++_i) \
;         __builtin_amdgcn_global_load_lds((const unsigned*)((const char*)(gbase) + (voff)[_i]), (PG8_LAS unsigned*)(lds + (bufoff) + ldsw + _i * 8192), 16, 0, 0); } while (0)
; #define PG8_LDA(dst, b, h) do { _Pragma("unroll") for (int m = 0; m < 4; ++m) _Pragma("unroll") for (int k = 0; k < 2; ++k) dst[m][k] = *(const PG8_LAS bf16x8*)(lds + PG8_SA(b, h) + aoff + m * 2048 + k * 1024); } while (0)
; #define PG8_LDB(dst, b, h) do { _Pragma("unroll") for (int n = 0; n < 2; ++n) _Pragma("unroll") for (int k = 0; k < 2; ++k) dst[n][k] = *(const PG8_LAS bf16x8*)(lds + PG8_SB(b, h) + boff + n * 2048 + k * 1024); } while (0)
; #define PG8_MMA(ai, bj, At, Bt) do { __builtin_amdgcn_s_setprio(1); _Pragma("unroll") for (int m = 0; m < 4; ++m) _Pragma("unroll") for (int n = 0; n < 2; ++n) _Pragma("unroll") for (int k = 0; k < 2; ++k) \
;         acc[ai][bj][m][n] = __builtin_amdgcn_mfma_f32_16x16x32_bf16(Bt[n][k], At[m][k], acc[ai][bj][m][n], 0, 0, 0); __builtin_amdgcn_s_setprio(0); } while (0)
; #define PG8_WAIT_V(n) asm volatile("s_waitcnt vmcnt(" #n ")" ::: "memory")
; template <class Epi, class Sched, bool ALIGN_EPI = false, bool SP2 = false>
; __device__ __forceinline__ void gemm_phase(PG8_LAS unsigned char* lds, const Gemm g, const Sched& S, const Epi& E) {
;     ...
;             PG8_LDB(B0, 0, 0); PG8_LDB(B1, 0, 1); PG8_SCHED; PG8_LDA(At, 0, 0); PG8_STAGE(PG8_SA(1, 1), a1 + hstep, voffA);
;             PG8_WAIT_V(8); PG8_WAIT_L(0); PG8_BAR; PG8_MMA(0, 0, At, B0); PG8_MMA(0, 1, At, B1); PG8_BAR; PG8_SCHED;
;             PG8_LDA(At, 0, 1); PG8_STAGE(PG8_SB(0, 0), b2, voffB); PG8_STAGE(PG8_SB(0, 1), b2 + hstep, voffB); PG8_STAGE(PG8_SA(0, 0), a2, voffA);
;             PG8_WAIT_V(8); PG8_WAIT_L(0); PG8_BAR; PG8_MMA(1, 0, At, B0); PG8_MMA(1, 1, At, B1); PG8_BAR; PG8_SCHED;
;             PG8_LDB(B0, 1, 0); PG8_LDB(B1, 1, 1); PG8_SCHED; PG8_LDA(At, 1, 0); PG8_STAGE(PG8_SA(0, 1), a2 + hstep, voffA);
;             PG8_WAIT_V(8); PG8_WAIT_L(0); PG8_BAR; PG8_MMA(0, 0, At, B0); PG8_MMA(0, 1, At, B1); PG8_BAR; PG8_SCHED;
;             PG8_LDA(At, 1, 1); PG8_STAGE(PG8_SB(1, 0), b3, voffB); PG8_STAGE(PG8_SB(1, 1), b3 + hstep, voffB); PG8_STAGE(PG8_SA(1, 0), a3, voffA);
;             PG8_WAIT_V(8); PG8_WAIT_L(0); PG8_BAR; PG8_MMA(1, 0, At, B0); PG8_MMA(1, 1, At, B1); PG8_BAR; PG8_SCHED;
	v_mfma_f32_16x16x32_bf16 v[128:131], v[156:159], v[182:185], v[128:131]
	v_mfma_f32_16x16x32_bf16 v[128:131], v[152:155], v[178:181], v[128:131]
	s_setprio 0
	s_add_i32 s44, s44, s57
	v_lshl_add_u64 v[200:201], v[200:201], 0, s[20:21]
	s_mov_b32 m0, s44
	ds_read_b128 v[178:181], v187 offset:49152
	ds_read_b128 v[182:185], v187 offset:50176
	ds_read_b128 v[206:209], v187 offset:51200
	ds_read_b128 v[210:213], v187 offset:52224
	ds_read_b128 v[214:217], v187 offset:53248
	ds_read_b128 v[218:221], v187 offset:54272
	ds_read_b128 v[222:225], v187 offset:55296
	ds_read_b128 v[226:229], v187 offset:56320
	global_load_lds_dwordx4 v[200:201], off
	s_add_i32 m0, s44, 0x2000
	s_add_u32 s28, s28, 0x160080
	v_lshl_add_u64 v[200:201], v[230:231], 0, s[20:21]
	s_addc_u32 s29, s29, 0
	s_add_i32 s44, s45, s57
	global_load_lds_dwordx4 v[200:201], off
	v_lshl_add_u64 v[200:201], s[28:29], 0, v[160:161]
	s_mov_b32 m0, s44
	s_nop 0
	global_load_lds_dwordx4 v[200:201], off
	v_lshl_add_u64 v[200:201], s[28:29], 0, v[162:163]
	s_add_i32 m0, s44, 0x2000
	s_nop 0
	global_load_lds_dwordx4 v[200:201], off
	v_lshl_add_u64 v[200:201], v[232:233], 0, s[20:21]
	s_mov_b32 m0, s67
	s_nop 0
	global_load_lds_dwordx4 v[200:201], off
	v_lshl_add_u64 v[200:201], v[234:235], 0, s[20:21]
	s_mov_b32 m0, s68
	s_nop 0
	global_load_lds_dwordx4 v[200:201], off
	s_waitcnt vmcnt(8)
	s_waitcnt lgkmcnt(0)
	s_barrier
	s_setprio 1
	s_waitcnt lgkmcnt(0)
	v_mfma_f32_16x16x32_bf16 v[60:63], v[76:79], v[178:181], v[60:63]
	v_mfma_f32_16x16x32_bf16 v[60:63], v[84:87], v[182:185], v[60:63]
	v_mfma_f32_16x16x32_bf16 v[44:47], v[84:87], v[210:213], v[44:47]
	v_mfma_f32_16x16x32_bf16 v[44:47], v[76:79], v[206:209], v[44:47]
	v_mfma_f32_16x16x32_bf16 v[28:31], v[76:79], v[214:217], v[28:31]
	v_mfma_f32_16x16x32_bf16 v[28:31], v[84:87], v[218:221], v[28:31]
	v_mfma_f32_16x16x32_bf16 v[12:15], v[84:87], v[226:229], v[12:15]
	v_mfma_f32_16x16x32_bf16 v[12:15], v[76:79], v[222:225], v[12:15]
	v_mfma_f32_16x16x32_bf16 v[8:11], v[92:95], v[222:225], v[8:11]
	v_mfma_f32_16x16x32_bf16 v[8:11], v[96:99], v[226:229], v[8:11]
	v_mfma_f32_16x16x32_bf16 v[24:27], v[96:99], v[218:221], v[24:27]
	v_mfma_f32_16x16x32_bf16 v[24:27], v[92:95], v[214:217], v[24:27]
	v_mfma_f32_16x16x32_bf16 v[40:43], v[92:95], v[206:209], v[40:43]
	v_mfma_f32_16x16x32_bf16 v[40:43], v[96:99], v[210:213], v[40:43]
	v_mfma_f32_16x16x32_bf16 v[56:59], v[96:99], v[182:185], v[56:59]
	v_mfma_f32_16x16x32_bf16 v[56:59], v[92:95], v[178:181], v[56:59]
	s_setprio 0
	s_setprio 1
	v_mfma_f32_16x16x32_bf16 v[52:55], v[144:147], v[178:181], v[52:55]
	v_mfma_f32_16x16x32_bf16 v[52:55], v[148:151], v[182:185], v[52:55]
	v_mfma_f32_16x16x32_bf16 v[36:39], v[148:151], v[210:213], v[36:39]
	v_mfma_f32_16x16x32_bf16 v[36:39], v[144:147], v[206:209], v[36:39]
	v_mfma_f32_16x16x32_bf16 v[20:23], v[144:147], v[214:217], v[20:23]
	v_mfma_f32_16x16x32_bf16 v[20:23], v[148:151], v[218:221], v[20:23]
	v_mfma_f32_16x16x32_bf16 v[4:7], v[148:151], v[226:229], v[4:7]
	v_mfma_f32_16x16x32_bf16 v[4:7], v[144:147], v[222:225], v[4:7]
	v_mfma_f32_16x16x32_bf16 v[0:3], v[152:155], v[222:225], v[0:3]
	v_mfma_f32_16x16x32_bf16 v[0:3], v[156:159], v[226:229], v[0:3]
	v_mfma_f32_16x16x32_bf16 v[16:19], v[156:159], v[218:221], v[16:19]
	v_mfma_f32_16x16x32_bf16 v[16:19], v[152:155], v[214:217], v[16:19]
	v_mfma_f32_16x16x32_bf16 v[32:35], v[152:155], v[206:209], v[32:35]
	v_mfma_f32_16x16x32_bf16 v[32:35], v[156:159], v[210:213], v[32:35]
	s_setprio 2
	s_barrier
	v_mfma_f32_16x16x32_bf16 v[48:51], v[156:159], v[182:185], v[48:51]
	v_mfma_f32_16x16x32_bf16 v[48:51], v[152:155], v[178:181], v[48:51]
	s_setprio 0
	s_add_i32 s77, s77, 2
	s_add_u32 s62, s62, 0x100
	s_addc_u32 s63, s63, 0
	s_add_u32 s34, s34, 0x100
	s_addc_u32 s35, s35, 0
	s_cmpk_gt_u32 s77, 0x55
	s_cbranch_scc0 .LBB0_602
	s_and_b64 vcc, exec, s[22:23]
	s_cbranch_vccz .LBB0_605
	s_barrier

; #define PG8_STAGE(bufoff, gbase, voff) do { _Pragma("unroll") for (int _i = 0; _i < 2; ++_i) \
;         __builtin_amdgcn_global_load_lds((const unsigned*)((const char*)(gbase) + (voff)[_i]), (PG8_LAS unsigned*)(lds + (bufoff) + ldsw + _i * 8192), 16, 0, 0); } while (0)
; #define PG8_LDA(dst, b, h) do { _Pragma("unroll") for (int m = 0; m < 4; ++m) _Pragma("unroll") for (int k = 0; k < 2; ++k) dst[m][k] = *(const PG8_LAS bf16x8*)(lds + PG8_SA(b, h) + aoff + m * 2048 + k * 1024); } while (0)
; #define PG8_LDB(dst, b, h) do { _Pragma("unroll") for (int n = 0; n < 2; ++n) _Pragma("unroll") for (int k = 0; k < 2; ++k) dst[n][k] = *(const PG8_LAS bf16x8*)(lds + PG8_SB(b, h) + boff + n * 2048 + k * 1024); } while (0)
; #define PG8_MMA(ai, bj, At, Bt) do { __builtin_amdgcn_s_setprio(1); _Pragma("unroll") for (int m = 0; m < 4; ++m) _Pragma("unroll") for (int n = 0; n < 2; ++n) _Pragma("unroll") for (int k = 0; k < 2; ++k) \
;         acc[ai][bj][m][n] = __builtin_amdgcn_mfma_f32_16x16x32_bf16(Bt[n][k], At[m][k], acc[ai][bj][m][n], 0, 0, 0); __builtin_amdgcn_s_setprio(0); } while (0)
; #define PG8_WAIT_V(n) asm volatile("s_waitcnt vmcnt(" #n ")" ::: "memory")
; template <class Epi, class Sched, bool ALIGN_EPI = false, bool SP2 = false>
; __device__ __forceinline__ void gemm_phase(PG8_LAS unsigned char* lds, const Gemm g, const Sched& S, const Epi& E) {
;     ...
;             PG8_LDB(B0, 0, 0); PG8_LDB(B1, 0, 1); PG8_SCHED; PG8_LDA(At, 0, 0); PG8_STAGE(PG8_SA(1, 1), a1 + hstep, voffA);
;             PG8_WAIT_V(8); PG8_WAIT_L(0); PG8_BAR; PG8_MMA(0, 0, At, B0); PG8_MMA(0, 1, At, B1); PG8_BAR; PG8_SCHED;
;             PG8_LDA(At, 0, 1); PG8_STAGE(PG8_SB(0, 0), b2, voffB); PG8_STAGE(PG8_SB(0, 1), b2 + hstep, voffB); PG8_STAGE(PG8_SA(0, 0), a2, voffA);
;             PG8_WAIT_V(8); PG8_WAIT_L(0); PG8_BAR; PG8_MMA(1, 0, At, B0); PG8_MMA(1, 1, At, B1); PG8_BAR; PG8_SCHED;
;             PG8_LDB(B0, 1, 0); PG8_LDB(B1, 1, 1); PG8_SCHED; PG8_LDA(At, 1, 0); PG8_STAGE(PG8_SA(0, 1), a2 + hstep, voffA);
;             PG8_WAIT_V(8); PG8_WAIT_L(0); PG8_BAR; PG8_MMA(0, 0, At, B0); PG8_MMA(0, 1, At, B1); PG8_BAR; PG8_SCHED;
;             PG8_LDA(At, 1, 1); PG8_STAGE(PG8_SB(1, 0), b3, voffB); PG8_STAGE(PG8_SB(1, 1), b3 + hstep, voffB); PG8_STAGE(PG8_SA(1, 0), a3, voffA);
;             PG8_WAIT_V(8); PG8_WAIT_L(0); PG8_BAR; PG8_MMA(1, 0, At, B0); PG8_MMA(1, 1, At, B1); PG8_BAR; PG8_SCHED;
.LBB0_719:
	ds_read_b128 v[88:91], v208
	ds_read_b128 v[96:99], v208 offset:1024
	ds_read_b128 v[136:139], v208 offset:2048
	ds_read_b128 v[140:143], v208 offset:3072
	ds_read_b128 v[144:147], v209
	ds_read_b128 v[148:151], v209 offset:1024
	ds_read_b128 v[152:155], v209 offset:2048
	ds_read_b128 v[156:159], v209 offset:3072
	s_add_u32 s44, s62, 0xfff80080
	s_addc_u32 s45, s63, -1
	s_cmp_eq_u32 s76, 28
	s_cselect_b32 s59, s29, s45
	s_cselect_b32 s58, s34, s44
	s_cselect_b32 s57, s23, s75
	s_cselect_b32 s56, s35, s74
	v_lshl_add_u64 v[200:201], s[62:63], 0, v[172:173]
	s_add_i32 m0, s49, 0xc000
	ds_read_b128 v[178:181], v210
	ds_read_b128 v[182:185], v210 offset:1024
	ds_read_b128 v[186:189], v210 offset:2048
	ds_read_b128 v[212:215], v210 offset:3072
	ds_read_b128 v[216:219], v210 offset:4096
	ds_read_b128 v[220:223], v210 offset:5120
	ds_read_b128 v[224:227], v210 offset:6144
	ds_read_b128 v[228:231], v210 offset:7168
	global_load_lds_dwordx4 v[200:201], off
	v_lshl_add_u64 v[200:201], s[62:63], 0, v[174:175]
	s_add_i32 m0, s49, 0xe000
	s_nop 0
	global_load_lds_dwordx4 v[200:201], off
	s_waitcnt vmcnt(8)
	s_waitcnt lgkmcnt(0)
	s_barrier
	s_setprio 1
	s_waitcnt lgkmcnt(0)
	v_mfma_f32_16x16x32_bf16 v[128:131], v[88:91], v[178:181], v[128:131]
	v_mfma_f32_16x16x32_bf16 v[128:131], v[96:99], v[182:185], v[128:131]
	v_mfma_f32_16x16x32_bf16 v[116:119], v[96:99], v[212:215], v[116:119]
	v_mfma_f32_16x16x32_bf16 v[116:119], v[88:91], v[186:189], v[116:119]
	v_mfma_f32_16x16x32_bf16 v[100:103], v[88:91], v[216:219], v[100:103]
	v_mfma_f32_16x16x32_bf16 v[100:103], v[96:99], v[220:223], v[100:103]
	v_mfma_f32_16x16x32_bf16 v[76:79], v[96:99], v[228:231], v[76:79]
	v_mfma_f32_16x16x32_bf16 v[76:79], v[88:91], v[224:227], v[76:79]
	v_mfma_f32_16x16x32_bf16 v[68:71], v[136:139], v[224:227], v[68:71]
	v_mfma_f32_16x16x32_bf16 v[68:71], v[140:143], v[228:231], v[68:71]
	v_mfma_f32_16x16x32_bf16 v[84:87], v[140:143], v[220:223], v[84:87]
	v_mfma_f32_16x16x32_bf16 v[84:87], v[136:139], v[216:219], v[84:87]
	v_mfma_f32_16x16x32_bf16 v[108:111], v[136:139], v[186:189], v[108:111]
	v_mfma_f32_16x16x32_bf16 v[108:111], v[140:143], v[212:215], v[108:111]
	v_mfma_f32_16x16x32_bf16 v[120:123], v[140:143], v[182:185], v[120:123]
	v_mfma_f32_16x16x32_bf16 v[120:123], v[136:139], v[178:181], v[120:123]
	s_setprio 0
	s_setprio 1
	v_mfma_f32_16x16x32_bf16 v[132:135], v[144:147], v[178:181], v[132:135]
	v_mfma_f32_16x16x32_bf16 v[132:135], v[148:151], v[182:185], v[132:135]
	v_mfma_f32_16x16x32_bf16 v[112:115], v[148:151], v[212:215], v[112:115]
	v_mfma_f32_16x16x32_bf16 v[112:115], v[144:147], v[186:189], v[112:115]
	v_mfma_f32_16x16x32_bf16 v[92:95], v[144:147], v[216:219], v[92:95]
	v_mfma_f32_16x16x32_bf16 v[92:95], v[148:151], v[220:223], v[92:95]
	v_mfma_f32_16x16x32_bf16 v[72:75], v[148:151], v[228:231], v[72:75]
	v_mfma_f32_16x16x32_bf16 v[72:75], v[144:147], v[224:227], v[72:75]
	v_mfma_f32_16x16x32_bf16 v[64:67], v[152:155], v[224:227], v[64:67]
	v_mfma_f32_16x16x32_bf16 v[64:67], v[156:159], v[228:231], v[64:67]
	v_mfma_f32_16x16x32_bf16 v[80:83], v[156:159], v[220:223], v[80:83]
	v_mfma_f32_16x16x32_bf16 v[80:83], v[152:155], v[216:219], v[80:83]
	v_mfma_f32_16x16x32_bf16 v[104:107], v[152:155], v[186:189], v[104:107]
	v_mfma_f32_16x16x32_bf16 v[104:107], v[156:159], v[212:215], v[104:107]
	s_setprio 2
	s_barrier
	v_mfma_f32_16x16x32_bf16 v[124:127], v[156:159], v[182:185], v[124:127]
	v_mfma_f32_16x16x32_bf16 v[124:127], v[152:155], v[178:181], v[124:127]
	s_setprio 0
	s_add_i32 s44, s71, s65
	v_lshl_add_u64 v[200:201], s[56:57], 0, v[164:165]
	s_mov_b32 m0, s44
	ds_read_b128 v[178:181], v210 offset:16384
	ds_read_b128 v[182:185], v210 offset:17408
	ds_read_b128 v[186:189], v210 offset:18432
	ds_read_b128 v[212:215], v210 offset:19456
	ds_read_b128 v[216:219], v210 offset:20480
	ds_read_b128 v[220:223], v210 offset:21504
	ds_read_b128 v[224:227], v210 offset:22528
	ds_read_b128 v[228:231], v210 offset:23552
	global_load_lds_dwordx4 v[200:201], off
	s_add_i32 m0, s44, 0x2000
	s_add_u32 s78, s56, 0x80000
	v_lshl_add_u64 v[232:233], s[56:57], 0, v[168:169]
	s_addc_u32 s79, s57, 0
	s_add_i32 s44, s72, s65
	global_load_lds_dwordx4 v[232:233], off
	v_lshl_add_u64 v[234:235], s[78:79], 0, v[164:165]
	s_mov_b32 m0, s44
	v_lshl_add_u64 v[236:237], s[58:59], 0, v[168:169]
	global_load_lds_dwordx4 v[234:235], off
	v_lshl_add_u64 v[234:235], s[78:79], 0, v[168:169]
	s_add_i32 m0, s44, 0x2000
	s_nop 0
	global_load_lds_dwordx4 v[234:235], off
	v_lshl_add_u64 v[234:235], s[58:59], 0, v[164:165]
	s_mov_b32 m0, s49
	s_nop 0
	global_load_lds_dwordx4 v[234:235], off
	s_mov_b32 m0, s61
	s_nop 0
	global_load_lds_dwordx4 v[236:237], off
	s_waitcnt vmcnt(8)
	s_waitcnt lgkmcnt(0)
	s_barrier
; #define PG8_STAGE(bufoff, gbase, voff) do { _Pragma("unroll") for (int _i = 0; _i < 2; ++_i) \
;         __builtin_amdgcn_global_load_lds((const unsigned*)((const char*)(gbase) + (voff)[_i]), (PG8_LAS unsigned*)(lds + (bufoff) + ldsw + _i * 8192), 16, 0, 0); } while (0)
; #define PG8_LDA(dst, b, h) do { _Pragma("unroll") for (int m = 0; m < 4; ++m) _Pragma("unroll") for (int k = 0; k < 2; ++k) dst[m][k] = *(const PG8_LAS bf16x8*)(lds + PG8_SA(b, h) + aoff + m * 2048 + k * 1024); } while (0)
; #define PG8_LDB(dst, b, h) do { _Pragma("unroll") for (int n = 0; n < 2; ++n) _Pragma("unroll") for (int k = 0; k < 2; ++k) dst[n][k] = *(const PG8_LAS bf16x8*)(lds + PG8_SB(b, h) + boff + n * 2048 + k * 1024); } while (0)
; #define PG8_MMA(ai, bj, At, Bt) do { __builtin_amdgcn_s_setprio(1); _Pragma("unroll") for (int m = 0; m < 4; ++m) _Pragma("unroll") for (int n = 0; n < 2; ++n) _Pragma("unroll") for (int k = 0; k < 2; ++k) \
;         acc[ai][bj][m][n] = __builtin_amdgcn_mfma_f32_16x16x32_bf16(Bt[n][k], At[m][k], acc[ai][bj][m][n], 0, 0, 0); __builtin_amdgcn_s_setprio(0); } while (0)
; #define PG8_WAIT_V(n) asm volatile("s_waitcnt vmcnt(" #n ")" ::: "memory")
; template <class Epi, class Sched, bool ALIGN_EPI = false, bool SP2 = false>
; __device__ __forceinline__ void gemm_phase(PG8_LAS unsigned char* lds, const Gemm g, const Sched& S, const Epi& E) {
;     ...
;             PG8_LDB(B0, 0, 0); PG8_LDB(B1, 0, 1); PG8_SCHED; PG8_LDA(At, 0, 0); PG8_STAGE(PG8_SA(1, 1), a1 + hstep, voffA);
;             PG8_WAIT_V(8); PG8_WAIT_L(0); PG8_BAR; PG8_MMA(0, 0, At, B0); PG8_MMA(0, 1, At, B1); PG8_BAR; PG8_SCHED;
;             PG8_LDA(At, 0, 1); PG8_STAGE(PG8_SB(0, 0), b2, voffB); PG8_STAGE(PG8_SB(0, 1), b2 + hstep, voffB); PG8_STAGE(PG8_SA(0, 0), a2, voffA);
;             PG8_WAIT_V(8); PG8_WAIT_L(0); PG8_BAR; PG8_MMA(1, 0, At, B0); PG8_MMA(1, 1, At, B1); PG8_BAR; PG8_SCHED;
;             PG8_LDB(B0, 1, 0); PG8_LDB(B1, 1, 1); PG8_SCHED; PG8_LDA(At, 1, 0); PG8_STAGE(PG8_SA(0, 1), a2 + hstep, voffA);
;             PG8_WAIT_V(8); PG8_WAIT_L(0); PG8_BAR; PG8_MMA(0, 0, At, B0); PG8_MMA(0, 1, At, B1); PG8_BAR; PG8_SCHED;
;             PG8_LDA(At, 1, 1); PG8_STAGE(PG8_SB(1, 0), b3, voffB); PG8_STAGE(PG8_SB(1, 1), b3 + hstep, voffB); PG8_STAGE(PG8_SA(1, 0), a3, voffA);
;             PG8_WAIT_V(8); PG8_WAIT_L(0); PG8_BAR; PG8_MMA(1, 0, At, B0); PG8_MMA(1, 1, At, B1); PG8_BAR; PG8_SCHED;
	s_setprio 1
	s_waitcnt lgkmcnt(0)
	v_mfma_f32_16x16x32_bf16 v[56:59], v[88:91], v[178:181], v[56:59]
	v_mfma_f32_16x16x32_bf16 v[56:59], v[96:99], v[182:185], v[56:59]
	v_mfma_f32_16x16x32_bf16 v[44:47], v[96:99], v[212:215], v[44:47]
	v_mfma_f32_16x16x32_bf16 v[44:47], v[88:91], v[186:189], v[44:47]
	v_mfma_f32_16x16x32_bf16 v[28:31], v[88:91], v[216:219], v[28:31]
	v_mfma_f32_16x16x32_bf16 v[28:31], v[96:99], v[220:223], v[28:31]
	v_mfma_f32_16x16x32_bf16 v[12:15], v[96:99], v[228:231], v[12:15]
	v_mfma_f32_16x16x32_bf16 v[12:15], v[88:91], v[224:227], v[12:15]
	v_mfma_f32_16x16x32_bf16 v[4:7], v[136:139], v[224:227], v[4:7]
	v_mfma_f32_16x16x32_bf16 v[4:7], v[140:143], v[228:231], v[4:7]
	v_mfma_f32_16x16x32_bf16 v[20:23], v[140:143], v[220:223], v[20:23]
	v_mfma_f32_16x16x32_bf16 v[20:23], v[136:139], v[216:219], v[20:23]
	v_mfma_f32_16x16x32_bf16 v[36:39], v[136:139], v[186:189], v[36:39]
	v_mfma_f32_16x16x32_bf16 v[36:39], v[140:143], v[212:215], v[36:39]
	v_mfma_f32_16x16x32_bf16 v[48:51], v[140:143], v[182:185], v[48:51]
	v_mfma_f32_16x16x32_bf16 v[48:51], v[136:139], v[178:181], v[48:51]
	s_setprio 0
	s_setprio 1
	v_mfma_f32_16x16x32_bf16 v[60:63], v[144:147], v[178:181], v[60:63]
	v_mfma_f32_16x16x32_bf16 v[60:63], v[148:151], v[182:185], v[60:63]
	v_mfma_f32_16x16x32_bf16 v[40:43], v[148:151], v[212:215], v[40:43]
	v_mfma_f32_16x16x32_bf16 v[40:43], v[144:147], v[186:189], v[40:43]
	v_mfma_f32_16x16x32_bf16 v[24:27], v[144:147], v[216:219], v[24:27]
	v_mfma_f32_16x16x32_bf16 v[24:27], v[148:151], v[220:223], v[24:27]
	v_mfma_f32_16x16x32_bf16 v[8:11], v[148:151], v[228:231], v[8:11]
	v_mfma_f32_16x16x32_bf16 v[8:11], v[144:147], v[224:227], v[8:11]
	v_mfma_f32_16x16x32_bf16 v[0:3], v[152:155], v[224:227], v[0:3]
	v_mfma_f32_16x16x32_bf16 v[0:3], v[156:159], v[228:231], v[0:3]
	v_mfma_f32_16x16x32_bf16 v[16:19], v[156:159], v[220:223], v[16:19]
	v_mfma_f32_16x16x32_bf16 v[16:19], v[152:155], v[216:219], v[16:19]
	v_mfma_f32_16x16x32_bf16 v[32:35], v[152:155], v[186:189], v[32:35]
	v_mfma_f32_16x16x32_bf16 v[32:35], v[156:159], v[212:215], v[32:35]
	s_setprio 2
	s_barrier
	v_mfma_f32_16x16x32_bf16 v[52:55], v[156:159], v[182:185], v[52:55]
	v_mfma_f32_16x16x32_bf16 v[52:55], v[152:155], v[178:181], v[52:55]
	s_setprio 0
	s_add_i32 s44, 0, 0x18000
	s_add_i32 s45, 0, 0x1c000
	v_add_u32_e32 v140, s44, v163
	v_add_u32_e32 v156, s45, v163
	ds_read_b128 v[88:91], v140
	ds_read_b128 v[96:99], v140 offset:1024
	ds_read_b128 v[136:139], v140 offset:2048
	ds_read_b128 v[140:143], v140 offset:3072
	ds_read_b128 v[144:147], v156
	ds_read_b128 v[148:151], v156 offset:1024
	ds_read_b128 v[152:155], v156 offset:2048
	ds_read_b128 v[156:159], v156 offset:3072
	s_add_u32 s58, s58, 0x80000
	s_addc_u32 s59, s59, 0
	s_mov_b32 m0, s66
	v_lshl_add_u64 v[238:239], s[58:59], 0, v[164:165]
	ds_read_b128 v[178:181], v210 offset:32768
	ds_read_b128 v[182:185], v210 offset:33792
	ds_read_b128 v[186:189], v210 offset:34816
	ds_read_b128 v[212:215], v210 offset:35840
	ds_read_b128 v[216:219], v210 offset:36864
	ds_read_b128 v[220:223], v210 offset:37888
	ds_read_b128 v[224:227], v210 offset:38912
	ds_read_b128 v[228:231], v210 offset:39936
	global_load_lds_dwordx4 v[238:239], off
	v_lshl_add_u64 v[238:239], s[58:59], 0, v[168:169]
	s_mov_b32 m0, s67
	s_nop 0
	global_load_lds_dwordx4 v[238:239], off
	s_waitcnt vmcnt(8)
	s_waitcnt lgkmcnt(0)
	s_barrier
	s_setprio 1
	s_waitcnt lgkmcnt(0)
	v_mfma_f32_16x16x32_bf16 v[128:131], v[88:91], v[178:181], v[128:131]
	v_mfma_f32_16x16x32_bf16 v[128:131], v[96:99], v[182:185], v[128:131]
	v_mfma_f32_16x16x32_bf16 v[116:119], v[96:99], v[212:215], v[116:119]
	v_mfma_f32_16x16x32_bf16 v[116:119], v[88:91], v[186:189], v[116:119]
	v_mfma_f32_16x16x32_bf16 v[100:103], v[88:91], v[216:219], v[100:103]
	v_mfma_f32_16x16x32_bf16 v[100:103], v[96:99], v[220:223], v[100:103]
	v_mfma_f32_16x16x32_bf16 v[76:79], v[96:99], v[228:231], v[76:79]
	v_mfma_f32_16x16x32_bf16 v[76:79], v[88:91], v[224:227], v[76:79]
	v_mfma_f32_16x16x32_bf16 v[68:71], v[136:139], v[224:227], v[68:71]
	v_mfma_f32_16x16x32_bf16 v[68:71], v[140:143], v[228:231], v[68:71]
	v_mfma_f32_16x16x32_bf16 v[84:87], v[140:143], v[220:223], v[84:87]
	v_mfma_f32_16x16x32_bf16 v[84:87], v[136:139], v[216:219], v[84:87]
	v_mfma_f32_16x16x32_bf16 v[108:111], v[136:139], v[186:189], v[108:111]
	v_mfma_f32_16x16x32_bf16 v[108:111], v[140:143], v[212:215], v[108:111]
	v_mfma_f32_16x16x32_bf16 v[120:123], v[140:143], v[182:185], v[120:123]
	v_mfma_f32_16x16x32_bf16 v[120:123], v[136:139], v[178:181], v[120:123]
	s_setprio 0
	s_setprio 1
	v_mfma_f32_16x16x32_bf16 v[132:135], v[144:147], v[178:181], v[132:135]
	v_mfma_f32_16x16x32_bf16 v[132:135], v[148:151], v[182:185], v[132:135]
	v_mfma_f32_16x16x32_bf16 v[112:115], v[148:151], v[212:215], v[112:115]
	v_mfma_f32_16x16x32_bf16 v[112:115], v[144:147], v[186:189], v[112:115]
	v_mfma_f32_16x16x32_bf16 v[92:95], v[144:147], v[216:219], v[92:95]
	v_mfma_f32_16x16x32_bf16 v[92:95], v[148:151], v[220:223], v[92:95]
	v_mfma_f32_16x16x32_bf16 v[72:75], v[148:151], v[228:231], v[72:75]
	v_mfma_f32_16x16x32_bf16 v[72:75], v[144:147], v[224:227], v[72:75]
	v_mfma_f32_16x16x32_bf16 v[64:67], v[152:155], v[224:227], v[64:67]
	v_mfma_f32_16x16x32_bf16 v[64:67], v[156:159], v[228:231], v[64:67]
	v_mfma_f32_16x16x32_bf16 v[80:83], v[156:159], v[220:223], v[80:83]
	v_mfma_f32_16x16x32_bf16 v[80:83], v[152:155], v[216:219], v[80:83]
	v_mfma_f32_16x16x32_bf16 v[104:107], v[152:155], v[186:189], v[104:107]
	v_mfma_f32_16x16x32_bf16 v[104:107], v[156:159], v[212:215], v[104:107]
	s_setprio 2
	s_barrier
; #define PG8_STAGE(bufoff, gbase, voff) do { _Pragma("unroll") for (int _i = 0; _i < 2; ++_i) \
;         __builtin_amdgcn_global_load_lds((const unsigned*)((const char*)(gbase) + (voff)[_i]), (PG8_LAS unsigned*)(lds + (bufoff) + ldsw + _i * 8192), 16, 0, 0); } while (0)
; #define PG8_LDA(dst, b, h) do { _Pragma("unroll") for (int m = 0; m < 4; ++m) _Pragma("unroll") for (int k = 0; k < 2; ++k) dst[m][k] = *(const PG8_LAS bf16x8*)(lds + PG8_SA(b, h) + aoff + m * 2048 + k * 1024); } while (0)
; #define PG8_LDB(dst, b, h) do { _Pragma("unroll") for (int n = 0; n < 2; ++n) _Pragma("unroll") for (int k = 0; k < 2; ++k) dst[n][k] = *(const PG8_LAS bf16x8*)(lds + PG8_SB(b, h) + boff + n * 2048 + k * 1024); } while (0)
; #define PG8_MMA(ai, bj, At, Bt) do { __builtin_amdgcn_s_setprio(1); _Pragma("unroll") for (int m = 0; m < 4; ++m) _Pragma("unroll") for (int n = 0; n < 2; ++n) _Pragma("unroll") for (int k = 0; k < 2; ++k) \
;         acc[ai][bj][m][n] = __builtin_amdgcn_mfma_f32_16x16x32_bf16(Bt[n][k], At[m][k], acc[ai][bj][m][n], 0, 0, 0); __builtin_amdgcn_s_setprio(0); } while (0)
; #define PG8_WAIT_V(n) asm volatile("s_waitcnt vmcnt(" #n ")" ::: "memory")
; template <class Epi, class Sched, bool ALIGN_EPI = false, bool SP2 = false>
; __device__ __forceinline__ void gemm_phase(PG8_LAS unsigned char* lds, const Gemm g, const Sched& S, const Epi& E) {
;     ...
;             PG8_LDB(B0, 0, 0); PG8_LDB(B1, 0, 1); PG8_SCHED; PG8_LDA(At, 0, 0); PG8_STAGE(PG8_SA(1, 1), a1 + hstep, voffA);
;             PG8_WAIT_V(8); PG8_WAIT_L(0); PG8_BAR; PG8_MMA(0, 0, At, B0); PG8_MMA(0, 1, At, B1); PG8_BAR; PG8_SCHED;
;             PG8_LDA(At, 0, 1); PG8_STAGE(PG8_SB(0, 0), b2, voffB); PG8_STAGE(PG8_SB(0, 1), b2 + hstep, voffB); PG8_STAGE(PG8_SA(0, 0), a2, voffA);
;             PG8_WAIT_V(8); PG8_WAIT_L(0); PG8_BAR; PG8_MMA(1, 0, At, B0); PG8_MMA(1, 1, At, B1); PG8_BAR; PG8_SCHED;
;             PG8_LDB(B0, 1, 0); PG8_LDB(B1, 1, 1); PG8_SCHED; PG8_LDA(At, 1, 0); PG8_STAGE(PG8_SA(0, 1), a2 + hstep, voffA);
;             PG8_WAIT_V(8); PG8_WAIT_L(0); PG8_BAR; PG8_MMA(0, 0, At, B0); PG8_MMA(0, 1, At, B1); PG8_BAR; PG8_SCHED;
;             PG8_LDA(At, 1, 1); PG8_STAGE(PG8_SB(1, 0), b3, voffB); PG8_STAGE(PG8_SB(1, 1), b3 + hstep, voffB); PG8_STAGE(PG8_SA(1, 0), a3, voffA);
;             PG8_WAIT_V(8); PG8_WAIT_L(0); PG8_BAR; PG8_MMA(1, 0, At, B0); PG8_MMA(1, 1, At, B1); PG8_BAR; PG8_SCHED;
	v_mfma_f32_16x16x32_bf16 v[124:127], v[156:159], v[182:185], v[124:127]
	v_mfma_f32_16x16x32_bf16 v[124:127], v[152:155], v[178:181], v[124:127]
	s_setprio 0
	s_add_i32 s44, s44, s65
	v_lshl_add_u64 v[200:201], v[200:201], 0, s[18:19]
	s_mov_b32 m0, s44
	ds_read_b128 v[178:181], v210 offset:49152
	ds_read_b128 v[182:185], v210 offset:50176
	ds_read_b128 v[186:189], v210 offset:51200
	ds_read_b128 v[212:215], v210 offset:52224
	ds_read_b128 v[216:219], v210 offset:53248
	ds_read_b128 v[220:223], v210 offset:54272
	ds_read_b128 v[224:227], v210 offset:55296
	ds_read_b128 v[228:231], v210 offset:56320
	global_load_lds_dwordx4 v[200:201], off
	s_add_i32 m0, s44, 0x2000
	s_add_u32 s56, s56, 0x80080
	v_lshl_add_u64 v[200:201], v[232:233], 0, s[18:19]
	s_addc_u32 s57, s57, 0
	s_add_i32 s44, s45, s65
	global_load_lds_dwordx4 v[200:201], off
	v_lshl_add_u64 v[200:201], s[56:57], 0, v[164:165]
	s_mov_b32 m0, s44
	s_nop 0
	global_load_lds_dwordx4 v[200:201], off
	v_lshl_add_u64 v[200:201], s[56:57], 0, v[168:169]
	s_add_i32 m0, s44, 0x2000
	s_nop 0
	global_load_lds_dwordx4 v[200:201], off
	v_lshl_add_u64 v[200:201], v[234:235], 0, s[18:19]
	s_mov_b32 m0, s68
	s_nop 0
	global_load_lds_dwordx4 v[200:201], off
	v_lshl_add_u64 v[200:201], v[236:237], 0, s[18:19]
	s_mov_b32 m0, s69
	s_nop 0
	global_load_lds_dwordx4 v[200:201], off
	s_waitcnt vmcnt(8)
	s_waitcnt lgkmcnt(0)
	s_barrier
	s_setprio 1
	s_waitcnt lgkmcnt(0)
	v_mfma_f32_16x16x32_bf16 v[56:59], v[88:91], v[178:181], v[56:59]
	v_mfma_f32_16x16x32_bf16 v[56:59], v[96:99], v[182:185], v[56:59]
	v_mfma_f32_16x16x32_bf16 v[44:47], v[96:99], v[212:215], v[44:47]
	v_mfma_f32_16x16x32_bf16 v[44:47], v[88:91], v[186:189], v[44:47]
	v_mfma_f32_16x16x32_bf16 v[28:31], v[88:91], v[216:219], v[28:31]
	v_mfma_f32_16x16x32_bf16 v[28:31], v[96:99], v[220:223], v[28:31]
	v_mfma_f32_16x16x32_bf16 v[12:15], v[96:99], v[228:231], v[12:15]
	v_mfma_f32_16x16x32_bf16 v[12:15], v[88:91], v[224:227], v[12:15]
	v_mfma_f32_16x16x32_bf16 v[4:7], v[136:139], v[224:227], v[4:7]
	v_mfma_f32_16x16x32_bf16 v[4:7], v[140:143], v[228:231], v[4:7]
	v_mfma_f32_16x16x32_bf16 v[20:23], v[140:143], v[220:223], v[20:23]
	v_mfma_f32_16x16x32_bf16 v[20:23], v[136:139], v[216:219], v[20:23]
	v_mfma_f32_16x16x32_bf16 v[36:39], v[136:139], v[186:189], v[36:39]
	v_mfma_f32_16x16x32_bf16 v[36:39], v[140:143], v[212:215], v[36:39]
	v_mfma_f32_16x16x32_bf16 v[48:51], v[140:143], v[182:185], v[48:51]
	v_mfma_f32_16x16x32_bf16 v[48:51], v[136:139], v[178:181], v[48:51]
	s_setprio 0
	s_setprio 1
	v_mfma_f32_16x16x32_bf16 v[60:63], v[144:147], v[178:181], v[60:63]
	v_mfma_f32_16x16x32_bf16 v[60:63], v[148:151], v[182:185], v[60:63]
	v_mfma_f32_16x16x32_bf16 v[40:43], v[148:151], v[212:215], v[40:43]
	v_mfma_f32_16x16x32_bf16 v[40:43], v[144:147], v[186:189], v[40:43]
	v_mfma_f32_16x16x32_bf16 v[24:27], v[144:147], v[216:219], v[24:27]
	v_mfma_f32_16x16x32_bf16 v[24:27], v[148:151], v[220:223], v[24:27]
	v_mfma_f32_16x16x32_bf16 v[8:11], v[148:151], v[228:231], v[8:11]
	v_mfma_f32_16x16x32_bf16 v[8:11], v[144:147], v[224:227], v[8:11]
	v_mfma_f32_16x16x32_bf16 v[0:3], v[152:155], v[224:227], v[0:3]
	v_mfma_f32_16x16x32_bf16 v[0:3], v[156:159], v[228:231], v[0:3]
	v_mfma_f32_16x16x32_bf16 v[16:19], v[156:159], v[220:223], v[16:19]
	v_mfma_f32_16x16x32_bf16 v[16:19], v[152:155], v[216:219], v[16:19]
	v_mfma_f32_16x16x32_bf16 v[32:35], v[152:155], v[186:189], v[32:35]
	v_mfma_f32_16x16x32_bf16 v[32:35], v[156:159], v[212:215], v[32:35]
	s_setprio 2
	s_barrier
	v_mfma_f32_16x16x32_bf16 v[52:55], v[156:159], v[182:185], v[52:55]
	v_mfma_f32_16x16x32_bf16 v[52:55], v[152:155], v[178:181], v[52:55]
	s_setprio 0
	s_add_i32 s76, s76, 2
	s_add_u32 s62, s62, 0x100
	s_addc_u32 s63, s63, 0
	s_add_u32 s74, s74, 0x100
	s_addc_u32 s75, s75, 0
	s_cmp_gt_u32 s76, 29
	s_cbranch_scc0 .LBB0_719
	s_and_b64 vcc, exec, s[20:21]
	s_cbranch_vccz .LBB0_722
	s_barrier

; #define PG8_STAGE(bufoff, gbase, voff) do { _Pragma("unroll") for (int _i = 0; _i < 2; ++_i) \
;         __builtin_amdgcn_global_load_lds((const unsigned*)((const char*)(gbase) + (voff)[_i]), (PG8_LAS unsigned*)(lds + (bufoff) + ldsw + _i * 8192), 16, 0, 0); } while (0)
; #define PG8_LDA(dst, b, h) do { _Pragma("unroll") for (int m = 0; m < 4; ++m) _Pragma("unroll") for (int k = 0; k < 2; ++k) dst[m][k] = *(const PG8_LAS bf16x8*)(lds + PG8_SA(b, h) + aoff + m * 2048 + k * 1024); } while (0)
; #define PG8_LDB(dst, b, h) do { _Pragma("unroll") for (int n = 0; n < 2; ++n) _Pragma("unroll") for (int k = 0; k < 2; ++k) dst[n][k] = *(const PG8_LAS bf16x8*)(lds + PG8_SB(b, h) + boff + n * 2048 + k * 1024); } while (0)
; #define PG8_MMA(ai, bj, At, Bt) do { __builtin_amdgcn_s_setprio(1); _Pragma("unroll") for (int m = 0; m < 4; ++m) _Pragma("unroll") for (int n = 0; n < 2; ++n) _Pragma("unroll") for (int k = 0; k < 2; ++k) \
;         acc[ai][bj][m][n] = __builtin_amdgcn_mfma_f32_16x16x32_bf16(Bt[n][k], At[m][k], acc[ai][bj][m][n], 0, 0, 0); __builtin_amdgcn_s_setprio(0); } while (0)
; #define PG8_WAIT_V(n) asm volatile("s_waitcnt vmcnt(" #n ")" ::: "memory")
; template <class Epi, class Sched, bool ALIGN_EPI = false, bool SP2 = false>
; __device__ __forceinline__ void gemm_phase(PG8_LAS unsigned char* lds, const Gemm g, const Sched& S, const Epi& E) {
;     ...
;             PG8_LDB(B0, 0, 0); PG8_LDB(B1, 0, 1); PG8_SCHED; PG8_LDA(At, 0, 0); PG8_STAGE(PG8_SA(1, 1), a1 + hstep, voffA);
;             PG8_WAIT_V(8); PG8_WAIT_L(0); PG8_BAR; PG8_MMA(0, 0, At, B0); PG8_MMA(0, 1, At, B1); PG8_BAR; PG8_SCHED;
;             PG8_LDA(At, 0, 1); PG8_STAGE(PG8_SB(0, 0), b2, voffB); PG8_STAGE(PG8_SB(0, 1), b2 + hstep, voffB); PG8_STAGE(PG8_SA(0, 0), a2, voffA);
;             PG8_WAIT_V(8); PG8_WAIT_L(0); PG8_BAR; PG8_MMA(1, 0, At, B0); PG8_MMA(1, 1, At, B1); PG8_BAR; PG8_SCHED;
;             PG8_LDB(B0, 1, 0); PG8_LDB(B1, 1, 1); PG8_SCHED; PG8_LDA(At, 1, 0); PG8_STAGE(PG8_SA(0, 1), a2 + hstep, voffA);
;             PG8_WAIT_V(8); PG8_WAIT_L(0); PG8_BAR; PG8_MMA(0, 0, At, B0); PG8_MMA(0, 1, At, B1); PG8_BAR; PG8_SCHED;
;             PG8_LDA(At, 1, 1); PG8_STAGE(PG8_SB(1, 0), b3, voffB); PG8_STAGE(PG8_SB(1, 1), b3 + hstep, voffB); PG8_STAGE(PG8_SA(1, 0), a3, voffA);
;             PG8_WAIT_V(8); PG8_WAIT_L(0); PG8_BAR; PG8_MMA(1, 0, At, B0); PG8_MMA(1, 1, At, B1); PG8_BAR; PG8_SCHED;
.LBB0_774:
	ds_read_b128 v[136:139], v156
	ds_read_b128 v[140:143], v156 offset:1024
	ds_read_b128 v[172:175], v156 offset:2048
	ds_read_b128 v[176:179], v156 offset:3072
	ds_read_b128 v[180:183], v157
	ds_read_b128 v[184:187], v157 offset:1024
	ds_read_b128 v[208:211], v157 offset:2048
	ds_read_b128 v[212:215], v157 offset:3072
	s_add_u32 s42, s40, 0xfff80080
	s_addc_u32 s43, s41, -1
	s_cmp_eq_u32 s71, 28
	s_cselect_b32 s49, s23, s43
	s_cselect_b32 s48, s34, s42
	s_cselect_b32 s43, s21, s70
	s_cselect_b32 s42, s35, s69
	v_lshl_add_u64 v[188:189], s[40:41], 0, v[128:129]
	s_add_i32 m0, s11, 0xc000
	ds_read_b128 v[216:219], v158
	ds_read_b128 v[220:223], v158 offset:1024
	ds_read_b128 v[224:227], v158 offset:2048
	ds_read_b128 v[228:231], v158 offset:3072
	ds_read_b128 v[232:235], v158 offset:4096
	ds_read_b128 v[236:239], v158 offset:5120
	ds_read_b128 v[240:243], v158 offset:6144
	ds_read_b128 v[244:247], v158 offset:7168
	global_load_lds_dwordx4 v[188:189], off
	v_lshl_add_u64 v[188:189], s[40:41], 0, v[130:131]
	s_add_i32 m0, s11, 0xe000
	s_nop 0
	global_load_lds_dwordx4 v[188:189], off
	s_waitcnt vmcnt(8)
	s_waitcnt lgkmcnt(0)
	s_barrier
	s_setprio 1
	s_waitcnt lgkmcnt(0)
	v_mfma_f32_16x16x32_bf16 v[124:127], v[136:139], v[216:219], v[124:127]
	v_mfma_f32_16x16x32_bf16 v[124:127], v[140:143], v[220:223], v[124:127]
	v_mfma_f32_16x16x32_bf16 v[108:111], v[140:143], v[228:231], v[108:111]
	v_mfma_f32_16x16x32_bf16 v[108:111], v[136:139], v[224:227], v[108:111]
	v_mfma_f32_16x16x32_bf16 v[96:99], v[136:139], v[232:235], v[96:99]
	v_mfma_f32_16x16x32_bf16 v[96:99], v[140:143], v[236:239], v[96:99]
	v_mfma_f32_16x16x32_bf16 v[80:83], v[140:143], v[244:247], v[80:83]
	v_mfma_f32_16x16x32_bf16 v[80:83], v[136:139], v[240:243], v[80:83]
	v_mfma_f32_16x16x32_bf16 v[72:75], v[172:175], v[240:243], v[72:75]
	v_mfma_f32_16x16x32_bf16 v[72:75], v[176:179], v[244:247], v[72:75]
	v_mfma_f32_16x16x32_bf16 v[88:91], v[176:179], v[236:239], v[88:91]
	v_mfma_f32_16x16x32_bf16 v[88:91], v[172:175], v[232:235], v[88:91]
	v_mfma_f32_16x16x32_bf16 v[104:107], v[172:175], v[224:227], v[104:107]
	v_mfma_f32_16x16x32_bf16 v[104:107], v[176:179], v[228:231], v[104:107]
	v_mfma_f32_16x16x32_bf16 v[120:123], v[176:179], v[220:223], v[120:123]
	v_mfma_f32_16x16x32_bf16 v[120:123], v[172:175], v[216:219], v[120:123]
	s_setprio 0
	s_setprio 1
	v_mfma_f32_16x16x32_bf16 v[116:119], v[180:183], v[216:219], v[116:119]
	v_mfma_f32_16x16x32_bf16 v[116:119], v[184:187], v[220:223], v[116:119]
	v_mfma_f32_16x16x32_bf16 v[100:103], v[184:187], v[228:231], v[100:103]
	v_mfma_f32_16x16x32_bf16 v[100:103], v[180:183], v[224:227], v[100:103]
	v_mfma_f32_16x16x32_bf16 v[84:87], v[180:183], v[232:235], v[84:87]
	v_mfma_f32_16x16x32_bf16 v[84:87], v[184:187], v[236:239], v[84:87]
	v_mfma_f32_16x16x32_bf16 v[68:71], v[184:187], v[244:247], v[68:71]
	v_mfma_f32_16x16x32_bf16 v[68:71], v[180:183], v[240:243], v[68:71]
	v_mfma_f32_16x16x32_bf16 v[64:67], v[208:211], v[240:243], v[64:67]
	v_mfma_f32_16x16x32_bf16 v[64:67], v[212:215], v[244:247], v[64:67]
	v_mfma_f32_16x16x32_bf16 v[76:79], v[212:215], v[236:239], v[76:79]
	v_mfma_f32_16x16x32_bf16 v[76:79], v[208:211], v[232:235], v[76:79]
	v_mfma_f32_16x16x32_bf16 v[92:95], v[208:211], v[224:227], v[92:95]
	v_mfma_f32_16x16x32_bf16 v[92:95], v[212:215], v[228:231], v[92:95]
	s_setprio 2
	s_barrier
	v_mfma_f32_16x16x32_bf16 v[112:115], v[212:215], v[220:223], v[112:115]
	v_mfma_f32_16x16x32_bf16 v[112:115], v[208:211], v[216:219], v[112:115]
	s_setprio 0
	s_add_i32 s44, s64, s52
	v_lshl_add_u64 v[188:189], s[42:43], 0, v[166:167]
	s_mov_b32 m0, s44
	ds_read_b128 v[216:219], v158 offset:16384
	ds_read_b128 v[220:223], v158 offset:17408
	ds_read_b128 v[224:227], v158 offset:18432
	ds_read_b128 v[228:231], v158 offset:19456
	ds_read_b128 v[232:235], v158 offset:20480
	ds_read_b128 v[236:239], v158 offset:21504
	ds_read_b128 v[240:243], v158 offset:22528
	ds_read_b128 v[244:247], v158 offset:23552
	global_load_lds_dwordx4 v[188:189], off
	s_add_i32 m0, s44, 0x2000
	s_add_u32 s72, s42, 0x80000
	v_lshl_add_u64 v[200:201], s[42:43], 0, v[170:171]
	s_addc_u32 s73, s43, 0
	s_add_i32 s44, s65, s52
	global_load_lds_dwordx4 v[200:201], off
	v_lshl_add_u64 v[248:249], s[72:73], 0, v[166:167]
	s_mov_b32 m0, s44
	v_lshl_add_u64 v[250:251], s[48:49], 0, v[168:169]
	global_load_lds_dwordx4 v[248:249], off
	v_lshl_add_u64 v[248:249], s[72:73], 0, v[170:171]
	s_add_i32 m0, s44, 0x2000
	s_nop 0
	global_load_lds_dwordx4 v[248:249], off
	v_lshl_add_u64 v[248:249], s[48:49], 0, v[164:165]
	s_mov_b32 m0, s11
	s_nop 0
	global_load_lds_dwordx4 v[248:249], off
	s_mov_b32 m0, s58
	s_nop 0
	global_load_lds_dwordx4 v[250:251], off
	s_waitcnt vmcnt(8)
	s_waitcnt lgkmcnt(0)
	s_barrier
; #define PG8_STAGE(bufoff, gbase, voff) do { _Pragma("unroll") for (int _i = 0; _i < 2; ++_i) \
;         __builtin_amdgcn_global_load_lds((const unsigned*)((const char*)(gbase) + (voff)[_i]), (PG8_LAS unsigned*)(lds + (bufoff) + ldsw + _i * 8192), 16, 0, 0); } while (0)
; #define PG8_LDA(dst, b, h) do { _Pragma("unroll") for (int m = 0; m < 4; ++m) _Pragma("unroll") for (int k = 0; k < 2; ++k) dst[m][k] = *(const PG8_LAS bf16x8*)(lds + PG8_SA(b, h) + aoff + m * 2048 + k * 1024); } while (0)
; #define PG8_LDB(dst, b, h) do { _Pragma("unroll") for (int n = 0; n < 2; ++n) _Pragma("unroll") for (int k = 0; k < 2; ++k) dst[n][k] = *(const PG8_LAS bf16x8*)(lds + PG8_SB(b, h) + boff + n * 2048 + k * 1024); } while (0)
; #define PG8_MMA(ai, bj, At, Bt) do { __builtin_amdgcn_s_setprio(1); _Pragma("unroll") for (int m = 0; m < 4; ++m) _Pragma("unroll") for (int n = 0; n < 2; ++n) _Pragma("unroll") for (int k = 0; k < 2; ++k) \
;         acc[ai][bj][m][n] = __builtin_amdgcn_mfma_f32_16x16x32_bf16(Bt[n][k], At[m][k], acc[ai][bj][m][n], 0, 0, 0); __builtin_amdgcn_s_setprio(0); } while (0)
; #define PG8_WAIT_V(n) asm volatile("s_waitcnt vmcnt(" #n ")" ::: "memory")
; template <class Epi, class Sched, bool ALIGN_EPI = false, bool SP2 = false>
; __device__ __forceinline__ void gemm_phase(PG8_LAS unsigned char* lds, const Gemm g, const Sched& S, const Epi& E) {
;     ...
;             PG8_LDB(B0, 0, 0); PG8_LDB(B1, 0, 1); PG8_SCHED; PG8_LDA(At, 0, 0); PG8_STAGE(PG8_SA(1, 1), a1 + hstep, voffA);
;             PG8_WAIT_V(8); PG8_WAIT_L(0); PG8_BAR; PG8_MMA(0, 0, At, B0); PG8_MMA(0, 1, At, B1); PG8_BAR; PG8_SCHED;
;             PG8_LDA(At, 0, 1); PG8_STAGE(PG8_SB(0, 0), b2, voffB); PG8_STAGE(PG8_SB(0, 1), b2 + hstep, voffB); PG8_STAGE(PG8_SA(0, 0), a2, voffA);
;             PG8_WAIT_V(8); PG8_WAIT_L(0); PG8_BAR; PG8_MMA(1, 0, At, B0); PG8_MMA(1, 1, At, B1); PG8_BAR; PG8_SCHED;
;             PG8_LDB(B0, 1, 0); PG8_LDB(B1, 1, 1); PG8_SCHED; PG8_LDA(At, 1, 0); PG8_STAGE(PG8_SA(0, 1), a2 + hstep, voffA);
;             PG8_WAIT_V(8); PG8_WAIT_L(0); PG8_BAR; PG8_MMA(0, 0, At, B0); PG8_MMA(0, 1, At, B1); PG8_BAR; PG8_SCHED;
;             PG8_LDA(At, 1, 1); PG8_STAGE(PG8_SB(1, 0), b3, voffB); PG8_STAGE(PG8_SB(1, 1), b3 + hstep, voffB); PG8_STAGE(PG8_SA(1, 0), a3, voffA);
;             PG8_WAIT_V(8); PG8_WAIT_L(0); PG8_BAR; PG8_MMA(1, 0, At, B0); PG8_MMA(1, 1, At, B1); PG8_BAR; PG8_SCHED;
	s_setprio 1
	s_waitcnt lgkmcnt(0)
	v_mfma_f32_16x16x32_bf16 v[60:63], v[136:139], v[216:219], v[60:63]
	v_mfma_f32_16x16x32_bf16 v[60:63], v[140:143], v[220:223], v[60:63]
	v_mfma_f32_16x16x32_bf16 v[48:51], v[140:143], v[228:231], v[48:51]
	v_mfma_f32_16x16x32_bf16 v[48:51], v[136:139], v[224:227], v[48:51]
	v_mfma_f32_16x16x32_bf16 v[32:35], v[136:139], v[232:235], v[32:35]
	v_mfma_f32_16x16x32_bf16 v[32:35], v[140:143], v[236:239], v[32:35]
	v_mfma_f32_16x16x32_bf16 v[12:15], v[140:143], v[244:247], v[12:15]
	v_mfma_f32_16x16x32_bf16 v[12:15], v[136:139], v[240:243], v[12:15]
	v_mfma_f32_16x16x32_bf16 v[8:11], v[172:175], v[240:243], v[8:11]
	v_mfma_f32_16x16x32_bf16 v[8:11], v[176:179], v[244:247], v[8:11]
	v_mfma_f32_16x16x32_bf16 v[24:27], v[176:179], v[236:239], v[24:27]
	v_mfma_f32_16x16x32_bf16 v[24:27], v[172:175], v[232:235], v[24:27]
	v_mfma_f32_16x16x32_bf16 v[40:43], v[172:175], v[224:227], v[40:43]
	v_mfma_f32_16x16x32_bf16 v[40:43], v[176:179], v[228:231], v[40:43]
	v_mfma_f32_16x16x32_bf16 v[56:59], v[176:179], v[220:223], v[56:59]
	v_mfma_f32_16x16x32_bf16 v[56:59], v[172:175], v[216:219], v[56:59]
	s_setprio 0
	s_setprio 1
	v_mfma_f32_16x16x32_bf16 v[52:55], v[180:183], v[216:219], v[52:55]
	v_mfma_f32_16x16x32_bf16 v[52:55], v[184:187], v[220:223], v[52:55]
	v_mfma_f32_16x16x32_bf16 v[36:39], v[184:187], v[228:231], v[36:39]
	v_mfma_f32_16x16x32_bf16 v[36:39], v[180:183], v[224:227], v[36:39]
	v_mfma_f32_16x16x32_bf16 v[20:23], v[180:183], v[232:235], v[20:23]
	v_mfma_f32_16x16x32_bf16 v[20:23], v[184:187], v[236:239], v[20:23]
	v_mfma_f32_16x16x32_bf16 v[4:7], v[184:187], v[244:247], v[4:7]
	v_mfma_f32_16x16x32_bf16 v[4:7], v[180:183], v[240:243], v[4:7]
	v_mfma_f32_16x16x32_bf16 v[0:3], v[208:211], v[240:243], v[0:3]
	v_mfma_f32_16x16x32_bf16 v[0:3], v[212:215], v[244:247], v[0:3]
	v_mfma_f32_16x16x32_bf16 v[16:19], v[212:215], v[236:239], v[16:19]
	v_mfma_f32_16x16x32_bf16 v[16:19], v[208:211], v[232:235], v[16:19]
	v_mfma_f32_16x16x32_bf16 v[28:31], v[208:211], v[224:227], v[28:31]
	v_mfma_f32_16x16x32_bf16 v[28:31], v[212:215], v[228:231], v[28:31]
	s_setprio 2
	s_barrier
	v_mfma_f32_16x16x32_bf16 v[44:47], v[212:215], v[220:223], v[44:47]
	v_mfma_f32_16x16x32_bf16 v[44:47], v[208:211], v[216:219], v[44:47]
	s_setprio 0
	s_add_i32 s44, 0, 0x18000
	v_add_u32_e32 v144, s44, v146
	s_add_i32 s45, 0, 0x1c000
	ds_read_b128 v[136:139], v144
	ds_read_b128 v[140:143], v144 offset:1024
	ds_read_b128 v[172:175], v144 offset:2048
	ds_read_b128 v[176:179], v144 offset:3072
	v_add_u32_e32 v144, s45, v146
	ds_read_b128 v[180:183], v144
	ds_read_b128 v[184:187], v144 offset:1024
	ds_read_b128 v[208:211], v144 offset:2048
	ds_read_b128 v[212:215], v144 offset:3072
	s_add_u32 s48, s48, 0x80000
	s_addc_u32 s49, s49, 0
	s_mov_b32 m0, s59
	v_lshl_add_u64 v[252:253], s[48:49], 0, v[164:165]
	ds_read_b128 v[216:219], v158 offset:32768
	ds_read_b128 v[220:223], v158 offset:33792
	ds_read_b128 v[224:227], v158 offset:34816
	ds_read_b128 v[228:231], v158 offset:35840
	ds_read_b128 v[232:235], v158 offset:36864
	ds_read_b128 v[236:239], v158 offset:37888
	ds_read_b128 v[240:243], v158 offset:38912
	ds_read_b128 v[244:247], v158 offset:39936
	global_load_lds_dwordx4 v[252:253], off
	v_lshl_add_u64 v[252:253], s[48:49], 0, v[168:169]
	s_mov_b32 m0, s60
	s_nop 0
	global_load_lds_dwordx4 v[252:253], off
	s_waitcnt vmcnt(8)
	s_waitcnt lgkmcnt(0)
	s_barrier
	s_setprio 1
	s_waitcnt lgkmcnt(0)
	v_mfma_f32_16x16x32_bf16 v[124:127], v[136:139], v[216:219], v[124:127]
	v_mfma_f32_16x16x32_bf16 v[124:127], v[140:143], v[220:223], v[124:127]
	v_mfma_f32_16x16x32_bf16 v[108:111], v[140:143], v[228:231], v[108:111]
	v_mfma_f32_16x16x32_bf16 v[108:111], v[136:139], v[224:227], v[108:111]
	v_mfma_f32_16x16x32_bf16 v[96:99], v[136:139], v[232:235], v[96:99]
	v_mfma_f32_16x16x32_bf16 v[96:99], v[140:143], v[236:239], v[96:99]
	v_mfma_f32_16x16x32_bf16 v[80:83], v[140:143], v[244:247], v[80:83]
	v_mfma_f32_16x16x32_bf16 v[80:83], v[136:139], v[240:243], v[80:83]
	v_mfma_f32_16x16x32_bf16 v[72:75], v[172:175], v[240:243], v[72:75]
	v_mfma_f32_16x16x32_bf16 v[72:75], v[176:179], v[244:247], v[72:75]
	v_mfma_f32_16x16x32_bf16 v[88:91], v[176:179], v[236:239], v[88:91]
	v_mfma_f32_16x16x32_bf16 v[88:91], v[172:175], v[232:235], v[88:91]
	v_mfma_f32_16x16x32_bf16 v[104:107], v[172:175], v[224:227], v[104:107]
	v_mfma_f32_16x16x32_bf16 v[104:107], v[176:179], v[228:231], v[104:107]
	v_mfma_f32_16x16x32_bf16 v[120:123], v[176:179], v[220:223], v[120:123]
	v_mfma_f32_16x16x32_bf16 v[120:123], v[172:175], v[216:219], v[120:123]
	s_setprio 0
	s_setprio 1
	v_mfma_f32_16x16x32_bf16 v[116:119], v[180:183], v[216:219], v[116:119]
	v_mfma_f32_16x16x32_bf16 v[116:119], v[184:187], v[220:223], v[116:119]
	v_mfma_f32_16x16x32_bf16 v[100:103], v[184:187], v[228:231], v[100:103]
	v_mfma_f32_16x16x32_bf16 v[100:103], v[180:183], v[224:227], v[100:103]
	v_mfma_f32_16x16x32_bf16 v[84:87], v[180:183], v[232:235], v[84:87]
	v_mfma_f32_16x16x32_bf16 v[84:87], v[184:187], v[236:239], v[84:87]
	v_mfma_f32_16x16x32_bf16 v[68:71], v[184:187], v[244:247], v[68:71]
	v_mfma_f32_16x16x32_bf16 v[68:71], v[180:183], v[240:243], v[68:71]
	v_mfma_f32_16x16x32_bf16 v[64:67], v[208:211], v[240:243], v[64:67]
	v_mfma_f32_16x16x32_bf16 v[64:67], v[212:215], v[244:247], v[64:67]
	v_mfma_f32_16x16x32_bf16 v[76:79], v[212:215], v[236:239], v[76:79]
	v_mfma_f32_16x16x32_bf16 v[76:79], v[208:211], v[232:235], v[76:79]
	v_mfma_f32_16x16x32_bf16 v[92:95], v[208:211], v[224:227], v[92:95]
	v_mfma_f32_16x16x32_bf16 v[92:95], v[212:215], v[228:231], v[92:95]
	s_setprio 2
	s_barrier
; #define PG8_STAGE(bufoff, gbase, voff) do { _Pragma("unroll") for (int _i = 0; _i < 2; ++_i) \
;         __builtin_amdgcn_global_load_lds((const unsigned*)((const char*)(gbase) + (voff)[_i]), (PG8_LAS unsigned*)(lds + (bufoff) + ldsw + _i * 8192), 16, 0, 0); } while (0)
; #define PG8_LDA(dst, b, h) do { _Pragma("unroll") for (int m = 0; m < 4; ++m) _Pragma("unroll") for (int k = 0; k < 2; ++k) dst[m][k] = *(const PG8_LAS bf16x8*)(lds + PG8_SA(b, h) + aoff + m * 2048 + k * 1024); } while (0)
; #define PG8_LDB(dst, b, h) do { _Pragma("unroll") for (int n = 0; n < 2; ++n) _Pragma("unroll") for (int k = 0; k < 2; ++k) dst[n][k] = *(const PG8_LAS bf16x8*)(lds + PG8_SB(b, h) + boff + n * 2048 + k * 1024); } while (0)
; #define PG8_MMA(ai, bj, At, Bt) do { __builtin_amdgcn_s_setprio(1); _Pragma("unroll") for (int m = 0; m < 4; ++m) _Pragma("unroll") for (int n = 0; n < 2; ++n) _Pragma("unroll") for (int k = 0; k < 2; ++k) \
;         acc[ai][bj][m][n] = __builtin_amdgcn_mfma_f32_16x16x32_bf16(Bt[n][k], At[m][k], acc[ai][bj][m][n], 0, 0, 0); __builtin_amdgcn_s_setprio(0); } while (0)
; #define PG8_WAIT_V(n) asm volatile("s_waitcnt vmcnt(" #n ")" ::: "memory")
; template <class Epi, class Sched, bool ALIGN_EPI = false, bool SP2 = false>
; __device__ __forceinline__ void gemm_phase(PG8_LAS unsigned char* lds, const Gemm g, const Sched& S, const Epi& E) {
;     ...
;             PG8_LDB(B0, 0, 0); PG8_LDB(B1, 0, 1); PG8_SCHED; PG8_LDA(At, 0, 0); PG8_STAGE(PG8_SA(1, 1), a1 + hstep, voffA);
;             PG8_WAIT_V(8); PG8_WAIT_L(0); PG8_BAR; PG8_MMA(0, 0, At, B0); PG8_MMA(0, 1, At, B1); PG8_BAR; PG8_SCHED;
;             PG8_LDA(At, 0, 1); PG8_STAGE(PG8_SB(0, 0), b2, voffB); PG8_STAGE(PG8_SB(0, 1), b2 + hstep, voffB); PG8_STAGE(PG8_SA(0, 0), a2, voffA);
;             PG8_WAIT_V(8); PG8_WAIT_L(0); PG8_BAR; PG8_MMA(1, 0, At, B0); PG8_MMA(1, 1, At, B1); PG8_BAR; PG8_SCHED;
;             PG8_LDB(B0, 1, 0); PG8_LDB(B1, 1, 1); PG8_SCHED; PG8_LDA(At, 1, 0); PG8_STAGE(PG8_SA(0, 1), a2 + hstep, voffA);
;             PG8_WAIT_V(8); PG8_WAIT_L(0); PG8_BAR; PG8_MMA(0, 0, At, B0); PG8_MMA(0, 1, At, B1); PG8_BAR; PG8_SCHED;
;             PG8_LDA(At, 1, 1); PG8_STAGE(PG8_SB(1, 0), b3, voffB); PG8_STAGE(PG8_SB(1, 1), b3 + hstep, voffB); PG8_STAGE(PG8_SA(1, 0), a3, voffA);
;             PG8_WAIT_V(8); PG8_WAIT_L(0); PG8_BAR; PG8_MMA(1, 0, At, B0); PG8_MMA(1, 1, At, B1); PG8_BAR; PG8_SCHED;
	v_mfma_f32_16x16x32_bf16 v[112:115], v[212:215], v[220:223], v[112:115]
	v_mfma_f32_16x16x32_bf16 v[112:115], v[208:211], v[216:219], v[112:115]
	s_setprio 0
	s_add_i32 s44, s44, s52
	v_lshl_add_u64 v[188:189], v[188:189], 0, s[16:17]
	s_mov_b32 m0, s44
	ds_read_b128 v[216:219], v158 offset:49152
	ds_read_b128 v[220:223], v158 offset:50176
	ds_read_b128 v[224:227], v158 offset:51200
	ds_read_b128 v[228:231], v158 offset:52224
	ds_read_b128 v[232:235], v158 offset:53248
	ds_read_b128 v[236:239], v158 offset:54272
	ds_read_b128 v[240:243], v158 offset:55296
	ds_read_b128 v[244:247], v158 offset:56320
	global_load_lds_dwordx4 v[188:189], off
	s_add_i32 m0, s44, 0x2000
	s_add_u32 s42, s42, 0x80080
	v_lshl_add_u64 v[188:189], v[200:201], 0, s[16:17]
	s_addc_u32 s43, s43, 0
	s_add_i32 s44, s45, s52
	global_load_lds_dwordx4 v[188:189], off
	v_lshl_add_u64 v[188:189], s[42:43], 0, v[166:167]
	s_mov_b32 m0, s44
	s_nop 0
	global_load_lds_dwordx4 v[188:189], off
	v_lshl_add_u64 v[188:189], s[42:43], 0, v[170:171]
	s_add_i32 m0, s44, 0x2000
	s_nop 0
	global_load_lds_dwordx4 v[188:189], off
	v_lshl_add_u64 v[188:189], v[248:249], 0, s[16:17]
	s_mov_b32 m0, s62
	s_nop 0
	global_load_lds_dwordx4 v[188:189], off
	v_lshl_add_u64 v[188:189], v[250:251], 0, s[16:17]
	s_mov_b32 m0, s63
	s_nop 0
	global_load_lds_dwordx4 v[188:189], off
	s_waitcnt vmcnt(8)
	s_waitcnt lgkmcnt(0)
	s_barrier
	s_setprio 1
	s_waitcnt lgkmcnt(0)
	v_mfma_f32_16x16x32_bf16 v[60:63], v[136:139], v[216:219], v[60:63]
	v_mfma_f32_16x16x32_bf16 v[60:63], v[140:143], v[220:223], v[60:63]
	v_mfma_f32_16x16x32_bf16 v[48:51], v[140:143], v[228:231], v[48:51]
	v_mfma_f32_16x16x32_bf16 v[48:51], v[136:139], v[224:227], v[48:51]
	v_mfma_f32_16x16x32_bf16 v[32:35], v[136:139], v[232:235], v[32:35]
	v_mfma_f32_16x16x32_bf16 v[32:35], v[140:143], v[236:239], v[32:35]
	v_mfma_f32_16x16x32_bf16 v[12:15], v[140:143], v[244:247], v[12:15]
	v_mfma_f32_16x16x32_bf16 v[12:15], v[136:139], v[240:243], v[12:15]
	v_mfma_f32_16x16x32_bf16 v[8:11], v[172:175], v[240:243], v[8:11]
	v_mfma_f32_16x16x32_bf16 v[8:11], v[176:179], v[244:247], v[8:11]
	v_mfma_f32_16x16x32_bf16 v[24:27], v[176:179], v[236:239], v[24:27]
	v_mfma_f32_16x16x32_bf16 v[24:27], v[172:175], v[232:235], v[24:27]
	v_mfma_f32_16x16x32_bf16 v[40:43], v[172:175], v[224:227], v[40:43]
	v_mfma_f32_16x16x32_bf16 v[40:43], v[176:179], v[228:231], v[40:43]
	v_mfma_f32_16x16x32_bf16 v[56:59], v[176:179], v[220:223], v[56:59]
	v_mfma_f32_16x16x32_bf16 v[56:59], v[172:175], v[216:219], v[56:59]
	s_setprio 0
	s_setprio 1
	v_mfma_f32_16x16x32_bf16 v[52:55], v[180:183], v[216:219], v[52:55]
	v_mfma_f32_16x16x32_bf16 v[52:55], v[184:187], v[220:223], v[52:55]
	v_mfma_f32_16x16x32_bf16 v[36:39], v[184:187], v[228:231], v[36:39]
	v_mfma_f32_16x16x32_bf16 v[36:39], v[180:183], v[224:227], v[36:39]
	v_mfma_f32_16x16x32_bf16 v[20:23], v[180:183], v[232:235], v[20:23]
	v_mfma_f32_16x16x32_bf16 v[20:23], v[184:187], v[236:239], v[20:23]
	v_mfma_f32_16x16x32_bf16 v[4:7], v[184:187], v[244:247], v[4:7]
	v_mfma_f32_16x16x32_bf16 v[4:7], v[180:183], v[240:243], v[4:7]
	v_mfma_f32_16x16x32_bf16 v[0:3], v[208:211], v[240:243], v[0:3]
	v_mfma_f32_16x16x32_bf16 v[0:3], v[212:215], v[244:247], v[0:3]
	v_mfma_f32_16x16x32_bf16 v[16:19], v[212:215], v[236:239], v[16:19]
	v_mfma_f32_16x16x32_bf16 v[16:19], v[208:211], v[232:235], v[16:19]
	v_mfma_f32_16x16x32_bf16 v[28:31], v[208:211], v[224:227], v[28:31]
	v_mfma_f32_16x16x32_bf16 v[28:31], v[212:215], v[228:231], v[28:31]
	s_setprio 2
	s_barrier
	v_mfma_f32_16x16x32_bf16 v[44:47], v[212:215], v[220:223], v[44:47]
	v_mfma_f32_16x16x32_bf16 v[44:47], v[208:211], v[216:219], v[44:47]
	s_setprio 0
	s_add_i32 s71, s71, 2
	s_add_u32 s40, s40, 0x100
	s_addc_u32 s41, s41, 0
	s_add_u32 s69, s69, 0x100
	s_addc_u32 s70, s70, 0
	s_cmp_gt_u32 s71, 29
	s_cbranch_scc0 .LBB0_774
	s_and_b64 vcc, exec, s[18:19]
	s_cbranch_vccz .LBB0_777
	s_barrier

; #define PG8_STAGE(bufoff, gbase, voff) do { _Pragma("unroll") for (int _i = 0; _i < 2; ++_i) \
;         __builtin_amdgcn_global_load_lds((const unsigned*)((const char*)(gbase) + (voff)[_i]), (PG8_LAS unsigned*)(lds + (bufoff) + ldsw + _i * 8192), 16, 0, 0); } while (0)
; #define PG8_LDA(dst, b, h) do { _Pragma("unroll") for (int m = 0; m < 4; ++m) _Pragma("unroll") for (int k = 0; k < 2; ++k) dst[m][k] = *(const PG8_LAS bf16x8*)(lds + PG8_SA(b, h) + aoff + m * 2048 + k * 1024); } while (0)
; #define PG8_LDB(dst, b, h) do { _Pragma("unroll") for (int n = 0; n < 2; ++n) _Pragma("unroll") for (int k = 0; k < 2; ++k) dst[n][k] = *(const PG8_LAS bf16x8*)(lds + PG8_SB(b, h) + boff + n * 2048 + k * 1024); } while (0)
; #define PG8_MMA(ai, bj, At, Bt) do { __builtin_amdgcn_s_setprio(1); _Pragma("unroll") for (int m = 0; m < 4; ++m) _Pragma("unroll") for (int n = 0; n < 2; ++n) _Pragma("unroll") for (int k = 0; k < 2; ++k) \
;         acc[ai][bj][m][n] = __builtin_amdgcn_mfma_f32_16x16x32_bf16(Bt[n][k], At[m][k], acc[ai][bj][m][n], 0, 0, 0); __builtin_amdgcn_s_setprio(0); } while (0)
; #define PG8_WAIT_V(n) asm volatile("s_waitcnt vmcnt(" #n ")" ::: "memory")
; template <class Epi, class Sched, bool ALIGN_EPI = false, bool SP2 = false>
; __device__ __forceinline__ void gemm_phase(PG8_LAS unsigned char* lds, const Gemm g, const Sched& S, const Epi& E) {
;     ...
;             PG8_LDB(B0, 0, 0); PG8_LDB(B1, 0, 1); PG8_SCHED; PG8_LDA(At, 0, 0); PG8_STAGE(PG8_SA(1, 1), a1 + hstep, voffA);
;             PG8_WAIT_V(8); PG8_WAIT_L(0); PG8_BAR; PG8_MMA(0, 0, At, B0); PG8_MMA(0, 1, At, B1); PG8_BAR; PG8_SCHED;
;             PG8_LDA(At, 0, 1); PG8_STAGE(PG8_SB(0, 0), b2, voffB); PG8_STAGE(PG8_SB(0, 1), b2 + hstep, voffB); PG8_STAGE(PG8_SA(0, 0), a2, voffA);
;             PG8_WAIT_V(8); PG8_WAIT_L(0); PG8_BAR; PG8_MMA(1, 0, At, B0); PG8_MMA(1, 1, At, B1); PG8_BAR; PG8_SCHED;
;             PG8_LDB(B0, 1, 0); PG8_LDB(B1, 1, 1); PG8_SCHED; PG8_LDA(At, 1, 0); PG8_STAGE(PG8_SA(0, 1), a2 + hstep, voffA);
;             PG8_WAIT_V(8); PG8_WAIT_L(0); PG8_BAR; PG8_MMA(0, 0, At, B0); PG8_MMA(0, 1, At, B1); PG8_BAR; PG8_SCHED;
;             PG8_LDA(At, 1, 1); PG8_STAGE(PG8_SB(1, 0), b3, voffB); PG8_STAGE(PG8_SB(1, 1), b3 + hstep, voffB); PG8_STAGE(PG8_SA(1, 0), a3, voffA);
;             PG8_WAIT_V(8); PG8_WAIT_L(0); PG8_BAR; PG8_MMA(1, 0, At, B0); PG8_MMA(1, 1, At, B1); PG8_BAR; PG8_SCHED;
.LBB0_837:
	ds_read_b128 v[134:137], v143
	ds_read_b128 v[146:149], v143 offset:1024
	ds_read_b128 v[150:153], v143 offset:2048
	ds_read_b128 v[154:157], v143 offset:3072
	ds_read_b128 v[172:175], v144
	ds_read_b128 v[176:179], v144 offset:1024
	ds_read_b128 v[180:183], v144 offset:2048
	ds_read_b128 v[184:187], v144 offset:3072
	s_add_u32 s44, s42, 0xffea0080
	s_addc_u32 s45, s43, -1
	s_cmpk_eq_i32 s75, 0x54
	s_cselect_b32 s53, s39, s45
	s_cselect_b32 s52, s38, s44
	s_cselect_b32 s49, s41, s35
	s_cselect_b32 s48, s40, s34
	v_lshl_add_u64 v[138:139], s[42:43], 0, v[128:129]
	s_add_i32 m0, s61, 0xc000
	ds_read_b128 v[208:211], v145
	ds_read_b128 v[212:215], v145 offset:1024
	ds_read_b128 v[216:219], v145 offset:2048
	ds_read_b128 v[220:223], v145 offset:3072
	ds_read_b128 v[224:227], v145 offset:4096
	ds_read_b128 v[228:231], v145 offset:5120
	ds_read_b128 v[232:235], v145 offset:6144
	ds_read_b128 v[236:239], v145 offset:7168
	global_load_lds_dwordx4 v[138:139], off
	v_lshl_add_u64 v[138:139], s[42:43], 0, v[130:131]
	s_add_i32 m0, s61, 0xe000
	s_nop 0
	global_load_lds_dwordx4 v[138:139], off
	s_waitcnt vmcnt(8)
	s_waitcnt lgkmcnt(0)
	s_barrier
	s_setprio 1
	s_waitcnt lgkmcnt(0)
	v_mfma_f32_16x16x32_bf16 v[124:127], v[134:137], v[208:211], v[124:127]
	v_mfma_f32_16x16x32_bf16 v[124:127], v[146:149], v[212:215], v[124:127]
	v_mfma_f32_16x16x32_bf16 v[116:119], v[146:149], v[220:223], v[116:119]
	v_mfma_f32_16x16x32_bf16 v[116:119], v[134:137], v[216:219], v[116:119]
	v_mfma_f32_16x16x32_bf16 v[92:95], v[134:137], v[224:227], v[92:95]
	v_mfma_f32_16x16x32_bf16 v[92:95], v[146:149], v[228:231], v[92:95]
	v_mfma_f32_16x16x32_bf16 v[84:87], v[146:149], v[236:239], v[84:87]
	v_mfma_f32_16x16x32_bf16 v[84:87], v[134:137], v[232:235], v[84:87]
	v_mfma_f32_16x16x32_bf16 v[80:83], v[150:153], v[232:235], v[80:83]
	v_mfma_f32_16x16x32_bf16 v[80:83], v[154:157], v[236:239], v[80:83]
	v_mfma_f32_16x16x32_bf16 v[88:91], v[154:157], v[228:231], v[88:91]
	v_mfma_f32_16x16x32_bf16 v[88:91], v[150:153], v[224:227], v[88:91]
	v_mfma_f32_16x16x32_bf16 v[112:115], v[150:153], v[216:219], v[112:115]
	v_mfma_f32_16x16x32_bf16 v[112:115], v[154:157], v[220:223], v[112:115]
	v_mfma_f32_16x16x32_bf16 v[120:123], v[154:157], v[212:215], v[120:123]
	v_mfma_f32_16x16x32_bf16 v[120:123], v[150:153], v[208:211], v[120:123]
	s_setprio 0
	s_setprio 1
	v_mfma_f32_16x16x32_bf16 v[108:111], v[172:175], v[208:211], v[108:111]
	v_mfma_f32_16x16x32_bf16 v[108:111], v[176:179], v[212:215], v[108:111]
	v_mfma_f32_16x16x32_bf16 v[100:103], v[176:179], v[220:223], v[100:103]
	v_mfma_f32_16x16x32_bf16 v[100:103], v[172:175], v[216:219], v[100:103]
	v_mfma_f32_16x16x32_bf16 v[76:79], v[172:175], v[224:227], v[76:79]
	v_mfma_f32_16x16x32_bf16 v[76:79], v[176:179], v[228:231], v[76:79]
	v_mfma_f32_16x16x32_bf16 v[68:71], v[176:179], v[236:239], v[68:71]
	v_mfma_f32_16x16x32_bf16 v[68:71], v[172:175], v[232:235], v[68:71]
	v_mfma_f32_16x16x32_bf16 v[64:67], v[180:183], v[232:235], v[64:67]
	v_mfma_f32_16x16x32_bf16 v[64:67], v[184:187], v[236:239], v[64:67]
	v_mfma_f32_16x16x32_bf16 v[72:75], v[184:187], v[228:231], v[72:75]
	v_mfma_f32_16x16x32_bf16 v[72:75], v[180:183], v[224:227], v[72:75]
	v_mfma_f32_16x16x32_bf16 v[96:99], v[180:183], v[216:219], v[96:99]
	v_mfma_f32_16x16x32_bf16 v[96:99], v[184:187], v[220:223], v[96:99]
	s_setprio 2
	s_barrier
	v_mfma_f32_16x16x32_bf16 v[104:107], v[184:187], v[212:215], v[104:107]
	v_mfma_f32_16x16x32_bf16 v[104:107], v[180:183], v[208:211], v[104:107]
	s_setprio 0
	s_add_i32 s44, s68, s60
	v_lshl_add_u64 v[138:139], s[48:49], 0, v[160:161]
	s_mov_b32 m0, s44
	ds_read_b128 v[208:211], v145 offset:16384
	ds_read_b128 v[212:215], v145 offset:17408
	ds_read_b128 v[216:219], v145 offset:18432
	ds_read_b128 v[220:223], v145 offset:19456
	ds_read_b128 v[224:227], v145 offset:20480
	ds_read_b128 v[228:231], v145 offset:21504
	ds_read_b128 v[232:235], v145 offset:22528
	ds_read_b128 v[236:239], v145 offset:23552
	global_load_lds_dwordx4 v[138:139], off
	s_add_i32 m0, s44, 0x2000
	s_add_u32 s76, s48, 0x160000
	v_lshl_add_u64 v[158:159], s[48:49], 0, v[162:163]
	s_addc_u32 s77, s49, 0
	s_add_i32 s44, s69, s60
	global_load_lds_dwordx4 v[158:159], off
	v_lshl_add_u64 v[188:189], s[76:77], 0, v[160:161]
	s_mov_b32 m0, s44
	v_lshl_add_u64 v[200:201], s[52:53], 0, v[162:163]
	global_load_lds_dwordx4 v[188:189], off
	v_lshl_add_u64 v[188:189], s[76:77], 0, v[162:163]
	s_add_i32 m0, s44, 0x2000
	s_nop 0
	global_load_lds_dwordx4 v[188:189], off
	v_lshl_add_u64 v[188:189], s[52:53], 0, v[160:161]
	s_mov_b32 m0, s61
	s_nop 0
	global_load_lds_dwordx4 v[188:189], off
	s_mov_b32 m0, s62
	s_nop 0
	global_load_lds_dwordx4 v[200:201], off
	s_waitcnt vmcnt(8)
	s_waitcnt lgkmcnt(0)
	s_barrier
; #define PG8_STAGE(bufoff, gbase, voff) do { _Pragma("unroll") for (int _i = 0; _i < 2; ++_i) \
;         __builtin_amdgcn_global_load_lds((const unsigned*)((const char*)(gbase) + (voff)[_i]), (PG8_LAS unsigned*)(lds + (bufoff) + ldsw + _i * 8192), 16, 0, 0); } while (0)
; #define PG8_LDA(dst, b, h) do { _Pragma("unroll") for (int m = 0; m < 4; ++m) _Pragma("unroll") for (int k = 0; k < 2; ++k) dst[m][k] = *(const PG8_LAS bf16x8*)(lds + PG8_SA(b, h) + aoff + m * 2048 + k * 1024); } while (0)
; #define PG8_LDB(dst, b, h) do { _Pragma("unroll") for (int n = 0; n < 2; ++n) _Pragma("unroll") for (int k = 0; k < 2; ++k) dst[n][k] = *(const PG8_LAS bf16x8*)(lds + PG8_SB(b, h) + boff + n * 2048 + k * 1024); } while (0)
; #define PG8_MMA(ai, bj, At, Bt) do { __builtin_amdgcn_s_setprio(1); _Pragma("unroll") for (int m = 0; m < 4; ++m) _Pragma("unroll") for (int n = 0; n < 2; ++n) _Pragma("unroll") for (int k = 0; k < 2; ++k) \
;         acc[ai][bj][m][n] = __builtin_amdgcn_mfma_f32_16x16x32_bf16(Bt[n][k], At[m][k], acc[ai][bj][m][n], 0, 0, 0); __builtin_amdgcn_s_setprio(0); } while (0)
; #define PG8_WAIT_V(n) asm volatile("s_waitcnt vmcnt(" #n ")" ::: "memory")
; template <class Epi, class Sched, bool ALIGN_EPI = false, bool SP2 = false>
; __device__ __forceinline__ void gemm_phase(PG8_LAS unsigned char* lds, const Gemm g, const Sched& S, const Epi& E) {
;     ...
;             PG8_LDB(B0, 0, 0); PG8_LDB(B1, 0, 1); PG8_SCHED; PG8_LDA(At, 0, 0); PG8_STAGE(PG8_SA(1, 1), a1 + hstep, voffA);
;             PG8_WAIT_V(8); PG8_WAIT_L(0); PG8_BAR; PG8_MMA(0, 0, At, B0); PG8_MMA(0, 1, At, B1); PG8_BAR; PG8_SCHED;
;             PG8_LDA(At, 0, 1); PG8_STAGE(PG8_SB(0, 0), b2, voffB); PG8_STAGE(PG8_SB(0, 1), b2 + hstep, voffB); PG8_STAGE(PG8_SA(0, 0), a2, voffA);
;             PG8_WAIT_V(8); PG8_WAIT_L(0); PG8_BAR; PG8_MMA(1, 0, At, B0); PG8_MMA(1, 1, At, B1); PG8_BAR; PG8_SCHED;
;             PG8_LDB(B0, 1, 0); PG8_LDB(B1, 1, 1); PG8_SCHED; PG8_LDA(At, 1, 0); PG8_STAGE(PG8_SA(0, 1), a2 + hstep, voffA);
;             PG8_WAIT_V(8); PG8_WAIT_L(0); PG8_BAR; PG8_MMA(0, 0, At, B0); PG8_MMA(0, 1, At, B1); PG8_BAR; PG8_SCHED;
;             PG8_LDA(At, 1, 1); PG8_STAGE(PG8_SB(1, 0), b3, voffB); PG8_STAGE(PG8_SB(1, 1), b3 + hstep, voffB); PG8_STAGE(PG8_SA(1, 0), a3, voffA);
;             PG8_WAIT_V(8); PG8_WAIT_L(0); PG8_BAR; PG8_MMA(1, 0, At, B0); PG8_MMA(1, 1, At, B1); PG8_BAR; PG8_SCHED;
	s_setprio 1
	s_waitcnt lgkmcnt(0)
	v_mfma_f32_16x16x32_bf16 v[60:63], v[134:137], v[208:211], v[60:63]
	v_mfma_f32_16x16x32_bf16 v[60:63], v[146:149], v[212:215], v[60:63]
	v_mfma_f32_16x16x32_bf16 v[52:55], v[146:149], v[220:223], v[52:55]
	v_mfma_f32_16x16x32_bf16 v[52:55], v[134:137], v[216:219], v[52:55]
	v_mfma_f32_16x16x32_bf16 v[28:31], v[134:137], v[224:227], v[28:31]
	v_mfma_f32_16x16x32_bf16 v[28:31], v[146:149], v[228:231], v[28:31]
	v_mfma_f32_16x16x32_bf16 v[20:23], v[146:149], v[236:239], v[20:23]
	v_mfma_f32_16x16x32_bf16 v[20:23], v[134:137], v[232:235], v[20:23]
	v_mfma_f32_16x16x32_bf16 v[16:19], v[150:153], v[232:235], v[16:19]
	v_mfma_f32_16x16x32_bf16 v[16:19], v[154:157], v[236:239], v[16:19]
	v_mfma_f32_16x16x32_bf16 v[24:27], v[154:157], v[228:231], v[24:27]
	v_mfma_f32_16x16x32_bf16 v[24:27], v[150:153], v[224:227], v[24:27]
	v_mfma_f32_16x16x32_bf16 v[48:51], v[150:153], v[216:219], v[48:51]
	v_mfma_f32_16x16x32_bf16 v[48:51], v[154:157], v[220:223], v[48:51]
	v_mfma_f32_16x16x32_bf16 v[56:59], v[154:157], v[212:215], v[56:59]
	v_mfma_f32_16x16x32_bf16 v[56:59], v[150:153], v[208:211], v[56:59]
	s_setprio 0
	s_setprio 1
	v_mfma_f32_16x16x32_bf16 v[44:47], v[172:175], v[208:211], v[44:47]
	v_mfma_f32_16x16x32_bf16 v[44:47], v[176:179], v[212:215], v[44:47]
	v_mfma_f32_16x16x32_bf16 v[36:39], v[176:179], v[220:223], v[36:39]
	v_mfma_f32_16x16x32_bf16 v[36:39], v[172:175], v[216:219], v[36:39]
	v_mfma_f32_16x16x32_bf16 v[12:15], v[172:175], v[224:227], v[12:15]
	v_mfma_f32_16x16x32_bf16 v[12:15], v[176:179], v[228:231], v[12:15]
	v_mfma_f32_16x16x32_bf16 v[4:7], v[176:179], v[236:239], v[4:7]
	v_mfma_f32_16x16x32_bf16 v[4:7], v[172:175], v[232:235], v[4:7]
	v_mfma_f32_16x16x32_bf16 v[0:3], v[180:183], v[232:235], v[0:3]
	v_mfma_f32_16x16x32_bf16 v[0:3], v[184:187], v[236:239], v[0:3]
	v_mfma_f32_16x16x32_bf16 v[8:11], v[184:187], v[228:231], v[8:11]
	v_mfma_f32_16x16x32_bf16 v[8:11], v[180:183], v[224:227], v[8:11]
	v_mfma_f32_16x16x32_bf16 v[32:35], v[180:183], v[216:219], v[32:35]
	v_mfma_f32_16x16x32_bf16 v[32:35], v[184:187], v[220:223], v[32:35]
	s_setprio 2
	s_barrier
	v_mfma_f32_16x16x32_bf16 v[40:43], v[184:187], v[212:215], v[40:43]
	v_mfma_f32_16x16x32_bf16 v[40:43], v[180:183], v[208:211], v[40:43]
	s_setprio 0
	s_add_i32 s44, 0, 0x18000
	s_add_i32 s45, 0, 0x1c000
	v_add_u32_e32 v154, s44, v141
	v_add_u32_e32 v165, s45, v141
	ds_read_b128 v[134:137], v154
	ds_read_b128 v[146:149], v154 offset:1024
	ds_read_b128 v[150:153], v154 offset:2048
	ds_read_b128 v[154:157], v154 offset:3072
	ds_read_b128 v[172:175], v165
	ds_read_b128 v[176:179], v165 offset:1024
	ds_read_b128 v[180:183], v165 offset:2048
	ds_read_b128 v[184:187], v165 offset:3072
	s_add_u32 s52, s52, 0x160000
	s_addc_u32 s53, s53, 0
	s_mov_b32 m0, s63
	v_lshl_add_u64 v[240:241], s[52:53], 0, v[160:161]
	ds_read_b128 v[208:211], v145 offset:32768
	ds_read_b128 v[212:215], v145 offset:33792
	ds_read_b128 v[216:219], v145 offset:34816
	ds_read_b128 v[220:223], v145 offset:35840
	ds_read_b128 v[224:227], v145 offset:36864
	ds_read_b128 v[228:231], v145 offset:37888
	ds_read_b128 v[232:235], v145 offset:38912
	ds_read_b128 v[236:239], v145 offset:39936
	global_load_lds_dwordx4 v[240:241], off
	v_lshl_add_u64 v[240:241], s[52:53], 0, v[162:163]
	s_mov_b32 m0, s64
	s_nop 0
	global_load_lds_dwordx4 v[240:241], off
	s_waitcnt vmcnt(8)
	s_waitcnt lgkmcnt(0)
	s_barrier
	s_setprio 1
	s_waitcnt lgkmcnt(0)
	v_mfma_f32_16x16x32_bf16 v[124:127], v[134:137], v[208:211], v[124:127]
	v_mfma_f32_16x16x32_bf16 v[124:127], v[146:149], v[212:215], v[124:127]
	v_mfma_f32_16x16x32_bf16 v[116:119], v[146:149], v[220:223], v[116:119]
	v_mfma_f32_16x16x32_bf16 v[116:119], v[134:137], v[216:219], v[116:119]
	v_mfma_f32_16x16x32_bf16 v[92:95], v[134:137], v[224:227], v[92:95]
	v_mfma_f32_16x16x32_bf16 v[92:95], v[146:149], v[228:231], v[92:95]
	v_mfma_f32_16x16x32_bf16 v[84:87], v[146:149], v[236:239], v[84:87]
	v_mfma_f32_16x16x32_bf16 v[84:87], v[134:137], v[232:235], v[84:87]
	v_mfma_f32_16x16x32_bf16 v[80:83], v[150:153], v[232:235], v[80:83]
	v_mfma_f32_16x16x32_bf16 v[80:83], v[154:157], v[236:239], v[80:83]
	v_mfma_f32_16x16x32_bf16 v[88:91], v[154:157], v[228:231], v[88:91]
	v_mfma_f32_16x16x32_bf16 v[88:91], v[150:153], v[224:227], v[88:91]
	v_mfma_f32_16x16x32_bf16 v[112:115], v[150:153], v[216:219], v[112:115]
	v_mfma_f32_16x16x32_bf16 v[112:115], v[154:157], v[220:223], v[112:115]
	v_mfma_f32_16x16x32_bf16 v[120:123], v[154:157], v[212:215], v[120:123]
	v_mfma_f32_16x16x32_bf16 v[120:123], v[150:153], v[208:211], v[120:123]
	s_setprio 0
	s_setprio 1
	v_mfma_f32_16x16x32_bf16 v[108:111], v[172:175], v[208:211], v[108:111]
	v_mfma_f32_16x16x32_bf16 v[108:111], v[176:179], v[212:215], v[108:111]
	v_mfma_f32_16x16x32_bf16 v[100:103], v[176:179], v[220:223], v[100:103]
	v_mfma_f32_16x16x32_bf16 v[100:103], v[172:175], v[216:219], v[100:103]
	v_mfma_f32_16x16x32_bf16 v[76:79], v[172:175], v[224:227], v[76:79]
	v_mfma_f32_16x16x32_bf16 v[76:79], v[176:179], v[228:231], v[76:79]
	v_mfma_f32_16x16x32_bf16 v[68:71], v[176:179], v[236:239], v[68:71]
	v_mfma_f32_16x16x32_bf16 v[68:71], v[172:175], v[232:235], v[68:71]
	v_mfma_f32_16x16x32_bf16 v[64:67], v[180:183], v[232:235], v[64:67]
	v_mfma_f32_16x16x32_bf16 v[64:67], v[184:187], v[236:239], v[64:67]
	v_mfma_f32_16x16x32_bf16 v[72:75], v[184:187], v[228:231], v[72:75]
	v_mfma_f32_16x16x32_bf16 v[72:75], v[180:183], v[224:227], v[72:75]
	v_mfma_f32_16x16x32_bf16 v[96:99], v[180:183], v[216:219], v[96:99]
	v_mfma_f32_16x16x32_bf16 v[96:99], v[184:187], v[220:223], v[96:99]
	s_setprio 2
	s_barrier
; #define PG8_STAGE(bufoff, gbase, voff) do { _Pragma("unroll") for (int _i = 0; _i < 2; ++_i) \
;         __builtin_amdgcn_global_load_lds((const unsigned*)((const char*)(gbase) + (voff)[_i]), (PG8_LAS unsigned*)(lds + (bufoff) + ldsw + _i * 8192), 16, 0, 0); } while (0)
; #define PG8_LDA(dst, b, h) do { _Pragma("unroll") for (int m = 0; m < 4; ++m) _Pragma("unroll") for (int k = 0; k < 2; ++k) dst[m][k] = *(const PG8_LAS bf16x8*)(lds + PG8_SA(b, h) + aoff + m * 2048 + k * 1024); } while (0)
; #define PG8_LDB(dst, b, h) do { _Pragma("unroll") for (int n = 0; n < 2; ++n) _Pragma("unroll") for (int k = 0; k < 2; ++k) dst[n][k] = *(const PG8_LAS bf16x8*)(lds + PG8_SB(b, h) + boff + n * 2048 + k * 1024); } while (0)
; #define PG8_MMA(ai, bj, At, Bt) do { __builtin_amdgcn_s_setprio(1); _Pragma("unroll") for (int m = 0; m < 4; ++m) _Pragma("unroll") for (int n = 0; n < 2; ++n) _Pragma("unroll") for (int k = 0; k < 2; ++k) \
;         acc[ai][bj][m][n] = __builtin_amdgcn_mfma_f32_16x16x32_bf16(Bt[n][k], At[m][k], acc[ai][bj][m][n], 0, 0, 0); __builtin_amdgcn_s_setprio(0); } while (0)
; #define PG8_WAIT_V(n) asm volatile("s_waitcnt vmcnt(" #n ")" ::: "memory")
; template <class Epi, class Sched, bool ALIGN_EPI = false, bool SP2 = false>
; __device__ __forceinline__ void gemm_phase(PG8_LAS unsigned char* lds, const Gemm g, const Sched& S, const Epi& E) {
;     ...
;             PG8_LDB(B0, 0, 0); PG8_LDB(B1, 0, 1); PG8_SCHED; PG8_LDA(At, 0, 0); PG8_STAGE(PG8_SA(1, 1), a1 + hstep, voffA);
;             PG8_WAIT_V(8); PG8_WAIT_L(0); PG8_BAR; PG8_MMA(0, 0, At, B0); PG8_MMA(0, 1, At, B1); PG8_BAR; PG8_SCHED;
;             PG8_LDA(At, 0, 1); PG8_STAGE(PG8_SB(0, 0), b2, voffB); PG8_STAGE(PG8_SB(0, 1), b2 + hstep, voffB); PG8_STAGE(PG8_SA(0, 0), a2, voffA);
;             PG8_WAIT_V(8); PG8_WAIT_L(0); PG8_BAR; PG8_MMA(1, 0, At, B0); PG8_MMA(1, 1, At, B1); PG8_BAR; PG8_SCHED;
;             PG8_LDB(B0, 1, 0); PG8_LDB(B1, 1, 1); PG8_SCHED; PG8_LDA(At, 1, 0); PG8_STAGE(PG8_SA(0, 1), a2 + hstep, voffA);
;             PG8_WAIT_V(8); PG8_WAIT_L(0); PG8_BAR; PG8_MMA(0, 0, At, B0); PG8_MMA(0, 1, At, B1); PG8_BAR; PG8_SCHED;
;             PG8_LDA(At, 1, 1); PG8_STAGE(PG8_SB(1, 0), b3, voffB); PG8_STAGE(PG8_SB(1, 1), b3 + hstep, voffB); PG8_STAGE(PG8_SA(1, 0), a3, voffA);
;             PG8_WAIT_V(8); PG8_WAIT_L(0); PG8_BAR; PG8_MMA(1, 0, At, B0); PG8_MMA(1, 1, At, B1); PG8_BAR; PG8_SCHED;
	v_mfma_f32_16x16x32_bf16 v[104:107], v[184:187], v[212:215], v[104:107]
	v_mfma_f32_16x16x32_bf16 v[104:107], v[180:183], v[208:211], v[104:107]
	s_setprio 0
	s_add_i32 s44, s44, s60
	v_lshl_add_u64 v[138:139], v[138:139], 0, s[16:17]
	s_mov_b32 m0, s44
	ds_read_b128 v[208:211], v145 offset:49152
	ds_read_b128 v[212:215], v145 offset:50176
	ds_read_b128 v[216:219], v145 offset:51200
	ds_read_b128 v[220:223], v145 offset:52224
	ds_read_b128 v[224:227], v145 offset:53248
	ds_read_b128 v[228:231], v145 offset:54272
	ds_read_b128 v[232:235], v145 offset:55296
	ds_read_b128 v[236:239], v145 offset:56320
	global_load_lds_dwordx4 v[138:139], off
	s_add_i32 m0, s44, 0x2000
	s_add_u32 s48, s48, 0x160080
	v_lshl_add_u64 v[138:139], v[158:159], 0, s[16:17]
	s_addc_u32 s49, s49, 0
	s_add_i32 s44, s45, s60
	global_load_lds_dwordx4 v[138:139], off
	v_lshl_add_u64 v[138:139], s[48:49], 0, v[160:161]
	s_mov_b32 m0, s44
	s_nop 0
	global_load_lds_dwordx4 v[138:139], off
	v_lshl_add_u64 v[138:139], s[48:49], 0, v[162:163]
	s_add_i32 m0, s44, 0x2000
	s_nop 0
	global_load_lds_dwordx4 v[138:139], off
	v_lshl_add_u64 v[138:139], v[188:189], 0, s[16:17]
	s_mov_b32 m0, s65
	s_nop 0
	global_load_lds_dwordx4 v[138:139], off
	v_lshl_add_u64 v[138:139], v[200:201], 0, s[16:17]
	s_mov_b32 m0, s66
	s_nop 0
	global_load_lds_dwordx4 v[138:139], off
	s_waitcnt vmcnt(8)
	s_waitcnt lgkmcnt(0)
	s_barrier
	s_setprio 1
	s_waitcnt lgkmcnt(0)
	v_mfma_f32_16x16x32_bf16 v[60:63], v[134:137], v[208:211], v[60:63]
	v_mfma_f32_16x16x32_bf16 v[60:63], v[146:149], v[212:215], v[60:63]
	v_mfma_f32_16x16x32_bf16 v[52:55], v[146:149], v[220:223], v[52:55]
	v_mfma_f32_16x16x32_bf16 v[52:55], v[134:137], v[216:219], v[52:55]
	v_mfma_f32_16x16x32_bf16 v[28:31], v[134:137], v[224:227], v[28:31]
	v_mfma_f32_16x16x32_bf16 v[28:31], v[146:149], v[228:231], v[28:31]
	v_mfma_f32_16x16x32_bf16 v[20:23], v[146:149], v[236:239], v[20:23]
	v_mfma_f32_16x16x32_bf16 v[20:23], v[134:137], v[232:235], v[20:23]
	v_mfma_f32_16x16x32_bf16 v[16:19], v[150:153], v[232:235], v[16:19]
	v_mfma_f32_16x16x32_bf16 v[16:19], v[154:157], v[236:239], v[16:19]
	v_mfma_f32_16x16x32_bf16 v[24:27], v[154:157], v[228:231], v[24:27]
	v_mfma_f32_16x16x32_bf16 v[24:27], v[150:153], v[224:227], v[24:27]
	v_mfma_f32_16x16x32_bf16 v[48:51], v[150:153], v[216:219], v[48:51]
	v_mfma_f32_16x16x32_bf16 v[48:51], v[154:157], v[220:223], v[48:51]
	v_mfma_f32_16x16x32_bf16 v[56:59], v[154:157], v[212:215], v[56:59]
	v_mfma_f32_16x16x32_bf16 v[56:59], v[150:153], v[208:211], v[56:59]
	s_setprio 0
	s_setprio 1
	v_mfma_f32_16x16x32_bf16 v[44:47], v[172:175], v[208:211], v[44:47]
	v_mfma_f32_16x16x32_bf16 v[44:47], v[176:179], v[212:215], v[44:47]
	v_mfma_f32_16x16x32_bf16 v[36:39], v[176:179], v[220:223], v[36:39]
	v_mfma_f32_16x16x32_bf16 v[36:39], v[172:175], v[216:219], v[36:39]
	v_mfma_f32_16x16x32_bf16 v[12:15], v[172:175], v[224:227], v[12:15]
	v_mfma_f32_16x16x32_bf16 v[12:15], v[176:179], v[228:231], v[12:15]
	v_mfma_f32_16x16x32_bf16 v[4:7], v[176:179], v[236:239], v[4:7]
	v_mfma_f32_16x16x32_bf16 v[4:7], v[172:175], v[232:235], v[4:7]
	v_mfma_f32_16x16x32_bf16 v[0:3], v[180:183], v[232:235], v[0:3]
	v_mfma_f32_16x16x32_bf16 v[0:3], v[184:187], v[236:239], v[0:3]
	v_mfma_f32_16x16x32_bf16 v[8:11], v[184:187], v[228:231], v[8:11]
	v_mfma_f32_16x16x32_bf16 v[8:11], v[180:183], v[224:227], v[8:11]
	v_mfma_f32_16x16x32_bf16 v[32:35], v[180:183], v[216:219], v[32:35]
	v_mfma_f32_16x16x32_bf16 v[32:35], v[184:187], v[220:223], v[32:35]
	s_setprio 2
	s_barrier
	v_mfma_f32_16x16x32_bf16 v[40:43], v[184:187], v[212:215], v[40:43]
	v_mfma_f32_16x16x32_bf16 v[40:43], v[180:183], v[208:211], v[40:43]
	s_setprio 0
	s_add_i32 s75, s75, 2
	s_add_u32 s42, s42, 0x100
	s_addc_u32 s43, s43, 0
	s_add_u32 s34, s34, 0x100
	s_addc_u32 s35, s35, 0
	s_cmpk_gt_u32 s75, 0x55
	s_cbranch_scc0 .LBB0_837
	s_and_b64 vcc, exec, s[18:19]
	s_cbranch_vccz .LBB0_840
	s_barrier

; #define PG8_STAGE(bufoff, gbase, voff) do { _Pragma("unroll") for (int _i = 0; _i < 2; ++_i) \
;         __builtin_amdgcn_global_load_lds((const unsigned*)((const char*)(gbase) + (voff)[_i]), (PG8_LAS unsigned*)(lds + (bufoff) + ldsw + _i * 8192), 16, 0, 0); } while (0)
; #define PG8_LDA(dst, b, h) do { _Pragma("unroll") for (int m = 0; m < 4; ++m) _Pragma("unroll") for (int k = 0; k < 2; ++k) dst[m][k] = *(const PG8_LAS bf16x8*)(lds + PG8_SA(b, h) + aoff + m * 2048 + k * 1024); } while (0)
; #define PG8_LDB(dst, b, h) do { _Pragma("unroll") for (int n = 0; n < 2; ++n) _Pragma("unroll") for (int k = 0; k < 2; ++k) dst[n][k] = *(const PG8_LAS bf16x8*)(lds + PG8_SB(b, h) + boff + n * 2048 + k * 1024); } while (0)
; #define PG8_MMA(ai, bj, At, Bt) do { __builtin_amdgcn_s_setprio(1); _Pragma("unroll") for (int m = 0; m < 4; ++m) _Pragma("unroll") for (int n = 0; n < 2; ++n) _Pragma("unroll") for (int k = 0; k < 2; ++k) \
;         acc[ai][bj][m][n] = __builtin_amdgcn_mfma_f32_16x16x32_bf16(Bt[n][k], At[m][k], acc[ai][bj][m][n], 0, 0, 0); __builtin_amdgcn_s_setprio(0); } while (0)
; #define PG8_WAIT_V(n) asm volatile("s_waitcnt vmcnt(" #n ")" ::: "memory")
; template <class Epi, class Sched, bool ALIGN_EPI = false, bool SP2 = false>
; __device__ __forceinline__ void gemm_phase(PG8_LAS unsigned char* lds, const Gemm g, const Sched& S, const Epi& E) {
;     ...
;             PG8_LDB(B0, 0, 0); PG8_LDB(B1, 0, 1); PG8_SCHED; PG8_LDA(At, 0, 0); PG8_STAGE(PG8_SA(1, 1), a1 + hstep, voffA);
;             PG8_WAIT_V(8); PG8_WAIT_L(0); PG8_BAR; PG8_MMA(0, 0, At, B0); PG8_MMA(0, 1, At, B1); PG8_BAR; PG8_SCHED;
;             PG8_LDA(At, 0, 1); PG8_STAGE(PG8_SB(0, 0), b2, voffB); PG8_STAGE(PG8_SB(0, 1), b2 + hstep, voffB); PG8_STAGE(PG8_SA(0, 0), a2, voffA);
;             PG8_WAIT_V(8); PG8_WAIT_L(0); PG8_BAR; PG8_MMA(1, 0, At, B0); PG8_MMA(1, 1, At, B1); PG8_BAR; PG8_SCHED;
;             PG8_LDB(B0, 1, 0); PG8_LDB(B1, 1, 1); PG8_SCHED; PG8_LDA(At, 1, 0); PG8_STAGE(PG8_SA(0, 1), a2 + hstep, voffA);
;             PG8_WAIT_V(8); PG8_WAIT_L(0); PG8_BAR; PG8_MMA(0, 0, At, B0); PG8_MMA(0, 1, At, B1); PG8_BAR; PG8_SCHED;
;             PG8_LDA(At, 1, 1); PG8_STAGE(PG8_SB(1, 0), b3, voffB); PG8_STAGE(PG8_SB(1, 1), b3 + hstep, voffB); PG8_STAGE(PG8_SA(1, 0), a3, voffA);
;             PG8_WAIT_V(8); PG8_WAIT_L(0); PG8_BAR; PG8_MMA(1, 0, At, B0); PG8_MMA(1, 1, At, B1); PG8_BAR; PG8_SCHED;
.LBB0_880:
	ds_read_b128 v[136:139], v156
	ds_read_b128 v[140:143], v156 offset:1024
	ds_read_b128 v[172:175], v156 offset:2048
	ds_read_b128 v[176:179], v156 offset:3072
	ds_read_b128 v[180:183], v157
	ds_read_b128 v[184:187], v157 offset:1024
	ds_read_b128 v[196:199], v157 offset:2048
	ds_read_b128 v[208:211], v157 offset:3072
	s_add_u32 s40, s38, 0xfff80080
	s_addc_u32 s41, s39, -1
	s_cmp_eq_u32 s63, 28
	s_cselect_b32 s43, s19, s41
	s_cselect_b32 s42, s34, s40
	s_cselect_b32 s41, s21, s62
	s_cselect_b32 s40, s35, s61
	v_lshl_add_u64 v[188:189], s[38:39], 0, v[128:129]
	s_add_i32 m0, s7, 0xc000
	ds_read_b128 v[212:215], v158
	ds_read_b128 v[216:219], v158 offset:1024
	ds_read_b128 v[220:223], v158 offset:2048
	ds_read_b128 v[224:227], v158 offset:3072
	ds_read_b128 v[228:231], v158 offset:4096
	ds_read_b128 v[232:235], v158 offset:5120
	ds_read_b128 v[236:239], v158 offset:6144
	ds_read_b128 v[240:243], v158 offset:7168
	global_load_lds_dwordx4 v[188:189], off
	v_lshl_add_u64 v[188:189], s[38:39], 0, v[130:131]
	s_add_i32 m0, s7, 0xe000
	s_nop 0
	global_load_lds_dwordx4 v[188:189], off
	s_waitcnt vmcnt(8)
	s_waitcnt lgkmcnt(0)
	s_barrier
	s_setprio 1
	s_waitcnt lgkmcnt(0)
	v_mfma_f32_16x16x32_bf16 v[124:127], v[136:139], v[212:215], v[124:127]
	v_mfma_f32_16x16x32_bf16 v[124:127], v[140:143], v[216:219], v[124:127]
	v_mfma_f32_16x16x32_bf16 v[108:111], v[140:143], v[224:227], v[108:111]
	v_mfma_f32_16x16x32_bf16 v[108:111], v[136:139], v[220:223], v[108:111]
	v_mfma_f32_16x16x32_bf16 v[96:99], v[136:139], v[228:231], v[96:99]
	v_mfma_f32_16x16x32_bf16 v[96:99], v[140:143], v[232:235], v[96:99]
	v_mfma_f32_16x16x32_bf16 v[80:83], v[140:143], v[240:243], v[80:83]
	v_mfma_f32_16x16x32_bf16 v[80:83], v[136:139], v[236:239], v[80:83]
	v_mfma_f32_16x16x32_bf16 v[72:75], v[172:175], v[236:239], v[72:75]
	v_mfma_f32_16x16x32_bf16 v[72:75], v[176:179], v[240:243], v[72:75]
	v_mfma_f32_16x16x32_bf16 v[88:91], v[176:179], v[232:235], v[88:91]
	v_mfma_f32_16x16x32_bf16 v[88:91], v[172:175], v[228:231], v[88:91]
	v_mfma_f32_16x16x32_bf16 v[104:107], v[172:175], v[220:223], v[104:107]
	v_mfma_f32_16x16x32_bf16 v[104:107], v[176:179], v[224:227], v[104:107]
	v_mfma_f32_16x16x32_bf16 v[120:123], v[176:179], v[216:219], v[120:123]
	v_mfma_f32_16x16x32_bf16 v[120:123], v[172:175], v[212:215], v[120:123]
	s_setprio 0
	s_setprio 1
	v_mfma_f32_16x16x32_bf16 v[116:119], v[180:183], v[212:215], v[116:119]
	v_mfma_f32_16x16x32_bf16 v[116:119], v[184:187], v[216:219], v[116:119]
	v_mfma_f32_16x16x32_bf16 v[100:103], v[184:187], v[224:227], v[100:103]
	v_mfma_f32_16x16x32_bf16 v[100:103], v[180:183], v[220:223], v[100:103]
	v_mfma_f32_16x16x32_bf16 v[84:87], v[180:183], v[228:231], v[84:87]
	v_mfma_f32_16x16x32_bf16 v[84:87], v[184:187], v[232:235], v[84:87]
	v_mfma_f32_16x16x32_bf16 v[68:71], v[184:187], v[240:243], v[68:71]
	v_mfma_f32_16x16x32_bf16 v[68:71], v[180:183], v[236:239], v[68:71]
	v_mfma_f32_16x16x32_bf16 v[64:67], v[196:199], v[236:239], v[64:67]
	v_mfma_f32_16x16x32_bf16 v[64:67], v[208:211], v[240:243], v[64:67]
	v_mfma_f32_16x16x32_bf16 v[76:79], v[208:211], v[232:235], v[76:79]
	v_mfma_f32_16x16x32_bf16 v[76:79], v[196:199], v[228:231], v[76:79]
	v_mfma_f32_16x16x32_bf16 v[92:95], v[196:199], v[220:223], v[92:95]
	v_mfma_f32_16x16x32_bf16 v[92:95], v[208:211], v[224:227], v[92:95]
	s_setprio 2
	s_barrier
	v_mfma_f32_16x16x32_bf16 v[112:115], v[208:211], v[216:219], v[112:115]
	v_mfma_f32_16x16x32_bf16 v[112:115], v[196:199], v[212:215], v[112:115]
	s_setprio 0
	s_add_i32 s44, s52, s33
	v_lshl_add_u64 v[188:189], s[40:41], 0, v[166:167]
	s_mov_b32 m0, s44
	ds_read_b128 v[212:215], v158 offset:16384
	ds_read_b128 v[216:219], v158 offset:17408
	ds_read_b128 v[220:223], v158 offset:18432
	ds_read_b128 v[224:227], v158 offset:19456
	ds_read_b128 v[228:231], v158 offset:20480
	ds_read_b128 v[232:235], v158 offset:21504
	ds_read_b128 v[236:239], v158 offset:22528
	ds_read_b128 v[240:243], v158 offset:23552
	global_load_lds_dwordx4 v[188:189], off
	s_add_i32 m0, s44, 0x2000
	s_add_u32 s64, s40, 0x80000
	v_lshl_add_u64 v[200:201], s[40:41], 0, v[170:171]
	s_addc_u32 s65, s41, 0
	s_add_i32 s44, s53, s33
	global_load_lds_dwordx4 v[200:201], off
	v_lshl_add_u64 v[244:245], s[64:65], 0, v[166:167]
	s_mov_b32 m0, s44
	v_lshl_add_u64 v[246:247], s[42:43], 0, v[168:169]
	global_load_lds_dwordx4 v[244:245], off
	v_lshl_add_u64 v[244:245], s[64:65], 0, v[170:171]
	s_add_i32 m0, s44, 0x2000
	s_nop 0
	global_load_lds_dwordx4 v[244:245], off
	v_lshl_add_u64 v[244:245], s[42:43], 0, v[164:165]
	s_mov_b32 m0, s7
	s_nop 0
	global_load_lds_dwordx4 v[244:245], off
	s_mov_b32 m0, s37
	s_nop 0
	global_load_lds_dwordx4 v[246:247], off
	s_waitcnt vmcnt(8)
	s_waitcnt lgkmcnt(0)
	s_barrier
; #define PG8_STAGE(bufoff, gbase, voff) do { _Pragma("unroll") for (int _i = 0; _i < 2; ++_i) \
;         __builtin_amdgcn_global_load_lds((const unsigned*)((const char*)(gbase) + (voff)[_i]), (PG8_LAS unsigned*)(lds + (bufoff) + ldsw + _i * 8192), 16, 0, 0); } while (0)
; #define PG8_LDA(dst, b, h) do { _Pragma("unroll") for (int m = 0; m < 4; ++m) _Pragma("unroll") for (int k = 0; k < 2; ++k) dst[m][k] = *(const PG8_LAS bf16x8*)(lds + PG8_SA(b, h) + aoff + m * 2048 + k * 1024); } while (0)
; #define PG8_LDB(dst, b, h) do { _Pragma("unroll") for (int n = 0; n < 2; ++n) _Pragma("unroll") for (int k = 0; k < 2; ++k) dst[n][k] = *(const PG8_LAS bf16x8*)(lds + PG8_SB(b, h) + boff + n * 2048 + k * 1024); } while (0)
; #define PG8_MMA(ai, bj, At, Bt) do { __builtin_amdgcn_s_setprio(1); _Pragma("unroll") for (int m = 0; m < 4; ++m) _Pragma("unroll") for (int n = 0; n < 2; ++n) _Pragma("unroll") for (int k = 0; k < 2; ++k) \
;         acc[ai][bj][m][n] = __builtin_amdgcn_mfma_f32_16x16x32_bf16(Bt[n][k], At[m][k], acc[ai][bj][m][n], 0, 0, 0); __builtin_amdgcn_s_setprio(0); } while (0)
; #define PG8_WAIT_V(n) asm volatile("s_waitcnt vmcnt(" #n ")" ::: "memory")
; template <class Epi, class Sched, bool ALIGN_EPI = false, bool SP2 = false>
; __device__ __forceinline__ void gemm_phase(PG8_LAS unsigned char* lds, const Gemm g, const Sched& S, const Epi& E) {
;     ...
;             PG8_LDB(B0, 0, 0); PG8_LDB(B1, 0, 1); PG8_SCHED; PG8_LDA(At, 0, 0); PG8_STAGE(PG8_SA(1, 1), a1 + hstep, voffA);
;             PG8_WAIT_V(8); PG8_WAIT_L(0); PG8_BAR; PG8_MMA(0, 0, At, B0); PG8_MMA(0, 1, At, B1); PG8_BAR; PG8_SCHED;
;             PG8_LDA(At, 0, 1); PG8_STAGE(PG8_SB(0, 0), b2, voffB); PG8_STAGE(PG8_SB(0, 1), b2 + hstep, voffB); PG8_STAGE(PG8_SA(0, 0), a2, voffA);
;             PG8_WAIT_V(8); PG8_WAIT_L(0); PG8_BAR; PG8_MMA(1, 0, At, B0); PG8_MMA(1, 1, At, B1); PG8_BAR; PG8_SCHED;
;             PG8_LDB(B0, 1, 0); PG8_LDB(B1, 1, 1); PG8_SCHED; PG8_LDA(At, 1, 0); PG8_STAGE(PG8_SA(0, 1), a2 + hstep, voffA);
;             PG8_WAIT_V(8); PG8_WAIT_L(0); PG8_BAR; PG8_MMA(0, 0, At, B0); PG8_MMA(0, 1, At, B1); PG8_BAR; PG8_SCHED;
;             PG8_LDA(At, 1, 1); PG8_STAGE(PG8_SB(1, 0), b3, voffB); PG8_STAGE(PG8_SB(1, 1), b3 + hstep, voffB); PG8_STAGE(PG8_SA(1, 0), a3, voffA);
;             PG8_WAIT_V(8); PG8_WAIT_L(0); PG8_BAR; PG8_MMA(1, 0, At, B0); PG8_MMA(1, 1, At, B1); PG8_BAR; PG8_SCHED;
	s_setprio 1
	s_waitcnt lgkmcnt(0)
	v_mfma_f32_16x16x32_bf16 v[60:63], v[136:139], v[212:215], v[60:63]
	v_mfma_f32_16x16x32_bf16 v[60:63], v[140:143], v[216:219], v[60:63]
	v_mfma_f32_16x16x32_bf16 v[48:51], v[140:143], v[224:227], v[48:51]
	v_mfma_f32_16x16x32_bf16 v[48:51], v[136:139], v[220:223], v[48:51]
	v_mfma_f32_16x16x32_bf16 v[32:35], v[136:139], v[228:231], v[32:35]
	v_mfma_f32_16x16x32_bf16 v[32:35], v[140:143], v[232:235], v[32:35]
	v_mfma_f32_16x16x32_bf16 v[12:15], v[140:143], v[240:243], v[12:15]
	v_mfma_f32_16x16x32_bf16 v[12:15], v[136:139], v[236:239], v[12:15]
	v_mfma_f32_16x16x32_bf16 v[8:11], v[172:175], v[236:239], v[8:11]
	v_mfma_f32_16x16x32_bf16 v[8:11], v[176:179], v[240:243], v[8:11]
	v_mfma_f32_16x16x32_bf16 v[24:27], v[176:179], v[232:235], v[24:27]
	v_mfma_f32_16x16x32_bf16 v[24:27], v[172:175], v[228:231], v[24:27]
	v_mfma_f32_16x16x32_bf16 v[40:43], v[172:175], v[220:223], v[40:43]
	v_mfma_f32_16x16x32_bf16 v[40:43], v[176:179], v[224:227], v[40:43]
	v_mfma_f32_16x16x32_bf16 v[56:59], v[176:179], v[216:219], v[56:59]
	v_mfma_f32_16x16x32_bf16 v[56:59], v[172:175], v[212:215], v[56:59]
	s_setprio 0
	s_setprio 1
	v_mfma_f32_16x16x32_bf16 v[52:55], v[180:183], v[212:215], v[52:55]
	v_mfma_f32_16x16x32_bf16 v[52:55], v[184:187], v[216:219], v[52:55]
	v_mfma_f32_16x16x32_bf16 v[36:39], v[184:187], v[224:227], v[36:39]
	v_mfma_f32_16x16x32_bf16 v[36:39], v[180:183], v[220:223], v[36:39]
	v_mfma_f32_16x16x32_bf16 v[20:23], v[180:183], v[228:231], v[20:23]
	v_mfma_f32_16x16x32_bf16 v[20:23], v[184:187], v[232:235], v[20:23]
	v_mfma_f32_16x16x32_bf16 v[4:7], v[184:187], v[240:243], v[4:7]
	v_mfma_f32_16x16x32_bf16 v[4:7], v[180:183], v[236:239], v[4:7]
	v_mfma_f32_16x16x32_bf16 v[0:3], v[196:199], v[236:239], v[0:3]
	v_mfma_f32_16x16x32_bf16 v[0:3], v[208:211], v[240:243], v[0:3]
	v_mfma_f32_16x16x32_bf16 v[16:19], v[208:211], v[232:235], v[16:19]
	v_mfma_f32_16x16x32_bf16 v[16:19], v[196:199], v[228:231], v[16:19]
	v_mfma_f32_16x16x32_bf16 v[28:31], v[196:199], v[220:223], v[28:31]
	v_mfma_f32_16x16x32_bf16 v[28:31], v[208:211], v[224:227], v[28:31]
	s_setprio 2
	s_barrier
	v_mfma_f32_16x16x32_bf16 v[44:47], v[208:211], v[216:219], v[44:47]
	v_mfma_f32_16x16x32_bf16 v[44:47], v[196:199], v[212:215], v[44:47]
	s_setprio 0
	s_add_i32 s44, 0, 0x18000
	v_add_u32_e32 v144, s44, v146
	s_add_i32 s45, 0, 0x1c000
	ds_read_b128 v[136:139], v144
	ds_read_b128 v[140:143], v144 offset:1024
	ds_read_b128 v[172:175], v144 offset:2048
	ds_read_b128 v[176:179], v144 offset:3072
	v_add_u32_e32 v144, s45, v146
	ds_read_b128 v[180:183], v144
	ds_read_b128 v[184:187], v144 offset:1024
	ds_read_b128 v[196:199], v144 offset:2048
	ds_read_b128 v[208:211], v144 offset:3072
	s_add_u32 s42, s42, 0x80000
	s_addc_u32 s43, s43, 0
	s_mov_b32 m0, s48
	v_lshl_add_u64 v[248:249], s[42:43], 0, v[164:165]
	ds_read_b128 v[212:215], v158 offset:32768
	ds_read_b128 v[216:219], v158 offset:33792
	ds_read_b128 v[220:223], v158 offset:34816
	ds_read_b128 v[224:227], v158 offset:35840
	ds_read_b128 v[228:231], v158 offset:36864
	ds_read_b128 v[232:235], v158 offset:37888
	ds_read_b128 v[236:239], v158 offset:38912
	ds_read_b128 v[240:243], v158 offset:39936
	global_load_lds_dwordx4 v[248:249], off
	v_lshl_add_u64 v[248:249], s[42:43], 0, v[168:169]
	s_mov_b32 m0, s49
	s_nop 0
	global_load_lds_dwordx4 v[248:249], off
	s_waitcnt vmcnt(8)
	s_waitcnt lgkmcnt(0)
	s_barrier
	s_setprio 1
	s_waitcnt lgkmcnt(0)
	v_mfma_f32_16x16x32_bf16 v[124:127], v[136:139], v[212:215], v[124:127]
	v_mfma_f32_16x16x32_bf16 v[124:127], v[140:143], v[216:219], v[124:127]
	v_mfma_f32_16x16x32_bf16 v[108:111], v[140:143], v[224:227], v[108:111]
	v_mfma_f32_16x16x32_bf16 v[108:111], v[136:139], v[220:223], v[108:111]
	v_mfma_f32_16x16x32_bf16 v[96:99], v[136:139], v[228:231], v[96:99]
	v_mfma_f32_16x16x32_bf16 v[96:99], v[140:143], v[232:235], v[96:99]
	v_mfma_f32_16x16x32_bf16 v[80:83], v[140:143], v[240:243], v[80:83]
	v_mfma_f32_16x16x32_bf16 v[80:83], v[136:139], v[236:239], v[80:83]
	v_mfma_f32_16x16x32_bf16 v[72:75], v[172:175], v[236:239], v[72:75]
	v_mfma_f32_16x16x32_bf16 v[72:75], v[176:179], v[240:243], v[72:75]
	v_mfma_f32_16x16x32_bf16 v[88:91], v[176:179], v[232:235], v[88:91]
	v_mfma_f32_16x16x32_bf16 v[88:91], v[172:175], v[228:231], v[88:91]
	v_mfma_f32_16x16x32_bf16 v[104:107], v[172:175], v[220:223], v[104:107]
	v_mfma_f32_16x16x32_bf16 v[104:107], v[176:179], v[224:227], v[104:107]
	v_mfma_f32_16x16x32_bf16 v[120:123], v[176:179], v[216:219], v[120:123]
	v_mfma_f32_16x16x32_bf16 v[120:123], v[172:175], v[212:215], v[120:123]
	s_setprio 0
	s_setprio 1
	v_mfma_f32_16x16x32_bf16 v[116:119], v[180:183], v[212:215], v[116:119]
	v_mfma_f32_16x16x32_bf16 v[116:119], v[184:187], v[216:219], v[116:119]
	v_mfma_f32_16x16x32_bf16 v[100:103], v[184:187], v[224:227], v[100:103]
	v_mfma_f32_16x16x32_bf16 v[100:103], v[180:183], v[220:223], v[100:103]
	v_mfma_f32_16x16x32_bf16 v[84:87], v[180:183], v[228:231], v[84:87]
	v_mfma_f32_16x16x32_bf16 v[84:87], v[184:187], v[232:235], v[84:87]
	v_mfma_f32_16x16x32_bf16 v[68:71], v[184:187], v[240:243], v[68:71]
	v_mfma_f32_16x16x32_bf16 v[68:71], v[180:183], v[236:239], v[68:71]
	v_mfma_f32_16x16x32_bf16 v[64:67], v[196:199], v[236:239], v[64:67]
	v_mfma_f32_16x16x32_bf16 v[64:67], v[208:211], v[240:243], v[64:67]
	v_mfma_f32_16x16x32_bf16 v[76:79], v[208:211], v[232:235], v[76:79]
	v_mfma_f32_16x16x32_bf16 v[76:79], v[196:199], v[228:231], v[76:79]
	v_mfma_f32_16x16x32_bf16 v[92:95], v[196:199], v[220:223], v[92:95]
	v_mfma_f32_16x16x32_bf16 v[92:95], v[208:211], v[224:227], v[92:95]
	s_setprio 2
	s_barrier
; #define PG8_STAGE(bufoff, gbase, voff) do { _Pragma("unroll") for (int _i = 0; _i < 2; ++_i) \
;         __builtin_amdgcn_global_load_lds((const unsigned*)((const char*)(gbase) + (voff)[_i]), (PG8_LAS unsigned*)(lds + (bufoff) + ldsw + _i * 8192), 16, 0, 0); } while (0)
; #define PG8_LDA(dst, b, h) do { _Pragma("unroll") for (int m = 0; m < 4; ++m) _Pragma("unroll") for (int k = 0; k < 2; ++k) dst[m][k] = *(const PG8_LAS bf16x8*)(lds + PG8_SA(b, h) + aoff + m * 2048 + k * 1024); } while (0)
; #define PG8_LDB(dst, b, h) do { _Pragma("unroll") for (int n = 0; n < 2; ++n) _Pragma("unroll") for (int k = 0; k < 2; ++k) dst[n][k] = *(const PG8_LAS bf16x8*)(lds + PG8_SB(b, h) + boff + n * 2048 + k * 1024); } while (0)
; #define PG8_MMA(ai, bj, At, Bt) do { __builtin_amdgcn_s_setprio(1); _Pragma("unroll") for (int m = 0; m < 4; ++m) _Pragma("unroll") for (int n = 0; n < 2; ++n) _Pragma("unroll") for (int k = 0; k < 2; ++k) \
;         acc[ai][bj][m][n] = __builtin_amdgcn_mfma_f32_16x16x32_bf16(Bt[n][k], At[m][k], acc[ai][bj][m][n], 0, 0, 0); __builtin_amdgcn_s_setprio(0); } while (0)
; #define PG8_WAIT_V(n) asm volatile("s_waitcnt vmcnt(" #n ")" ::: "memory")
; template <class Epi, class Sched, bool ALIGN_EPI = false, bool SP2 = false>
; __device__ __forceinline__ void gemm_phase(PG8_LAS unsigned char* lds, const Gemm g, const Sched& S, const Epi& E) {
;     ...
;             PG8_LDB(B0, 0, 0); PG8_LDB(B1, 0, 1); PG8_SCHED; PG8_LDA(At, 0, 0); PG8_STAGE(PG8_SA(1, 1), a1 + hstep, voffA);
;             PG8_WAIT_V(8); PG8_WAIT_L(0); PG8_BAR; PG8_MMA(0, 0, At, B0); PG8_MMA(0, 1, At, B1); PG8_BAR; PG8_SCHED;
;             PG8_LDA(At, 0, 1); PG8_STAGE(PG8_SB(0, 0), b2, voffB); PG8_STAGE(PG8_SB(0, 1), b2 + hstep, voffB); PG8_STAGE(PG8_SA(0, 0), a2, voffA);
;             PG8_WAIT_V(8); PG8_WAIT_L(0); PG8_BAR; PG8_MMA(1, 0, At, B0); PG8_MMA(1, 1, At, B1); PG8_BAR; PG8_SCHED;
;             PG8_LDB(B0, 1, 0); PG8_LDB(B1, 1, 1); PG8_SCHED; PG8_LDA(At, 1, 0); PG8_STAGE(PG8_SA(0, 1), a2 + hstep, voffA);
;             PG8_WAIT_V(8); PG8_WAIT_L(0); PG8_BAR; PG8_MMA(0, 0, At, B0); PG8_MMA(0, 1, At, B1); PG8_BAR; PG8_SCHED;
;             PG8_LDA(At, 1, 1); PG8_STAGE(PG8_SB(1, 0), b3, voffB); PG8_STAGE(PG8_SB(1, 1), b3 + hstep, voffB); PG8_STAGE(PG8_SA(1, 0), a3, voffA);
;             PG8_WAIT_V(8); PG8_WAIT_L(0); PG8_BAR; PG8_MMA(1, 0, At, B0); PG8_MMA(1, 1, At, B1); PG8_BAR; PG8_SCHED;
	v_mfma_f32_16x16x32_bf16 v[112:115], v[208:211], v[216:219], v[112:115]
	v_mfma_f32_16x16x32_bf16 v[112:115], v[196:199], v[212:215], v[112:115]
	s_setprio 0
	s_add_i32 s42, s44, s33
	v_lshl_add_u64 v[188:189], v[188:189], 0, s[14:15]
	s_mov_b32 m0, s42
	ds_read_b128 v[212:215], v158 offset:49152
	ds_read_b128 v[216:219], v158 offset:50176
	ds_read_b128 v[220:223], v158 offset:51200
	ds_read_b128 v[224:227], v158 offset:52224
	ds_read_b128 v[228:231], v158 offset:53248
	ds_read_b128 v[232:235], v158 offset:54272
	ds_read_b128 v[236:239], v158 offset:55296
	ds_read_b128 v[240:243], v158 offset:56320
	global_load_lds_dwordx4 v[188:189], off
	s_add_i32 m0, s42, 0x2000
	s_add_u32 s40, s40, 0x80080
	v_lshl_add_u64 v[188:189], v[200:201], 0, s[14:15]
	s_addc_u32 s41, s41, 0
	s_add_i32 s42, s45, s33
	global_load_lds_dwordx4 v[188:189], off
	v_lshl_add_u64 v[188:189], s[40:41], 0, v[166:167]
	s_mov_b32 m0, s42
	s_nop 0
	global_load_lds_dwordx4 v[188:189], off
	v_lshl_add_u64 v[188:189], s[40:41], 0, v[170:171]
	s_add_i32 m0, s42, 0x2000
	s_nop 0
	global_load_lds_dwordx4 v[188:189], off
	v_lshl_add_u64 v[188:189], v[244:245], 0, s[14:15]
	s_mov_b32 m0, s50
	s_nop 0
	global_load_lds_dwordx4 v[188:189], off
	v_lshl_add_u64 v[188:189], v[246:247], 0, s[14:15]
	s_mov_b32 m0, s51
	s_nop 0
	global_load_lds_dwordx4 v[188:189], off
	s_waitcnt vmcnt(8)
	s_waitcnt lgkmcnt(0)
	s_barrier
	s_setprio 1
	s_waitcnt lgkmcnt(0)
	v_mfma_f32_16x16x32_bf16 v[60:63], v[136:139], v[212:215], v[60:63]
	v_mfma_f32_16x16x32_bf16 v[60:63], v[140:143], v[216:219], v[60:63]
	v_mfma_f32_16x16x32_bf16 v[48:51], v[140:143], v[224:227], v[48:51]
	v_mfma_f32_16x16x32_bf16 v[48:51], v[136:139], v[220:223], v[48:51]
	v_mfma_f32_16x16x32_bf16 v[32:35], v[136:139], v[228:231], v[32:35]
	v_mfma_f32_16x16x32_bf16 v[32:35], v[140:143], v[232:235], v[32:35]
	v_mfma_f32_16x16x32_bf16 v[12:15], v[140:143], v[240:243], v[12:15]
	v_mfma_f32_16x16x32_bf16 v[12:15], v[136:139], v[236:239], v[12:15]
	v_mfma_f32_16x16x32_bf16 v[8:11], v[172:175], v[236:239], v[8:11]
	v_mfma_f32_16x16x32_bf16 v[8:11], v[176:179], v[240:243], v[8:11]
	v_mfma_f32_16x16x32_bf16 v[24:27], v[176:179], v[232:235], v[24:27]
	v_mfma_f32_16x16x32_bf16 v[24:27], v[172:175], v[228:231], v[24:27]
	v_mfma_f32_16x16x32_bf16 v[40:43], v[172:175], v[220:223], v[40:43]
	v_mfma_f32_16x16x32_bf16 v[40:43], v[176:179], v[224:227], v[40:43]
	v_mfma_f32_16x16x32_bf16 v[56:59], v[176:179], v[216:219], v[56:59]
	v_mfma_f32_16x16x32_bf16 v[56:59], v[172:175], v[212:215], v[56:59]
	s_setprio 0
	s_setprio 1
	v_mfma_f32_16x16x32_bf16 v[52:55], v[180:183], v[212:215], v[52:55]
	v_mfma_f32_16x16x32_bf16 v[52:55], v[184:187], v[216:219], v[52:55]
	v_mfma_f32_16x16x32_bf16 v[36:39], v[184:187], v[224:227], v[36:39]
	v_mfma_f32_16x16x32_bf16 v[36:39], v[180:183], v[220:223], v[36:39]
	v_mfma_f32_16x16x32_bf16 v[20:23], v[180:183], v[228:231], v[20:23]
	v_mfma_f32_16x16x32_bf16 v[20:23], v[184:187], v[232:235], v[20:23]
	v_mfma_f32_16x16x32_bf16 v[4:7], v[184:187], v[240:243], v[4:7]
	v_mfma_f32_16x16x32_bf16 v[4:7], v[180:183], v[236:239], v[4:7]
	v_mfma_f32_16x16x32_bf16 v[0:3], v[196:199], v[236:239], v[0:3]
	v_mfma_f32_16x16x32_bf16 v[0:3], v[208:211], v[240:243], v[0:3]
	v_mfma_f32_16x16x32_bf16 v[16:19], v[208:211], v[232:235], v[16:19]
	v_mfma_f32_16x16x32_bf16 v[16:19], v[196:199], v[228:231], v[16:19]
	v_mfma_f32_16x16x32_bf16 v[28:31], v[196:199], v[220:223], v[28:31]
	v_mfma_f32_16x16x32_bf16 v[28:31], v[208:211], v[224:227], v[28:31]
	s_setprio 2
	s_barrier
	v_mfma_f32_16x16x32_bf16 v[44:47], v[208:211], v[216:219], v[44:47]
	v_mfma_f32_16x16x32_bf16 v[44:47], v[196:199], v[212:215], v[44:47]
	s_setprio 0
	s_add_i32 s63, s63, 2
	s_add_u32 s38, s38, 0x100
	s_addc_u32 s39, s39, 0
	s_add_u32 s61, s61, 0x100
	s_addc_u32 s62, s62, 0
	s_cmp_gt_u32 s63, 29
	s_cbranch_scc0 .LBB0_880
	s_and_b64 vcc, exec, s[16:17]
	s_cbranch_vccz .LBB0_883
	s_barrier

; #define PG8_STAGE(bufoff, gbase, voff) do { _Pragma("unroll") for (int _i = 0; _i < 2; ++_i) \
;         __builtin_amdgcn_global_load_lds((const unsigned*)((const char*)(gbase) + (voff)[_i]), (PG8_LAS unsigned*)(lds + (bufoff) + ldsw + _i * 8192), 16, 0, 0); } while (0)
; #define PG8_LDA(dst, b, h) do { _Pragma("unroll") for (int m = 0; m < 4; ++m) _Pragma("unroll") for (int k = 0; k < 2; ++k) dst[m][k] = *(const PG8_LAS bf16x8*)(lds + PG8_SA(b, h) + aoff + m * 2048 + k * 1024); } while (0)
; #define PG8_LDB(dst, b, h) do { _Pragma("unroll") for (int n = 0; n < 2; ++n) _Pragma("unroll") for (int k = 0; k < 2; ++k) dst[n][k] = *(const PG8_LAS bf16x8*)(lds + PG8_SB(b, h) + boff + n * 2048 + k * 1024); } while (0)
; #define PG8_MMA(ai, bj, At, Bt) do { __builtin_amdgcn_s_setprio(1); _Pragma("unroll") for (int m = 0; m < 4; ++m) _Pragma("unroll") for (int n = 0; n < 2; ++n) _Pragma("unroll") for (int k = 0; k < 2; ++k) \
;         acc[ai][bj][m][n] = __builtin_amdgcn_mfma_f32_16x16x32_bf16(Bt[n][k], At[m][k], acc[ai][bj][m][n], 0, 0, 0); __builtin_amdgcn_s_setprio(0); } while (0)
; #define PG8_WAIT_V(n) asm volatile("s_waitcnt vmcnt(" #n ")" ::: "memory")
; template <class Epi, class Sched, bool ALIGN_EPI = false, bool SP2 = false>
; __device__ __forceinline__ void gemm_phase(PG8_LAS unsigned char* lds, const Gemm g, const Sched& S, const Epi& E) {
;     ...
;             PG8_LDB(B0, 0, 0); PG8_LDB(B1, 0, 1); PG8_SCHED; PG8_LDA(At, 0, 0); PG8_STAGE(PG8_SA(1, 1), a1 + hstep, voffA);
;             PG8_WAIT_V(8); PG8_WAIT_L(0); PG8_BAR; PG8_MMA(0, 0, At, B0); PG8_MMA(0, 1, At, B1); PG8_BAR; PG8_SCHED;
;             PG8_LDA(At, 0, 1); PG8_STAGE(PG8_SB(0, 0), b2, voffB); PG8_STAGE(PG8_SB(0, 1), b2 + hstep, voffB); PG8_STAGE(PG8_SA(0, 0), a2, voffA);
;             PG8_WAIT_V(8); PG8_WAIT_L(0); PG8_BAR; PG8_MMA(1, 0, At, B0); PG8_MMA(1, 1, At, B1); PG8_BAR; PG8_SCHED;
;             PG8_LDB(B0, 1, 0); PG8_LDB(B1, 1, 1); PG8_SCHED; PG8_LDA(At, 1, 0); PG8_STAGE(PG8_SA(0, 1), a2 + hstep, voffA);
;             PG8_WAIT_V(8); PG8_WAIT_L(0); PG8_BAR; PG8_MMA(0, 0, At, B0); PG8_MMA(0, 1, At, B1); PG8_BAR; PG8_SCHED;
;             PG8_LDA(At, 1, 1); PG8_STAGE(PG8_SB(1, 0), b3, voffB); PG8_STAGE(PG8_SB(1, 1), b3 + hstep, voffB); PG8_STAGE(PG8_SA(1, 0), a3, voffA);
;             PG8_WAIT_V(8); PG8_WAIT_L(0); PG8_BAR; PG8_MMA(1, 0, At, B0); PG8_MMA(1, 1, At, B1); PG8_BAR; PG8_SCHED;
.LBB0_937:
	ds_read_b128 v[128:131], v199
	ds_read_b128 v[132:135], v199 offset:1024
	ds_read_b128 v[136:139], v199 offset:2048
	ds_read_b128 v[140:143], v199 offset:3072
	ds_read_b128 v[150:153], v200
	ds_read_b128 v[154:157], v200 offset:1024
	ds_read_b128 v[164:167], v200 offset:2048
	ds_read_b128 v[168:171], v200 offset:3072
	s_add_u32 s22, s20, 0xffea0080
	s_addc_u32 s23, s21, -1
	s_cmpk_eq_i32 s49, 0x54
	s_cselect_b32 s25, s17, s23
	s_cselect_b32 s24, s16, s22
	s_cselect_b32 s23, s19, s48
	s_cselect_b32 s22, s18, s47
	v_lshl_add_u64 v[158:159], s[20:21], 0, v[144:145]
	s_add_i32 m0, s31, 0xc000
	ds_read_b128 v[172:175], v201
	ds_read_b128 v[176:179], v201 offset:1024
	ds_read_b128 v[180:183], v201 offset:2048
	ds_read_b128 v[184:187], v201 offset:3072
	ds_read_b128 v[188:191], v201 offset:4096
	ds_read_b128 v[204:207], v201 offset:5120
	ds_read_b128 v[208:211], v201 offset:6144
	ds_read_b128 v[212:215], v201 offset:7168
	global_load_lds_dwordx4 v[158:159], off
	v_lshl_add_u64 v[158:159], s[20:21], 0, v[146:147]
	s_add_i32 m0, s31, 0xe000
	s_nop 0
	global_load_lds_dwordx4 v[158:159], off
	s_waitcnt vmcnt(8)
	s_waitcnt lgkmcnt(0)
	s_barrier
	s_setprio 1
	s_waitcnt lgkmcnt(0)
	v_mfma_f32_16x16x32_bf16 v[124:127], v[128:131], v[172:175], v[124:127]
	v_mfma_f32_16x16x32_bf16 v[124:127], v[132:135], v[176:179], v[124:127]
	v_mfma_f32_16x16x32_bf16 v[108:111], v[132:135], v[184:187], v[108:111]
	v_mfma_f32_16x16x32_bf16 v[108:111], v[128:131], v[180:183], v[108:111]
	v_mfma_f32_16x16x32_bf16 v[92:95], v[128:131], v[188:191], v[92:95]
	v_mfma_f32_16x16x32_bf16 v[92:95], v[132:135], v[204:207], v[92:95]
	v_mfma_f32_16x16x32_bf16 v[76:79], v[132:135], v[212:215], v[76:79]
	v_mfma_f32_16x16x32_bf16 v[76:79], v[128:131], v[208:211], v[76:79]
	v_mfma_f32_16x16x32_bf16 v[72:75], v[136:139], v[208:211], v[72:75]
	v_mfma_f32_16x16x32_bf16 v[72:75], v[140:143], v[212:215], v[72:75]
	v_mfma_f32_16x16x32_bf16 v[88:91], v[140:143], v[204:207], v[88:91]
	v_mfma_f32_16x16x32_bf16 v[88:91], v[136:139], v[188:191], v[88:91]
	v_mfma_f32_16x16x32_bf16 v[104:107], v[136:139], v[180:183], v[104:107]
	v_mfma_f32_16x16x32_bf16 v[104:107], v[140:143], v[184:187], v[104:107]
	v_mfma_f32_16x16x32_bf16 v[120:123], v[140:143], v[176:179], v[120:123]
	v_mfma_f32_16x16x32_bf16 v[120:123], v[136:139], v[172:175], v[120:123]
	s_setprio 0
	s_setprio 1
	v_mfma_f32_16x16x32_bf16 v[116:119], v[150:153], v[172:175], v[116:119]
	v_mfma_f32_16x16x32_bf16 v[116:119], v[154:157], v[176:179], v[116:119]
	v_mfma_f32_16x16x32_bf16 v[100:103], v[154:157], v[184:187], v[100:103]
	v_mfma_f32_16x16x32_bf16 v[100:103], v[150:153], v[180:183], v[100:103]
	v_mfma_f32_16x16x32_bf16 v[84:87], v[150:153], v[188:191], v[84:87]
	v_mfma_f32_16x16x32_bf16 v[84:87], v[154:157], v[204:207], v[84:87]
	v_mfma_f32_16x16x32_bf16 v[68:71], v[154:157], v[212:215], v[68:71]
	v_mfma_f32_16x16x32_bf16 v[68:71], v[150:153], v[208:211], v[68:71]
	v_mfma_f32_16x16x32_bf16 v[64:67], v[164:167], v[208:211], v[64:67]
	v_mfma_f32_16x16x32_bf16 v[64:67], v[168:171], v[212:215], v[64:67]
	v_mfma_f32_16x16x32_bf16 v[80:83], v[168:171], v[204:207], v[80:83]
	v_mfma_f32_16x16x32_bf16 v[80:83], v[164:167], v[188:191], v[80:83]
	v_mfma_f32_16x16x32_bf16 v[96:99], v[164:167], v[180:183], v[96:99]
	v_mfma_f32_16x16x32_bf16 v[96:99], v[168:171], v[184:187], v[96:99]
	s_setprio 2
	s_barrier
	v_mfma_f32_16x16x32_bf16 v[112:115], v[168:171], v[176:179], v[112:115]
	v_mfma_f32_16x16x32_bf16 v[112:115], v[164:167], v[172:175], v[112:115]
	s_setprio 0
	s_add_i32 s50, s41, s30
	v_lshl_add_u64 v[158:159], s[22:23], 0, v[160:161]
	s_mov_b32 m0, s50
	ds_read_b128 v[172:175], v201 offset:16384
	ds_read_b128 v[176:179], v201 offset:17408
	ds_read_b128 v[180:183], v201 offset:18432
	ds_read_b128 v[184:187], v201 offset:19456
	ds_read_b128 v[188:191], v201 offset:20480
	ds_read_b128 v[204:207], v201 offset:21504
	ds_read_b128 v[208:211], v201 offset:22528
	ds_read_b128 v[212:215], v201 offset:23552
	global_load_lds_dwordx4 v[158:159], off
	s_add_i32 m0, s50, 0x2000
	s_add_u32 s50, s22, 0x160000
	v_lshl_add_u64 v[192:193], s[22:23], 0, v[162:163]
	s_addc_u32 s51, s23, 0
	s_add_i32 s52, s42, s30
	global_load_lds_dwordx4 v[192:193], off
	v_lshl_add_u64 v[216:217], s[50:51], 0, v[160:161]
	s_mov_b32 m0, s52
	v_lshl_add_u64 v[218:219], s[24:25], 0, v[162:163]
	global_load_lds_dwordx4 v[216:217], off
	v_lshl_add_u64 v[216:217], s[50:51], 0, v[162:163]
	s_add_i32 m0, s52, 0x2000
	s_nop 0
	global_load_lds_dwordx4 v[216:217], off
	v_lshl_add_u64 v[216:217], s[24:25], 0, v[160:161]
	s_mov_b32 m0, s31
	s_nop 0
	global_load_lds_dwordx4 v[216:217], off
	s_mov_b32 m0, s33
	s_nop 0
	global_load_lds_dwordx4 v[218:219], off
	s_waitcnt vmcnt(8)
	s_waitcnt lgkmcnt(0)
	s_barrier
; #define PG8_STAGE(bufoff, gbase, voff) do { _Pragma("unroll") for (int _i = 0; _i < 2; ++_i) \
;         __builtin_amdgcn_global_load_lds((const unsigned*)((const char*)(gbase) + (voff)[_i]), (PG8_LAS unsigned*)(lds + (bufoff) + ldsw + _i * 8192), 16, 0, 0); } while (0)
; #define PG8_LDA(dst, b, h) do { _Pragma("unroll") for (int m = 0; m < 4; ++m) _Pragma("unroll") for (int k = 0; k < 2; ++k) dst[m][k] = *(const PG8_LAS bf16x8*)(lds + PG8_SA(b, h) + aoff + m * 2048 + k * 1024); } while (0)
; #define PG8_LDB(dst, b, h) do { _Pragma("unroll") for (int n = 0; n < 2; ++n) _Pragma("unroll") for (int k = 0; k < 2; ++k) dst[n][k] = *(const PG8_LAS bf16x8*)(lds + PG8_SB(b, h) + boff + n * 2048 + k * 1024); } while (0)
; #define PG8_MMA(ai, bj, At, Bt) do { __builtin_amdgcn_s_setprio(1); _Pragma("unroll") for (int m = 0; m < 4; ++m) _Pragma("unroll") for (int n = 0; n < 2; ++n) _Pragma("unroll") for (int k = 0; k < 2; ++k) \
;         acc[ai][bj][m][n] = __builtin_amdgcn_mfma_f32_16x16x32_bf16(Bt[n][k], At[m][k], acc[ai][bj][m][n], 0, 0, 0); __builtin_amdgcn_s_setprio(0); } while (0)
; #define PG8_WAIT_V(n) asm volatile("s_waitcnt vmcnt(" #n ")" ::: "memory")
; template <class Epi, class Sched, bool ALIGN_EPI = false, bool SP2 = false>
; __device__ __forceinline__ void gemm_phase(PG8_LAS unsigned char* lds, const Gemm g, const Sched& S, const Epi& E) {
;     ...
;             PG8_LDB(B0, 0, 0); PG8_LDB(B1, 0, 1); PG8_SCHED; PG8_LDA(At, 0, 0); PG8_STAGE(PG8_SA(1, 1), a1 + hstep, voffA);
;             PG8_WAIT_V(8); PG8_WAIT_L(0); PG8_BAR; PG8_MMA(0, 0, At, B0); PG8_MMA(0, 1, At, B1); PG8_BAR; PG8_SCHED;
;             PG8_LDA(At, 0, 1); PG8_STAGE(PG8_SB(0, 0), b2, voffB); PG8_STAGE(PG8_SB(0, 1), b2 + hstep, voffB); PG8_STAGE(PG8_SA(0, 0), a2, voffA);
;             PG8_WAIT_V(8); PG8_WAIT_L(0); PG8_BAR; PG8_MMA(1, 0, At, B0); PG8_MMA(1, 1, At, B1); PG8_BAR; PG8_SCHED;
;             PG8_LDB(B0, 1, 0); PG8_LDB(B1, 1, 1); PG8_SCHED; PG8_LDA(At, 1, 0); PG8_STAGE(PG8_SA(0, 1), a2 + hstep, voffA);
;             PG8_WAIT_V(8); PG8_WAIT_L(0); PG8_BAR; PG8_MMA(0, 0, At, B0); PG8_MMA(0, 1, At, B1); PG8_BAR; PG8_SCHED;
;             PG8_LDA(At, 1, 1); PG8_STAGE(PG8_SB(1, 0), b3, voffB); PG8_STAGE(PG8_SB(1, 1), b3 + hstep, voffB); PG8_STAGE(PG8_SA(1, 0), a3, voffA);
;             PG8_WAIT_V(8); PG8_WAIT_L(0); PG8_BAR; PG8_MMA(1, 0, At, B0); PG8_MMA(1, 1, At, B1); PG8_BAR; PG8_SCHED;
	s_setprio 1
	s_waitcnt lgkmcnt(0)
	v_mfma_f32_16x16x32_bf16 v[60:63], v[128:131], v[172:175], v[60:63]
	v_mfma_f32_16x16x32_bf16 v[60:63], v[132:135], v[176:179], v[60:63]
	v_mfma_f32_16x16x32_bf16 v[44:47], v[132:135], v[184:187], v[44:47]
	v_mfma_f32_16x16x32_bf16 v[44:47], v[128:131], v[180:183], v[44:47]
	v_mfma_f32_16x16x32_bf16 v[28:31], v[128:131], v[188:191], v[28:31]
	v_mfma_f32_16x16x32_bf16 v[28:31], v[132:135], v[204:207], v[28:31]
	v_mfma_f32_16x16x32_bf16 v[12:15], v[132:135], v[212:215], v[12:15]
	v_mfma_f32_16x16x32_bf16 v[12:15], v[128:131], v[208:211], v[12:15]
	v_mfma_f32_16x16x32_bf16 v[8:11], v[136:139], v[208:211], v[8:11]
	v_mfma_f32_16x16x32_bf16 v[8:11], v[140:143], v[212:215], v[8:11]
	v_mfma_f32_16x16x32_bf16 v[24:27], v[140:143], v[204:207], v[24:27]
	v_mfma_f32_16x16x32_bf16 v[24:27], v[136:139], v[188:191], v[24:27]
	v_mfma_f32_16x16x32_bf16 v[40:43], v[136:139], v[180:183], v[40:43]
	v_mfma_f32_16x16x32_bf16 v[40:43], v[140:143], v[184:187], v[40:43]
	v_mfma_f32_16x16x32_bf16 v[56:59], v[140:143], v[176:179], v[56:59]
	v_mfma_f32_16x16x32_bf16 v[56:59], v[136:139], v[172:175], v[56:59]
	s_setprio 0
	s_setprio 1
	v_mfma_f32_16x16x32_bf16 v[52:55], v[150:153], v[172:175], v[52:55]
	v_mfma_f32_16x16x32_bf16 v[52:55], v[154:157], v[176:179], v[52:55]
	v_mfma_f32_16x16x32_bf16 v[36:39], v[154:157], v[184:187], v[36:39]
	v_mfma_f32_16x16x32_bf16 v[36:39], v[150:153], v[180:183], v[36:39]
	v_mfma_f32_16x16x32_bf16 v[20:23], v[150:153], v[188:191], v[20:23]
	v_mfma_f32_16x16x32_bf16 v[20:23], v[154:157], v[204:207], v[20:23]
	v_mfma_f32_16x16x32_bf16 v[4:7], v[154:157], v[212:215], v[4:7]
	v_mfma_f32_16x16x32_bf16 v[4:7], v[150:153], v[208:211], v[4:7]
	v_mfma_f32_16x16x32_bf16 v[0:3], v[164:167], v[208:211], v[0:3]
	v_mfma_f32_16x16x32_bf16 v[0:3], v[168:171], v[212:215], v[0:3]
	v_mfma_f32_16x16x32_bf16 v[16:19], v[168:171], v[204:207], v[16:19]
	v_mfma_f32_16x16x32_bf16 v[16:19], v[164:167], v[188:191], v[16:19]
	v_mfma_f32_16x16x32_bf16 v[32:35], v[164:167], v[180:183], v[32:35]
	v_mfma_f32_16x16x32_bf16 v[32:35], v[168:171], v[184:187], v[32:35]
	s_setprio 2
	s_barrier
	v_mfma_f32_16x16x32_bf16 v[48:51], v[168:171], v[176:179], v[48:51]
	v_mfma_f32_16x16x32_bf16 v[48:51], v[164:167], v[172:175], v[48:51]
	s_setprio 0
	s_add_i32 s50, 0, 0x18000
	s_add_i32 s51, 0, 0x1c000
	v_add_u32_e32 v140, s50, v196
	v_add_u32_e32 v168, s51, v196
	ds_read_b128 v[128:131], v140
	ds_read_b128 v[132:135], v140 offset:1024
	ds_read_b128 v[136:139], v140 offset:2048
	ds_read_b128 v[140:143], v140 offset:3072
	ds_read_b128 v[150:153], v168
	ds_read_b128 v[154:157], v168 offset:1024
	ds_read_b128 v[164:167], v168 offset:2048
	ds_read_b128 v[168:171], v168 offset:3072
	s_add_u32 s24, s24, 0x160000
	s_addc_u32 s25, s25, 0
	s_mov_b32 m0, s34
	v_lshl_add_u64 v[220:221], s[24:25], 0, v[160:161]
	ds_read_b128 v[172:175], v201 offset:32768
	ds_read_b128 v[176:179], v201 offset:33792
	ds_read_b128 v[180:183], v201 offset:34816
	ds_read_b128 v[184:187], v201 offset:35840
	ds_read_b128 v[188:191], v201 offset:36864
	ds_read_b128 v[204:207], v201 offset:37888
	ds_read_b128 v[208:211], v201 offset:38912
	ds_read_b128 v[212:215], v201 offset:39936
	global_load_lds_dwordx4 v[220:221], off
	v_lshl_add_u64 v[220:221], s[24:25], 0, v[162:163]
	s_mov_b32 m0, s35
	s_nop 0
	global_load_lds_dwordx4 v[220:221], off
	s_waitcnt vmcnt(8)
	s_waitcnt lgkmcnt(0)
	s_barrier
	s_setprio 1
	s_waitcnt lgkmcnt(0)
	v_mfma_f32_16x16x32_bf16 v[124:127], v[128:131], v[172:175], v[124:127]
	v_mfma_f32_16x16x32_bf16 v[124:127], v[132:135], v[176:179], v[124:127]
	v_mfma_f32_16x16x32_bf16 v[108:111], v[132:135], v[184:187], v[108:111]
	v_mfma_f32_16x16x32_bf16 v[108:111], v[128:131], v[180:183], v[108:111]
	v_mfma_f32_16x16x32_bf16 v[92:95], v[128:131], v[188:191], v[92:95]
	v_mfma_f32_16x16x32_bf16 v[92:95], v[132:135], v[204:207], v[92:95]
	v_mfma_f32_16x16x32_bf16 v[76:79], v[132:135], v[212:215], v[76:79]
	v_mfma_f32_16x16x32_bf16 v[76:79], v[128:131], v[208:211], v[76:79]
	v_mfma_f32_16x16x32_bf16 v[72:75], v[136:139], v[208:211], v[72:75]
	v_mfma_f32_16x16x32_bf16 v[72:75], v[140:143], v[212:215], v[72:75]
	v_mfma_f32_16x16x32_bf16 v[88:91], v[140:143], v[204:207], v[88:91]
	v_mfma_f32_16x16x32_bf16 v[88:91], v[136:139], v[188:191], v[88:91]
	v_mfma_f32_16x16x32_bf16 v[104:107], v[136:139], v[180:183], v[104:107]
	v_mfma_f32_16x16x32_bf16 v[104:107], v[140:143], v[184:187], v[104:107]
	v_mfma_f32_16x16x32_bf16 v[120:123], v[140:143], v[176:179], v[120:123]
	v_mfma_f32_16x16x32_bf16 v[120:123], v[136:139], v[172:175], v[120:123]
	s_setprio 0
	s_setprio 1
	v_mfma_f32_16x16x32_bf16 v[116:119], v[150:153], v[172:175], v[116:119]
	v_mfma_f32_16x16x32_bf16 v[116:119], v[154:157], v[176:179], v[116:119]
	v_mfma_f32_16x16x32_bf16 v[100:103], v[154:157], v[184:187], v[100:103]
	v_mfma_f32_16x16x32_bf16 v[100:103], v[150:153], v[180:183], v[100:103]
	v_mfma_f32_16x16x32_bf16 v[84:87], v[150:153], v[188:191], v[84:87]
	v_mfma_f32_16x16x32_bf16 v[84:87], v[154:157], v[204:207], v[84:87]
	v_mfma_f32_16x16x32_bf16 v[68:71], v[154:157], v[212:215], v[68:71]
	v_mfma_f32_16x16x32_bf16 v[68:71], v[150:153], v[208:211], v[68:71]
	v_mfma_f32_16x16x32_bf16 v[64:67], v[164:167], v[208:211], v[64:67]
	v_mfma_f32_16x16x32_bf16 v[64:67], v[168:171], v[212:215], v[64:67]
	v_mfma_f32_16x16x32_bf16 v[80:83], v[168:171], v[204:207], v[80:83]
	v_mfma_f32_16x16x32_bf16 v[80:83], v[164:167], v[188:191], v[80:83]
	v_mfma_f32_16x16x32_bf16 v[96:99], v[164:167], v[180:183], v[96:99]
	v_mfma_f32_16x16x32_bf16 v[96:99], v[168:171], v[184:187], v[96:99]
	s_setprio 2
	s_barrier
; #define PG8_STAGE(bufoff, gbase, voff) do { _Pragma("unroll") for (int _i = 0; _i < 2; ++_i) \
;         __builtin_amdgcn_global_load_lds((const unsigned*)((const char*)(gbase) + (voff)[_i]), (PG8_LAS unsigned*)(lds + (bufoff) + ldsw + _i * 8192), 16, 0, 0); } while (0)
; #define PG8_LDA(dst, b, h) do { _Pragma("unroll") for (int m = 0; m < 4; ++m) _Pragma("unroll") for (int k = 0; k < 2; ++k) dst[m][k] = *(const PG8_LAS bf16x8*)(lds + PG8_SA(b, h) + aoff + m * 2048 + k * 1024); } while (0)
; #define PG8_LDB(dst, b, h) do { _Pragma("unroll") for (int n = 0; n < 2; ++n) _Pragma("unroll") for (int k = 0; k < 2; ++k) dst[n][k] = *(const PG8_LAS bf16x8*)(lds + PG8_SB(b, h) + boff + n * 2048 + k * 1024); } while (0)
; #define PG8_MMA(ai, bj, At, Bt) do { __builtin_amdgcn_s_setprio(1); _Pragma("unroll") for (int m = 0; m < 4; ++m) _Pragma("unroll") for (int n = 0; n < 2; ++n) _Pragma("unroll") for (int k = 0; k < 2; ++k) \
;         acc[ai][bj][m][n] = __builtin_amdgcn_mfma_f32_16x16x32_bf16(Bt[n][k], At[m][k], acc[ai][bj][m][n], 0, 0, 0); __builtin_amdgcn_s_setprio(0); } while (0)
; #define PG8_WAIT_V(n) asm volatile("s_waitcnt vmcnt(" #n ")" ::: "memory")
; template <class Epi, class Sched, bool ALIGN_EPI = false, bool SP2 = false>
; __device__ __forceinline__ void gemm_phase(PG8_LAS unsigned char* lds, const Gemm g, const Sched& S, const Epi& E) {
;     ...
;             PG8_LDB(B0, 0, 0); PG8_LDB(B1, 0, 1); PG8_SCHED; PG8_LDA(At, 0, 0); PG8_STAGE(PG8_SA(1, 1), a1 + hstep, voffA);
;             PG8_WAIT_V(8); PG8_WAIT_L(0); PG8_BAR; PG8_MMA(0, 0, At, B0); PG8_MMA(0, 1, At, B1); PG8_BAR; PG8_SCHED;
;             PG8_LDA(At, 0, 1); PG8_STAGE(PG8_SB(0, 0), b2, voffB); PG8_STAGE(PG8_SB(0, 1), b2 + hstep, voffB); PG8_STAGE(PG8_SA(0, 0), a2, voffA);
;             PG8_WAIT_V(8); PG8_WAIT_L(0); PG8_BAR; PG8_MMA(1, 0, At, B0); PG8_MMA(1, 1, At, B1); PG8_BAR; PG8_SCHED;
;             PG8_LDB(B0, 1, 0); PG8_LDB(B1, 1, 1); PG8_SCHED; PG8_LDA(At, 1, 0); PG8_STAGE(PG8_SA(0, 1), a2 + hstep, voffA);
;             PG8_WAIT_V(8); PG8_WAIT_L(0); PG8_BAR; PG8_MMA(0, 0, At, B0); PG8_MMA(0, 1, At, B1); PG8_BAR; PG8_SCHED;
;             PG8_LDA(At, 1, 1); PG8_STAGE(PG8_SB(1, 0), b3, voffB); PG8_STAGE(PG8_SB(1, 1), b3 + hstep, voffB); PG8_STAGE(PG8_SA(1, 0), a3, voffA);
;             PG8_WAIT_V(8); PG8_WAIT_L(0); PG8_BAR; PG8_MMA(1, 0, At, B0); PG8_MMA(1, 1, At, B1); PG8_BAR; PG8_SCHED;
	v_mfma_f32_16x16x32_bf16 v[112:115], v[168:171], v[176:179], v[112:115]
	v_mfma_f32_16x16x32_bf16 v[112:115], v[164:167], v[172:175], v[112:115]
	s_setprio 0
	s_add_i32 s24, s50, s30
	v_lshl_add_u64 v[158:159], v[158:159], 0, s[12:13]
	s_mov_b32 m0, s24
	ds_read_b128 v[172:175], v201 offset:49152
	ds_read_b128 v[176:179], v201 offset:50176
	ds_read_b128 v[180:183], v201 offset:51200
	ds_read_b128 v[184:187], v201 offset:52224
	ds_read_b128 v[188:191], v201 offset:53248
	ds_read_b128 v[204:207], v201 offset:54272
	ds_read_b128 v[208:211], v201 offset:55296
	ds_read_b128 v[212:215], v201 offset:56320
	global_load_lds_dwordx4 v[158:159], off
	s_add_i32 m0, s24, 0x2000
	s_add_u32 s22, s22, 0x160080
	v_lshl_add_u64 v[158:159], v[192:193], 0, s[12:13]
	s_addc_u32 s23, s23, 0
	s_add_i32 s24, s51, s30
	global_load_lds_dwordx4 v[158:159], off
	v_lshl_add_u64 v[158:159], s[22:23], 0, v[160:161]
	s_mov_b32 m0, s24
	s_nop 0
	global_load_lds_dwordx4 v[158:159], off
	v_lshl_add_u64 v[158:159], s[22:23], 0, v[162:163]
	s_add_i32 m0, s24, 0x2000
	s_nop 0
	global_load_lds_dwordx4 v[158:159], off
	v_lshl_add_u64 v[158:159], v[216:217], 0, s[12:13]
	s_mov_b32 m0, s39
	s_nop 0
	global_load_lds_dwordx4 v[158:159], off
	v_lshl_add_u64 v[158:159], v[218:219], 0, s[12:13]
	s_mov_b32 m0, s40
	s_nop 0
	global_load_lds_dwordx4 v[158:159], off
	s_waitcnt vmcnt(8)
	s_waitcnt lgkmcnt(0)
	s_barrier
	s_setprio 1
	s_waitcnt lgkmcnt(0)
	v_mfma_f32_16x16x32_bf16 v[60:63], v[128:131], v[172:175], v[60:63]
	v_mfma_f32_16x16x32_bf16 v[60:63], v[132:135], v[176:179], v[60:63]
	v_mfma_f32_16x16x32_bf16 v[44:47], v[132:135], v[184:187], v[44:47]
	v_mfma_f32_16x16x32_bf16 v[44:47], v[128:131], v[180:183], v[44:47]
	v_mfma_f32_16x16x32_bf16 v[28:31], v[128:131], v[188:191], v[28:31]
	v_mfma_f32_16x16x32_bf16 v[28:31], v[132:135], v[204:207], v[28:31]
	v_mfma_f32_16x16x32_bf16 v[12:15], v[132:135], v[212:215], v[12:15]
	v_mfma_f32_16x16x32_bf16 v[12:15], v[128:131], v[208:211], v[12:15]
	v_mfma_f32_16x16x32_bf16 v[8:11], v[136:139], v[208:211], v[8:11]
	v_mfma_f32_16x16x32_bf16 v[8:11], v[140:143], v[212:215], v[8:11]
	v_mfma_f32_16x16x32_bf16 v[24:27], v[140:143], v[204:207], v[24:27]
	v_mfma_f32_16x16x32_bf16 v[24:27], v[136:139], v[188:191], v[24:27]
	v_mfma_f32_16x16x32_bf16 v[40:43], v[136:139], v[180:183], v[40:43]
	v_mfma_f32_16x16x32_bf16 v[40:43], v[140:143], v[184:187], v[40:43]
	v_mfma_f32_16x16x32_bf16 v[56:59], v[140:143], v[176:179], v[56:59]
	v_mfma_f32_16x16x32_bf16 v[56:59], v[136:139], v[172:175], v[56:59]
	s_setprio 0
	s_setprio 1
	v_mfma_f32_16x16x32_bf16 v[52:55], v[150:153], v[172:175], v[52:55]
	v_mfma_f32_16x16x32_bf16 v[52:55], v[154:157], v[176:179], v[52:55]
	v_mfma_f32_16x16x32_bf16 v[36:39], v[154:157], v[184:187], v[36:39]
	v_mfma_f32_16x16x32_bf16 v[36:39], v[150:153], v[180:183], v[36:39]
	v_mfma_f32_16x16x32_bf16 v[20:23], v[150:153], v[188:191], v[20:23]
	v_mfma_f32_16x16x32_bf16 v[20:23], v[154:157], v[204:207], v[20:23]
	v_mfma_f32_16x16x32_bf16 v[4:7], v[154:157], v[212:215], v[4:7]
	v_mfma_f32_16x16x32_bf16 v[4:7], v[150:153], v[208:211], v[4:7]
	v_mfma_f32_16x16x32_bf16 v[0:3], v[164:167], v[208:211], v[0:3]
	v_mfma_f32_16x16x32_bf16 v[0:3], v[168:171], v[212:215], v[0:3]
	v_mfma_f32_16x16x32_bf16 v[16:19], v[168:171], v[204:207], v[16:19]
	v_mfma_f32_16x16x32_bf16 v[16:19], v[164:167], v[188:191], v[16:19]
	v_mfma_f32_16x16x32_bf16 v[32:35], v[164:167], v[180:183], v[32:35]
	v_mfma_f32_16x16x32_bf16 v[32:35], v[168:171], v[184:187], v[32:35]
	s_setprio 2
	s_barrier
	v_mfma_f32_16x16x32_bf16 v[48:51], v[168:171], v[176:179], v[48:51]
	v_mfma_f32_16x16x32_bf16 v[48:51], v[164:167], v[172:175], v[48:51]
	s_setprio 0
	s_add_i32 s49, s49, 2
	s_add_u32 s20, s20, 0x100
	s_addc_u32 s21, s21, 0
	s_add_u32 s47, s47, 0x100
	s_addc_u32 s48, s48, 0
	s_cmpk_gt_u32 s49, 0x55
	s_cbranch_scc0 .LBB0_937
	s_and_b64 vcc, exec, s[14:15]
	s_cbranch_vccz .LBB0_940
	s_barrier
